# GEMM K loops without the per-segment s_setprio toggles (416 instructions)
# speedup vs baseline: 1.0015x; 1.0015x over previous
.LBB0_271:
	s_ashr_i32 s37, s36, 31
	s_lshl_b64 s[38:39], s[36:37], 19
	s_add_u32 s38, s58, s38
	s_addc_u32 s39, s59, s39
	s_and_b64 s[40:41], s[4:5], exec
	s_cselect_b32 s37, s39, s61
	s_cselect_b32 s43, s38, s60
	s_ashr_i32 s35, s34, 31
	s_lshl_b64 s[40:41], s[34:35], 19
	s_add_u32 s40, s66, s40
	s_addc_u32 s41, s67, s41
	s_and_b64 s[64:65], s[4:5], exec
	s_cselect_b32 s35, s41, s63
	s_cselect_b32 s55, s40, s62
	s_add_u32 s60, s60, 0x40080
	s_addc_u32 s61, s61, 0
	s_add_u32 s84, s62, 0x100
	s_addc_u32 s85, s63, 0
	s_mov_b32 s86, -2
	ds_read_b128 v[146:149], v153
	ds_read_b128 v[156:159], v153 offset:1024
	ds_read_b128 v[160:163], v153 offset:2048
	ds_read_b128 v[164:167], v153 offset:3072
	ds_read_b128 v[168:171], v154
	ds_read_b128 v[172:175], v154 offset:1024
	ds_read_b128 v[176:179], v154 offset:2048
	ds_read_b128 v[180:183], v154 offset:3072
	s_add_u32 s62, s60, 0xfffc0080
	s_addc_u32 s63, s61, -1
	s_cmp_eq_u32 s86, 12
	s_cselect_b32 s65, s37, s63
	s_cselect_b32 s64, s43, s62
	s_cselect_b32 s63, s35, s85
	s_cselect_b32 s62, s55, s84
	s_add_i32 m0, s69, 0xc000
	ds_read_b128 v[184:187], v155
	ds_read_b128 v[192:195], v155 offset:1024
	ds_read_b128 v[196:199], v155 offset:2048
	ds_read_b128 v[200:203], v155 offset:3072
	ds_read_b128 v[204:207], v155 offset:4096
	ds_read_b128 v[208:211], v155 offset:5120
	ds_read_b128 v[212:215], v155 offset:6144
	ds_read_b128 v[216:219], v155 offset:7168
	global_load_lds_dwordx4 v138, s[60:61]
	v_lshl_add_u64 v[188:189], s[60:61], 0, v[140:141]
	s_add_i32 m0, s69, 0xe000
	s_nop 0
	global_load_lds_dwordx4 v[188:189], off
	s_waitcnt vmcnt(8)
	s_waitcnt lgkmcnt(0)
	s_barrier
	s_waitcnt lgkmcnt(0)
	v_mfma_f32_16x16x32_bf16 v[124:127], v[146:149], v[184:187], 0
	v_mfma_f32_16x16x32_bf16 v[120:123], v[160:163], v[184:187], 0
	v_mfma_f32_16x16x32_bf16 v[116:119], v[146:149], v[196:199], 0
	v_mfma_f32_16x16x32_bf16 v[108:111], v[160:163], v[196:199], 0
	v_mfma_f32_16x16x32_bf16 v[100:103], v[146:149], v[204:207], 0
	v_mfma_f32_16x16x32_bf16 v[92:95], v[160:163], v[204:207], 0
	v_mfma_f32_16x16x32_bf16 v[84:87], v[146:149], v[212:215], 0
	v_mfma_f32_16x16x32_bf16 v[76:79], v[160:163], v[212:215], 0
	v_mfma_f32_16x16x32_bf16 v[124:127], v[156:159], v[192:195], v[124:127]
	v_mfma_f32_16x16x32_bf16 v[120:123], v[164:167], v[192:195], v[120:123]
	v_mfma_f32_16x16x32_bf16 v[116:119], v[156:159], v[200:203], v[116:119]
	v_mfma_f32_16x16x32_bf16 v[108:111], v[164:167], v[200:203], v[108:111]
	v_mfma_f32_16x16x32_bf16 v[100:103], v[156:159], v[208:211], v[100:103]
	v_mfma_f32_16x16x32_bf16 v[92:95], v[164:167], v[208:211], v[92:95]
	v_mfma_f32_16x16x32_bf16 v[84:87], v[156:159], v[216:219], v[84:87]
	v_mfma_f32_16x16x32_bf16 v[76:79], v[164:167], v[216:219], v[76:79]
	v_mfma_f32_16x16x32_bf16 v[112:115], v[168:171], v[184:187], 0
	v_mfma_f32_16x16x32_bf16 v[104:107], v[176:179], v[184:187], 0
	v_mfma_f32_16x16x32_bf16 v[96:99], v[168:171], v[196:199], 0
	v_mfma_f32_16x16x32_bf16 v[88:91], v[176:179], v[196:199], 0
	v_mfma_f32_16x16x32_bf16 v[80:83], v[168:171], v[204:207], 0
	v_mfma_f32_16x16x32_bf16 v[72:75], v[176:179], v[204:207], 0
	v_mfma_f32_16x16x32_bf16 v[68:71], v[168:171], v[212:215], 0
	v_mfma_f32_16x16x32_bf16 v[64:67], v[176:179], v[212:215], 0
	v_mfma_f32_16x16x32_bf16 v[112:115], v[172:175], v[192:195], v[112:115]
	v_mfma_f32_16x16x32_bf16 v[104:107], v[180:183], v[192:195], v[104:107]
	v_mfma_f32_16x16x32_bf16 v[96:99], v[172:175], v[200:203], v[96:99]
	v_mfma_f32_16x16x32_bf16 v[88:91], v[180:183], v[200:203], v[88:91]
	v_mfma_f32_16x16x32_bf16 v[80:83], v[172:175], v[208:211], v[80:83]
	v_mfma_f32_16x16x32_bf16 v[72:75], v[180:183], v[208:211], v[72:75]
	v_mfma_f32_16x16x32_bf16 v[68:71], v[172:175], v[216:219], v[68:71]
	v_mfma_f32_16x16x32_bf16 v[64:67], v[180:183], v[216:219], v[64:67]
	s_barrier
	s_add_i32 s87, s76, s68
	v_lshl_add_u64 v[188:189], s[62:63], 0, v[132:133]
	s_mov_b32 m0, s87
	ds_read_b128 v[184:187], v155 offset:16384
	ds_read_b128 v[192:195], v155 offset:17408
	ds_read_b128 v[196:199], v155 offset:18432
	ds_read_b128 v[200:203], v155 offset:19456
	ds_read_b128 v[204:207], v155 offset:20480
	ds_read_b128 v[208:211], v155 offset:21504
	ds_read_b128 v[212:215], v155 offset:22528
	ds_read_b128 v[216:219], v155 offset:23552
	global_load_lds_dwordx4 v[188:189], off
	s_add_i32 m0, s87, 0x2000
	s_add_u32 s88, s62, 0x40000
	v_lshl_add_u64 v[220:221], s[62:63], 0, v[128:129]
	s_addc_u32 s89, s63, 0
	s_add_i32 s87, s77, s68
	global_load_lds_dwordx4 v[220:221], off
	s_mov_b32 m0, s87
	v_lshl_add_u64 v[224:225], s[64:65], 0, v[130:131]
	global_load_lds_dwordx4 v132, s[88:89]
	s_add_i32 m0, s87, 0x2000
	s_nop 0
	global_load_lds_dwordx4 v128, s[88:89]
	v_lshl_add_u64 v[222:223], s[64:65], 0, v[134:135]
	s_mov_b32 m0, s69
	s_nop 0
	global_load_lds_dwordx4 v[222:223], off
	s_mov_b32 m0, s70
	s_nop 0
	global_load_lds_dwordx4 v[224:225], off
	s_waitcnt vmcnt(8)
	s_waitcnt lgkmcnt(0)
	s_barrier
	s_waitcnt lgkmcnt(0)
	v_mfma_f32_16x16x32_bf16 v[60:63], v[146:149], v[184:187], 0
	v_mfma_f32_16x16x32_bf16 v[56:59], v[160:163], v[184:187], 0
	v_mfma_f32_16x16x32_bf16 v[52:55], v[146:149], v[196:199], 0
	v_mfma_f32_16x16x32_bf16 v[44:47], v[160:163], v[196:199], 0
	v_mfma_f32_16x16x32_bf16 v[36:39], v[146:149], v[204:207], 0
	v_mfma_f32_16x16x32_bf16 v[28:31], v[160:163], v[204:207], 0
	v_mfma_f32_16x16x32_bf16 v[20:23], v[146:149], v[212:215], 0
	v_mfma_f32_16x16x32_bf16 v[12:15], v[160:163], v[212:215], 0
	v_mfma_f32_16x16x32_bf16 v[60:63], v[156:159], v[192:195], v[60:63]
	v_mfma_f32_16x16x32_bf16 v[56:59], v[164:167], v[192:195], v[56:59]
	v_mfma_f32_16x16x32_bf16 v[52:55], v[156:159], v[200:203], v[52:55]
	v_mfma_f32_16x16x32_bf16 v[44:47], v[164:167], v[200:203], v[44:47]
	v_mfma_f32_16x16x32_bf16 v[36:39], v[156:159], v[208:211], v[36:39]
	v_mfma_f32_16x16x32_bf16 v[28:31], v[164:167], v[208:211], v[28:31]
	v_mfma_f32_16x16x32_bf16 v[20:23], v[156:159], v[216:219], v[20:23]
	v_mfma_f32_16x16x32_bf16 v[12:15], v[164:167], v[216:219], v[12:15]
	v_mfma_f32_16x16x32_bf16 v[48:51], v[168:171], v[184:187], 0
	v_mfma_f32_16x16x32_bf16 v[40:43], v[176:179], v[184:187], 0
	v_mfma_f32_16x16x32_bf16 v[32:35], v[168:171], v[196:199], 0
	v_mfma_f32_16x16x32_bf16 v[24:27], v[176:179], v[196:199], 0
	v_mfma_f32_16x16x32_bf16 v[16:19], v[168:171], v[204:207], 0
	v_mfma_f32_16x16x32_bf16 v[8:11], v[176:179], v[204:207], 0
	v_mfma_f32_16x16x32_bf16 v[4:7], v[168:171], v[212:215], 0
	v_mfma_f32_16x16x32_bf16 v[0:3], v[176:179], v[212:215], 0
	v_mfma_f32_16x16x32_bf16 v[48:51], v[172:175], v[192:195], v[48:51]
	v_mfma_f32_16x16x32_bf16 v[40:43], v[180:183], v[192:195], v[40:43]
	v_mfma_f32_16x16x32_bf16 v[32:35], v[172:175], v[200:203], v[32:35]
	v_mfma_f32_16x16x32_bf16 v[24:27], v[180:183], v[200:203], v[24:27]
	v_mfma_f32_16x16x32_bf16 v[16:19], v[172:175], v[208:211], v[16:19]
	v_mfma_f32_16x16x32_bf16 v[8:11], v[180:183], v[208:211], v[8:11]
	v_mfma_f32_16x16x32_bf16 v[4:7], v[172:175], v[216:219], v[4:7]
	v_mfma_f32_16x16x32_bf16 v[0:3], v[180:183], v[216:219], v[0:3]
	s_barrier
	s_add_i32 s87, 0, 0x18000
	s_add_i32 s88, 0, 0x1c000
	v_add_u32_e32 v164, s87, v151
	v_add_u32_e32 v180, s88, v151
	ds_read_b128 v[146:149], v164
	ds_read_b128 v[156:159], v164 offset:1024
	ds_read_b128 v[160:163], v164 offset:2048
	ds_read_b128 v[164:167], v164 offset:3072
	ds_read_b128 v[168:171], v180
	ds_read_b128 v[172:175], v180 offset:1024
	ds_read_b128 v[176:179], v180 offset:2048
	ds_read_b128 v[180:183], v180 offset:3072
	s_add_u32 s64, s64, 0x40000
	s_addc_u32 s65, s65, 0
	s_mov_b32 m0, s71
	ds_read_b128 v[184:187], v155 offset:32768
	ds_read_b128 v[192:195], v155 offset:33792
	ds_read_b128 v[196:199], v155 offset:34816
	ds_read_b128 v[200:203], v155 offset:35840
	ds_read_b128 v[204:207], v155 offset:36864
	ds_read_b128 v[208:211], v155 offset:37888
	ds_read_b128 v[212:215], v155 offset:38912
	ds_read_b128 v[216:219], v155 offset:39936
	global_load_lds_dwordx4 v134, s[64:65]
	s_mov_b32 m0, s72
	s_nop 0
	global_load_lds_dwordx4 v130, s[64:65]
	s_waitcnt vmcnt(8)
	s_waitcnt lgkmcnt(0)
	s_barrier
	s_waitcnt lgkmcnt(0)
	v_mfma_f32_16x16x32_bf16 v[124:127], v[146:149], v[184:187], v[124:127]
	v_mfma_f32_16x16x32_bf16 v[120:123], v[160:163], v[184:187], v[120:123]
	v_mfma_f32_16x16x32_bf16 v[116:119], v[146:149], v[196:199], v[116:119]
	v_mfma_f32_16x16x32_bf16 v[108:111], v[160:163], v[196:199], v[108:111]
	v_mfma_f32_16x16x32_bf16 v[100:103], v[146:149], v[204:207], v[100:103]
	v_mfma_f32_16x16x32_bf16 v[92:95], v[160:163], v[204:207], v[92:95]
	v_mfma_f32_16x16x32_bf16 v[84:87], v[146:149], v[212:215], v[84:87]
	v_mfma_f32_16x16x32_bf16 v[76:79], v[160:163], v[212:215], v[76:79]
	v_mfma_f32_16x16x32_bf16 v[124:127], v[156:159], v[192:195], v[124:127]
	v_mfma_f32_16x16x32_bf16 v[120:123], v[164:167], v[192:195], v[120:123]
	v_mfma_f32_16x16x32_bf16 v[116:119], v[156:159], v[200:203], v[116:119]
	v_mfma_f32_16x16x32_bf16 v[108:111], v[164:167], v[200:203], v[108:111]
	v_mfma_f32_16x16x32_bf16 v[100:103], v[156:159], v[208:211], v[100:103]
	v_mfma_f32_16x16x32_bf16 v[92:95], v[164:167], v[208:211], v[92:95]
	v_mfma_f32_16x16x32_bf16 v[84:87], v[156:159], v[216:219], v[84:87]
	v_mfma_f32_16x16x32_bf16 v[76:79], v[164:167], v[216:219], v[76:79]
	v_mfma_f32_16x16x32_bf16 v[112:115], v[168:171], v[184:187], v[112:115]
	v_mfma_f32_16x16x32_bf16 v[104:107], v[176:179], v[184:187], v[104:107]
	v_mfma_f32_16x16x32_bf16 v[96:99], v[168:171], v[196:199], v[96:99]
	v_mfma_f32_16x16x32_bf16 v[88:91], v[176:179], v[196:199], v[88:91]
	v_mfma_f32_16x16x32_bf16 v[80:83], v[168:171], v[204:207], v[80:83]
	v_mfma_f32_16x16x32_bf16 v[72:75], v[176:179], v[204:207], v[72:75]
	v_mfma_f32_16x16x32_bf16 v[68:71], v[168:171], v[212:215], v[68:71]
	v_mfma_f32_16x16x32_bf16 v[64:67], v[176:179], v[212:215], v[64:67]
	v_mfma_f32_16x16x32_bf16 v[112:115], v[172:175], v[192:195], v[112:115]
	v_mfma_f32_16x16x32_bf16 v[104:107], v[180:183], v[192:195], v[104:107]
	v_mfma_f32_16x16x32_bf16 v[96:99], v[172:175], v[200:203], v[96:99]
	v_mfma_f32_16x16x32_bf16 v[88:91], v[180:183], v[200:203], v[88:91]
	v_mfma_f32_16x16x32_bf16 v[80:83], v[172:175], v[208:211], v[80:83]
	v_mfma_f32_16x16x32_bf16 v[72:75], v[180:183], v[208:211], v[72:75]
	v_mfma_f32_16x16x32_bf16 v[68:71], v[172:175], v[216:219], v[68:71]
	v_mfma_f32_16x16x32_bf16 v[64:67], v[180:183], v[216:219], v[64:67]
	s_barrier
	s_add_i32 s64, s87, s68
	v_lshl_add_u64 v[188:189], v[188:189], 0, s[10:11]
	s_mov_b32 m0, s64
	ds_read_b128 v[184:187], v155 offset:49152
	ds_read_b128 v[192:195], v155 offset:50176
	ds_read_b128 v[196:199], v155 offset:51200
	ds_read_b128 v[200:203], v155 offset:52224
	ds_read_b128 v[204:207], v155 offset:53248
	ds_read_b128 v[208:211], v155 offset:54272
	ds_read_b128 v[212:215], v155 offset:55296
	ds_read_b128 v[216:219], v155 offset:56320
	global_load_lds_dwordx4 v[188:189], off
	s_add_i32 m0, s64, 0x2000
	s_add_u32 s62, s62, 0x40080
	v_lshl_add_u64 v[188:189], v[220:221], 0, s[10:11]
	s_addc_u32 s63, s63, 0
	s_add_i32 s64, s88, s68
	global_load_lds_dwordx4 v[188:189], off
	s_mov_b32 m0, s64
	s_nop 0
	global_load_lds_dwordx4 v132, s[62:63]
	s_add_i32 m0, s64, 0x2000
	s_nop 0
	global_load_lds_dwordx4 v128, s[62:63]
	v_lshl_add_u64 v[188:189], v[222:223], 0, s[10:11]
	s_mov_b32 m0, s33
	s_nop 0
	global_load_lds_dwordx4 v[188:189], off
	v_lshl_add_u64 v[188:189], v[224:225], 0, s[10:11]
	s_mov_b32 m0, s74
	s_nop 0
	global_load_lds_dwordx4 v[188:189], off
	s_waitcnt vmcnt(8)
	s_waitcnt lgkmcnt(0)
	s_barrier
	s_waitcnt lgkmcnt(0)
	v_mfma_f32_16x16x32_bf16 v[60:63], v[146:149], v[184:187], v[60:63]
	v_mfma_f32_16x16x32_bf16 v[56:59], v[160:163], v[184:187], v[56:59]
	v_mfma_f32_16x16x32_bf16 v[52:55], v[146:149], v[196:199], v[52:55]
	v_mfma_f32_16x16x32_bf16 v[44:47], v[160:163], v[196:199], v[44:47]
	v_mfma_f32_16x16x32_bf16 v[36:39], v[146:149], v[204:207], v[36:39]
	v_mfma_f32_16x16x32_bf16 v[28:31], v[160:163], v[204:207], v[28:31]
	v_mfma_f32_16x16x32_bf16 v[20:23], v[146:149], v[212:215], v[20:23]
	v_mfma_f32_16x16x32_bf16 v[12:15], v[160:163], v[212:215], v[12:15]
	v_mfma_f32_16x16x32_bf16 v[60:63], v[156:159], v[192:195], v[60:63]
	v_mfma_f32_16x16x32_bf16 v[56:59], v[164:167], v[192:195], v[56:59]
	v_mfma_f32_16x16x32_bf16 v[52:55], v[156:159], v[200:203], v[52:55]
	v_mfma_f32_16x16x32_bf16 v[44:47], v[164:167], v[200:203], v[44:47]
	v_mfma_f32_16x16x32_bf16 v[36:39], v[156:159], v[208:211], v[36:39]
	v_mfma_f32_16x16x32_bf16 v[28:31], v[164:167], v[208:211], v[28:31]
	v_mfma_f32_16x16x32_bf16 v[20:23], v[156:159], v[216:219], v[20:23]
	v_mfma_f32_16x16x32_bf16 v[12:15], v[164:167], v[216:219], v[12:15]
	v_mfma_f32_16x16x32_bf16 v[48:51], v[168:171], v[184:187], v[48:51]
	v_mfma_f32_16x16x32_bf16 v[40:43], v[176:179], v[184:187], v[40:43]
	v_mfma_f32_16x16x32_bf16 v[32:35], v[168:171], v[196:199], v[32:35]
	v_mfma_f32_16x16x32_bf16 v[24:27], v[176:179], v[196:199], v[24:27]
	v_mfma_f32_16x16x32_bf16 v[16:19], v[168:171], v[204:207], v[16:19]
	v_mfma_f32_16x16x32_bf16 v[8:11], v[176:179], v[204:207], v[8:11]
	v_mfma_f32_16x16x32_bf16 v[4:7], v[168:171], v[212:215], v[4:7]
	v_mfma_f32_16x16x32_bf16 v[0:3], v[176:179], v[212:215], v[0:3]
	v_mfma_f32_16x16x32_bf16 v[48:51], v[172:175], v[192:195], v[48:51]
	v_mfma_f32_16x16x32_bf16 v[40:43], v[180:183], v[192:195], v[40:43]
	v_mfma_f32_16x16x32_bf16 v[32:35], v[172:175], v[200:203], v[32:35]
	v_mfma_f32_16x16x32_bf16 v[24:27], v[180:183], v[200:203], v[24:27]
	v_mfma_f32_16x16x32_bf16 v[16:19], v[172:175], v[208:211], v[16:19]
	v_mfma_f32_16x16x32_bf16 v[8:11], v[180:183], v[208:211], v[8:11]
	v_mfma_f32_16x16x32_bf16 v[4:7], v[172:175], v[216:219], v[4:7]
	v_mfma_f32_16x16x32_bf16 v[0:3], v[180:183], v[216:219], v[0:3]
	s_barrier
	s_add_i32 s86, s86, 2
	s_add_u32 s60, s60, 0x100
	s_addc_u32 s61, s61, 0
	s_add_u32 s84, s84, 0x100
	s_addc_u32 s85, s85, 0
	s_cmp_gt_u32 s86, 13
	s_cbranch_scc0 .LBB0_272
	s_branch .Lpeel_exit0
.LBB0_272:
	ds_read_b128 v[146:149], v153
	ds_read_b128 v[156:159], v153 offset:1024
	ds_read_b128 v[160:163], v153 offset:2048
	ds_read_b128 v[164:167], v153 offset:3072
	ds_read_b128 v[168:171], v154
	ds_read_b128 v[172:175], v154 offset:1024
	ds_read_b128 v[176:179], v154 offset:2048
	ds_read_b128 v[180:183], v154 offset:3072
	s_add_u32 s62, s60, 0xfffc0080
	s_addc_u32 s63, s61, -1
	s_cmp_eq_u32 s86, 12
	s_cselect_b32 s65, s37, s63
	s_cselect_b32 s64, s43, s62
	s_cselect_b32 s63, s35, s85
	s_cselect_b32 s62, s55, s84
	s_add_i32 m0, s69, 0xc000
	ds_read_b128 v[184:187], v155
	ds_read_b128 v[192:195], v155 offset:1024
	ds_read_b128 v[196:199], v155 offset:2048
	ds_read_b128 v[200:203], v155 offset:3072
	ds_read_b128 v[204:207], v155 offset:4096
	ds_read_b128 v[208:211], v155 offset:5120
	ds_read_b128 v[212:215], v155 offset:6144
	ds_read_b128 v[216:219], v155 offset:7168
	global_load_lds_dwordx4 v138, s[60:61]
	v_lshl_add_u64 v[188:189], s[60:61], 0, v[140:141]
	s_add_i32 m0, s69, 0xe000
	s_nop 0
	global_load_lds_dwordx4 v[188:189], off
	s_waitcnt vmcnt(8)
	s_waitcnt lgkmcnt(0)
	s_barrier
	s_waitcnt lgkmcnt(0)
	v_mfma_f32_16x16x32_bf16 v[124:127], v[146:149], v[184:187], v[124:127]
	v_mfma_f32_16x16x32_bf16 v[120:123], v[160:163], v[184:187], v[120:123]
	v_mfma_f32_16x16x32_bf16 v[116:119], v[146:149], v[196:199], v[116:119]
	v_mfma_f32_16x16x32_bf16 v[108:111], v[160:163], v[196:199], v[108:111]
	v_mfma_f32_16x16x32_bf16 v[100:103], v[146:149], v[204:207], v[100:103]
	v_mfma_f32_16x16x32_bf16 v[92:95], v[160:163], v[204:207], v[92:95]
	v_mfma_f32_16x16x32_bf16 v[84:87], v[146:149], v[212:215], v[84:87]
	v_mfma_f32_16x16x32_bf16 v[76:79], v[160:163], v[212:215], v[76:79]
	v_mfma_f32_16x16x32_bf16 v[124:127], v[156:159], v[192:195], v[124:127]
	v_mfma_f32_16x16x32_bf16 v[120:123], v[164:167], v[192:195], v[120:123]
	v_mfma_f32_16x16x32_bf16 v[116:119], v[156:159], v[200:203], v[116:119]
	v_mfma_f32_16x16x32_bf16 v[108:111], v[164:167], v[200:203], v[108:111]
	v_mfma_f32_16x16x32_bf16 v[100:103], v[156:159], v[208:211], v[100:103]
	v_mfma_f32_16x16x32_bf16 v[92:95], v[164:167], v[208:211], v[92:95]
	v_mfma_f32_16x16x32_bf16 v[84:87], v[156:159], v[216:219], v[84:87]
	v_mfma_f32_16x16x32_bf16 v[76:79], v[164:167], v[216:219], v[76:79]
	v_mfma_f32_16x16x32_bf16 v[112:115], v[168:171], v[184:187], v[112:115]
	v_mfma_f32_16x16x32_bf16 v[104:107], v[176:179], v[184:187], v[104:107]
	v_mfma_f32_16x16x32_bf16 v[96:99], v[168:171], v[196:199], v[96:99]
	v_mfma_f32_16x16x32_bf16 v[88:91], v[176:179], v[196:199], v[88:91]
	v_mfma_f32_16x16x32_bf16 v[80:83], v[168:171], v[204:207], v[80:83]
	v_mfma_f32_16x16x32_bf16 v[72:75], v[176:179], v[204:207], v[72:75]
	v_mfma_f32_16x16x32_bf16 v[68:71], v[168:171], v[212:215], v[68:71]
	v_mfma_f32_16x16x32_bf16 v[64:67], v[176:179], v[212:215], v[64:67]
	v_mfma_f32_16x16x32_bf16 v[112:115], v[172:175], v[192:195], v[112:115]
	v_mfma_f32_16x16x32_bf16 v[104:107], v[180:183], v[192:195], v[104:107]
	v_mfma_f32_16x16x32_bf16 v[96:99], v[172:175], v[200:203], v[96:99]
	v_mfma_f32_16x16x32_bf16 v[88:91], v[180:183], v[200:203], v[88:91]
	v_mfma_f32_16x16x32_bf16 v[80:83], v[172:175], v[208:211], v[80:83]
	v_mfma_f32_16x16x32_bf16 v[72:75], v[180:183], v[208:211], v[72:75]
	v_mfma_f32_16x16x32_bf16 v[68:71], v[172:175], v[216:219], v[68:71]
	v_mfma_f32_16x16x32_bf16 v[64:67], v[180:183], v[216:219], v[64:67]
	s_barrier
	s_add_i32 s87, s76, s68
	v_lshl_add_u64 v[188:189], s[62:63], 0, v[132:133]
	s_mov_b32 m0, s87
	ds_read_b128 v[184:187], v155 offset:16384
	ds_read_b128 v[192:195], v155 offset:17408
	ds_read_b128 v[196:199], v155 offset:18432
	ds_read_b128 v[200:203], v155 offset:19456
	ds_read_b128 v[204:207], v155 offset:20480
	ds_read_b128 v[208:211], v155 offset:21504
	ds_read_b128 v[212:215], v155 offset:22528
	ds_read_b128 v[216:219], v155 offset:23552
	global_load_lds_dwordx4 v[188:189], off
	s_add_i32 m0, s87, 0x2000
	s_add_u32 s88, s62, 0x40000
	v_lshl_add_u64 v[220:221], s[62:63], 0, v[128:129]
	s_addc_u32 s89, s63, 0
	s_add_i32 s87, s77, s68
	global_load_lds_dwordx4 v[220:221], off
	s_mov_b32 m0, s87
	v_lshl_add_u64 v[224:225], s[64:65], 0, v[130:131]
	global_load_lds_dwordx4 v132, s[88:89]
	s_add_i32 m0, s87, 0x2000
	s_nop 0
	global_load_lds_dwordx4 v128, s[88:89]
	v_lshl_add_u64 v[222:223], s[64:65], 0, v[134:135]
	s_mov_b32 m0, s69
	s_nop 0
	global_load_lds_dwordx4 v[222:223], off
	s_mov_b32 m0, s70
	s_nop 0
	global_load_lds_dwordx4 v[224:225], off
	s_waitcnt vmcnt(8)
	s_waitcnt lgkmcnt(0)
	s_barrier
	s_waitcnt lgkmcnt(0)
	v_mfma_f32_16x16x32_bf16 v[60:63], v[146:149], v[184:187], v[60:63]
	v_mfma_f32_16x16x32_bf16 v[56:59], v[160:163], v[184:187], v[56:59]
	v_mfma_f32_16x16x32_bf16 v[52:55], v[146:149], v[196:199], v[52:55]
	v_mfma_f32_16x16x32_bf16 v[44:47], v[160:163], v[196:199], v[44:47]
	v_mfma_f32_16x16x32_bf16 v[36:39], v[146:149], v[204:207], v[36:39]
	v_mfma_f32_16x16x32_bf16 v[28:31], v[160:163], v[204:207], v[28:31]
	v_mfma_f32_16x16x32_bf16 v[20:23], v[146:149], v[212:215], v[20:23]
	v_mfma_f32_16x16x32_bf16 v[12:15], v[160:163], v[212:215], v[12:15]
	v_mfma_f32_16x16x32_bf16 v[60:63], v[156:159], v[192:195], v[60:63]
	v_mfma_f32_16x16x32_bf16 v[56:59], v[164:167], v[192:195], v[56:59]
	v_mfma_f32_16x16x32_bf16 v[52:55], v[156:159], v[200:203], v[52:55]
	v_mfma_f32_16x16x32_bf16 v[44:47], v[164:167], v[200:203], v[44:47]
	v_mfma_f32_16x16x32_bf16 v[36:39], v[156:159], v[208:211], v[36:39]
	v_mfma_f32_16x16x32_bf16 v[28:31], v[164:167], v[208:211], v[28:31]
	v_mfma_f32_16x16x32_bf16 v[20:23], v[156:159], v[216:219], v[20:23]
	v_mfma_f32_16x16x32_bf16 v[12:15], v[164:167], v[216:219], v[12:15]
	v_mfma_f32_16x16x32_bf16 v[48:51], v[168:171], v[184:187], v[48:51]
	v_mfma_f32_16x16x32_bf16 v[40:43], v[176:179], v[184:187], v[40:43]
	v_mfma_f32_16x16x32_bf16 v[32:35], v[168:171], v[196:199], v[32:35]
	v_mfma_f32_16x16x32_bf16 v[24:27], v[176:179], v[196:199], v[24:27]
	v_mfma_f32_16x16x32_bf16 v[16:19], v[168:171], v[204:207], v[16:19]
	v_mfma_f32_16x16x32_bf16 v[8:11], v[176:179], v[204:207], v[8:11]
	v_mfma_f32_16x16x32_bf16 v[4:7], v[168:171], v[212:215], v[4:7]
	v_mfma_f32_16x16x32_bf16 v[0:3], v[176:179], v[212:215], v[0:3]
	v_mfma_f32_16x16x32_bf16 v[48:51], v[172:175], v[192:195], v[48:51]
	v_mfma_f32_16x16x32_bf16 v[40:43], v[180:183], v[192:195], v[40:43]
	v_mfma_f32_16x16x32_bf16 v[32:35], v[172:175], v[200:203], v[32:35]
	v_mfma_f32_16x16x32_bf16 v[24:27], v[180:183], v[200:203], v[24:27]
	v_mfma_f32_16x16x32_bf16 v[16:19], v[172:175], v[208:211], v[16:19]
	v_mfma_f32_16x16x32_bf16 v[8:11], v[180:183], v[208:211], v[8:11]
	v_mfma_f32_16x16x32_bf16 v[4:7], v[172:175], v[216:219], v[4:7]
	v_mfma_f32_16x16x32_bf16 v[0:3], v[180:183], v[216:219], v[0:3]
	s_barrier
	s_add_i32 s87, 0, 0x18000
	s_add_i32 s88, 0, 0x1c000
	v_add_u32_e32 v164, s87, v151
	v_add_u32_e32 v180, s88, v151
	ds_read_b128 v[146:149], v164
	ds_read_b128 v[156:159], v164 offset:1024
	ds_read_b128 v[160:163], v164 offset:2048
	ds_read_b128 v[164:167], v164 offset:3072
	ds_read_b128 v[168:171], v180
	ds_read_b128 v[172:175], v180 offset:1024
	ds_read_b128 v[176:179], v180 offset:2048
	ds_read_b128 v[180:183], v180 offset:3072
	s_add_u32 s64, s64, 0x40000
	s_addc_u32 s65, s65, 0
	s_mov_b32 m0, s71
	ds_read_b128 v[184:187], v155 offset:32768
	ds_read_b128 v[192:195], v155 offset:33792
	ds_read_b128 v[196:199], v155 offset:34816
	ds_read_b128 v[200:203], v155 offset:35840
	ds_read_b128 v[204:207], v155 offset:36864
	ds_read_b128 v[208:211], v155 offset:37888
	ds_read_b128 v[212:215], v155 offset:38912
	ds_read_b128 v[216:219], v155 offset:39936
	global_load_lds_dwordx4 v134, s[64:65]
	s_mov_b32 m0, s72
	s_nop 0
	global_load_lds_dwordx4 v130, s[64:65]
	s_waitcnt vmcnt(8)
	s_waitcnt lgkmcnt(0)
	s_barrier
	s_waitcnt lgkmcnt(0)
	v_mfma_f32_16x16x32_bf16 v[124:127], v[146:149], v[184:187], v[124:127]
	v_mfma_f32_16x16x32_bf16 v[120:123], v[160:163], v[184:187], v[120:123]
	v_mfma_f32_16x16x32_bf16 v[116:119], v[146:149], v[196:199], v[116:119]
	v_mfma_f32_16x16x32_bf16 v[108:111], v[160:163], v[196:199], v[108:111]
	v_mfma_f32_16x16x32_bf16 v[100:103], v[146:149], v[204:207], v[100:103]
	v_mfma_f32_16x16x32_bf16 v[92:95], v[160:163], v[204:207], v[92:95]
	v_mfma_f32_16x16x32_bf16 v[84:87], v[146:149], v[212:215], v[84:87]
	v_mfma_f32_16x16x32_bf16 v[76:79], v[160:163], v[212:215], v[76:79]
	v_mfma_f32_16x16x32_bf16 v[124:127], v[156:159], v[192:195], v[124:127]
	v_mfma_f32_16x16x32_bf16 v[120:123], v[164:167], v[192:195], v[120:123]
	v_mfma_f32_16x16x32_bf16 v[116:119], v[156:159], v[200:203], v[116:119]
	v_mfma_f32_16x16x32_bf16 v[108:111], v[164:167], v[200:203], v[108:111]
	v_mfma_f32_16x16x32_bf16 v[100:103], v[156:159], v[208:211], v[100:103]
	v_mfma_f32_16x16x32_bf16 v[92:95], v[164:167], v[208:211], v[92:95]
	v_mfma_f32_16x16x32_bf16 v[84:87], v[156:159], v[216:219], v[84:87]
	v_mfma_f32_16x16x32_bf16 v[76:79], v[164:167], v[216:219], v[76:79]
	v_mfma_f32_16x16x32_bf16 v[112:115], v[168:171], v[184:187], v[112:115]
	v_mfma_f32_16x16x32_bf16 v[104:107], v[176:179], v[184:187], v[104:107]
	v_mfma_f32_16x16x32_bf16 v[96:99], v[168:171], v[196:199], v[96:99]
	v_mfma_f32_16x16x32_bf16 v[88:91], v[176:179], v[196:199], v[88:91]
	v_mfma_f32_16x16x32_bf16 v[80:83], v[168:171], v[204:207], v[80:83]
	v_mfma_f32_16x16x32_bf16 v[72:75], v[176:179], v[204:207], v[72:75]
	v_mfma_f32_16x16x32_bf16 v[68:71], v[168:171], v[212:215], v[68:71]
	v_mfma_f32_16x16x32_bf16 v[64:67], v[176:179], v[212:215], v[64:67]
	v_mfma_f32_16x16x32_bf16 v[112:115], v[172:175], v[192:195], v[112:115]
	v_mfma_f32_16x16x32_bf16 v[104:107], v[180:183], v[192:195], v[104:107]
	v_mfma_f32_16x16x32_bf16 v[96:99], v[172:175], v[200:203], v[96:99]
	v_mfma_f32_16x16x32_bf16 v[88:91], v[180:183], v[200:203], v[88:91]
	v_mfma_f32_16x16x32_bf16 v[80:83], v[172:175], v[208:211], v[80:83]
	v_mfma_f32_16x16x32_bf16 v[72:75], v[180:183], v[208:211], v[72:75]
	v_mfma_f32_16x16x32_bf16 v[68:71], v[172:175], v[216:219], v[68:71]
	v_mfma_f32_16x16x32_bf16 v[64:67], v[180:183], v[216:219], v[64:67]
	s_barrier
	s_add_i32 s64, s87, s68
	v_lshl_add_u64 v[188:189], v[188:189], 0, s[10:11]
	s_mov_b32 m0, s64
	ds_read_b128 v[184:187], v155 offset:49152
	ds_read_b128 v[192:195], v155 offset:50176
	ds_read_b128 v[196:199], v155 offset:51200
	ds_read_b128 v[200:203], v155 offset:52224
	ds_read_b128 v[204:207], v155 offset:53248
	ds_read_b128 v[208:211], v155 offset:54272
	ds_read_b128 v[212:215], v155 offset:55296
	ds_read_b128 v[216:219], v155 offset:56320
	global_load_lds_dwordx4 v[188:189], off
	s_add_i32 m0, s64, 0x2000
	s_add_u32 s62, s62, 0x40080
	v_lshl_add_u64 v[188:189], v[220:221], 0, s[10:11]
	s_addc_u32 s63, s63, 0
	s_add_i32 s64, s88, s68
	global_load_lds_dwordx4 v[188:189], off
	s_mov_b32 m0, s64
	s_nop 0
	global_load_lds_dwordx4 v132, s[62:63]
	s_add_i32 m0, s64, 0x2000
	s_nop 0
	global_load_lds_dwordx4 v128, s[62:63]
	v_lshl_add_u64 v[188:189], v[222:223], 0, s[10:11]
	s_mov_b32 m0, s33
	s_nop 0
	global_load_lds_dwordx4 v[188:189], off
	v_lshl_add_u64 v[188:189], v[224:225], 0, s[10:11]
	s_mov_b32 m0, s74
	s_nop 0
	global_load_lds_dwordx4 v[188:189], off
	s_waitcnt vmcnt(8)
	s_waitcnt lgkmcnt(0)
	s_barrier
	s_waitcnt lgkmcnt(0)
	v_mfma_f32_16x16x32_bf16 v[60:63], v[146:149], v[184:187], v[60:63]
	v_mfma_f32_16x16x32_bf16 v[56:59], v[160:163], v[184:187], v[56:59]
	v_mfma_f32_16x16x32_bf16 v[52:55], v[146:149], v[196:199], v[52:55]
	v_mfma_f32_16x16x32_bf16 v[44:47], v[160:163], v[196:199], v[44:47]
	v_mfma_f32_16x16x32_bf16 v[36:39], v[146:149], v[204:207], v[36:39]
	v_mfma_f32_16x16x32_bf16 v[28:31], v[160:163], v[204:207], v[28:31]
	v_mfma_f32_16x16x32_bf16 v[20:23], v[146:149], v[212:215], v[20:23]
	v_mfma_f32_16x16x32_bf16 v[12:15], v[160:163], v[212:215], v[12:15]
	v_mfma_f32_16x16x32_bf16 v[60:63], v[156:159], v[192:195], v[60:63]
	v_mfma_f32_16x16x32_bf16 v[56:59], v[164:167], v[192:195], v[56:59]
	v_mfma_f32_16x16x32_bf16 v[52:55], v[156:159], v[200:203], v[52:55]
	v_mfma_f32_16x16x32_bf16 v[44:47], v[164:167], v[200:203], v[44:47]
	v_mfma_f32_16x16x32_bf16 v[36:39], v[156:159], v[208:211], v[36:39]
	v_mfma_f32_16x16x32_bf16 v[28:31], v[164:167], v[208:211], v[28:31]
	v_mfma_f32_16x16x32_bf16 v[20:23], v[156:159], v[216:219], v[20:23]
	v_mfma_f32_16x16x32_bf16 v[12:15], v[164:167], v[216:219], v[12:15]
	v_mfma_f32_16x16x32_bf16 v[48:51], v[168:171], v[184:187], v[48:51]
	v_mfma_f32_16x16x32_bf16 v[40:43], v[176:179], v[184:187], v[40:43]
	v_mfma_f32_16x16x32_bf16 v[32:35], v[168:171], v[196:199], v[32:35]
	v_mfma_f32_16x16x32_bf16 v[24:27], v[176:179], v[196:199], v[24:27]
	v_mfma_f32_16x16x32_bf16 v[16:19], v[168:171], v[204:207], v[16:19]
	v_mfma_f32_16x16x32_bf16 v[8:11], v[176:179], v[204:207], v[8:11]
	v_mfma_f32_16x16x32_bf16 v[4:7], v[168:171], v[212:215], v[4:7]
	v_mfma_f32_16x16x32_bf16 v[0:3], v[176:179], v[212:215], v[0:3]
	v_mfma_f32_16x16x32_bf16 v[48:51], v[172:175], v[192:195], v[48:51]
	v_mfma_f32_16x16x32_bf16 v[40:43], v[180:183], v[192:195], v[40:43]
	v_mfma_f32_16x16x32_bf16 v[32:35], v[172:175], v[200:203], v[32:35]
	v_mfma_f32_16x16x32_bf16 v[24:27], v[180:183], v[200:203], v[24:27]
	v_mfma_f32_16x16x32_bf16 v[16:19], v[172:175], v[208:211], v[16:19]
	v_mfma_f32_16x16x32_bf16 v[8:11], v[180:183], v[208:211], v[8:11]
	v_mfma_f32_16x16x32_bf16 v[4:7], v[172:175], v[216:219], v[4:7]
	v_mfma_f32_16x16x32_bf16 v[0:3], v[180:183], v[216:219], v[0:3]
	s_barrier
	s_add_i32 s86, s86, 2
	s_add_u32 s60, s60, 0x100
	s_addc_u32 s61, s61, 0
	s_add_u32 s84, s84, 0x100
	s_addc_u32 s85, s85, 0
	s_cmp_gt_u32 s86, 13
	s_cbranch_scc0 .LBB0_272

.LBB0_301:
	s_ashr_i32 s27, s26, 31
	s_lshl_b64 s[28:29], s[26:27], 19
	s_add_u32 s28, s43, s28
	s_addc_u32 s29, s52, s29
	s_and_b64 s[30:31], s[4:5], exec
	s_cselect_b32 s27, s29, s37
	s_cselect_b32 s55, s28, s36
	s_ashr_i32 s25, s24, 31
	s_lshl_b64 s[30:31], s[24:25], 19
	s_add_u32 s30, s58, s30
	s_addc_u32 s31, s59, s31
	s_and_b64 s[40:41], s[4:5], exec
	s_cselect_b32 s25, s31, s39
	s_cselect_b32 s72, s30, s38
	s_add_u32 s36, s36, 0x40080
	s_addc_u32 s37, s37, 0
	s_add_u32 s73, s38, 0x100
	s_addc_u32 s74, s39, 0
	s_mov_b32 s75, -2
	ds_read_b128 v[152:155], v149
	ds_read_b128 v[156:159], v149 offset:1024
	ds_read_b128 v[160:163], v149 offset:2048
	ds_read_b128 v[164:167], v149 offset:3072
	ds_read_b128 v[168:171], v150
	ds_read_b128 v[172:175], v150 offset:1024
	ds_read_b128 v[176:179], v150 offset:2048
	ds_read_b128 v[180:183], v150 offset:3072
	s_add_u32 s38, s36, 0xfffc0080
	s_addc_u32 s39, s37, -1
	s_cmp_eq_u32 s75, 12
	s_cselect_b32 s41, s27, s39
	s_cselect_b32 s40, s55, s38
	s_cselect_b32 s39, s25, s74
	s_cselect_b32 s38, s72, s73
	v_lshl_add_u64 v[144:145], s[36:37], 0, v[136:137]
	s_add_i32 m0, s35, 0xc000
	ds_read_b128 v[184:187], v151
	ds_read_b128 v[192:195], v151 offset:1024
	ds_read_b128 v[196:199], v151 offset:2048
	ds_read_b128 v[200:203], v151 offset:3072
	ds_read_b128 v[204:207], v151 offset:4096
	ds_read_b128 v[208:211], v151 offset:5120
	ds_read_b128 v[212:215], v151 offset:6144
	ds_read_b128 v[216:219], v151 offset:7168
	global_load_lds_dwordx4 v[144:145], off
	s_add_i32 m0, s35, 0xe000
	s_nop 0
	global_load_lds_dwordx4 v138, s[36:37]
	s_waitcnt vmcnt(8)
	s_waitcnt lgkmcnt(0)
	s_barrier
	s_waitcnt lgkmcnt(0)
	v_mfma_f32_16x16x32_bf16 v[124:127], v[152:155], v[184:187], 0
	v_mfma_f32_16x16x32_bf16 v[120:123], v[160:163], v[184:187], 0
	v_mfma_f32_16x16x32_bf16 v[116:119], v[152:155], v[196:199], 0
	v_mfma_f32_16x16x32_bf16 v[108:111], v[160:163], v[196:199], 0
	v_mfma_f32_16x16x32_bf16 v[100:103], v[152:155], v[204:207], 0
	v_mfma_f32_16x16x32_bf16 v[92:95], v[160:163], v[204:207], 0
	v_mfma_f32_16x16x32_bf16 v[84:87], v[152:155], v[212:215], 0
	v_mfma_f32_16x16x32_bf16 v[76:79], v[160:163], v[212:215], 0
	v_mfma_f32_16x16x32_bf16 v[124:127], v[156:159], v[192:195], v[124:127]
	v_mfma_f32_16x16x32_bf16 v[120:123], v[164:167], v[192:195], v[120:123]
	v_mfma_f32_16x16x32_bf16 v[116:119], v[156:159], v[200:203], v[116:119]
	v_mfma_f32_16x16x32_bf16 v[108:111], v[164:167], v[200:203], v[108:111]
	v_mfma_f32_16x16x32_bf16 v[100:103], v[156:159], v[208:211], v[100:103]
	v_mfma_f32_16x16x32_bf16 v[92:95], v[164:167], v[208:211], v[92:95]
	v_mfma_f32_16x16x32_bf16 v[84:87], v[156:159], v[216:219], v[84:87]
	v_mfma_f32_16x16x32_bf16 v[76:79], v[164:167], v[216:219], v[76:79]
	v_mfma_f32_16x16x32_bf16 v[112:115], v[168:171], v[184:187], 0
	v_mfma_f32_16x16x32_bf16 v[104:107], v[176:179], v[184:187], 0
	v_mfma_f32_16x16x32_bf16 v[96:99], v[168:171], v[196:199], 0
	v_mfma_f32_16x16x32_bf16 v[88:91], v[176:179], v[196:199], 0
	v_mfma_f32_16x16x32_bf16 v[80:83], v[168:171], v[204:207], 0
	v_mfma_f32_16x16x32_bf16 v[72:75], v[176:179], v[204:207], 0
	v_mfma_f32_16x16x32_bf16 v[68:71], v[168:171], v[212:215], 0
	v_mfma_f32_16x16x32_bf16 v[64:67], v[176:179], v[212:215], 0
	v_mfma_f32_16x16x32_bf16 v[112:115], v[172:175], v[192:195], v[112:115]
	v_mfma_f32_16x16x32_bf16 v[104:107], v[180:183], v[192:195], v[104:107]
	v_mfma_f32_16x16x32_bf16 v[96:99], v[172:175], v[200:203], v[96:99]
	v_mfma_f32_16x16x32_bf16 v[88:91], v[180:183], v[200:203], v[88:91]
	v_mfma_f32_16x16x32_bf16 v[80:83], v[172:175], v[208:211], v[80:83]
	v_mfma_f32_16x16x32_bf16 v[72:75], v[180:183], v[208:211], v[72:75]
	v_mfma_f32_16x16x32_bf16 v[68:71], v[172:175], v[216:219], v[68:71]
	v_mfma_f32_16x16x32_bf16 v[64:67], v[180:183], v[216:219], v[64:67]
	s_barrier
	s_add_i32 s76, s66, s53
	v_lshl_add_u64 v[144:145], s[38:39], 0, v[130:131]
	s_mov_b32 m0, s76
	ds_read_b128 v[184:187], v151 offset:16384
	ds_read_b128 v[192:195], v151 offset:17408
	ds_read_b128 v[196:199], v151 offset:18432
	ds_read_b128 v[200:203], v151 offset:19456
	ds_read_b128 v[204:207], v151 offset:20480
	ds_read_b128 v[208:211], v151 offset:21504
	ds_read_b128 v[212:215], v151 offset:22528
	ds_read_b128 v[216:219], v151 offset:23552
	global_load_lds_dwordx4 v[144:145], off
	s_add_i32 m0, s76, 0x2000
	s_add_u32 s76, s38, 0x40000
	v_lshl_add_u64 v[188:189], s[38:39], 0, v[134:135]
	s_addc_u32 s77, s39, 0
	s_add_i32 s80, s67, s53
	global_load_lds_dwordx4 v[188:189], off
	s_mov_b32 m0, s80
	v_lshl_add_u64 v[222:223], s[40:41], 0, v[132:133]
	global_load_lds_dwordx4 v130, s[76:77]
	s_add_i32 m0, s80, 0x2000
	s_nop 0
	global_load_lds_dwordx4 v134, s[76:77]
	v_lshl_add_u64 v[220:221], s[40:41], 0, v[128:129]
	s_mov_b32 m0, s35
	s_nop 0
	global_load_lds_dwordx4 v[220:221], off
	s_mov_b32 m0, s33
	s_nop 0
	global_load_lds_dwordx4 v[222:223], off
	s_waitcnt vmcnt(8)
	s_waitcnt lgkmcnt(0)
	s_barrier
	s_waitcnt lgkmcnt(0)
	v_mfma_f32_16x16x32_bf16 v[60:63], v[152:155], v[184:187], 0
	v_mfma_f32_16x16x32_bf16 v[56:59], v[160:163], v[184:187], 0
	v_mfma_f32_16x16x32_bf16 v[52:55], v[152:155], v[196:199], 0
	v_mfma_f32_16x16x32_bf16 v[44:47], v[160:163], v[196:199], 0
	v_mfma_f32_16x16x32_bf16 v[36:39], v[152:155], v[204:207], 0
	v_mfma_f32_16x16x32_bf16 v[28:31], v[160:163], v[204:207], 0
	v_mfma_f32_16x16x32_bf16 v[20:23], v[152:155], v[212:215], 0
	v_mfma_f32_16x16x32_bf16 v[12:15], v[160:163], v[212:215], 0
	v_mfma_f32_16x16x32_bf16 v[60:63], v[156:159], v[192:195], v[60:63]
	v_mfma_f32_16x16x32_bf16 v[56:59], v[164:167], v[192:195], v[56:59]
	v_mfma_f32_16x16x32_bf16 v[52:55], v[156:159], v[200:203], v[52:55]
	v_mfma_f32_16x16x32_bf16 v[44:47], v[164:167], v[200:203], v[44:47]
	v_mfma_f32_16x16x32_bf16 v[36:39], v[156:159], v[208:211], v[36:39]
	v_mfma_f32_16x16x32_bf16 v[28:31], v[164:167], v[208:211], v[28:31]
	v_mfma_f32_16x16x32_bf16 v[20:23], v[156:159], v[216:219], v[20:23]
	v_mfma_f32_16x16x32_bf16 v[12:15], v[164:167], v[216:219], v[12:15]
	v_mfma_f32_16x16x32_bf16 v[48:51], v[168:171], v[184:187], 0
	v_mfma_f32_16x16x32_bf16 v[40:43], v[176:179], v[184:187], 0
	v_mfma_f32_16x16x32_bf16 v[32:35], v[168:171], v[196:199], 0
	v_mfma_f32_16x16x32_bf16 v[24:27], v[176:179], v[196:199], 0
	v_mfma_f32_16x16x32_bf16 v[16:19], v[168:171], v[204:207], 0
	v_mfma_f32_16x16x32_bf16 v[8:11], v[176:179], v[204:207], 0
	v_mfma_f32_16x16x32_bf16 v[4:7], v[168:171], v[212:215], 0
	v_mfma_f32_16x16x32_bf16 v[0:3], v[176:179], v[212:215], 0
	v_mfma_f32_16x16x32_bf16 v[48:51], v[172:175], v[192:195], v[48:51]
	v_mfma_f32_16x16x32_bf16 v[40:43], v[180:183], v[192:195], v[40:43]
	v_mfma_f32_16x16x32_bf16 v[32:35], v[172:175], v[200:203], v[32:35]
	v_mfma_f32_16x16x32_bf16 v[24:27], v[180:183], v[200:203], v[24:27]
	v_mfma_f32_16x16x32_bf16 v[16:19], v[172:175], v[208:211], v[16:19]
	v_mfma_f32_16x16x32_bf16 v[8:11], v[180:183], v[208:211], v[8:11]
	v_mfma_f32_16x16x32_bf16 v[4:7], v[172:175], v[216:219], v[4:7]
	v_mfma_f32_16x16x32_bf16 v[0:3], v[180:183], v[216:219], v[0:3]
	s_barrier
	s_add_i32 s76, 0, 0x18000
	s_add_i32 s77, 0, 0x1c000
	v_add_u32_e32 v164, s76, v147
	v_add_u32_e32 v180, s77, v147
	ds_read_b128 v[152:155], v164
	ds_read_b128 v[156:159], v164 offset:1024
	ds_read_b128 v[160:163], v164 offset:2048
	ds_read_b128 v[164:167], v164 offset:3072
	ds_read_b128 v[168:171], v180
	ds_read_b128 v[172:175], v180 offset:1024
	ds_read_b128 v[176:179], v180 offset:2048
	ds_read_b128 v[180:183], v180 offset:3072
	s_add_u32 s40, s40, 0x40000
	s_addc_u32 s41, s41, 0
	s_mov_b32 m0, s60
	ds_read_b128 v[184:187], v151 offset:32768
	ds_read_b128 v[192:195], v151 offset:33792
	ds_read_b128 v[196:199], v151 offset:34816
	ds_read_b128 v[200:203], v151 offset:35840
	ds_read_b128 v[204:207], v151 offset:36864
	ds_read_b128 v[208:211], v151 offset:37888
	ds_read_b128 v[212:215], v151 offset:38912
	ds_read_b128 v[216:219], v151 offset:39936
	global_load_lds_dwordx4 v128, s[40:41]
	s_mov_b32 m0, s61
	s_nop 0
	global_load_lds_dwordx4 v132, s[40:41]
	s_waitcnt vmcnt(8)
	s_waitcnt lgkmcnt(0)
	s_barrier
	s_waitcnt lgkmcnt(0)
	v_mfma_f32_16x16x32_bf16 v[124:127], v[152:155], v[184:187], v[124:127]
	v_mfma_f32_16x16x32_bf16 v[120:123], v[160:163], v[184:187], v[120:123]
	v_mfma_f32_16x16x32_bf16 v[116:119], v[152:155], v[196:199], v[116:119]
	v_mfma_f32_16x16x32_bf16 v[108:111], v[160:163], v[196:199], v[108:111]
	v_mfma_f32_16x16x32_bf16 v[100:103], v[152:155], v[204:207], v[100:103]
	v_mfma_f32_16x16x32_bf16 v[92:95], v[160:163], v[204:207], v[92:95]
	v_mfma_f32_16x16x32_bf16 v[84:87], v[152:155], v[212:215], v[84:87]
	v_mfma_f32_16x16x32_bf16 v[76:79], v[160:163], v[212:215], v[76:79]
	v_mfma_f32_16x16x32_bf16 v[124:127], v[156:159], v[192:195], v[124:127]
	v_mfma_f32_16x16x32_bf16 v[120:123], v[164:167], v[192:195], v[120:123]
	v_mfma_f32_16x16x32_bf16 v[116:119], v[156:159], v[200:203], v[116:119]
	v_mfma_f32_16x16x32_bf16 v[108:111], v[164:167], v[200:203], v[108:111]
	v_mfma_f32_16x16x32_bf16 v[100:103], v[156:159], v[208:211], v[100:103]
	v_mfma_f32_16x16x32_bf16 v[92:95], v[164:167], v[208:211], v[92:95]
	v_mfma_f32_16x16x32_bf16 v[84:87], v[156:159], v[216:219], v[84:87]
	v_mfma_f32_16x16x32_bf16 v[76:79], v[164:167], v[216:219], v[76:79]
	v_mfma_f32_16x16x32_bf16 v[112:115], v[168:171], v[184:187], v[112:115]
	v_mfma_f32_16x16x32_bf16 v[104:107], v[176:179], v[184:187], v[104:107]
	v_mfma_f32_16x16x32_bf16 v[96:99], v[168:171], v[196:199], v[96:99]
	v_mfma_f32_16x16x32_bf16 v[88:91], v[176:179], v[196:199], v[88:91]
	v_mfma_f32_16x16x32_bf16 v[80:83], v[168:171], v[204:207], v[80:83]
	v_mfma_f32_16x16x32_bf16 v[72:75], v[176:179], v[204:207], v[72:75]
	v_mfma_f32_16x16x32_bf16 v[68:71], v[168:171], v[212:215], v[68:71]
	v_mfma_f32_16x16x32_bf16 v[64:67], v[176:179], v[212:215], v[64:67]
	v_mfma_f32_16x16x32_bf16 v[112:115], v[172:175], v[192:195], v[112:115]
	v_mfma_f32_16x16x32_bf16 v[104:107], v[180:183], v[192:195], v[104:107]
	v_mfma_f32_16x16x32_bf16 v[96:99], v[172:175], v[200:203], v[96:99]
	v_mfma_f32_16x16x32_bf16 v[88:91], v[180:183], v[200:203], v[88:91]
	v_mfma_f32_16x16x32_bf16 v[80:83], v[172:175], v[208:211], v[80:83]
	v_mfma_f32_16x16x32_bf16 v[72:75], v[180:183], v[208:211], v[72:75]
	v_mfma_f32_16x16x32_bf16 v[68:71], v[172:175], v[216:219], v[68:71]
	v_mfma_f32_16x16x32_bf16 v[64:67], v[180:183], v[216:219], v[64:67]
	s_barrier
	s_add_i32 s40, s76, s53
	v_lshl_add_u64 v[144:145], v[144:145], 0, s[12:13]
	s_mov_b32 m0, s40
	ds_read_b128 v[184:187], v151 offset:49152
	ds_read_b128 v[192:195], v151 offset:50176
	ds_read_b128 v[196:199], v151 offset:51200
	ds_read_b128 v[200:203], v151 offset:52224
	ds_read_b128 v[204:207], v151 offset:53248
	ds_read_b128 v[208:211], v151 offset:54272
	ds_read_b128 v[212:215], v151 offset:55296
	ds_read_b128 v[216:219], v151 offset:56320
	global_load_lds_dwordx4 v[144:145], off
	s_add_i32 m0, s40, 0x2000
	s_add_u32 s38, s38, 0x40080
	v_lshl_add_u64 v[144:145], v[188:189], 0, s[12:13]
	s_addc_u32 s39, s39, 0
	s_add_i32 s40, s77, s53
	global_load_lds_dwordx4 v[144:145], off
	s_mov_b32 m0, s40
	s_nop 0
	global_load_lds_dwordx4 v130, s[38:39]
	s_add_i32 m0, s40, 0x2000
	s_nop 0
	global_load_lds_dwordx4 v134, s[38:39]
	v_lshl_add_u64 v[144:145], v[220:221], 0, s[12:13]
	s_mov_b32 m0, s63
	s_nop 0
	global_load_lds_dwordx4 v[144:145], off
	v_lshl_add_u64 v[144:145], v[222:223], 0, s[12:13]
	s_mov_b32 m0, s64
	s_nop 0
	global_load_lds_dwordx4 v[144:145], off
	s_waitcnt vmcnt(8)
	s_waitcnt lgkmcnt(0)
	s_barrier
	s_waitcnt lgkmcnt(0)
	v_mfma_f32_16x16x32_bf16 v[60:63], v[152:155], v[184:187], v[60:63]
	v_mfma_f32_16x16x32_bf16 v[56:59], v[160:163], v[184:187], v[56:59]
	v_mfma_f32_16x16x32_bf16 v[52:55], v[152:155], v[196:199], v[52:55]
	v_mfma_f32_16x16x32_bf16 v[44:47], v[160:163], v[196:199], v[44:47]
	v_mfma_f32_16x16x32_bf16 v[36:39], v[152:155], v[204:207], v[36:39]
	v_mfma_f32_16x16x32_bf16 v[28:31], v[160:163], v[204:207], v[28:31]
	v_mfma_f32_16x16x32_bf16 v[20:23], v[152:155], v[212:215], v[20:23]
	v_mfma_f32_16x16x32_bf16 v[12:15], v[160:163], v[212:215], v[12:15]
	v_mfma_f32_16x16x32_bf16 v[60:63], v[156:159], v[192:195], v[60:63]
	v_mfma_f32_16x16x32_bf16 v[56:59], v[164:167], v[192:195], v[56:59]
	v_mfma_f32_16x16x32_bf16 v[52:55], v[156:159], v[200:203], v[52:55]
	v_mfma_f32_16x16x32_bf16 v[44:47], v[164:167], v[200:203], v[44:47]
	v_mfma_f32_16x16x32_bf16 v[36:39], v[156:159], v[208:211], v[36:39]
	v_mfma_f32_16x16x32_bf16 v[28:31], v[164:167], v[208:211], v[28:31]
	v_mfma_f32_16x16x32_bf16 v[20:23], v[156:159], v[216:219], v[20:23]
	v_mfma_f32_16x16x32_bf16 v[12:15], v[164:167], v[216:219], v[12:15]
	v_mfma_f32_16x16x32_bf16 v[48:51], v[168:171], v[184:187], v[48:51]
	v_mfma_f32_16x16x32_bf16 v[40:43], v[176:179], v[184:187], v[40:43]
	v_mfma_f32_16x16x32_bf16 v[32:35], v[168:171], v[196:199], v[32:35]
	v_mfma_f32_16x16x32_bf16 v[24:27], v[176:179], v[196:199], v[24:27]
	v_mfma_f32_16x16x32_bf16 v[16:19], v[168:171], v[204:207], v[16:19]
	v_mfma_f32_16x16x32_bf16 v[8:11], v[176:179], v[204:207], v[8:11]
	v_mfma_f32_16x16x32_bf16 v[4:7], v[168:171], v[212:215], v[4:7]
	v_mfma_f32_16x16x32_bf16 v[0:3], v[176:179], v[212:215], v[0:3]
	v_mfma_f32_16x16x32_bf16 v[48:51], v[172:175], v[192:195], v[48:51]
	v_mfma_f32_16x16x32_bf16 v[40:43], v[180:183], v[192:195], v[40:43]
	v_mfma_f32_16x16x32_bf16 v[32:35], v[172:175], v[200:203], v[32:35]
	v_mfma_f32_16x16x32_bf16 v[24:27], v[180:183], v[200:203], v[24:27]
	v_mfma_f32_16x16x32_bf16 v[16:19], v[172:175], v[208:211], v[16:19]
	v_mfma_f32_16x16x32_bf16 v[8:11], v[180:183], v[208:211], v[8:11]
	v_mfma_f32_16x16x32_bf16 v[4:7], v[172:175], v[216:219], v[4:7]
	v_mfma_f32_16x16x32_bf16 v[0:3], v[180:183], v[216:219], v[0:3]
	s_barrier
	s_add_i32 s75, s75, 2
	s_add_u32 s36, s36, 0x100
	s_addc_u32 s37, s37, 0
	s_add_u32 s73, s73, 0x100
	s_addc_u32 s74, s74, 0
	s_cmp_gt_u32 s75, 13
	s_cbranch_scc0 .LBB0_302
	s_branch .Lpeel_exit1
.LBB0_302:
	ds_read_b128 v[152:155], v149
	ds_read_b128 v[156:159], v149 offset:1024
	ds_read_b128 v[160:163], v149 offset:2048
	ds_read_b128 v[164:167], v149 offset:3072
	ds_read_b128 v[168:171], v150
	ds_read_b128 v[172:175], v150 offset:1024
	ds_read_b128 v[176:179], v150 offset:2048
	ds_read_b128 v[180:183], v150 offset:3072
	s_add_u32 s38, s36, 0xfffc0080
	s_addc_u32 s39, s37, -1
	s_cmp_eq_u32 s75, 12
	s_cselect_b32 s41, s27, s39
	s_cselect_b32 s40, s55, s38
	s_cselect_b32 s39, s25, s74
	s_cselect_b32 s38, s72, s73
	v_lshl_add_u64 v[144:145], s[36:37], 0, v[136:137]
	s_add_i32 m0, s35, 0xc000
	ds_read_b128 v[184:187], v151
	ds_read_b128 v[192:195], v151 offset:1024
	ds_read_b128 v[196:199], v151 offset:2048
	ds_read_b128 v[200:203], v151 offset:3072
	ds_read_b128 v[204:207], v151 offset:4096
	ds_read_b128 v[208:211], v151 offset:5120
	ds_read_b128 v[212:215], v151 offset:6144
	ds_read_b128 v[216:219], v151 offset:7168
	global_load_lds_dwordx4 v[144:145], off
	s_add_i32 m0, s35, 0xe000
	s_nop 0
	global_load_lds_dwordx4 v138, s[36:37]
	s_waitcnt vmcnt(8)
	s_waitcnt lgkmcnt(0)
	s_barrier
	s_waitcnt lgkmcnt(0)
	v_mfma_f32_16x16x32_bf16 v[124:127], v[152:155], v[184:187], v[124:127]
	v_mfma_f32_16x16x32_bf16 v[120:123], v[160:163], v[184:187], v[120:123]
	v_mfma_f32_16x16x32_bf16 v[116:119], v[152:155], v[196:199], v[116:119]
	v_mfma_f32_16x16x32_bf16 v[108:111], v[160:163], v[196:199], v[108:111]
	v_mfma_f32_16x16x32_bf16 v[100:103], v[152:155], v[204:207], v[100:103]
	v_mfma_f32_16x16x32_bf16 v[92:95], v[160:163], v[204:207], v[92:95]
	v_mfma_f32_16x16x32_bf16 v[84:87], v[152:155], v[212:215], v[84:87]
	v_mfma_f32_16x16x32_bf16 v[76:79], v[160:163], v[212:215], v[76:79]
	v_mfma_f32_16x16x32_bf16 v[124:127], v[156:159], v[192:195], v[124:127]
	v_mfma_f32_16x16x32_bf16 v[120:123], v[164:167], v[192:195], v[120:123]
	v_mfma_f32_16x16x32_bf16 v[116:119], v[156:159], v[200:203], v[116:119]
	v_mfma_f32_16x16x32_bf16 v[108:111], v[164:167], v[200:203], v[108:111]
	v_mfma_f32_16x16x32_bf16 v[100:103], v[156:159], v[208:211], v[100:103]
	v_mfma_f32_16x16x32_bf16 v[92:95], v[164:167], v[208:211], v[92:95]
	v_mfma_f32_16x16x32_bf16 v[84:87], v[156:159], v[216:219], v[84:87]
	v_mfma_f32_16x16x32_bf16 v[76:79], v[164:167], v[216:219], v[76:79]
	v_mfma_f32_16x16x32_bf16 v[112:115], v[168:171], v[184:187], v[112:115]
	v_mfma_f32_16x16x32_bf16 v[104:107], v[176:179], v[184:187], v[104:107]
	v_mfma_f32_16x16x32_bf16 v[96:99], v[168:171], v[196:199], v[96:99]
	v_mfma_f32_16x16x32_bf16 v[88:91], v[176:179], v[196:199], v[88:91]
	v_mfma_f32_16x16x32_bf16 v[80:83], v[168:171], v[204:207], v[80:83]
	v_mfma_f32_16x16x32_bf16 v[72:75], v[176:179], v[204:207], v[72:75]
	v_mfma_f32_16x16x32_bf16 v[68:71], v[168:171], v[212:215], v[68:71]
	v_mfma_f32_16x16x32_bf16 v[64:67], v[176:179], v[212:215], v[64:67]
	v_mfma_f32_16x16x32_bf16 v[112:115], v[172:175], v[192:195], v[112:115]
	v_mfma_f32_16x16x32_bf16 v[104:107], v[180:183], v[192:195], v[104:107]
	v_mfma_f32_16x16x32_bf16 v[96:99], v[172:175], v[200:203], v[96:99]
	v_mfma_f32_16x16x32_bf16 v[88:91], v[180:183], v[200:203], v[88:91]
	v_mfma_f32_16x16x32_bf16 v[80:83], v[172:175], v[208:211], v[80:83]
	v_mfma_f32_16x16x32_bf16 v[72:75], v[180:183], v[208:211], v[72:75]
	v_mfma_f32_16x16x32_bf16 v[68:71], v[172:175], v[216:219], v[68:71]
	v_mfma_f32_16x16x32_bf16 v[64:67], v[180:183], v[216:219], v[64:67]
	s_barrier
	s_add_i32 s76, s66, s53
	v_lshl_add_u64 v[144:145], s[38:39], 0, v[130:131]
	s_mov_b32 m0, s76
	ds_read_b128 v[184:187], v151 offset:16384
	ds_read_b128 v[192:195], v151 offset:17408
	ds_read_b128 v[196:199], v151 offset:18432
	ds_read_b128 v[200:203], v151 offset:19456
	ds_read_b128 v[204:207], v151 offset:20480
	ds_read_b128 v[208:211], v151 offset:21504
	ds_read_b128 v[212:215], v151 offset:22528
	ds_read_b128 v[216:219], v151 offset:23552
	global_load_lds_dwordx4 v[144:145], off
	s_add_i32 m0, s76, 0x2000
	s_add_u32 s76, s38, 0x40000
	v_lshl_add_u64 v[188:189], s[38:39], 0, v[134:135]
	s_addc_u32 s77, s39, 0
	s_add_i32 s80, s67, s53
	global_load_lds_dwordx4 v[188:189], off
	s_mov_b32 m0, s80
	v_lshl_add_u64 v[222:223], s[40:41], 0, v[132:133]
	global_load_lds_dwordx4 v130, s[76:77]
	s_add_i32 m0, s80, 0x2000
	s_nop 0
	global_load_lds_dwordx4 v134, s[76:77]
	v_lshl_add_u64 v[220:221], s[40:41], 0, v[128:129]
	s_mov_b32 m0, s35
	s_nop 0
	global_load_lds_dwordx4 v[220:221], off
	s_mov_b32 m0, s33
	s_nop 0
	global_load_lds_dwordx4 v[222:223], off
	s_waitcnt vmcnt(8)
	s_waitcnt lgkmcnt(0)
	s_barrier
	s_waitcnt lgkmcnt(0)
	v_mfma_f32_16x16x32_bf16 v[60:63], v[152:155], v[184:187], v[60:63]
	v_mfma_f32_16x16x32_bf16 v[56:59], v[160:163], v[184:187], v[56:59]
	v_mfma_f32_16x16x32_bf16 v[52:55], v[152:155], v[196:199], v[52:55]
	v_mfma_f32_16x16x32_bf16 v[44:47], v[160:163], v[196:199], v[44:47]
	v_mfma_f32_16x16x32_bf16 v[36:39], v[152:155], v[204:207], v[36:39]
	v_mfma_f32_16x16x32_bf16 v[28:31], v[160:163], v[204:207], v[28:31]
	v_mfma_f32_16x16x32_bf16 v[20:23], v[152:155], v[212:215], v[20:23]
	v_mfma_f32_16x16x32_bf16 v[12:15], v[160:163], v[212:215], v[12:15]
	v_mfma_f32_16x16x32_bf16 v[60:63], v[156:159], v[192:195], v[60:63]
	v_mfma_f32_16x16x32_bf16 v[56:59], v[164:167], v[192:195], v[56:59]
	v_mfma_f32_16x16x32_bf16 v[52:55], v[156:159], v[200:203], v[52:55]
	v_mfma_f32_16x16x32_bf16 v[44:47], v[164:167], v[200:203], v[44:47]
	v_mfma_f32_16x16x32_bf16 v[36:39], v[156:159], v[208:211], v[36:39]
	v_mfma_f32_16x16x32_bf16 v[28:31], v[164:167], v[208:211], v[28:31]
	v_mfma_f32_16x16x32_bf16 v[20:23], v[156:159], v[216:219], v[20:23]
	v_mfma_f32_16x16x32_bf16 v[12:15], v[164:167], v[216:219], v[12:15]
	v_mfma_f32_16x16x32_bf16 v[48:51], v[168:171], v[184:187], v[48:51]
	v_mfma_f32_16x16x32_bf16 v[40:43], v[176:179], v[184:187], v[40:43]
	v_mfma_f32_16x16x32_bf16 v[32:35], v[168:171], v[196:199], v[32:35]
	v_mfma_f32_16x16x32_bf16 v[24:27], v[176:179], v[196:199], v[24:27]
	v_mfma_f32_16x16x32_bf16 v[16:19], v[168:171], v[204:207], v[16:19]
	v_mfma_f32_16x16x32_bf16 v[8:11], v[176:179], v[204:207], v[8:11]
	v_mfma_f32_16x16x32_bf16 v[4:7], v[168:171], v[212:215], v[4:7]
	v_mfma_f32_16x16x32_bf16 v[0:3], v[176:179], v[212:215], v[0:3]
	v_mfma_f32_16x16x32_bf16 v[48:51], v[172:175], v[192:195], v[48:51]
	v_mfma_f32_16x16x32_bf16 v[40:43], v[180:183], v[192:195], v[40:43]
	v_mfma_f32_16x16x32_bf16 v[32:35], v[172:175], v[200:203], v[32:35]
	v_mfma_f32_16x16x32_bf16 v[24:27], v[180:183], v[200:203], v[24:27]
	v_mfma_f32_16x16x32_bf16 v[16:19], v[172:175], v[208:211], v[16:19]
	v_mfma_f32_16x16x32_bf16 v[8:11], v[180:183], v[208:211], v[8:11]
	v_mfma_f32_16x16x32_bf16 v[4:7], v[172:175], v[216:219], v[4:7]
	v_mfma_f32_16x16x32_bf16 v[0:3], v[180:183], v[216:219], v[0:3]
	s_barrier
	s_add_i32 s76, 0, 0x18000
	s_add_i32 s77, 0, 0x1c000
	v_add_u32_e32 v164, s76, v147
	v_add_u32_e32 v180, s77, v147
	ds_read_b128 v[152:155], v164
	ds_read_b128 v[156:159], v164 offset:1024
	ds_read_b128 v[160:163], v164 offset:2048
	ds_read_b128 v[164:167], v164 offset:3072
	ds_read_b128 v[168:171], v180
	ds_read_b128 v[172:175], v180 offset:1024
	ds_read_b128 v[176:179], v180 offset:2048
	ds_read_b128 v[180:183], v180 offset:3072
	s_add_u32 s40, s40, 0x40000
	s_addc_u32 s41, s41, 0
	s_mov_b32 m0, s60
	ds_read_b128 v[184:187], v151 offset:32768
	ds_read_b128 v[192:195], v151 offset:33792
	ds_read_b128 v[196:199], v151 offset:34816
	ds_read_b128 v[200:203], v151 offset:35840
	ds_read_b128 v[204:207], v151 offset:36864
	ds_read_b128 v[208:211], v151 offset:37888
	ds_read_b128 v[212:215], v151 offset:38912
	ds_read_b128 v[216:219], v151 offset:39936
	global_load_lds_dwordx4 v128, s[40:41]
	s_mov_b32 m0, s61
	s_nop 0
	global_load_lds_dwordx4 v132, s[40:41]
	s_waitcnt vmcnt(8)
	s_waitcnt lgkmcnt(0)
	s_barrier
	s_waitcnt lgkmcnt(0)
	v_mfma_f32_16x16x32_bf16 v[124:127], v[152:155], v[184:187], v[124:127]
	v_mfma_f32_16x16x32_bf16 v[120:123], v[160:163], v[184:187], v[120:123]
	v_mfma_f32_16x16x32_bf16 v[116:119], v[152:155], v[196:199], v[116:119]
	v_mfma_f32_16x16x32_bf16 v[108:111], v[160:163], v[196:199], v[108:111]
	v_mfma_f32_16x16x32_bf16 v[100:103], v[152:155], v[204:207], v[100:103]
	v_mfma_f32_16x16x32_bf16 v[92:95], v[160:163], v[204:207], v[92:95]
	v_mfma_f32_16x16x32_bf16 v[84:87], v[152:155], v[212:215], v[84:87]
	v_mfma_f32_16x16x32_bf16 v[76:79], v[160:163], v[212:215], v[76:79]
	v_mfma_f32_16x16x32_bf16 v[124:127], v[156:159], v[192:195], v[124:127]
	v_mfma_f32_16x16x32_bf16 v[120:123], v[164:167], v[192:195], v[120:123]
	v_mfma_f32_16x16x32_bf16 v[116:119], v[156:159], v[200:203], v[116:119]
	v_mfma_f32_16x16x32_bf16 v[108:111], v[164:167], v[200:203], v[108:111]
	v_mfma_f32_16x16x32_bf16 v[100:103], v[156:159], v[208:211], v[100:103]
	v_mfma_f32_16x16x32_bf16 v[92:95], v[164:167], v[208:211], v[92:95]
	v_mfma_f32_16x16x32_bf16 v[84:87], v[156:159], v[216:219], v[84:87]
	v_mfma_f32_16x16x32_bf16 v[76:79], v[164:167], v[216:219], v[76:79]
	v_mfma_f32_16x16x32_bf16 v[112:115], v[168:171], v[184:187], v[112:115]
	v_mfma_f32_16x16x32_bf16 v[104:107], v[176:179], v[184:187], v[104:107]
	v_mfma_f32_16x16x32_bf16 v[96:99], v[168:171], v[196:199], v[96:99]
	v_mfma_f32_16x16x32_bf16 v[88:91], v[176:179], v[196:199], v[88:91]
	v_mfma_f32_16x16x32_bf16 v[80:83], v[168:171], v[204:207], v[80:83]
	v_mfma_f32_16x16x32_bf16 v[72:75], v[176:179], v[204:207], v[72:75]
	v_mfma_f32_16x16x32_bf16 v[68:71], v[168:171], v[212:215], v[68:71]
	v_mfma_f32_16x16x32_bf16 v[64:67], v[176:179], v[212:215], v[64:67]
	v_mfma_f32_16x16x32_bf16 v[112:115], v[172:175], v[192:195], v[112:115]
	v_mfma_f32_16x16x32_bf16 v[104:107], v[180:183], v[192:195], v[104:107]
	v_mfma_f32_16x16x32_bf16 v[96:99], v[172:175], v[200:203], v[96:99]
	v_mfma_f32_16x16x32_bf16 v[88:91], v[180:183], v[200:203], v[88:91]
	v_mfma_f32_16x16x32_bf16 v[80:83], v[172:175], v[208:211], v[80:83]
	v_mfma_f32_16x16x32_bf16 v[72:75], v[180:183], v[208:211], v[72:75]
	v_mfma_f32_16x16x32_bf16 v[68:71], v[172:175], v[216:219], v[68:71]
	v_mfma_f32_16x16x32_bf16 v[64:67], v[180:183], v[216:219], v[64:67]
	s_barrier
	s_add_i32 s40, s76, s53
	v_lshl_add_u64 v[144:145], v[144:145], 0, s[12:13]
	s_mov_b32 m0, s40
	ds_read_b128 v[184:187], v151 offset:49152
	ds_read_b128 v[192:195], v151 offset:50176
	ds_read_b128 v[196:199], v151 offset:51200
	ds_read_b128 v[200:203], v151 offset:52224
	ds_read_b128 v[204:207], v151 offset:53248
	ds_read_b128 v[208:211], v151 offset:54272
	ds_read_b128 v[212:215], v151 offset:55296
	ds_read_b128 v[216:219], v151 offset:56320
	global_load_lds_dwordx4 v[144:145], off
	s_add_i32 m0, s40, 0x2000
	s_add_u32 s38, s38, 0x40080
	v_lshl_add_u64 v[144:145], v[188:189], 0, s[12:13]
	s_addc_u32 s39, s39, 0
	s_add_i32 s40, s77, s53
	global_load_lds_dwordx4 v[144:145], off
	s_mov_b32 m0, s40
	s_nop 0
	global_load_lds_dwordx4 v130, s[38:39]
	s_add_i32 m0, s40, 0x2000
	s_nop 0
	global_load_lds_dwordx4 v134, s[38:39]
	v_lshl_add_u64 v[144:145], v[220:221], 0, s[12:13]
	s_mov_b32 m0, s63
	s_nop 0
	global_load_lds_dwordx4 v[144:145], off
	v_lshl_add_u64 v[144:145], v[222:223], 0, s[12:13]
	s_mov_b32 m0, s64
	s_nop 0
	global_load_lds_dwordx4 v[144:145], off
	s_waitcnt vmcnt(8)
	s_waitcnt lgkmcnt(0)
	s_barrier
	s_waitcnt lgkmcnt(0)
	v_mfma_f32_16x16x32_bf16 v[60:63], v[152:155], v[184:187], v[60:63]
	v_mfma_f32_16x16x32_bf16 v[56:59], v[160:163], v[184:187], v[56:59]
	v_mfma_f32_16x16x32_bf16 v[52:55], v[152:155], v[196:199], v[52:55]
	v_mfma_f32_16x16x32_bf16 v[44:47], v[160:163], v[196:199], v[44:47]
	v_mfma_f32_16x16x32_bf16 v[36:39], v[152:155], v[204:207], v[36:39]
	v_mfma_f32_16x16x32_bf16 v[28:31], v[160:163], v[204:207], v[28:31]
	v_mfma_f32_16x16x32_bf16 v[20:23], v[152:155], v[212:215], v[20:23]
	v_mfma_f32_16x16x32_bf16 v[12:15], v[160:163], v[212:215], v[12:15]
	v_mfma_f32_16x16x32_bf16 v[60:63], v[156:159], v[192:195], v[60:63]
	v_mfma_f32_16x16x32_bf16 v[56:59], v[164:167], v[192:195], v[56:59]
	v_mfma_f32_16x16x32_bf16 v[52:55], v[156:159], v[200:203], v[52:55]
	v_mfma_f32_16x16x32_bf16 v[44:47], v[164:167], v[200:203], v[44:47]
	v_mfma_f32_16x16x32_bf16 v[36:39], v[156:159], v[208:211], v[36:39]
	v_mfma_f32_16x16x32_bf16 v[28:31], v[164:167], v[208:211], v[28:31]
	v_mfma_f32_16x16x32_bf16 v[20:23], v[156:159], v[216:219], v[20:23]
	v_mfma_f32_16x16x32_bf16 v[12:15], v[164:167], v[216:219], v[12:15]
	v_mfma_f32_16x16x32_bf16 v[48:51], v[168:171], v[184:187], v[48:51]
	v_mfma_f32_16x16x32_bf16 v[40:43], v[176:179], v[184:187], v[40:43]
	v_mfma_f32_16x16x32_bf16 v[32:35], v[168:171], v[196:199], v[32:35]
	v_mfma_f32_16x16x32_bf16 v[24:27], v[176:179], v[196:199], v[24:27]
	v_mfma_f32_16x16x32_bf16 v[16:19], v[168:171], v[204:207], v[16:19]
	v_mfma_f32_16x16x32_bf16 v[8:11], v[176:179], v[204:207], v[8:11]
	v_mfma_f32_16x16x32_bf16 v[4:7], v[168:171], v[212:215], v[4:7]
	v_mfma_f32_16x16x32_bf16 v[0:3], v[176:179], v[212:215], v[0:3]
	v_mfma_f32_16x16x32_bf16 v[48:51], v[172:175], v[192:195], v[48:51]
	v_mfma_f32_16x16x32_bf16 v[40:43], v[180:183], v[192:195], v[40:43]
	v_mfma_f32_16x16x32_bf16 v[32:35], v[172:175], v[200:203], v[32:35]
	v_mfma_f32_16x16x32_bf16 v[24:27], v[180:183], v[200:203], v[24:27]
	v_mfma_f32_16x16x32_bf16 v[16:19], v[172:175], v[208:211], v[16:19]
	v_mfma_f32_16x16x32_bf16 v[8:11], v[180:183], v[208:211], v[8:11]
	v_mfma_f32_16x16x32_bf16 v[4:7], v[172:175], v[216:219], v[4:7]
	v_mfma_f32_16x16x32_bf16 v[0:3], v[180:183], v[216:219], v[0:3]
	s_barrier
	s_add_i32 s75, s75, 2
	s_add_u32 s36, s36, 0x100
	s_addc_u32 s37, s37, 0
	s_add_u32 s73, s73, 0x100
	s_addc_u32 s74, s74, 0
	s_cmp_gt_u32 s75, 13
	s_cbranch_scc0 .LBB0_302

.LBB0_699:
	s_ashr_i32 s25, s24, 31
	s_lshl_b64 s[26:27], s[24:25], 19
	s_add_u32 s26, s58, s26
	s_addc_u32 s27, s59, s27
	s_and_b64 s[28:29], s[4:5], exec
	s_cselect_b32 s25, s27, s35
	s_cselect_b32 s55, s26, s34
	s_ashr_i32 s23, s22, 31
	s_lshl_b64 s[28:29], s[22:23], 19
	s_add_u32 s28, s43, s28
	s_addc_u32 s29, s52, s29
	s_and_b64 s[40:41], s[4:5], exec
	s_cselect_b32 s23, s29, s39
	s_cselect_b32 s72, s28, s38
	s_add_u32 s34, s34, 0x40080
	s_addc_u32 s35, s35, 0
	s_add_u32 s73, s38, 0x100
	s_addc_u32 s74, s39, 0
	s_mov_b32 s75, -2
	ds_read_b128 v[152:155], v149
	ds_read_b128 v[156:159], v149 offset:1024
	ds_read_b128 v[160:163], v149 offset:2048
	ds_read_b128 v[164:167], v149 offset:3072
	ds_read_b128 v[168:171], v150
	ds_read_b128 v[172:175], v150 offset:1024
	ds_read_b128 v[176:179], v150 offset:2048
	ds_read_b128 v[180:183], v150 offset:3072
	s_add_u32 s38, s34, 0xfffc0080
	s_addc_u32 s39, s35, -1
	s_cmp_eq_u32 s75, 12
	s_cselect_b32 s41, s25, s39
	s_cselect_b32 s40, s55, s38
	s_cselect_b32 s39, s23, s74
	s_cselect_b32 s38, s72, s73
	s_add_i32 m0, s31, 0xc000
	ds_read_b128 v[184:187], v151
	ds_read_b128 v[192:195], v151 offset:1024
	ds_read_b128 v[196:199], v151 offset:2048
	ds_read_b128 v[200:203], v151 offset:3072
	ds_read_b128 v[204:207], v151 offset:4096
	ds_read_b128 v[208:211], v151 offset:5120
	ds_read_b128 v[212:215], v151 offset:6144
	ds_read_b128 v[216:219], v151 offset:7168
	global_load_lds_dwordx4 v136, s[34:35]
	s_add_i32 m0, s31, 0xe000
	s_nop 0
	global_load_lds_dwordx4 v138, s[34:35]
	s_waitcnt vmcnt(8)
	s_waitcnt lgkmcnt(0)
	s_barrier
	s_waitcnt lgkmcnt(0)
	v_mfma_f32_16x16x32_bf16 v[124:127], v[152:155], v[184:187], 0
	v_mfma_f32_16x16x32_bf16 v[120:123], v[160:163], v[184:187], 0
	v_mfma_f32_16x16x32_bf16 v[116:119], v[152:155], v[196:199], 0
	v_mfma_f32_16x16x32_bf16 v[108:111], v[160:163], v[196:199], 0
	v_mfma_f32_16x16x32_bf16 v[100:103], v[152:155], v[204:207], 0
	v_mfma_f32_16x16x32_bf16 v[92:95], v[160:163], v[204:207], 0
	v_mfma_f32_16x16x32_bf16 v[84:87], v[152:155], v[212:215], 0
	v_mfma_f32_16x16x32_bf16 v[76:79], v[160:163], v[212:215], 0
	v_mfma_f32_16x16x32_bf16 v[124:127], v[156:159], v[192:195], v[124:127]
	v_mfma_f32_16x16x32_bf16 v[120:123], v[164:167], v[192:195], v[120:123]
	v_mfma_f32_16x16x32_bf16 v[116:119], v[156:159], v[200:203], v[116:119]
	v_mfma_f32_16x16x32_bf16 v[108:111], v[164:167], v[200:203], v[108:111]
	v_mfma_f32_16x16x32_bf16 v[100:103], v[156:159], v[208:211], v[100:103]
	v_mfma_f32_16x16x32_bf16 v[92:95], v[164:167], v[208:211], v[92:95]
	v_mfma_f32_16x16x32_bf16 v[84:87], v[156:159], v[216:219], v[84:87]
	v_mfma_f32_16x16x32_bf16 v[76:79], v[164:167], v[216:219], v[76:79]
	v_mfma_f32_16x16x32_bf16 v[112:115], v[168:171], v[184:187], 0
	v_mfma_f32_16x16x32_bf16 v[104:107], v[176:179], v[184:187], 0
	v_mfma_f32_16x16x32_bf16 v[96:99], v[168:171], v[196:199], 0
	v_mfma_f32_16x16x32_bf16 v[88:91], v[176:179], v[196:199], 0
	v_mfma_f32_16x16x32_bf16 v[80:83], v[168:171], v[204:207], 0
	v_mfma_f32_16x16x32_bf16 v[72:75], v[176:179], v[204:207], 0
	v_mfma_f32_16x16x32_bf16 v[68:71], v[168:171], v[212:215], 0
	v_mfma_f32_16x16x32_bf16 v[64:67], v[176:179], v[212:215], 0
	v_mfma_f32_16x16x32_bf16 v[112:115], v[172:175], v[192:195], v[112:115]
	v_mfma_f32_16x16x32_bf16 v[104:107], v[180:183], v[192:195], v[104:107]
	v_mfma_f32_16x16x32_bf16 v[96:99], v[172:175], v[200:203], v[96:99]
	v_mfma_f32_16x16x32_bf16 v[88:91], v[180:183], v[200:203], v[88:91]
	v_mfma_f32_16x16x32_bf16 v[80:83], v[172:175], v[208:211], v[80:83]
	v_mfma_f32_16x16x32_bf16 v[72:75], v[180:183], v[208:211], v[72:75]
	v_mfma_f32_16x16x32_bf16 v[68:71], v[172:175], v[216:219], v[68:71]
	v_mfma_f32_16x16x32_bf16 v[64:67], v[180:183], v[216:219], v[64:67]
	s_barrier
	s_add_i32 s76, s66, s53
	v_lshl_add_u64 v[144:145], s[38:39], 0, v[130:131]
	s_mov_b32 m0, s76
	ds_read_b128 v[184:187], v151 offset:16384
	ds_read_b128 v[192:195], v151 offset:17408
	ds_read_b128 v[196:199], v151 offset:18432
	ds_read_b128 v[200:203], v151 offset:19456
	ds_read_b128 v[204:207], v151 offset:20480
	ds_read_b128 v[208:211], v151 offset:21504
	ds_read_b128 v[212:215], v151 offset:22528
	ds_read_b128 v[216:219], v151 offset:23552
	global_load_lds_dwordx4 v[144:145], off
	s_add_i32 m0, s76, 0x2000
	s_add_u32 s76, s38, 0x40000
	v_lshl_add_u64 v[188:189], s[38:39], 0, v[134:135]
	s_addc_u32 s77, s39, 0
	s_add_i32 s79, s67, s53
	global_load_lds_dwordx4 v[188:189], off
	s_mov_b32 m0, s79
	v_lshl_add_u64 v[222:223], s[40:41], 0, v[132:133]
	global_load_lds_dwordx4 v130, s[76:77]
	s_add_i32 m0, s79, 0x2000
	s_nop 0
	global_load_lds_dwordx4 v134, s[76:77]
	v_lshl_add_u64 v[220:221], s[40:41], 0, v[128:129]
	s_mov_b32 m0, s31
	s_nop 0
	global_load_lds_dwordx4 v[220:221], off
	s_mov_b32 m0, s33
	s_nop 0
	global_load_lds_dwordx4 v[222:223], off
	s_waitcnt vmcnt(8)
	s_waitcnt lgkmcnt(0)
	s_barrier
	s_waitcnt lgkmcnt(0)
	v_mfma_f32_16x16x32_bf16 v[60:63], v[152:155], v[184:187], 0
	v_mfma_f32_16x16x32_bf16 v[56:59], v[160:163], v[184:187], 0
	v_mfma_f32_16x16x32_bf16 v[52:55], v[152:155], v[196:199], 0
	v_mfma_f32_16x16x32_bf16 v[44:47], v[160:163], v[196:199], 0
	v_mfma_f32_16x16x32_bf16 v[36:39], v[152:155], v[204:207], 0
	v_mfma_f32_16x16x32_bf16 v[28:31], v[160:163], v[204:207], 0
	v_mfma_f32_16x16x32_bf16 v[20:23], v[152:155], v[212:215], 0
	v_mfma_f32_16x16x32_bf16 v[12:15], v[160:163], v[212:215], 0
	v_mfma_f32_16x16x32_bf16 v[60:63], v[156:159], v[192:195], v[60:63]
	v_mfma_f32_16x16x32_bf16 v[56:59], v[164:167], v[192:195], v[56:59]
	v_mfma_f32_16x16x32_bf16 v[52:55], v[156:159], v[200:203], v[52:55]
	v_mfma_f32_16x16x32_bf16 v[44:47], v[164:167], v[200:203], v[44:47]
	v_mfma_f32_16x16x32_bf16 v[36:39], v[156:159], v[208:211], v[36:39]
	v_mfma_f32_16x16x32_bf16 v[28:31], v[164:167], v[208:211], v[28:31]
	v_mfma_f32_16x16x32_bf16 v[20:23], v[156:159], v[216:219], v[20:23]
	v_mfma_f32_16x16x32_bf16 v[12:15], v[164:167], v[216:219], v[12:15]
	v_mfma_f32_16x16x32_bf16 v[48:51], v[168:171], v[184:187], 0
	v_mfma_f32_16x16x32_bf16 v[40:43], v[176:179], v[184:187], 0
	v_mfma_f32_16x16x32_bf16 v[32:35], v[168:171], v[196:199], 0
	v_mfma_f32_16x16x32_bf16 v[24:27], v[176:179], v[196:199], 0
	v_mfma_f32_16x16x32_bf16 v[16:19], v[168:171], v[204:207], 0
	v_mfma_f32_16x16x32_bf16 v[8:11], v[176:179], v[204:207], 0
	v_mfma_f32_16x16x32_bf16 v[4:7], v[168:171], v[212:215], 0
	v_mfma_f32_16x16x32_bf16 v[0:3], v[176:179], v[212:215], 0
	v_mfma_f32_16x16x32_bf16 v[48:51], v[172:175], v[192:195], v[48:51]
	v_mfma_f32_16x16x32_bf16 v[40:43], v[180:183], v[192:195], v[40:43]
	v_mfma_f32_16x16x32_bf16 v[32:35], v[172:175], v[200:203], v[32:35]
	v_mfma_f32_16x16x32_bf16 v[24:27], v[180:183], v[200:203], v[24:27]
	v_mfma_f32_16x16x32_bf16 v[16:19], v[172:175], v[208:211], v[16:19]
	v_mfma_f32_16x16x32_bf16 v[8:11], v[180:183], v[208:211], v[8:11]
	v_mfma_f32_16x16x32_bf16 v[4:7], v[172:175], v[216:219], v[4:7]
	v_mfma_f32_16x16x32_bf16 v[0:3], v[180:183], v[216:219], v[0:3]
	s_barrier
	s_add_i32 s76, 0, 0x18000
	s_add_i32 s77, 0, 0x1c000
	v_add_u32_e32 v164, s76, v147
	v_add_u32_e32 v180, s77, v147
	ds_read_b128 v[152:155], v164
	ds_read_b128 v[156:159], v164 offset:1024
	ds_read_b128 v[160:163], v164 offset:2048
	ds_read_b128 v[164:167], v164 offset:3072
	ds_read_b128 v[168:171], v180
	ds_read_b128 v[172:175], v180 offset:1024
	ds_read_b128 v[176:179], v180 offset:2048
	ds_read_b128 v[180:183], v180 offset:3072
	s_add_u32 s40, s40, 0x40000
	s_addc_u32 s41, s41, 0
	s_mov_b32 m0, s60
	ds_read_b128 v[184:187], v151 offset:32768
	ds_read_b128 v[192:195], v151 offset:33792
	ds_read_b128 v[196:199], v151 offset:34816
	ds_read_b128 v[200:203], v151 offset:35840
	ds_read_b128 v[204:207], v151 offset:36864
	ds_read_b128 v[208:211], v151 offset:37888
	ds_read_b128 v[212:215], v151 offset:38912
	ds_read_b128 v[216:219], v151 offset:39936
	global_load_lds_dwordx4 v128, s[40:41]
	s_mov_b32 m0, s61
	s_nop 0
	global_load_lds_dwordx4 v132, s[40:41]
	s_waitcnt vmcnt(8)
	s_waitcnt lgkmcnt(0)
	s_barrier
	s_waitcnt lgkmcnt(0)
	v_mfma_f32_16x16x32_bf16 v[124:127], v[152:155], v[184:187], v[124:127]
	v_mfma_f32_16x16x32_bf16 v[120:123], v[160:163], v[184:187], v[120:123]
	v_mfma_f32_16x16x32_bf16 v[116:119], v[152:155], v[196:199], v[116:119]
	v_mfma_f32_16x16x32_bf16 v[108:111], v[160:163], v[196:199], v[108:111]
	v_mfma_f32_16x16x32_bf16 v[100:103], v[152:155], v[204:207], v[100:103]
	v_mfma_f32_16x16x32_bf16 v[92:95], v[160:163], v[204:207], v[92:95]
	v_mfma_f32_16x16x32_bf16 v[84:87], v[152:155], v[212:215], v[84:87]
	v_mfma_f32_16x16x32_bf16 v[76:79], v[160:163], v[212:215], v[76:79]
	v_mfma_f32_16x16x32_bf16 v[124:127], v[156:159], v[192:195], v[124:127]
	v_mfma_f32_16x16x32_bf16 v[120:123], v[164:167], v[192:195], v[120:123]
	v_mfma_f32_16x16x32_bf16 v[116:119], v[156:159], v[200:203], v[116:119]
	v_mfma_f32_16x16x32_bf16 v[108:111], v[164:167], v[200:203], v[108:111]
	v_mfma_f32_16x16x32_bf16 v[100:103], v[156:159], v[208:211], v[100:103]
	v_mfma_f32_16x16x32_bf16 v[92:95], v[164:167], v[208:211], v[92:95]
	v_mfma_f32_16x16x32_bf16 v[84:87], v[156:159], v[216:219], v[84:87]
	v_mfma_f32_16x16x32_bf16 v[76:79], v[164:167], v[216:219], v[76:79]
	v_mfma_f32_16x16x32_bf16 v[112:115], v[168:171], v[184:187], v[112:115]
	v_mfma_f32_16x16x32_bf16 v[104:107], v[176:179], v[184:187], v[104:107]
	v_mfma_f32_16x16x32_bf16 v[96:99], v[168:171], v[196:199], v[96:99]
	v_mfma_f32_16x16x32_bf16 v[88:91], v[176:179], v[196:199], v[88:91]
	v_mfma_f32_16x16x32_bf16 v[80:83], v[168:171], v[204:207], v[80:83]
	v_mfma_f32_16x16x32_bf16 v[72:75], v[176:179], v[204:207], v[72:75]
	v_mfma_f32_16x16x32_bf16 v[68:71], v[168:171], v[212:215], v[68:71]
	v_mfma_f32_16x16x32_bf16 v[64:67], v[176:179], v[212:215], v[64:67]
	v_mfma_f32_16x16x32_bf16 v[112:115], v[172:175], v[192:195], v[112:115]
	v_mfma_f32_16x16x32_bf16 v[104:107], v[180:183], v[192:195], v[104:107]
	v_mfma_f32_16x16x32_bf16 v[96:99], v[172:175], v[200:203], v[96:99]
	v_mfma_f32_16x16x32_bf16 v[88:91], v[180:183], v[200:203], v[88:91]
	v_mfma_f32_16x16x32_bf16 v[80:83], v[172:175], v[208:211], v[80:83]
	v_mfma_f32_16x16x32_bf16 v[72:75], v[180:183], v[208:211], v[72:75]
	v_mfma_f32_16x16x32_bf16 v[68:71], v[172:175], v[216:219], v[68:71]
	v_mfma_f32_16x16x32_bf16 v[64:67], v[180:183], v[216:219], v[64:67]
	s_barrier
	s_add_i32 s40, s76, s53
	v_lshl_add_u64 v[144:145], v[144:145], 0, s[12:13]
	s_mov_b32 m0, s40
	ds_read_b128 v[184:187], v151 offset:49152
	ds_read_b128 v[192:195], v151 offset:50176
	ds_read_b128 v[196:199], v151 offset:51200
	ds_read_b128 v[200:203], v151 offset:52224
	ds_read_b128 v[204:207], v151 offset:53248
	ds_read_b128 v[208:211], v151 offset:54272
	ds_read_b128 v[212:215], v151 offset:55296
	ds_read_b128 v[216:219], v151 offset:56320
	global_load_lds_dwordx4 v[144:145], off
	s_add_i32 m0, s40, 0x2000
	s_add_u32 s38, s38, 0x40080
	v_lshl_add_u64 v[144:145], v[188:189], 0, s[12:13]
	s_addc_u32 s39, s39, 0
	s_add_i32 s40, s77, s53
	global_load_lds_dwordx4 v[144:145], off
	s_mov_b32 m0, s40
	s_nop 0
	global_load_lds_dwordx4 v130, s[38:39]
	s_add_i32 m0, s40, 0x2000
	s_nop 0
	global_load_lds_dwordx4 v134, s[38:39]
	v_lshl_add_u64 v[144:145], v[220:221], 0, s[12:13]
	s_mov_b32 m0, s63
	s_nop 0
	global_load_lds_dwordx4 v[144:145], off
	v_lshl_add_u64 v[144:145], v[222:223], 0, s[12:13]
	s_mov_b32 m0, s64
	s_nop 0
	global_load_lds_dwordx4 v[144:145], off
	s_waitcnt vmcnt(8)
	s_waitcnt lgkmcnt(0)
	s_barrier
	s_waitcnt lgkmcnt(0)
	v_mfma_f32_16x16x32_bf16 v[60:63], v[152:155], v[184:187], v[60:63]
	v_mfma_f32_16x16x32_bf16 v[56:59], v[160:163], v[184:187], v[56:59]
	v_mfma_f32_16x16x32_bf16 v[52:55], v[152:155], v[196:199], v[52:55]
	v_mfma_f32_16x16x32_bf16 v[44:47], v[160:163], v[196:199], v[44:47]
	v_mfma_f32_16x16x32_bf16 v[36:39], v[152:155], v[204:207], v[36:39]
	v_mfma_f32_16x16x32_bf16 v[28:31], v[160:163], v[204:207], v[28:31]
	v_mfma_f32_16x16x32_bf16 v[20:23], v[152:155], v[212:215], v[20:23]
	v_mfma_f32_16x16x32_bf16 v[12:15], v[160:163], v[212:215], v[12:15]
	v_mfma_f32_16x16x32_bf16 v[60:63], v[156:159], v[192:195], v[60:63]
	v_mfma_f32_16x16x32_bf16 v[56:59], v[164:167], v[192:195], v[56:59]
	v_mfma_f32_16x16x32_bf16 v[52:55], v[156:159], v[200:203], v[52:55]
	v_mfma_f32_16x16x32_bf16 v[44:47], v[164:167], v[200:203], v[44:47]
	v_mfma_f32_16x16x32_bf16 v[36:39], v[156:159], v[208:211], v[36:39]
	v_mfma_f32_16x16x32_bf16 v[28:31], v[164:167], v[208:211], v[28:31]
	v_mfma_f32_16x16x32_bf16 v[20:23], v[156:159], v[216:219], v[20:23]
	v_mfma_f32_16x16x32_bf16 v[12:15], v[164:167], v[216:219], v[12:15]
	v_mfma_f32_16x16x32_bf16 v[48:51], v[168:171], v[184:187], v[48:51]
	v_mfma_f32_16x16x32_bf16 v[40:43], v[176:179], v[184:187], v[40:43]
	v_mfma_f32_16x16x32_bf16 v[32:35], v[168:171], v[196:199], v[32:35]
	v_mfma_f32_16x16x32_bf16 v[24:27], v[176:179], v[196:199], v[24:27]
	v_mfma_f32_16x16x32_bf16 v[16:19], v[168:171], v[204:207], v[16:19]
	v_mfma_f32_16x16x32_bf16 v[8:11], v[176:179], v[204:207], v[8:11]
	v_mfma_f32_16x16x32_bf16 v[4:7], v[168:171], v[212:215], v[4:7]
	v_mfma_f32_16x16x32_bf16 v[0:3], v[176:179], v[212:215], v[0:3]
	v_mfma_f32_16x16x32_bf16 v[48:51], v[172:175], v[192:195], v[48:51]
	v_mfma_f32_16x16x32_bf16 v[40:43], v[180:183], v[192:195], v[40:43]
	v_mfma_f32_16x16x32_bf16 v[32:35], v[172:175], v[200:203], v[32:35]
	v_mfma_f32_16x16x32_bf16 v[24:27], v[180:183], v[200:203], v[24:27]
	v_mfma_f32_16x16x32_bf16 v[16:19], v[172:175], v[208:211], v[16:19]
	v_mfma_f32_16x16x32_bf16 v[8:11], v[180:183], v[208:211], v[8:11]
	v_mfma_f32_16x16x32_bf16 v[4:7], v[172:175], v[216:219], v[4:7]
	v_mfma_f32_16x16x32_bf16 v[0:3], v[180:183], v[216:219], v[0:3]
	s_barrier
	s_add_i32 s75, s75, 2
	s_add_u32 s34, s34, 0x100
	s_addc_u32 s35, s35, 0
	s_add_u32 s73, s73, 0x100
	s_addc_u32 s74, s74, 0
	s_cmp_gt_u32 s75, 13
	s_cbranch_scc0 .LBB0_700
	s_branch .Lpeel_exit2
.LBB0_700:
	ds_read_b128 v[152:155], v149
	ds_read_b128 v[156:159], v149 offset:1024
	ds_read_b128 v[160:163], v149 offset:2048
	ds_read_b128 v[164:167], v149 offset:3072
	ds_read_b128 v[168:171], v150
	ds_read_b128 v[172:175], v150 offset:1024
	ds_read_b128 v[176:179], v150 offset:2048
	ds_read_b128 v[180:183], v150 offset:3072
	s_add_u32 s38, s34, 0xfffc0080
	s_addc_u32 s39, s35, -1
	s_cmp_eq_u32 s75, 12
	s_cselect_b32 s41, s25, s39
	s_cselect_b32 s40, s55, s38
	s_cselect_b32 s39, s23, s74
	s_cselect_b32 s38, s72, s73
	s_add_i32 m0, s31, 0xc000
	ds_read_b128 v[184:187], v151
	ds_read_b128 v[192:195], v151 offset:1024
	ds_read_b128 v[196:199], v151 offset:2048
	ds_read_b128 v[200:203], v151 offset:3072
	ds_read_b128 v[204:207], v151 offset:4096
	ds_read_b128 v[208:211], v151 offset:5120
	ds_read_b128 v[212:215], v151 offset:6144
	ds_read_b128 v[216:219], v151 offset:7168
	global_load_lds_dwordx4 v136, s[34:35]
	s_add_i32 m0, s31, 0xe000
	s_nop 0
	global_load_lds_dwordx4 v138, s[34:35]
	s_waitcnt vmcnt(8)
	s_waitcnt lgkmcnt(0)
	s_barrier
	s_waitcnt lgkmcnt(0)
	v_mfma_f32_16x16x32_bf16 v[124:127], v[152:155], v[184:187], v[124:127]
	v_mfma_f32_16x16x32_bf16 v[120:123], v[160:163], v[184:187], v[120:123]
	v_mfma_f32_16x16x32_bf16 v[116:119], v[152:155], v[196:199], v[116:119]
	v_mfma_f32_16x16x32_bf16 v[108:111], v[160:163], v[196:199], v[108:111]
	v_mfma_f32_16x16x32_bf16 v[100:103], v[152:155], v[204:207], v[100:103]
	v_mfma_f32_16x16x32_bf16 v[92:95], v[160:163], v[204:207], v[92:95]
	v_mfma_f32_16x16x32_bf16 v[84:87], v[152:155], v[212:215], v[84:87]
	v_mfma_f32_16x16x32_bf16 v[76:79], v[160:163], v[212:215], v[76:79]
	v_mfma_f32_16x16x32_bf16 v[124:127], v[156:159], v[192:195], v[124:127]
	v_mfma_f32_16x16x32_bf16 v[120:123], v[164:167], v[192:195], v[120:123]
	v_mfma_f32_16x16x32_bf16 v[116:119], v[156:159], v[200:203], v[116:119]
	v_mfma_f32_16x16x32_bf16 v[108:111], v[164:167], v[200:203], v[108:111]
	v_mfma_f32_16x16x32_bf16 v[100:103], v[156:159], v[208:211], v[100:103]
	v_mfma_f32_16x16x32_bf16 v[92:95], v[164:167], v[208:211], v[92:95]
	v_mfma_f32_16x16x32_bf16 v[84:87], v[156:159], v[216:219], v[84:87]
	v_mfma_f32_16x16x32_bf16 v[76:79], v[164:167], v[216:219], v[76:79]
	v_mfma_f32_16x16x32_bf16 v[112:115], v[168:171], v[184:187], v[112:115]
	v_mfma_f32_16x16x32_bf16 v[104:107], v[176:179], v[184:187], v[104:107]
	v_mfma_f32_16x16x32_bf16 v[96:99], v[168:171], v[196:199], v[96:99]
	v_mfma_f32_16x16x32_bf16 v[88:91], v[176:179], v[196:199], v[88:91]
	v_mfma_f32_16x16x32_bf16 v[80:83], v[168:171], v[204:207], v[80:83]
	v_mfma_f32_16x16x32_bf16 v[72:75], v[176:179], v[204:207], v[72:75]
	v_mfma_f32_16x16x32_bf16 v[68:71], v[168:171], v[212:215], v[68:71]
	v_mfma_f32_16x16x32_bf16 v[64:67], v[176:179], v[212:215], v[64:67]
	v_mfma_f32_16x16x32_bf16 v[112:115], v[172:175], v[192:195], v[112:115]
	v_mfma_f32_16x16x32_bf16 v[104:107], v[180:183], v[192:195], v[104:107]
	v_mfma_f32_16x16x32_bf16 v[96:99], v[172:175], v[200:203], v[96:99]
	v_mfma_f32_16x16x32_bf16 v[88:91], v[180:183], v[200:203], v[88:91]
	v_mfma_f32_16x16x32_bf16 v[80:83], v[172:175], v[208:211], v[80:83]
	v_mfma_f32_16x16x32_bf16 v[72:75], v[180:183], v[208:211], v[72:75]
	v_mfma_f32_16x16x32_bf16 v[68:71], v[172:175], v[216:219], v[68:71]
	v_mfma_f32_16x16x32_bf16 v[64:67], v[180:183], v[216:219], v[64:67]
	s_barrier
	s_add_i32 s76, s66, s53
	v_lshl_add_u64 v[144:145], s[38:39], 0, v[130:131]
	s_mov_b32 m0, s76
	ds_read_b128 v[184:187], v151 offset:16384
	ds_read_b128 v[192:195], v151 offset:17408
	ds_read_b128 v[196:199], v151 offset:18432
	ds_read_b128 v[200:203], v151 offset:19456
	ds_read_b128 v[204:207], v151 offset:20480
	ds_read_b128 v[208:211], v151 offset:21504
	ds_read_b128 v[212:215], v151 offset:22528
	ds_read_b128 v[216:219], v151 offset:23552
	global_load_lds_dwordx4 v[144:145], off
	s_add_i32 m0, s76, 0x2000
	s_add_u32 s76, s38, 0x40000
	v_lshl_add_u64 v[188:189], s[38:39], 0, v[134:135]
	s_addc_u32 s77, s39, 0
	s_add_i32 s79, s67, s53
	global_load_lds_dwordx4 v[188:189], off
	s_mov_b32 m0, s79
	v_lshl_add_u64 v[222:223], s[40:41], 0, v[132:133]
	global_load_lds_dwordx4 v130, s[76:77]
	s_add_i32 m0, s79, 0x2000
	s_nop 0
	global_load_lds_dwordx4 v134, s[76:77]
	v_lshl_add_u64 v[220:221], s[40:41], 0, v[128:129]
	s_mov_b32 m0, s31
	s_nop 0
	global_load_lds_dwordx4 v[220:221], off
	s_mov_b32 m0, s33
	s_nop 0
	global_load_lds_dwordx4 v[222:223], off
	s_waitcnt vmcnt(8)
	s_waitcnt lgkmcnt(0)
	s_barrier
	s_waitcnt lgkmcnt(0)
	v_mfma_f32_16x16x32_bf16 v[60:63], v[152:155], v[184:187], v[60:63]
	v_mfma_f32_16x16x32_bf16 v[56:59], v[160:163], v[184:187], v[56:59]
	v_mfma_f32_16x16x32_bf16 v[52:55], v[152:155], v[196:199], v[52:55]
	v_mfma_f32_16x16x32_bf16 v[44:47], v[160:163], v[196:199], v[44:47]
	v_mfma_f32_16x16x32_bf16 v[36:39], v[152:155], v[204:207], v[36:39]
	v_mfma_f32_16x16x32_bf16 v[28:31], v[160:163], v[204:207], v[28:31]
	v_mfma_f32_16x16x32_bf16 v[20:23], v[152:155], v[212:215], v[20:23]
	v_mfma_f32_16x16x32_bf16 v[12:15], v[160:163], v[212:215], v[12:15]
	v_mfma_f32_16x16x32_bf16 v[60:63], v[156:159], v[192:195], v[60:63]
	v_mfma_f32_16x16x32_bf16 v[56:59], v[164:167], v[192:195], v[56:59]
	v_mfma_f32_16x16x32_bf16 v[52:55], v[156:159], v[200:203], v[52:55]
	v_mfma_f32_16x16x32_bf16 v[44:47], v[164:167], v[200:203], v[44:47]
	v_mfma_f32_16x16x32_bf16 v[36:39], v[156:159], v[208:211], v[36:39]
	v_mfma_f32_16x16x32_bf16 v[28:31], v[164:167], v[208:211], v[28:31]
	v_mfma_f32_16x16x32_bf16 v[20:23], v[156:159], v[216:219], v[20:23]
	v_mfma_f32_16x16x32_bf16 v[12:15], v[164:167], v[216:219], v[12:15]
	v_mfma_f32_16x16x32_bf16 v[48:51], v[168:171], v[184:187], v[48:51]
	v_mfma_f32_16x16x32_bf16 v[40:43], v[176:179], v[184:187], v[40:43]
	v_mfma_f32_16x16x32_bf16 v[32:35], v[168:171], v[196:199], v[32:35]
	v_mfma_f32_16x16x32_bf16 v[24:27], v[176:179], v[196:199], v[24:27]
	v_mfma_f32_16x16x32_bf16 v[16:19], v[168:171], v[204:207], v[16:19]
	v_mfma_f32_16x16x32_bf16 v[8:11], v[176:179], v[204:207], v[8:11]
	v_mfma_f32_16x16x32_bf16 v[4:7], v[168:171], v[212:215], v[4:7]
	v_mfma_f32_16x16x32_bf16 v[0:3], v[176:179], v[212:215], v[0:3]
	v_mfma_f32_16x16x32_bf16 v[48:51], v[172:175], v[192:195], v[48:51]
	v_mfma_f32_16x16x32_bf16 v[40:43], v[180:183], v[192:195], v[40:43]
	v_mfma_f32_16x16x32_bf16 v[32:35], v[172:175], v[200:203], v[32:35]
	v_mfma_f32_16x16x32_bf16 v[24:27], v[180:183], v[200:203], v[24:27]
	v_mfma_f32_16x16x32_bf16 v[16:19], v[172:175], v[208:211], v[16:19]
	v_mfma_f32_16x16x32_bf16 v[8:11], v[180:183], v[208:211], v[8:11]
	v_mfma_f32_16x16x32_bf16 v[4:7], v[172:175], v[216:219], v[4:7]
	v_mfma_f32_16x16x32_bf16 v[0:3], v[180:183], v[216:219], v[0:3]
	s_barrier
	s_add_i32 s76, 0, 0x18000
	s_add_i32 s77, 0, 0x1c000
	v_add_u32_e32 v164, s76, v147
	v_add_u32_e32 v180, s77, v147
	ds_read_b128 v[152:155], v164
	ds_read_b128 v[156:159], v164 offset:1024
	ds_read_b128 v[160:163], v164 offset:2048
	ds_read_b128 v[164:167], v164 offset:3072
	ds_read_b128 v[168:171], v180
	ds_read_b128 v[172:175], v180 offset:1024
	ds_read_b128 v[176:179], v180 offset:2048
	ds_read_b128 v[180:183], v180 offset:3072
	s_add_u32 s40, s40, 0x40000
	s_addc_u32 s41, s41, 0
	s_mov_b32 m0, s60
	ds_read_b128 v[184:187], v151 offset:32768
	ds_read_b128 v[192:195], v151 offset:33792
	ds_read_b128 v[196:199], v151 offset:34816
	ds_read_b128 v[200:203], v151 offset:35840
	ds_read_b128 v[204:207], v151 offset:36864
	ds_read_b128 v[208:211], v151 offset:37888
	ds_read_b128 v[212:215], v151 offset:38912
	ds_read_b128 v[216:219], v151 offset:39936
	global_load_lds_dwordx4 v128, s[40:41]
	s_mov_b32 m0, s61
	s_nop 0
	global_load_lds_dwordx4 v132, s[40:41]
	s_waitcnt vmcnt(8)
	s_waitcnt lgkmcnt(0)
	s_barrier
	s_waitcnt lgkmcnt(0)
	v_mfma_f32_16x16x32_bf16 v[124:127], v[152:155], v[184:187], v[124:127]
	v_mfma_f32_16x16x32_bf16 v[120:123], v[160:163], v[184:187], v[120:123]
	v_mfma_f32_16x16x32_bf16 v[116:119], v[152:155], v[196:199], v[116:119]
	v_mfma_f32_16x16x32_bf16 v[108:111], v[160:163], v[196:199], v[108:111]
	v_mfma_f32_16x16x32_bf16 v[100:103], v[152:155], v[204:207], v[100:103]
	v_mfma_f32_16x16x32_bf16 v[92:95], v[160:163], v[204:207], v[92:95]
	v_mfma_f32_16x16x32_bf16 v[84:87], v[152:155], v[212:215], v[84:87]
	v_mfma_f32_16x16x32_bf16 v[76:79], v[160:163], v[212:215], v[76:79]
	v_mfma_f32_16x16x32_bf16 v[124:127], v[156:159], v[192:195], v[124:127]
	v_mfma_f32_16x16x32_bf16 v[120:123], v[164:167], v[192:195], v[120:123]
	v_mfma_f32_16x16x32_bf16 v[116:119], v[156:159], v[200:203], v[116:119]
	v_mfma_f32_16x16x32_bf16 v[108:111], v[164:167], v[200:203], v[108:111]
	v_mfma_f32_16x16x32_bf16 v[100:103], v[156:159], v[208:211], v[100:103]
	v_mfma_f32_16x16x32_bf16 v[92:95], v[164:167], v[208:211], v[92:95]
	v_mfma_f32_16x16x32_bf16 v[84:87], v[156:159], v[216:219], v[84:87]
	v_mfma_f32_16x16x32_bf16 v[76:79], v[164:167], v[216:219], v[76:79]
	v_mfma_f32_16x16x32_bf16 v[112:115], v[168:171], v[184:187], v[112:115]
	v_mfma_f32_16x16x32_bf16 v[104:107], v[176:179], v[184:187], v[104:107]
	v_mfma_f32_16x16x32_bf16 v[96:99], v[168:171], v[196:199], v[96:99]
	v_mfma_f32_16x16x32_bf16 v[88:91], v[176:179], v[196:199], v[88:91]
	v_mfma_f32_16x16x32_bf16 v[80:83], v[168:171], v[204:207], v[80:83]
	v_mfma_f32_16x16x32_bf16 v[72:75], v[176:179], v[204:207], v[72:75]
	v_mfma_f32_16x16x32_bf16 v[68:71], v[168:171], v[212:215], v[68:71]
	v_mfma_f32_16x16x32_bf16 v[64:67], v[176:179], v[212:215], v[64:67]
	v_mfma_f32_16x16x32_bf16 v[112:115], v[172:175], v[192:195], v[112:115]
	v_mfma_f32_16x16x32_bf16 v[104:107], v[180:183], v[192:195], v[104:107]
	v_mfma_f32_16x16x32_bf16 v[96:99], v[172:175], v[200:203], v[96:99]
	v_mfma_f32_16x16x32_bf16 v[88:91], v[180:183], v[200:203], v[88:91]
	v_mfma_f32_16x16x32_bf16 v[80:83], v[172:175], v[208:211], v[80:83]
	v_mfma_f32_16x16x32_bf16 v[72:75], v[180:183], v[208:211], v[72:75]
	v_mfma_f32_16x16x32_bf16 v[68:71], v[172:175], v[216:219], v[68:71]
	v_mfma_f32_16x16x32_bf16 v[64:67], v[180:183], v[216:219], v[64:67]
	s_barrier
	s_add_i32 s40, s76, s53
	v_lshl_add_u64 v[144:145], v[144:145], 0, s[12:13]
	s_mov_b32 m0, s40
	ds_read_b128 v[184:187], v151 offset:49152
	ds_read_b128 v[192:195], v151 offset:50176
	ds_read_b128 v[196:199], v151 offset:51200
	ds_read_b128 v[200:203], v151 offset:52224
	ds_read_b128 v[204:207], v151 offset:53248
	ds_read_b128 v[208:211], v151 offset:54272
	ds_read_b128 v[212:215], v151 offset:55296
	ds_read_b128 v[216:219], v151 offset:56320
	global_load_lds_dwordx4 v[144:145], off
	s_add_i32 m0, s40, 0x2000
	s_add_u32 s38, s38, 0x40080
	v_lshl_add_u64 v[144:145], v[188:189], 0, s[12:13]
	s_addc_u32 s39, s39, 0
	s_add_i32 s40, s77, s53
	global_load_lds_dwordx4 v[144:145], off
	s_mov_b32 m0, s40
	s_nop 0
	global_load_lds_dwordx4 v130, s[38:39]
	s_add_i32 m0, s40, 0x2000
	s_nop 0
	global_load_lds_dwordx4 v134, s[38:39]
	v_lshl_add_u64 v[144:145], v[220:221], 0, s[12:13]
	s_mov_b32 m0, s63
	s_nop 0
	global_load_lds_dwordx4 v[144:145], off
	v_lshl_add_u64 v[144:145], v[222:223], 0, s[12:13]
	s_mov_b32 m0, s64
	s_nop 0
	global_load_lds_dwordx4 v[144:145], off
	s_waitcnt vmcnt(8)
	s_waitcnt lgkmcnt(0)
	s_barrier
	s_waitcnt lgkmcnt(0)
	v_mfma_f32_16x16x32_bf16 v[60:63], v[152:155], v[184:187], v[60:63]
	v_mfma_f32_16x16x32_bf16 v[56:59], v[160:163], v[184:187], v[56:59]
	v_mfma_f32_16x16x32_bf16 v[52:55], v[152:155], v[196:199], v[52:55]
	v_mfma_f32_16x16x32_bf16 v[44:47], v[160:163], v[196:199], v[44:47]
	v_mfma_f32_16x16x32_bf16 v[36:39], v[152:155], v[204:207], v[36:39]
	v_mfma_f32_16x16x32_bf16 v[28:31], v[160:163], v[204:207], v[28:31]
	v_mfma_f32_16x16x32_bf16 v[20:23], v[152:155], v[212:215], v[20:23]
	v_mfma_f32_16x16x32_bf16 v[12:15], v[160:163], v[212:215], v[12:15]
	v_mfma_f32_16x16x32_bf16 v[60:63], v[156:159], v[192:195], v[60:63]
	v_mfma_f32_16x16x32_bf16 v[56:59], v[164:167], v[192:195], v[56:59]
	v_mfma_f32_16x16x32_bf16 v[52:55], v[156:159], v[200:203], v[52:55]
	v_mfma_f32_16x16x32_bf16 v[44:47], v[164:167], v[200:203], v[44:47]
	v_mfma_f32_16x16x32_bf16 v[36:39], v[156:159], v[208:211], v[36:39]
	v_mfma_f32_16x16x32_bf16 v[28:31], v[164:167], v[208:211], v[28:31]
	v_mfma_f32_16x16x32_bf16 v[20:23], v[156:159], v[216:219], v[20:23]
	v_mfma_f32_16x16x32_bf16 v[12:15], v[164:167], v[216:219], v[12:15]
	v_mfma_f32_16x16x32_bf16 v[48:51], v[168:171], v[184:187], v[48:51]
	v_mfma_f32_16x16x32_bf16 v[40:43], v[176:179], v[184:187], v[40:43]
	v_mfma_f32_16x16x32_bf16 v[32:35], v[168:171], v[196:199], v[32:35]
	v_mfma_f32_16x16x32_bf16 v[24:27], v[176:179], v[196:199], v[24:27]
	v_mfma_f32_16x16x32_bf16 v[16:19], v[168:171], v[204:207], v[16:19]
	v_mfma_f32_16x16x32_bf16 v[8:11], v[176:179], v[204:207], v[8:11]
	v_mfma_f32_16x16x32_bf16 v[4:7], v[168:171], v[212:215], v[4:7]
	v_mfma_f32_16x16x32_bf16 v[0:3], v[176:179], v[212:215], v[0:3]
	v_mfma_f32_16x16x32_bf16 v[48:51], v[172:175], v[192:195], v[48:51]
	v_mfma_f32_16x16x32_bf16 v[40:43], v[180:183], v[192:195], v[40:43]
	v_mfma_f32_16x16x32_bf16 v[32:35], v[172:175], v[200:203], v[32:35]
	v_mfma_f32_16x16x32_bf16 v[24:27], v[180:183], v[200:203], v[24:27]
	v_mfma_f32_16x16x32_bf16 v[16:19], v[172:175], v[208:211], v[16:19]
	v_mfma_f32_16x16x32_bf16 v[8:11], v[180:183], v[208:211], v[8:11]
	v_mfma_f32_16x16x32_bf16 v[4:7], v[172:175], v[216:219], v[4:7]
	v_mfma_f32_16x16x32_bf16 v[0:3], v[180:183], v[216:219], v[0:3]
	s_barrier
	s_add_i32 s75, s75, 2
	s_add_u32 s34, s34, 0x100
	s_addc_u32 s35, s35, 0
	s_add_u32 s73, s73, 0x100
	s_addc_u32 s74, s74, 0
	s_cmp_gt_u32 s75, 13
	s_cbranch_scc0 .LBB0_700

.LBB0_836:
	s_ashr_i32 s25, s24, 31
	s_lshl_b64 s[26:27], s[24:25], 19
	s_add_u32 s26, s58, s26
	s_addc_u32 s27, s59, s27
	s_and_b64 s[28:29], s[4:5], exec
	s_cselect_b32 s25, s27, s35
	s_cselect_b32 s54, s26, s34
	s_ashr_i32 s23, s22, 31
	s_lshl_b64 s[28:29], s[22:23], 19
	s_add_u32 s28, s61, s28
	s_addc_u32 s29, s62, s29
	s_and_b64 s[42:43], s[4:5], exec
	s_cselect_b32 s23, s29, s41
	s_cselect_b32 s55, s28, s40
	s_add_u32 s34, s34, 0x40080
	s_addc_u32 s35, s35, 0
	s_add_u32 s75, s40, 0x100
	s_addc_u32 s76, s41, 0
	s_mov_b32 s77, -2
	ds_read_b128 v[152:155], v149
	ds_read_b128 v[156:159], v149 offset:1024
	ds_read_b128 v[160:163], v149 offset:2048
	ds_read_b128 v[164:167], v149 offset:3072
	ds_read_b128 v[168:171], v150
	ds_read_b128 v[172:175], v150 offset:1024
	ds_read_b128 v[176:179], v150 offset:2048
	ds_read_b128 v[180:183], v150 offset:3072
	s_add_u32 s40, s34, 0xfffc0080
	s_addc_u32 s41, s35, -1
	s_cmp_eq_u32 s77, 12
	s_cselect_b32 s43, s25, s41
	s_cselect_b32 s42, s54, s40
	s_cselect_b32 s41, s23, s76
	s_cselect_b32 s40, s55, s75
	s_add_i32 m0, s31, 0xc000
	ds_read_b128 v[184:187], v151
	ds_read_b128 v[192:195], v151 offset:1024
	ds_read_b128 v[196:199], v151 offset:2048
	ds_read_b128 v[200:203], v151 offset:3072
	ds_read_b128 v[204:207], v151 offset:4096
	ds_read_b128 v[208:211], v151 offset:5120
	ds_read_b128 v[212:215], v151 offset:6144
	ds_read_b128 v[216:219], v151 offset:7168
	global_load_lds_dwordx4 v136, s[34:35]
	s_add_i32 m0, s31, 0xe000
	s_nop 0
	global_load_lds_dwordx4 v138, s[34:35]
	s_waitcnt vmcnt(8)
	s_waitcnt lgkmcnt(0)
	s_barrier
	s_waitcnt lgkmcnt(0)
	v_mfma_f32_16x16x32_bf16 v[124:127], v[152:155], v[184:187], 0
	v_mfma_f32_16x16x32_bf16 v[120:123], v[160:163], v[184:187], 0
	v_mfma_f32_16x16x32_bf16 v[108:111], v[152:155], v[196:199], 0
	v_mfma_f32_16x16x32_bf16 v[104:107], v[160:163], v[196:199], 0
	v_mfma_f32_16x16x32_bf16 v[92:95], v[152:155], v[204:207], 0
	v_mfma_f32_16x16x32_bf16 v[88:91], v[160:163], v[204:207], 0
	v_mfma_f32_16x16x32_bf16 v[76:79], v[152:155], v[212:215], 0
	v_mfma_f32_16x16x32_bf16 v[72:75], v[160:163], v[212:215], 0
	v_mfma_f32_16x16x32_bf16 v[124:127], v[156:159], v[192:195], v[124:127]
	v_mfma_f32_16x16x32_bf16 v[120:123], v[164:167], v[192:195], v[120:123]
	v_mfma_f32_16x16x32_bf16 v[108:111], v[156:159], v[200:203], v[108:111]
	v_mfma_f32_16x16x32_bf16 v[104:107], v[164:167], v[200:203], v[104:107]
	v_mfma_f32_16x16x32_bf16 v[92:95], v[156:159], v[208:211], v[92:95]
	v_mfma_f32_16x16x32_bf16 v[88:91], v[164:167], v[208:211], v[88:91]
	v_mfma_f32_16x16x32_bf16 v[76:79], v[156:159], v[216:219], v[76:79]
	v_mfma_f32_16x16x32_bf16 v[72:75], v[164:167], v[216:219], v[72:75]
	v_mfma_f32_16x16x32_bf16 v[116:119], v[168:171], v[184:187], 0
	v_mfma_f32_16x16x32_bf16 v[112:115], v[176:179], v[184:187], 0
	v_mfma_f32_16x16x32_bf16 v[100:103], v[168:171], v[196:199], 0
	v_mfma_f32_16x16x32_bf16 v[96:99], v[176:179], v[196:199], 0
	v_mfma_f32_16x16x32_bf16 v[84:87], v[168:171], v[204:207], 0
	v_mfma_f32_16x16x32_bf16 v[80:83], v[176:179], v[204:207], 0
	v_mfma_f32_16x16x32_bf16 v[68:71], v[168:171], v[212:215], 0
	v_mfma_f32_16x16x32_bf16 v[64:67], v[176:179], v[212:215], 0
	v_mfma_f32_16x16x32_bf16 v[116:119], v[172:175], v[192:195], v[116:119]
	v_mfma_f32_16x16x32_bf16 v[112:115], v[180:183], v[192:195], v[112:115]
	v_mfma_f32_16x16x32_bf16 v[100:103], v[172:175], v[200:203], v[100:103]
	v_mfma_f32_16x16x32_bf16 v[96:99], v[180:183], v[200:203], v[96:99]
	v_mfma_f32_16x16x32_bf16 v[84:87], v[172:175], v[208:211], v[84:87]
	v_mfma_f32_16x16x32_bf16 v[80:83], v[180:183], v[208:211], v[80:83]
	v_mfma_f32_16x16x32_bf16 v[68:71], v[172:175], v[216:219], v[68:71]
	v_mfma_f32_16x16x32_bf16 v[64:67], v[180:183], v[216:219], v[64:67]
	s_barrier
	s_add_i32 s79, s69, s63
	v_lshl_add_u64 v[144:145], s[40:41], 0, v[130:131]
	s_mov_b32 m0, s79
	ds_read_b128 v[184:187], v151 offset:16384
	ds_read_b128 v[192:195], v151 offset:17408
	ds_read_b128 v[196:199], v151 offset:18432
	ds_read_b128 v[200:203], v151 offset:19456
	ds_read_b128 v[204:207], v151 offset:20480
	ds_read_b128 v[208:211], v151 offset:21504
	ds_read_b128 v[212:215], v151 offset:22528
	ds_read_b128 v[216:219], v151 offset:23552
	global_load_lds_dwordx4 v[144:145], off
	s_add_i32 m0, s79, 0x2000
	s_add_u32 s80, s40, 0x40000
	v_lshl_add_u64 v[188:189], s[40:41], 0, v[134:135]
	s_addc_u32 s81, s41, 0
	s_add_i32 s79, s70, s63
	global_load_lds_dwordx4 v[188:189], off
	s_mov_b32 m0, s79
	v_lshl_add_u64 v[222:223], s[42:43], 0, v[132:133]
	global_load_lds_dwordx4 v130, s[80:81]
	s_add_i32 m0, s79, 0x2000
	s_nop 0
	global_load_lds_dwordx4 v134, s[80:81]
	v_lshl_add_u64 v[220:221], s[42:43], 0, v[128:129]
	s_mov_b32 m0, s31
	s_nop 0
	global_load_lds_dwordx4 v[220:221], off
	s_mov_b32 m0, s64
	s_nop 0
	global_load_lds_dwordx4 v[222:223], off
	s_waitcnt vmcnt(8)
	s_waitcnt lgkmcnt(0)
	s_barrier
	s_waitcnt lgkmcnt(0)
	v_mfma_f32_16x16x32_bf16 v[60:63], v[152:155], v[184:187], 0
	v_mfma_f32_16x16x32_bf16 v[56:59], v[160:163], v[184:187], 0
	v_mfma_f32_16x16x32_bf16 v[44:47], v[152:155], v[196:199], 0
	v_mfma_f32_16x16x32_bf16 v[40:43], v[160:163], v[196:199], 0
	v_mfma_f32_16x16x32_bf16 v[28:31], v[152:155], v[204:207], 0
	v_mfma_f32_16x16x32_bf16 v[24:27], v[160:163], v[204:207], 0
	v_mfma_f32_16x16x32_bf16 v[12:15], v[152:155], v[212:215], 0
	v_mfma_f32_16x16x32_bf16 v[8:11], v[160:163], v[212:215], 0
	v_mfma_f32_16x16x32_bf16 v[60:63], v[156:159], v[192:195], v[60:63]
	v_mfma_f32_16x16x32_bf16 v[56:59], v[164:167], v[192:195], v[56:59]
	v_mfma_f32_16x16x32_bf16 v[44:47], v[156:159], v[200:203], v[44:47]
	v_mfma_f32_16x16x32_bf16 v[40:43], v[164:167], v[200:203], v[40:43]
	v_mfma_f32_16x16x32_bf16 v[28:31], v[156:159], v[208:211], v[28:31]
	v_mfma_f32_16x16x32_bf16 v[24:27], v[164:167], v[208:211], v[24:27]
	v_mfma_f32_16x16x32_bf16 v[12:15], v[156:159], v[216:219], v[12:15]
	v_mfma_f32_16x16x32_bf16 v[8:11], v[164:167], v[216:219], v[8:11]
	v_mfma_f32_16x16x32_bf16 v[52:55], v[168:171], v[184:187], 0
	v_mfma_f32_16x16x32_bf16 v[48:51], v[176:179], v[184:187], 0
	v_mfma_f32_16x16x32_bf16 v[36:39], v[168:171], v[196:199], 0
	v_mfma_f32_16x16x32_bf16 v[32:35], v[176:179], v[196:199], 0
	v_mfma_f32_16x16x32_bf16 v[20:23], v[168:171], v[204:207], 0
	v_mfma_f32_16x16x32_bf16 v[16:19], v[176:179], v[204:207], 0
	v_mfma_f32_16x16x32_bf16 v[4:7], v[168:171], v[212:215], 0
	v_mfma_f32_16x16x32_bf16 v[0:3], v[176:179], v[212:215], 0
	v_mfma_f32_16x16x32_bf16 v[52:55], v[172:175], v[192:195], v[52:55]
	v_mfma_f32_16x16x32_bf16 v[48:51], v[180:183], v[192:195], v[48:51]
	v_mfma_f32_16x16x32_bf16 v[36:39], v[172:175], v[200:203], v[36:39]
	v_mfma_f32_16x16x32_bf16 v[32:35], v[180:183], v[200:203], v[32:35]
	v_mfma_f32_16x16x32_bf16 v[20:23], v[172:175], v[208:211], v[20:23]
	v_mfma_f32_16x16x32_bf16 v[16:19], v[180:183], v[208:211], v[16:19]
	v_mfma_f32_16x16x32_bf16 v[4:7], v[172:175], v[216:219], v[4:7]
	v_mfma_f32_16x16x32_bf16 v[0:3], v[180:183], v[216:219], v[0:3]
	s_barrier
	s_add_i32 s79, 0, 0x18000
	s_add_i32 s80, 0, 0x1c000
	v_add_u32_e32 v164, s79, v147
	v_add_u32_e32 v180, s80, v147
	ds_read_b128 v[152:155], v164
	ds_read_b128 v[156:159], v164 offset:1024
	ds_read_b128 v[160:163], v164 offset:2048
	ds_read_b128 v[164:167], v164 offset:3072
	ds_read_b128 v[168:171], v180
	ds_read_b128 v[172:175], v180 offset:1024
	ds_read_b128 v[176:179], v180 offset:2048
	ds_read_b128 v[180:183], v180 offset:3072
	s_add_u32 s42, s42, 0x40000
	s_addc_u32 s43, s43, 0
	s_mov_b32 m0, s65
	ds_read_b128 v[184:187], v151 offset:32768
	ds_read_b128 v[192:195], v151 offset:33792
	ds_read_b128 v[196:199], v151 offset:34816
	ds_read_b128 v[200:203], v151 offset:35840
	ds_read_b128 v[204:207], v151 offset:36864
	ds_read_b128 v[208:211], v151 offset:37888
	ds_read_b128 v[212:215], v151 offset:38912
	ds_read_b128 v[216:219], v151 offset:39936
	global_load_lds_dwordx4 v128, s[42:43]
	s_mov_b32 m0, s66
	s_nop 0
	global_load_lds_dwordx4 v132, s[42:43]
	s_waitcnt vmcnt(8)
	s_waitcnt lgkmcnt(0)
	s_barrier
	s_waitcnt lgkmcnt(0)
	v_mfma_f32_16x16x32_bf16 v[124:127], v[152:155], v[184:187], v[124:127]
	v_mfma_f32_16x16x32_bf16 v[120:123], v[160:163], v[184:187], v[120:123]
	v_mfma_f32_16x16x32_bf16 v[108:111], v[152:155], v[196:199], v[108:111]
	v_mfma_f32_16x16x32_bf16 v[104:107], v[160:163], v[196:199], v[104:107]
	v_mfma_f32_16x16x32_bf16 v[92:95], v[152:155], v[204:207], v[92:95]
	v_mfma_f32_16x16x32_bf16 v[88:91], v[160:163], v[204:207], v[88:91]
	v_mfma_f32_16x16x32_bf16 v[76:79], v[152:155], v[212:215], v[76:79]
	v_mfma_f32_16x16x32_bf16 v[72:75], v[160:163], v[212:215], v[72:75]
	v_mfma_f32_16x16x32_bf16 v[124:127], v[156:159], v[192:195], v[124:127]
	v_mfma_f32_16x16x32_bf16 v[120:123], v[164:167], v[192:195], v[120:123]
	v_mfma_f32_16x16x32_bf16 v[108:111], v[156:159], v[200:203], v[108:111]
	v_mfma_f32_16x16x32_bf16 v[104:107], v[164:167], v[200:203], v[104:107]
	v_mfma_f32_16x16x32_bf16 v[92:95], v[156:159], v[208:211], v[92:95]
	v_mfma_f32_16x16x32_bf16 v[88:91], v[164:167], v[208:211], v[88:91]
	v_mfma_f32_16x16x32_bf16 v[76:79], v[156:159], v[216:219], v[76:79]
	v_mfma_f32_16x16x32_bf16 v[72:75], v[164:167], v[216:219], v[72:75]
	v_mfma_f32_16x16x32_bf16 v[116:119], v[168:171], v[184:187], v[116:119]
	v_mfma_f32_16x16x32_bf16 v[112:115], v[176:179], v[184:187], v[112:115]
	v_mfma_f32_16x16x32_bf16 v[100:103], v[168:171], v[196:199], v[100:103]
	v_mfma_f32_16x16x32_bf16 v[96:99], v[176:179], v[196:199], v[96:99]
	v_mfma_f32_16x16x32_bf16 v[84:87], v[168:171], v[204:207], v[84:87]
	v_mfma_f32_16x16x32_bf16 v[80:83], v[176:179], v[204:207], v[80:83]
	v_mfma_f32_16x16x32_bf16 v[68:71], v[168:171], v[212:215], v[68:71]
	v_mfma_f32_16x16x32_bf16 v[64:67], v[176:179], v[212:215], v[64:67]
	v_mfma_f32_16x16x32_bf16 v[116:119], v[172:175], v[192:195], v[116:119]
	v_mfma_f32_16x16x32_bf16 v[112:115], v[180:183], v[192:195], v[112:115]
	v_mfma_f32_16x16x32_bf16 v[100:103], v[172:175], v[200:203], v[100:103]
	v_mfma_f32_16x16x32_bf16 v[96:99], v[180:183], v[200:203], v[96:99]
	v_mfma_f32_16x16x32_bf16 v[84:87], v[172:175], v[208:211], v[84:87]
	v_mfma_f32_16x16x32_bf16 v[80:83], v[180:183], v[208:211], v[80:83]
	v_mfma_f32_16x16x32_bf16 v[68:71], v[172:175], v[216:219], v[68:71]
	v_mfma_f32_16x16x32_bf16 v[64:67], v[180:183], v[216:219], v[64:67]
	s_barrier
	s_add_i32 s42, s79, s63
	v_lshl_add_u64 v[144:145], v[144:145], 0, s[10:11]
	s_mov_b32 m0, s42
	ds_read_b128 v[184:187], v151 offset:49152
	ds_read_b128 v[192:195], v151 offset:50176
	ds_read_b128 v[196:199], v151 offset:51200
	ds_read_b128 v[200:203], v151 offset:52224
	ds_read_b128 v[204:207], v151 offset:53248
	ds_read_b128 v[208:211], v151 offset:54272
	ds_read_b128 v[212:215], v151 offset:55296
	ds_read_b128 v[216:219], v151 offset:56320
	global_load_lds_dwordx4 v[144:145], off
	s_add_i32 m0, s42, 0x2000
	s_add_u32 s40, s40, 0x40080
	v_lshl_add_u64 v[144:145], v[188:189], 0, s[10:11]
	s_addc_u32 s41, s41, 0
	s_add_i32 s42, s80, s63
	global_load_lds_dwordx4 v[144:145], off
	s_mov_b32 m0, s42
	s_nop 0
	global_load_lds_dwordx4 v130, s[40:41]
	s_add_i32 m0, s42, 0x2000
	s_nop 0
	global_load_lds_dwordx4 v134, s[40:41]
	v_lshl_add_u64 v[144:145], v[220:221], 0, s[10:11]
	s_mov_b32 m0, s52
	s_nop 0
	global_load_lds_dwordx4 v[144:145], off
	v_lshl_add_u64 v[144:145], v[222:223], 0, s[10:11]
	s_mov_b32 m0, s53
	s_nop 0
	global_load_lds_dwordx4 v[144:145], off
	s_waitcnt vmcnt(8)
	s_waitcnt lgkmcnt(0)
	s_barrier
	s_waitcnt lgkmcnt(0)
	v_mfma_f32_16x16x32_bf16 v[60:63], v[152:155], v[184:187], v[60:63]
	v_mfma_f32_16x16x32_bf16 v[56:59], v[160:163], v[184:187], v[56:59]
	v_mfma_f32_16x16x32_bf16 v[44:47], v[152:155], v[196:199], v[44:47]
	v_mfma_f32_16x16x32_bf16 v[40:43], v[160:163], v[196:199], v[40:43]
	v_mfma_f32_16x16x32_bf16 v[28:31], v[152:155], v[204:207], v[28:31]
	v_mfma_f32_16x16x32_bf16 v[24:27], v[160:163], v[204:207], v[24:27]
	v_mfma_f32_16x16x32_bf16 v[12:15], v[152:155], v[212:215], v[12:15]
	v_mfma_f32_16x16x32_bf16 v[8:11], v[160:163], v[212:215], v[8:11]
	v_mfma_f32_16x16x32_bf16 v[60:63], v[156:159], v[192:195], v[60:63]
	v_mfma_f32_16x16x32_bf16 v[56:59], v[164:167], v[192:195], v[56:59]
	v_mfma_f32_16x16x32_bf16 v[44:47], v[156:159], v[200:203], v[44:47]
	v_mfma_f32_16x16x32_bf16 v[40:43], v[164:167], v[200:203], v[40:43]
	v_mfma_f32_16x16x32_bf16 v[28:31], v[156:159], v[208:211], v[28:31]
	v_mfma_f32_16x16x32_bf16 v[24:27], v[164:167], v[208:211], v[24:27]
	v_mfma_f32_16x16x32_bf16 v[12:15], v[156:159], v[216:219], v[12:15]
	v_mfma_f32_16x16x32_bf16 v[8:11], v[164:167], v[216:219], v[8:11]
	v_mfma_f32_16x16x32_bf16 v[52:55], v[168:171], v[184:187], v[52:55]
	v_mfma_f32_16x16x32_bf16 v[48:51], v[176:179], v[184:187], v[48:51]
	v_mfma_f32_16x16x32_bf16 v[36:39], v[168:171], v[196:199], v[36:39]
	v_mfma_f32_16x16x32_bf16 v[32:35], v[176:179], v[196:199], v[32:35]
	v_mfma_f32_16x16x32_bf16 v[20:23], v[168:171], v[204:207], v[20:23]
	v_mfma_f32_16x16x32_bf16 v[16:19], v[176:179], v[204:207], v[16:19]
	v_mfma_f32_16x16x32_bf16 v[4:7], v[168:171], v[212:215], v[4:7]
	v_mfma_f32_16x16x32_bf16 v[0:3], v[176:179], v[212:215], v[0:3]
	v_mfma_f32_16x16x32_bf16 v[52:55], v[172:175], v[192:195], v[52:55]
	v_mfma_f32_16x16x32_bf16 v[48:51], v[180:183], v[192:195], v[48:51]
	v_mfma_f32_16x16x32_bf16 v[36:39], v[172:175], v[200:203], v[36:39]
	v_mfma_f32_16x16x32_bf16 v[32:35], v[180:183], v[200:203], v[32:35]
	v_mfma_f32_16x16x32_bf16 v[20:23], v[172:175], v[208:211], v[20:23]
	v_mfma_f32_16x16x32_bf16 v[16:19], v[180:183], v[208:211], v[16:19]
	v_mfma_f32_16x16x32_bf16 v[4:7], v[172:175], v[216:219], v[4:7]
	v_mfma_f32_16x16x32_bf16 v[0:3], v[180:183], v[216:219], v[0:3]
	s_barrier
	s_add_i32 s77, s77, 2
	s_add_u32 s34, s34, 0x100
	s_addc_u32 s35, s35, 0
	s_add_u32 s75, s75, 0x100
	s_addc_u32 s76, s76, 0
	s_cmp_gt_u32 s77, 13
	s_cbranch_scc0 .LBB0_837
	s_branch .Lpeel_exit3
.LBB0_837:
	ds_read_b128 v[152:155], v149
	ds_read_b128 v[156:159], v149 offset:1024
	ds_read_b128 v[160:163], v149 offset:2048
	ds_read_b128 v[164:167], v149 offset:3072
	ds_read_b128 v[168:171], v150
	ds_read_b128 v[172:175], v150 offset:1024
	ds_read_b128 v[176:179], v150 offset:2048
	ds_read_b128 v[180:183], v150 offset:3072
	s_add_u32 s40, s34, 0xfffc0080
	s_addc_u32 s41, s35, -1
	s_cmp_eq_u32 s77, 12
	s_cselect_b32 s43, s25, s41
	s_cselect_b32 s42, s54, s40
	s_cselect_b32 s41, s23, s76
	s_cselect_b32 s40, s55, s75
	s_add_i32 m0, s31, 0xc000
	ds_read_b128 v[184:187], v151
	ds_read_b128 v[192:195], v151 offset:1024
	ds_read_b128 v[196:199], v151 offset:2048
	ds_read_b128 v[200:203], v151 offset:3072
	ds_read_b128 v[204:207], v151 offset:4096
	ds_read_b128 v[208:211], v151 offset:5120
	ds_read_b128 v[212:215], v151 offset:6144
	ds_read_b128 v[216:219], v151 offset:7168
	global_load_lds_dwordx4 v136, s[34:35]
	s_add_i32 m0, s31, 0xe000
	s_nop 0
	global_load_lds_dwordx4 v138, s[34:35]
	s_waitcnt vmcnt(8)
	s_waitcnt lgkmcnt(0)
	s_barrier
	s_waitcnt lgkmcnt(0)
	v_mfma_f32_16x16x32_bf16 v[124:127], v[152:155], v[184:187], v[124:127]
	v_mfma_f32_16x16x32_bf16 v[120:123], v[160:163], v[184:187], v[120:123]
	v_mfma_f32_16x16x32_bf16 v[108:111], v[152:155], v[196:199], v[108:111]
	v_mfma_f32_16x16x32_bf16 v[104:107], v[160:163], v[196:199], v[104:107]
	v_mfma_f32_16x16x32_bf16 v[92:95], v[152:155], v[204:207], v[92:95]
	v_mfma_f32_16x16x32_bf16 v[88:91], v[160:163], v[204:207], v[88:91]
	v_mfma_f32_16x16x32_bf16 v[76:79], v[152:155], v[212:215], v[76:79]
	v_mfma_f32_16x16x32_bf16 v[72:75], v[160:163], v[212:215], v[72:75]
	v_mfma_f32_16x16x32_bf16 v[124:127], v[156:159], v[192:195], v[124:127]
	v_mfma_f32_16x16x32_bf16 v[120:123], v[164:167], v[192:195], v[120:123]
	v_mfma_f32_16x16x32_bf16 v[108:111], v[156:159], v[200:203], v[108:111]
	v_mfma_f32_16x16x32_bf16 v[104:107], v[164:167], v[200:203], v[104:107]
	v_mfma_f32_16x16x32_bf16 v[92:95], v[156:159], v[208:211], v[92:95]
	v_mfma_f32_16x16x32_bf16 v[88:91], v[164:167], v[208:211], v[88:91]
	v_mfma_f32_16x16x32_bf16 v[76:79], v[156:159], v[216:219], v[76:79]
	v_mfma_f32_16x16x32_bf16 v[72:75], v[164:167], v[216:219], v[72:75]
	v_mfma_f32_16x16x32_bf16 v[116:119], v[168:171], v[184:187], v[116:119]
	v_mfma_f32_16x16x32_bf16 v[112:115], v[176:179], v[184:187], v[112:115]
	v_mfma_f32_16x16x32_bf16 v[100:103], v[168:171], v[196:199], v[100:103]
	v_mfma_f32_16x16x32_bf16 v[96:99], v[176:179], v[196:199], v[96:99]
	v_mfma_f32_16x16x32_bf16 v[84:87], v[168:171], v[204:207], v[84:87]
	v_mfma_f32_16x16x32_bf16 v[80:83], v[176:179], v[204:207], v[80:83]
	v_mfma_f32_16x16x32_bf16 v[68:71], v[168:171], v[212:215], v[68:71]
	v_mfma_f32_16x16x32_bf16 v[64:67], v[176:179], v[212:215], v[64:67]
	v_mfma_f32_16x16x32_bf16 v[116:119], v[172:175], v[192:195], v[116:119]
	v_mfma_f32_16x16x32_bf16 v[112:115], v[180:183], v[192:195], v[112:115]
	v_mfma_f32_16x16x32_bf16 v[100:103], v[172:175], v[200:203], v[100:103]
	v_mfma_f32_16x16x32_bf16 v[96:99], v[180:183], v[200:203], v[96:99]
	v_mfma_f32_16x16x32_bf16 v[84:87], v[172:175], v[208:211], v[84:87]
	v_mfma_f32_16x16x32_bf16 v[80:83], v[180:183], v[208:211], v[80:83]
	v_mfma_f32_16x16x32_bf16 v[68:71], v[172:175], v[216:219], v[68:71]
	v_mfma_f32_16x16x32_bf16 v[64:67], v[180:183], v[216:219], v[64:67]
	s_barrier
	s_add_i32 s79, s69, s63
	v_lshl_add_u64 v[144:145], s[40:41], 0, v[130:131]
	s_mov_b32 m0, s79
	ds_read_b128 v[184:187], v151 offset:16384
	ds_read_b128 v[192:195], v151 offset:17408
	ds_read_b128 v[196:199], v151 offset:18432
	ds_read_b128 v[200:203], v151 offset:19456
	ds_read_b128 v[204:207], v151 offset:20480
	ds_read_b128 v[208:211], v151 offset:21504
	ds_read_b128 v[212:215], v151 offset:22528
	ds_read_b128 v[216:219], v151 offset:23552
	global_load_lds_dwordx4 v[144:145], off
	s_add_i32 m0, s79, 0x2000
	s_add_u32 s80, s40, 0x40000
	v_lshl_add_u64 v[188:189], s[40:41], 0, v[134:135]
	s_addc_u32 s81, s41, 0
	s_add_i32 s79, s70, s63
	global_load_lds_dwordx4 v[188:189], off
	s_mov_b32 m0, s79
	v_lshl_add_u64 v[222:223], s[42:43], 0, v[132:133]
	global_load_lds_dwordx4 v130, s[80:81]
	s_add_i32 m0, s79, 0x2000
	s_nop 0
	global_load_lds_dwordx4 v134, s[80:81]
	v_lshl_add_u64 v[220:221], s[42:43], 0, v[128:129]
	s_mov_b32 m0, s31
	s_nop 0
	global_load_lds_dwordx4 v[220:221], off
	s_mov_b32 m0, s64
	s_nop 0
	global_load_lds_dwordx4 v[222:223], off
	s_waitcnt vmcnt(8)
	s_waitcnt lgkmcnt(0)
	s_barrier
	s_waitcnt lgkmcnt(0)
	v_mfma_f32_16x16x32_bf16 v[60:63], v[152:155], v[184:187], v[60:63]
	v_mfma_f32_16x16x32_bf16 v[56:59], v[160:163], v[184:187], v[56:59]
	v_mfma_f32_16x16x32_bf16 v[44:47], v[152:155], v[196:199], v[44:47]
	v_mfma_f32_16x16x32_bf16 v[40:43], v[160:163], v[196:199], v[40:43]
	v_mfma_f32_16x16x32_bf16 v[28:31], v[152:155], v[204:207], v[28:31]
	v_mfma_f32_16x16x32_bf16 v[24:27], v[160:163], v[204:207], v[24:27]
	v_mfma_f32_16x16x32_bf16 v[12:15], v[152:155], v[212:215], v[12:15]
	v_mfma_f32_16x16x32_bf16 v[8:11], v[160:163], v[212:215], v[8:11]
	v_mfma_f32_16x16x32_bf16 v[60:63], v[156:159], v[192:195], v[60:63]
	v_mfma_f32_16x16x32_bf16 v[56:59], v[164:167], v[192:195], v[56:59]
	v_mfma_f32_16x16x32_bf16 v[44:47], v[156:159], v[200:203], v[44:47]
	v_mfma_f32_16x16x32_bf16 v[40:43], v[164:167], v[200:203], v[40:43]
	v_mfma_f32_16x16x32_bf16 v[28:31], v[156:159], v[208:211], v[28:31]
	v_mfma_f32_16x16x32_bf16 v[24:27], v[164:167], v[208:211], v[24:27]
	v_mfma_f32_16x16x32_bf16 v[12:15], v[156:159], v[216:219], v[12:15]
	v_mfma_f32_16x16x32_bf16 v[8:11], v[164:167], v[216:219], v[8:11]
	v_mfma_f32_16x16x32_bf16 v[52:55], v[168:171], v[184:187], v[52:55]
	v_mfma_f32_16x16x32_bf16 v[48:51], v[176:179], v[184:187], v[48:51]
	v_mfma_f32_16x16x32_bf16 v[36:39], v[168:171], v[196:199], v[36:39]
	v_mfma_f32_16x16x32_bf16 v[32:35], v[176:179], v[196:199], v[32:35]
	v_mfma_f32_16x16x32_bf16 v[20:23], v[168:171], v[204:207], v[20:23]
	v_mfma_f32_16x16x32_bf16 v[16:19], v[176:179], v[204:207], v[16:19]
	v_mfma_f32_16x16x32_bf16 v[4:7], v[168:171], v[212:215], v[4:7]
	v_mfma_f32_16x16x32_bf16 v[0:3], v[176:179], v[212:215], v[0:3]
	v_mfma_f32_16x16x32_bf16 v[52:55], v[172:175], v[192:195], v[52:55]
	v_mfma_f32_16x16x32_bf16 v[48:51], v[180:183], v[192:195], v[48:51]
	v_mfma_f32_16x16x32_bf16 v[36:39], v[172:175], v[200:203], v[36:39]
	v_mfma_f32_16x16x32_bf16 v[32:35], v[180:183], v[200:203], v[32:35]
	v_mfma_f32_16x16x32_bf16 v[20:23], v[172:175], v[208:211], v[20:23]
	v_mfma_f32_16x16x32_bf16 v[16:19], v[180:183], v[208:211], v[16:19]
	v_mfma_f32_16x16x32_bf16 v[4:7], v[172:175], v[216:219], v[4:7]
	v_mfma_f32_16x16x32_bf16 v[0:3], v[180:183], v[216:219], v[0:3]
	s_barrier
	s_add_i32 s79, 0, 0x18000
	s_add_i32 s80, 0, 0x1c000
	v_add_u32_e32 v164, s79, v147
	v_add_u32_e32 v180, s80, v147
	ds_read_b128 v[152:155], v164
	ds_read_b128 v[156:159], v164 offset:1024
	ds_read_b128 v[160:163], v164 offset:2048
	ds_read_b128 v[164:167], v164 offset:3072
	ds_read_b128 v[168:171], v180
	ds_read_b128 v[172:175], v180 offset:1024
	ds_read_b128 v[176:179], v180 offset:2048
	ds_read_b128 v[180:183], v180 offset:3072
	s_add_u32 s42, s42, 0x40000
	s_addc_u32 s43, s43, 0
	s_mov_b32 m0, s65
	ds_read_b128 v[184:187], v151 offset:32768
	ds_read_b128 v[192:195], v151 offset:33792
	ds_read_b128 v[196:199], v151 offset:34816
	ds_read_b128 v[200:203], v151 offset:35840
	ds_read_b128 v[204:207], v151 offset:36864
	ds_read_b128 v[208:211], v151 offset:37888
	ds_read_b128 v[212:215], v151 offset:38912
	ds_read_b128 v[216:219], v151 offset:39936
	global_load_lds_dwordx4 v128, s[42:43]
	s_mov_b32 m0, s66
	s_nop 0
	global_load_lds_dwordx4 v132, s[42:43]
	s_waitcnt vmcnt(8)
	s_waitcnt lgkmcnt(0)
	s_barrier
	s_waitcnt lgkmcnt(0)
	v_mfma_f32_16x16x32_bf16 v[124:127], v[152:155], v[184:187], v[124:127]
	v_mfma_f32_16x16x32_bf16 v[120:123], v[160:163], v[184:187], v[120:123]
	v_mfma_f32_16x16x32_bf16 v[108:111], v[152:155], v[196:199], v[108:111]
	v_mfma_f32_16x16x32_bf16 v[104:107], v[160:163], v[196:199], v[104:107]
	v_mfma_f32_16x16x32_bf16 v[92:95], v[152:155], v[204:207], v[92:95]
	v_mfma_f32_16x16x32_bf16 v[88:91], v[160:163], v[204:207], v[88:91]
	v_mfma_f32_16x16x32_bf16 v[76:79], v[152:155], v[212:215], v[76:79]
	v_mfma_f32_16x16x32_bf16 v[72:75], v[160:163], v[212:215], v[72:75]
	v_mfma_f32_16x16x32_bf16 v[124:127], v[156:159], v[192:195], v[124:127]
	v_mfma_f32_16x16x32_bf16 v[120:123], v[164:167], v[192:195], v[120:123]
	v_mfma_f32_16x16x32_bf16 v[108:111], v[156:159], v[200:203], v[108:111]
	v_mfma_f32_16x16x32_bf16 v[104:107], v[164:167], v[200:203], v[104:107]
	v_mfma_f32_16x16x32_bf16 v[92:95], v[156:159], v[208:211], v[92:95]
	v_mfma_f32_16x16x32_bf16 v[88:91], v[164:167], v[208:211], v[88:91]
	v_mfma_f32_16x16x32_bf16 v[76:79], v[156:159], v[216:219], v[76:79]
	v_mfma_f32_16x16x32_bf16 v[72:75], v[164:167], v[216:219], v[72:75]
	v_mfma_f32_16x16x32_bf16 v[116:119], v[168:171], v[184:187], v[116:119]
	v_mfma_f32_16x16x32_bf16 v[112:115], v[176:179], v[184:187], v[112:115]
	v_mfma_f32_16x16x32_bf16 v[100:103], v[168:171], v[196:199], v[100:103]
	v_mfma_f32_16x16x32_bf16 v[96:99], v[176:179], v[196:199], v[96:99]
	v_mfma_f32_16x16x32_bf16 v[84:87], v[168:171], v[204:207], v[84:87]
	v_mfma_f32_16x16x32_bf16 v[80:83], v[176:179], v[204:207], v[80:83]
	v_mfma_f32_16x16x32_bf16 v[68:71], v[168:171], v[212:215], v[68:71]
	v_mfma_f32_16x16x32_bf16 v[64:67], v[176:179], v[212:215], v[64:67]
	v_mfma_f32_16x16x32_bf16 v[116:119], v[172:175], v[192:195], v[116:119]
	v_mfma_f32_16x16x32_bf16 v[112:115], v[180:183], v[192:195], v[112:115]
	v_mfma_f32_16x16x32_bf16 v[100:103], v[172:175], v[200:203], v[100:103]
	v_mfma_f32_16x16x32_bf16 v[96:99], v[180:183], v[200:203], v[96:99]
	v_mfma_f32_16x16x32_bf16 v[84:87], v[172:175], v[208:211], v[84:87]
	v_mfma_f32_16x16x32_bf16 v[80:83], v[180:183], v[208:211], v[80:83]
	v_mfma_f32_16x16x32_bf16 v[68:71], v[172:175], v[216:219], v[68:71]
	v_mfma_f32_16x16x32_bf16 v[64:67], v[180:183], v[216:219], v[64:67]
	s_barrier
	s_add_i32 s42, s79, s63
	v_lshl_add_u64 v[144:145], v[144:145], 0, s[10:11]
	s_mov_b32 m0, s42
	ds_read_b128 v[184:187], v151 offset:49152
	ds_read_b128 v[192:195], v151 offset:50176
	ds_read_b128 v[196:199], v151 offset:51200
	ds_read_b128 v[200:203], v151 offset:52224
	ds_read_b128 v[204:207], v151 offset:53248
	ds_read_b128 v[208:211], v151 offset:54272
	ds_read_b128 v[212:215], v151 offset:55296
	ds_read_b128 v[216:219], v151 offset:56320
	global_load_lds_dwordx4 v[144:145], off
	s_add_i32 m0, s42, 0x2000
	s_add_u32 s40, s40, 0x40080
	v_lshl_add_u64 v[144:145], v[188:189], 0, s[10:11]
	s_addc_u32 s41, s41, 0
	s_add_i32 s42, s80, s63
	global_load_lds_dwordx4 v[144:145], off
	s_mov_b32 m0, s42
	s_nop 0
	global_load_lds_dwordx4 v130, s[40:41]
	s_add_i32 m0, s42, 0x2000
	s_nop 0
	global_load_lds_dwordx4 v134, s[40:41]
	v_lshl_add_u64 v[144:145], v[220:221], 0, s[10:11]
	s_mov_b32 m0, s52
	s_nop 0
	global_load_lds_dwordx4 v[144:145], off
	v_lshl_add_u64 v[144:145], v[222:223], 0, s[10:11]
	s_mov_b32 m0, s53
	s_nop 0
	global_load_lds_dwordx4 v[144:145], off
	s_waitcnt vmcnt(8)
	s_waitcnt lgkmcnt(0)
	s_barrier
	s_waitcnt lgkmcnt(0)
	v_mfma_f32_16x16x32_bf16 v[60:63], v[152:155], v[184:187], v[60:63]
	v_mfma_f32_16x16x32_bf16 v[56:59], v[160:163], v[184:187], v[56:59]
	v_mfma_f32_16x16x32_bf16 v[44:47], v[152:155], v[196:199], v[44:47]
	v_mfma_f32_16x16x32_bf16 v[40:43], v[160:163], v[196:199], v[40:43]
	v_mfma_f32_16x16x32_bf16 v[28:31], v[152:155], v[204:207], v[28:31]
	v_mfma_f32_16x16x32_bf16 v[24:27], v[160:163], v[204:207], v[24:27]
	v_mfma_f32_16x16x32_bf16 v[12:15], v[152:155], v[212:215], v[12:15]
	v_mfma_f32_16x16x32_bf16 v[8:11], v[160:163], v[212:215], v[8:11]
	v_mfma_f32_16x16x32_bf16 v[60:63], v[156:159], v[192:195], v[60:63]
	v_mfma_f32_16x16x32_bf16 v[56:59], v[164:167], v[192:195], v[56:59]
	v_mfma_f32_16x16x32_bf16 v[44:47], v[156:159], v[200:203], v[44:47]
	v_mfma_f32_16x16x32_bf16 v[40:43], v[164:167], v[200:203], v[40:43]
	v_mfma_f32_16x16x32_bf16 v[28:31], v[156:159], v[208:211], v[28:31]
	v_mfma_f32_16x16x32_bf16 v[24:27], v[164:167], v[208:211], v[24:27]
	v_mfma_f32_16x16x32_bf16 v[12:15], v[156:159], v[216:219], v[12:15]
	v_mfma_f32_16x16x32_bf16 v[8:11], v[164:167], v[216:219], v[8:11]
	v_mfma_f32_16x16x32_bf16 v[52:55], v[168:171], v[184:187], v[52:55]
	v_mfma_f32_16x16x32_bf16 v[48:51], v[176:179], v[184:187], v[48:51]
	v_mfma_f32_16x16x32_bf16 v[36:39], v[168:171], v[196:199], v[36:39]
	v_mfma_f32_16x16x32_bf16 v[32:35], v[176:179], v[196:199], v[32:35]
	v_mfma_f32_16x16x32_bf16 v[20:23], v[168:171], v[204:207], v[20:23]
	v_mfma_f32_16x16x32_bf16 v[16:19], v[176:179], v[204:207], v[16:19]
	v_mfma_f32_16x16x32_bf16 v[4:7], v[168:171], v[212:215], v[4:7]
	v_mfma_f32_16x16x32_bf16 v[0:3], v[176:179], v[212:215], v[0:3]
	v_mfma_f32_16x16x32_bf16 v[52:55], v[172:175], v[192:195], v[52:55]
	v_mfma_f32_16x16x32_bf16 v[48:51], v[180:183], v[192:195], v[48:51]
	v_mfma_f32_16x16x32_bf16 v[36:39], v[172:175], v[200:203], v[36:39]
	v_mfma_f32_16x16x32_bf16 v[32:35], v[180:183], v[200:203], v[32:35]
	v_mfma_f32_16x16x32_bf16 v[20:23], v[172:175], v[208:211], v[20:23]
	v_mfma_f32_16x16x32_bf16 v[16:19], v[180:183], v[208:211], v[16:19]
	v_mfma_f32_16x16x32_bf16 v[4:7], v[172:175], v[216:219], v[4:7]
	v_mfma_f32_16x16x32_bf16 v[0:3], v[180:183], v[216:219], v[0:3]
	s_barrier
	s_add_i32 s77, s77, 2
	s_add_u32 s34, s34, 0x100
	s_addc_u32 s35, s35, 0
	s_add_u32 s75, s75, 0x100
	s_addc_u32 s76, s76, 0
	s_cmp_gt_u32 s77, 13
	s_cbranch_scc0 .LBB0_837

.LBB0_915:
	s_ashr_i32 s25, s24, 31
	s_lshl_b64 s[26:27], s[24:25], 21
	s_add_u32 s26, s56, s26
	s_addc_u32 s27, s57, s27
	s_and_b64 s[28:29], s[4:5], exec
	s_cselect_b32 s25, s27, s35
	s_cselect_b32 s55, s26, s34
	s_ashr_i32 s23, s22, 31
	s_lshl_b64 s[28:29], s[22:23], 21
	s_add_u32 s28, s53, s28
	s_addc_u32 s29, s60, s29
	s_and_b64 s[42:43], s[4:5], exec
	s_cselect_b32 s23, s29, s41
	s_cselect_b32 s74, s28, s40
	s_add_u32 s34, s34, 0x100080
	s_addc_u32 s35, s35, 0
	s_add_u32 s75, s40, 0x100
	s_addc_u32 s76, s41, 0
	s_mov_b32 s77, -2
	ds_read_b128 v[152:155], v149
	ds_read_b128 v[156:159], v149 offset:1024
	ds_read_b128 v[160:163], v149 offset:2048
	ds_read_b128 v[164:167], v149 offset:3072
	ds_read_b128 v[168:171], v150
	ds_read_b128 v[172:175], v150 offset:1024
	ds_read_b128 v[176:179], v150 offset:2048
	ds_read_b128 v[180:183], v150 offset:3072
	s_add_u32 s40, s34, 0xfff00080
	s_addc_u32 s41, s35, -1
	s_cmp_eq_u32 s77, 60
	s_cselect_b32 s43, s25, s41
	s_cselect_b32 s42, s55, s40
	s_cselect_b32 s41, s23, s76
	s_cselect_b32 s40, s74, s75
	s_add_i32 m0, s31, 0xc000
	ds_read_b128 v[184:187], v151
	ds_read_b128 v[192:195], v151 offset:1024
	ds_read_b128 v[196:199], v151 offset:2048
	ds_read_b128 v[200:203], v151 offset:3072
	ds_read_b128 v[204:207], v151 offset:4096
	ds_read_b128 v[208:211], v151 offset:5120
	ds_read_b128 v[212:215], v151 offset:6144
	ds_read_b128 v[216:219], v151 offset:7168
	global_load_lds_dwordx4 v136, s[34:35]
	s_add_i32 m0, s31, 0xe000
	s_nop 0
	global_load_lds_dwordx4 v138, s[34:35]
	s_waitcnt vmcnt(8)
	s_waitcnt lgkmcnt(0)
	s_barrier
	s_waitcnt lgkmcnt(0)
	v_mfma_f32_16x16x32_bf16 v[124:127], v[152:155], v[184:187], 0
	v_mfma_f32_16x16x32_bf16 v[120:123], v[160:163], v[184:187], 0
	v_mfma_f32_16x16x32_bf16 v[116:119], v[152:155], v[196:199], 0
	v_mfma_f32_16x16x32_bf16 v[108:111], v[160:163], v[196:199], 0
	v_mfma_f32_16x16x32_bf16 v[100:103], v[152:155], v[204:207], 0
	v_mfma_f32_16x16x32_bf16 v[92:95], v[160:163], v[204:207], 0
	v_mfma_f32_16x16x32_bf16 v[84:87], v[152:155], v[212:215], 0
	v_mfma_f32_16x16x32_bf16 v[76:79], v[160:163], v[212:215], 0
	v_mfma_f32_16x16x32_bf16 v[124:127], v[156:159], v[192:195], v[124:127]
	v_mfma_f32_16x16x32_bf16 v[120:123], v[164:167], v[192:195], v[120:123]
	v_mfma_f32_16x16x32_bf16 v[116:119], v[156:159], v[200:203], v[116:119]
	v_mfma_f32_16x16x32_bf16 v[108:111], v[164:167], v[200:203], v[108:111]
	v_mfma_f32_16x16x32_bf16 v[100:103], v[156:159], v[208:211], v[100:103]
	v_mfma_f32_16x16x32_bf16 v[92:95], v[164:167], v[208:211], v[92:95]
	v_mfma_f32_16x16x32_bf16 v[84:87], v[156:159], v[216:219], v[84:87]
	v_mfma_f32_16x16x32_bf16 v[76:79], v[164:167], v[216:219], v[76:79]
	v_mfma_f32_16x16x32_bf16 v[112:115], v[168:171], v[184:187], 0
	v_mfma_f32_16x16x32_bf16 v[104:107], v[176:179], v[184:187], 0
	v_mfma_f32_16x16x32_bf16 v[96:99], v[168:171], v[196:199], 0
	v_mfma_f32_16x16x32_bf16 v[88:91], v[176:179], v[196:199], 0
	v_mfma_f32_16x16x32_bf16 v[80:83], v[168:171], v[204:207], 0
	v_mfma_f32_16x16x32_bf16 v[72:75], v[176:179], v[204:207], 0
	v_mfma_f32_16x16x32_bf16 v[68:71], v[168:171], v[212:215], 0
	v_mfma_f32_16x16x32_bf16 v[64:67], v[176:179], v[212:215], 0
	v_mfma_f32_16x16x32_bf16 v[112:115], v[172:175], v[192:195], v[112:115]
	v_mfma_f32_16x16x32_bf16 v[104:107], v[180:183], v[192:195], v[104:107]
	v_mfma_f32_16x16x32_bf16 v[96:99], v[172:175], v[200:203], v[96:99]
	v_mfma_f32_16x16x32_bf16 v[88:91], v[180:183], v[200:203], v[88:91]
	v_mfma_f32_16x16x32_bf16 v[80:83], v[172:175], v[208:211], v[80:83]
	v_mfma_f32_16x16x32_bf16 v[72:75], v[180:183], v[208:211], v[72:75]
	v_mfma_f32_16x16x32_bf16 v[68:71], v[172:175], v[216:219], v[68:71]
	v_mfma_f32_16x16x32_bf16 v[64:67], v[180:183], v[216:219], v[64:67]
	s_barrier
	s_add_i32 s79, s68, s61
	v_lshl_add_u64 v[144:145], s[40:41], 0, v[130:131]
	s_mov_b32 m0, s79
	ds_read_b128 v[184:187], v151 offset:16384
	ds_read_b128 v[192:195], v151 offset:17408
	ds_read_b128 v[196:199], v151 offset:18432
	ds_read_b128 v[200:203], v151 offset:19456
	ds_read_b128 v[204:207], v151 offset:20480
	ds_read_b128 v[208:211], v151 offset:21504
	ds_read_b128 v[212:215], v151 offset:22528
	ds_read_b128 v[216:219], v151 offset:23552
	global_load_lds_dwordx4 v[144:145], off
	s_add_i32 m0, s79, 0x2000
	s_add_u32 s80, s40, 0x100000
	v_lshl_add_u64 v[188:189], s[40:41], 0, v[134:135]
	s_addc_u32 s81, s41, 0
	s_add_i32 s79, s69, s61
	global_load_lds_dwordx4 v[188:189], off
	s_mov_b32 m0, s79
	v_lshl_add_u64 v[222:223], s[42:43], 0, v[132:133]
	global_load_lds_dwordx4 v130, s[80:81]
	s_add_i32 m0, s79, 0x2000
	s_nop 0
	global_load_lds_dwordx4 v134, s[80:81]
	v_lshl_add_u64 v[220:221], s[42:43], 0, v[128:129]
	s_mov_b32 m0, s31
	s_nop 0
	global_load_lds_dwordx4 v[220:221], off
	s_mov_b32 m0, s33
	s_nop 0
	global_load_lds_dwordx4 v[222:223], off
	s_waitcnt vmcnt(8)
	s_waitcnt lgkmcnt(0)
	s_barrier
	s_waitcnt lgkmcnt(0)
	v_mfma_f32_16x16x32_bf16 v[60:63], v[152:155], v[184:187], 0
	v_mfma_f32_16x16x32_bf16 v[56:59], v[160:163], v[184:187], 0
	v_mfma_f32_16x16x32_bf16 v[52:55], v[152:155], v[196:199], 0
	v_mfma_f32_16x16x32_bf16 v[44:47], v[160:163], v[196:199], 0
	v_mfma_f32_16x16x32_bf16 v[36:39], v[152:155], v[204:207], 0
	v_mfma_f32_16x16x32_bf16 v[28:31], v[160:163], v[204:207], 0
	v_mfma_f32_16x16x32_bf16 v[20:23], v[152:155], v[212:215], 0
	v_mfma_f32_16x16x32_bf16 v[12:15], v[160:163], v[212:215], 0
	v_mfma_f32_16x16x32_bf16 v[60:63], v[156:159], v[192:195], v[60:63]
	v_mfma_f32_16x16x32_bf16 v[56:59], v[164:167], v[192:195], v[56:59]
	v_mfma_f32_16x16x32_bf16 v[52:55], v[156:159], v[200:203], v[52:55]
	v_mfma_f32_16x16x32_bf16 v[44:47], v[164:167], v[200:203], v[44:47]
	v_mfma_f32_16x16x32_bf16 v[36:39], v[156:159], v[208:211], v[36:39]
	v_mfma_f32_16x16x32_bf16 v[28:31], v[164:167], v[208:211], v[28:31]
	v_mfma_f32_16x16x32_bf16 v[20:23], v[156:159], v[216:219], v[20:23]
	v_mfma_f32_16x16x32_bf16 v[12:15], v[164:167], v[216:219], v[12:15]
	v_mfma_f32_16x16x32_bf16 v[48:51], v[168:171], v[184:187], 0
	v_mfma_f32_16x16x32_bf16 v[40:43], v[176:179], v[184:187], 0
	v_mfma_f32_16x16x32_bf16 v[32:35], v[168:171], v[196:199], 0
	v_mfma_f32_16x16x32_bf16 v[24:27], v[176:179], v[196:199], 0
	v_mfma_f32_16x16x32_bf16 v[16:19], v[168:171], v[204:207], 0
	v_mfma_f32_16x16x32_bf16 v[8:11], v[176:179], v[204:207], 0
	v_mfma_f32_16x16x32_bf16 v[4:7], v[168:171], v[212:215], 0
	v_mfma_f32_16x16x32_bf16 v[0:3], v[176:179], v[212:215], 0
	v_mfma_f32_16x16x32_bf16 v[48:51], v[172:175], v[192:195], v[48:51]
	v_mfma_f32_16x16x32_bf16 v[40:43], v[180:183], v[192:195], v[40:43]
	v_mfma_f32_16x16x32_bf16 v[32:35], v[172:175], v[200:203], v[32:35]
	v_mfma_f32_16x16x32_bf16 v[24:27], v[180:183], v[200:203], v[24:27]
	v_mfma_f32_16x16x32_bf16 v[16:19], v[172:175], v[208:211], v[16:19]
	v_mfma_f32_16x16x32_bf16 v[8:11], v[180:183], v[208:211], v[8:11]
	v_mfma_f32_16x16x32_bf16 v[4:7], v[172:175], v[216:219], v[4:7]
	v_mfma_f32_16x16x32_bf16 v[0:3], v[180:183], v[216:219], v[0:3]
	s_barrier
	s_add_i32 s79, 0, 0x18000
	s_add_i32 s80, 0, 0x1c000
	v_add_u32_e32 v164, s79, v147
	v_add_u32_e32 v180, s80, v147
	ds_read_b128 v[152:155], v164
	ds_read_b128 v[156:159], v164 offset:1024
	ds_read_b128 v[160:163], v164 offset:2048
	ds_read_b128 v[164:167], v164 offset:3072
	ds_read_b128 v[168:171], v180
	ds_read_b128 v[172:175], v180 offset:1024
	ds_read_b128 v[176:179], v180 offset:2048
	ds_read_b128 v[180:183], v180 offset:3072
	s_add_u32 s42, s42, 0x100000
	s_addc_u32 s43, s43, 0
	s_mov_b32 m0, s62
	ds_read_b128 v[184:187], v151 offset:32768
	ds_read_b128 v[192:195], v151 offset:33792
	ds_read_b128 v[196:199], v151 offset:34816
	ds_read_b128 v[200:203], v151 offset:35840
	ds_read_b128 v[204:207], v151 offset:36864
	ds_read_b128 v[208:211], v151 offset:37888
	ds_read_b128 v[212:215], v151 offset:38912
	ds_read_b128 v[216:219], v151 offset:39936
	global_load_lds_dwordx4 v128, s[42:43]
	s_mov_b32 m0, s63
	s_nop 0
	global_load_lds_dwordx4 v132, s[42:43]
	s_waitcnt vmcnt(8)
	s_waitcnt lgkmcnt(0)
	s_barrier
	s_waitcnt lgkmcnt(0)
	v_mfma_f32_16x16x32_bf16 v[124:127], v[152:155], v[184:187], v[124:127]
	v_mfma_f32_16x16x32_bf16 v[120:123], v[160:163], v[184:187], v[120:123]
	v_mfma_f32_16x16x32_bf16 v[116:119], v[152:155], v[196:199], v[116:119]
	v_mfma_f32_16x16x32_bf16 v[108:111], v[160:163], v[196:199], v[108:111]
	v_mfma_f32_16x16x32_bf16 v[100:103], v[152:155], v[204:207], v[100:103]
	v_mfma_f32_16x16x32_bf16 v[92:95], v[160:163], v[204:207], v[92:95]
	v_mfma_f32_16x16x32_bf16 v[84:87], v[152:155], v[212:215], v[84:87]
	v_mfma_f32_16x16x32_bf16 v[76:79], v[160:163], v[212:215], v[76:79]
	v_mfma_f32_16x16x32_bf16 v[124:127], v[156:159], v[192:195], v[124:127]
	v_mfma_f32_16x16x32_bf16 v[120:123], v[164:167], v[192:195], v[120:123]
	v_mfma_f32_16x16x32_bf16 v[116:119], v[156:159], v[200:203], v[116:119]
	v_mfma_f32_16x16x32_bf16 v[108:111], v[164:167], v[200:203], v[108:111]
	v_mfma_f32_16x16x32_bf16 v[100:103], v[156:159], v[208:211], v[100:103]
	v_mfma_f32_16x16x32_bf16 v[92:95], v[164:167], v[208:211], v[92:95]
	v_mfma_f32_16x16x32_bf16 v[84:87], v[156:159], v[216:219], v[84:87]
	v_mfma_f32_16x16x32_bf16 v[76:79], v[164:167], v[216:219], v[76:79]
	v_mfma_f32_16x16x32_bf16 v[112:115], v[168:171], v[184:187], v[112:115]
	v_mfma_f32_16x16x32_bf16 v[104:107], v[176:179], v[184:187], v[104:107]
	v_mfma_f32_16x16x32_bf16 v[96:99], v[168:171], v[196:199], v[96:99]
	v_mfma_f32_16x16x32_bf16 v[88:91], v[176:179], v[196:199], v[88:91]
	v_mfma_f32_16x16x32_bf16 v[80:83], v[168:171], v[204:207], v[80:83]
	v_mfma_f32_16x16x32_bf16 v[72:75], v[176:179], v[204:207], v[72:75]
	v_mfma_f32_16x16x32_bf16 v[68:71], v[168:171], v[212:215], v[68:71]
	v_mfma_f32_16x16x32_bf16 v[64:67], v[176:179], v[212:215], v[64:67]
	v_mfma_f32_16x16x32_bf16 v[112:115], v[172:175], v[192:195], v[112:115]
	v_mfma_f32_16x16x32_bf16 v[104:107], v[180:183], v[192:195], v[104:107]
	v_mfma_f32_16x16x32_bf16 v[96:99], v[172:175], v[200:203], v[96:99]
	v_mfma_f32_16x16x32_bf16 v[88:91], v[180:183], v[200:203], v[88:91]
	v_mfma_f32_16x16x32_bf16 v[80:83], v[172:175], v[208:211], v[80:83]
	v_mfma_f32_16x16x32_bf16 v[72:75], v[180:183], v[208:211], v[72:75]
	v_mfma_f32_16x16x32_bf16 v[68:71], v[172:175], v[216:219], v[68:71]
	v_mfma_f32_16x16x32_bf16 v[64:67], v[180:183], v[216:219], v[64:67]
	s_barrier
	s_add_i32 s42, s79, s61
	v_lshl_add_u64 v[144:145], v[144:145], 0, s[10:11]
	s_mov_b32 m0, s42
	ds_read_b128 v[184:187], v151 offset:49152
	ds_read_b128 v[192:195], v151 offset:50176
	ds_read_b128 v[196:199], v151 offset:51200
	ds_read_b128 v[200:203], v151 offset:52224
	ds_read_b128 v[204:207], v151 offset:53248
	ds_read_b128 v[208:211], v151 offset:54272
	ds_read_b128 v[212:215], v151 offset:55296
	ds_read_b128 v[216:219], v151 offset:56320
	global_load_lds_dwordx4 v[144:145], off
	s_add_i32 m0, s42, 0x2000
	s_add_u32 s40, s40, 0x100080
	v_lshl_add_u64 v[144:145], v[188:189], 0, s[10:11]
	s_addc_u32 s41, s41, 0
	s_add_i32 s42, s80, s61
	global_load_lds_dwordx4 v[144:145], off
	s_mov_b32 m0, s42
	s_nop 0
	global_load_lds_dwordx4 v130, s[40:41]
	s_add_i32 m0, s42, 0x2000
	s_nop 0
	global_load_lds_dwordx4 v134, s[40:41]
	v_lshl_add_u64 v[144:145], v[220:221], 0, s[10:11]
	s_mov_b32 m0, s65
	s_nop 0
	global_load_lds_dwordx4 v[144:145], off
	v_lshl_add_u64 v[144:145], v[222:223], 0, s[10:11]
	s_mov_b32 m0, s66
	s_nop 0
	global_load_lds_dwordx4 v[144:145], off
	s_waitcnt vmcnt(8)
	s_waitcnt lgkmcnt(0)
	s_barrier
	s_waitcnt lgkmcnt(0)
	v_mfma_f32_16x16x32_bf16 v[60:63], v[152:155], v[184:187], v[60:63]
	v_mfma_f32_16x16x32_bf16 v[56:59], v[160:163], v[184:187], v[56:59]
	v_mfma_f32_16x16x32_bf16 v[52:55], v[152:155], v[196:199], v[52:55]
	v_mfma_f32_16x16x32_bf16 v[44:47], v[160:163], v[196:199], v[44:47]
	v_mfma_f32_16x16x32_bf16 v[36:39], v[152:155], v[204:207], v[36:39]
	v_mfma_f32_16x16x32_bf16 v[28:31], v[160:163], v[204:207], v[28:31]
	v_mfma_f32_16x16x32_bf16 v[20:23], v[152:155], v[212:215], v[20:23]
	v_mfma_f32_16x16x32_bf16 v[12:15], v[160:163], v[212:215], v[12:15]
	v_mfma_f32_16x16x32_bf16 v[60:63], v[156:159], v[192:195], v[60:63]
	v_mfma_f32_16x16x32_bf16 v[56:59], v[164:167], v[192:195], v[56:59]
	v_mfma_f32_16x16x32_bf16 v[52:55], v[156:159], v[200:203], v[52:55]
	v_mfma_f32_16x16x32_bf16 v[44:47], v[164:167], v[200:203], v[44:47]
	v_mfma_f32_16x16x32_bf16 v[36:39], v[156:159], v[208:211], v[36:39]
	v_mfma_f32_16x16x32_bf16 v[28:31], v[164:167], v[208:211], v[28:31]
	v_mfma_f32_16x16x32_bf16 v[20:23], v[156:159], v[216:219], v[20:23]
	v_mfma_f32_16x16x32_bf16 v[12:15], v[164:167], v[216:219], v[12:15]
	v_mfma_f32_16x16x32_bf16 v[48:51], v[168:171], v[184:187], v[48:51]
	v_mfma_f32_16x16x32_bf16 v[40:43], v[176:179], v[184:187], v[40:43]
	v_mfma_f32_16x16x32_bf16 v[32:35], v[168:171], v[196:199], v[32:35]
	v_mfma_f32_16x16x32_bf16 v[24:27], v[176:179], v[196:199], v[24:27]
	v_mfma_f32_16x16x32_bf16 v[16:19], v[168:171], v[204:207], v[16:19]
	v_mfma_f32_16x16x32_bf16 v[8:11], v[176:179], v[204:207], v[8:11]
	v_mfma_f32_16x16x32_bf16 v[4:7], v[168:171], v[212:215], v[4:7]
	v_mfma_f32_16x16x32_bf16 v[0:3], v[176:179], v[212:215], v[0:3]
	v_mfma_f32_16x16x32_bf16 v[48:51], v[172:175], v[192:195], v[48:51]
	v_mfma_f32_16x16x32_bf16 v[40:43], v[180:183], v[192:195], v[40:43]
	v_mfma_f32_16x16x32_bf16 v[32:35], v[172:175], v[200:203], v[32:35]
	v_mfma_f32_16x16x32_bf16 v[24:27], v[180:183], v[200:203], v[24:27]
	v_mfma_f32_16x16x32_bf16 v[16:19], v[172:175], v[208:211], v[16:19]
	v_mfma_f32_16x16x32_bf16 v[8:11], v[180:183], v[208:211], v[8:11]
	v_mfma_f32_16x16x32_bf16 v[4:7], v[172:175], v[216:219], v[4:7]
	v_mfma_f32_16x16x32_bf16 v[0:3], v[180:183], v[216:219], v[0:3]
	s_barrier
	s_add_i32 s77, s77, 2
	s_add_u32 s34, s34, 0x100
	s_addc_u32 s35, s35, 0
	s_add_u32 s75, s75, 0x100
	s_addc_u32 s76, s76, 0
	s_cmp_gt_u32 s77, 61
	s_cbranch_scc0 .LBB0_916
	s_branch .Lpeel_exit4
.LBB0_916:
	ds_read_b128 v[152:155], v149
	ds_read_b128 v[156:159], v149 offset:1024
	ds_read_b128 v[160:163], v149 offset:2048
	ds_read_b128 v[164:167], v149 offset:3072
	ds_read_b128 v[168:171], v150
	ds_read_b128 v[172:175], v150 offset:1024
	ds_read_b128 v[176:179], v150 offset:2048
	ds_read_b128 v[180:183], v150 offset:3072
	s_add_u32 s40, s34, 0xfff00080
	s_addc_u32 s41, s35, -1
	s_cmp_eq_u32 s77, 60
	s_cselect_b32 s43, s25, s41
	s_cselect_b32 s42, s55, s40
	s_cselect_b32 s41, s23, s76
	s_cselect_b32 s40, s74, s75
	s_add_i32 m0, s31, 0xc000
	ds_read_b128 v[184:187], v151
	ds_read_b128 v[192:195], v151 offset:1024
	ds_read_b128 v[196:199], v151 offset:2048
	ds_read_b128 v[200:203], v151 offset:3072
	ds_read_b128 v[204:207], v151 offset:4096
	ds_read_b128 v[208:211], v151 offset:5120
	ds_read_b128 v[212:215], v151 offset:6144
	ds_read_b128 v[216:219], v151 offset:7168
	global_load_lds_dwordx4 v136, s[34:35]
	s_add_i32 m0, s31, 0xe000
	s_nop 0
	global_load_lds_dwordx4 v138, s[34:35]
	s_waitcnt vmcnt(8)
	s_waitcnt lgkmcnt(0)
	s_barrier
	s_waitcnt lgkmcnt(0)
	v_mfma_f32_16x16x32_bf16 v[124:127], v[152:155], v[184:187], v[124:127]
	v_mfma_f32_16x16x32_bf16 v[120:123], v[160:163], v[184:187], v[120:123]
	v_mfma_f32_16x16x32_bf16 v[116:119], v[152:155], v[196:199], v[116:119]
	v_mfma_f32_16x16x32_bf16 v[108:111], v[160:163], v[196:199], v[108:111]
	v_mfma_f32_16x16x32_bf16 v[100:103], v[152:155], v[204:207], v[100:103]
	v_mfma_f32_16x16x32_bf16 v[92:95], v[160:163], v[204:207], v[92:95]
	v_mfma_f32_16x16x32_bf16 v[84:87], v[152:155], v[212:215], v[84:87]
	v_mfma_f32_16x16x32_bf16 v[76:79], v[160:163], v[212:215], v[76:79]
	v_mfma_f32_16x16x32_bf16 v[124:127], v[156:159], v[192:195], v[124:127]
	v_mfma_f32_16x16x32_bf16 v[120:123], v[164:167], v[192:195], v[120:123]
	v_mfma_f32_16x16x32_bf16 v[116:119], v[156:159], v[200:203], v[116:119]
	v_mfma_f32_16x16x32_bf16 v[108:111], v[164:167], v[200:203], v[108:111]
	v_mfma_f32_16x16x32_bf16 v[100:103], v[156:159], v[208:211], v[100:103]
	v_mfma_f32_16x16x32_bf16 v[92:95], v[164:167], v[208:211], v[92:95]
	v_mfma_f32_16x16x32_bf16 v[84:87], v[156:159], v[216:219], v[84:87]
	v_mfma_f32_16x16x32_bf16 v[76:79], v[164:167], v[216:219], v[76:79]
	v_mfma_f32_16x16x32_bf16 v[112:115], v[168:171], v[184:187], v[112:115]
	v_mfma_f32_16x16x32_bf16 v[104:107], v[176:179], v[184:187], v[104:107]
	v_mfma_f32_16x16x32_bf16 v[96:99], v[168:171], v[196:199], v[96:99]
	v_mfma_f32_16x16x32_bf16 v[88:91], v[176:179], v[196:199], v[88:91]
	v_mfma_f32_16x16x32_bf16 v[80:83], v[168:171], v[204:207], v[80:83]
	v_mfma_f32_16x16x32_bf16 v[72:75], v[176:179], v[204:207], v[72:75]
	v_mfma_f32_16x16x32_bf16 v[68:71], v[168:171], v[212:215], v[68:71]
	v_mfma_f32_16x16x32_bf16 v[64:67], v[176:179], v[212:215], v[64:67]
	v_mfma_f32_16x16x32_bf16 v[112:115], v[172:175], v[192:195], v[112:115]
	v_mfma_f32_16x16x32_bf16 v[104:107], v[180:183], v[192:195], v[104:107]
	v_mfma_f32_16x16x32_bf16 v[96:99], v[172:175], v[200:203], v[96:99]
	v_mfma_f32_16x16x32_bf16 v[88:91], v[180:183], v[200:203], v[88:91]
	v_mfma_f32_16x16x32_bf16 v[80:83], v[172:175], v[208:211], v[80:83]
	v_mfma_f32_16x16x32_bf16 v[72:75], v[180:183], v[208:211], v[72:75]
	v_mfma_f32_16x16x32_bf16 v[68:71], v[172:175], v[216:219], v[68:71]
	v_mfma_f32_16x16x32_bf16 v[64:67], v[180:183], v[216:219], v[64:67]
	s_barrier
	s_add_i32 s79, s68, s61
	v_lshl_add_u64 v[144:145], s[40:41], 0, v[130:131]
	s_mov_b32 m0, s79
	ds_read_b128 v[184:187], v151 offset:16384
	ds_read_b128 v[192:195], v151 offset:17408
	ds_read_b128 v[196:199], v151 offset:18432
	ds_read_b128 v[200:203], v151 offset:19456
	ds_read_b128 v[204:207], v151 offset:20480
	ds_read_b128 v[208:211], v151 offset:21504
	ds_read_b128 v[212:215], v151 offset:22528
	ds_read_b128 v[216:219], v151 offset:23552
	global_load_lds_dwordx4 v[144:145], off
	s_add_i32 m0, s79, 0x2000
	s_add_u32 s80, s40, 0x100000
	v_lshl_add_u64 v[188:189], s[40:41], 0, v[134:135]
	s_addc_u32 s81, s41, 0
	s_add_i32 s79, s69, s61
	global_load_lds_dwordx4 v[188:189], off
	s_mov_b32 m0, s79
	v_lshl_add_u64 v[222:223], s[42:43], 0, v[132:133]
	global_load_lds_dwordx4 v130, s[80:81]
	s_add_i32 m0, s79, 0x2000
	s_nop 0
	global_load_lds_dwordx4 v134, s[80:81]
	v_lshl_add_u64 v[220:221], s[42:43], 0, v[128:129]
	s_mov_b32 m0, s31
	s_nop 0
	global_load_lds_dwordx4 v[220:221], off
	s_mov_b32 m0, s33
	s_nop 0
	global_load_lds_dwordx4 v[222:223], off
	s_waitcnt vmcnt(8)
	s_waitcnt lgkmcnt(0)
	s_barrier
	s_waitcnt lgkmcnt(0)
	v_mfma_f32_16x16x32_bf16 v[60:63], v[152:155], v[184:187], v[60:63]
	v_mfma_f32_16x16x32_bf16 v[56:59], v[160:163], v[184:187], v[56:59]
	v_mfma_f32_16x16x32_bf16 v[52:55], v[152:155], v[196:199], v[52:55]
	v_mfma_f32_16x16x32_bf16 v[44:47], v[160:163], v[196:199], v[44:47]
	v_mfma_f32_16x16x32_bf16 v[36:39], v[152:155], v[204:207], v[36:39]
	v_mfma_f32_16x16x32_bf16 v[28:31], v[160:163], v[204:207], v[28:31]
	v_mfma_f32_16x16x32_bf16 v[20:23], v[152:155], v[212:215], v[20:23]
	v_mfma_f32_16x16x32_bf16 v[12:15], v[160:163], v[212:215], v[12:15]
	v_mfma_f32_16x16x32_bf16 v[60:63], v[156:159], v[192:195], v[60:63]
	v_mfma_f32_16x16x32_bf16 v[56:59], v[164:167], v[192:195], v[56:59]
	v_mfma_f32_16x16x32_bf16 v[52:55], v[156:159], v[200:203], v[52:55]
	v_mfma_f32_16x16x32_bf16 v[44:47], v[164:167], v[200:203], v[44:47]
	v_mfma_f32_16x16x32_bf16 v[36:39], v[156:159], v[208:211], v[36:39]
	v_mfma_f32_16x16x32_bf16 v[28:31], v[164:167], v[208:211], v[28:31]
	v_mfma_f32_16x16x32_bf16 v[20:23], v[156:159], v[216:219], v[20:23]
	v_mfma_f32_16x16x32_bf16 v[12:15], v[164:167], v[216:219], v[12:15]
	v_mfma_f32_16x16x32_bf16 v[48:51], v[168:171], v[184:187], v[48:51]
	v_mfma_f32_16x16x32_bf16 v[40:43], v[176:179], v[184:187], v[40:43]
	v_mfma_f32_16x16x32_bf16 v[32:35], v[168:171], v[196:199], v[32:35]
	v_mfma_f32_16x16x32_bf16 v[24:27], v[176:179], v[196:199], v[24:27]
	v_mfma_f32_16x16x32_bf16 v[16:19], v[168:171], v[204:207], v[16:19]
	v_mfma_f32_16x16x32_bf16 v[8:11], v[176:179], v[204:207], v[8:11]
	v_mfma_f32_16x16x32_bf16 v[4:7], v[168:171], v[212:215], v[4:7]
	v_mfma_f32_16x16x32_bf16 v[0:3], v[176:179], v[212:215], v[0:3]
	v_mfma_f32_16x16x32_bf16 v[48:51], v[172:175], v[192:195], v[48:51]
	v_mfma_f32_16x16x32_bf16 v[40:43], v[180:183], v[192:195], v[40:43]
	v_mfma_f32_16x16x32_bf16 v[32:35], v[172:175], v[200:203], v[32:35]
	v_mfma_f32_16x16x32_bf16 v[24:27], v[180:183], v[200:203], v[24:27]
	v_mfma_f32_16x16x32_bf16 v[16:19], v[172:175], v[208:211], v[16:19]
	v_mfma_f32_16x16x32_bf16 v[8:11], v[180:183], v[208:211], v[8:11]
	v_mfma_f32_16x16x32_bf16 v[4:7], v[172:175], v[216:219], v[4:7]
	v_mfma_f32_16x16x32_bf16 v[0:3], v[180:183], v[216:219], v[0:3]
	s_barrier
	s_add_i32 s79, 0, 0x18000
	s_add_i32 s80, 0, 0x1c000
	v_add_u32_e32 v164, s79, v147
	v_add_u32_e32 v180, s80, v147
	ds_read_b128 v[152:155], v164
	ds_read_b128 v[156:159], v164 offset:1024
	ds_read_b128 v[160:163], v164 offset:2048
	ds_read_b128 v[164:167], v164 offset:3072
	ds_read_b128 v[168:171], v180
	ds_read_b128 v[172:175], v180 offset:1024
	ds_read_b128 v[176:179], v180 offset:2048
	ds_read_b128 v[180:183], v180 offset:3072
	s_add_u32 s42, s42, 0x100000
	s_addc_u32 s43, s43, 0
	s_mov_b32 m0, s62
	ds_read_b128 v[184:187], v151 offset:32768
	ds_read_b128 v[192:195], v151 offset:33792
	ds_read_b128 v[196:199], v151 offset:34816
	ds_read_b128 v[200:203], v151 offset:35840
	ds_read_b128 v[204:207], v151 offset:36864
	ds_read_b128 v[208:211], v151 offset:37888
	ds_read_b128 v[212:215], v151 offset:38912
	ds_read_b128 v[216:219], v151 offset:39936
	global_load_lds_dwordx4 v128, s[42:43]
	s_mov_b32 m0, s63
	s_nop 0
	global_load_lds_dwordx4 v132, s[42:43]
	s_waitcnt vmcnt(8)
	s_waitcnt lgkmcnt(0)
	s_barrier
	s_waitcnt lgkmcnt(0)
	v_mfma_f32_16x16x32_bf16 v[124:127], v[152:155], v[184:187], v[124:127]
	v_mfma_f32_16x16x32_bf16 v[120:123], v[160:163], v[184:187], v[120:123]
	v_mfma_f32_16x16x32_bf16 v[116:119], v[152:155], v[196:199], v[116:119]
	v_mfma_f32_16x16x32_bf16 v[108:111], v[160:163], v[196:199], v[108:111]
	v_mfma_f32_16x16x32_bf16 v[100:103], v[152:155], v[204:207], v[100:103]
	v_mfma_f32_16x16x32_bf16 v[92:95], v[160:163], v[204:207], v[92:95]
	v_mfma_f32_16x16x32_bf16 v[84:87], v[152:155], v[212:215], v[84:87]
	v_mfma_f32_16x16x32_bf16 v[76:79], v[160:163], v[212:215], v[76:79]
	v_mfma_f32_16x16x32_bf16 v[124:127], v[156:159], v[192:195], v[124:127]
	v_mfma_f32_16x16x32_bf16 v[120:123], v[164:167], v[192:195], v[120:123]
	v_mfma_f32_16x16x32_bf16 v[116:119], v[156:159], v[200:203], v[116:119]
	v_mfma_f32_16x16x32_bf16 v[108:111], v[164:167], v[200:203], v[108:111]
	v_mfma_f32_16x16x32_bf16 v[100:103], v[156:159], v[208:211], v[100:103]
	v_mfma_f32_16x16x32_bf16 v[92:95], v[164:167], v[208:211], v[92:95]
	v_mfma_f32_16x16x32_bf16 v[84:87], v[156:159], v[216:219], v[84:87]
	v_mfma_f32_16x16x32_bf16 v[76:79], v[164:167], v[216:219], v[76:79]
	v_mfma_f32_16x16x32_bf16 v[112:115], v[168:171], v[184:187], v[112:115]
	v_mfma_f32_16x16x32_bf16 v[104:107], v[176:179], v[184:187], v[104:107]
	v_mfma_f32_16x16x32_bf16 v[96:99], v[168:171], v[196:199], v[96:99]
	v_mfma_f32_16x16x32_bf16 v[88:91], v[176:179], v[196:199], v[88:91]
	v_mfma_f32_16x16x32_bf16 v[80:83], v[168:171], v[204:207], v[80:83]
	v_mfma_f32_16x16x32_bf16 v[72:75], v[176:179], v[204:207], v[72:75]
	v_mfma_f32_16x16x32_bf16 v[68:71], v[168:171], v[212:215], v[68:71]
	v_mfma_f32_16x16x32_bf16 v[64:67], v[176:179], v[212:215], v[64:67]
	v_mfma_f32_16x16x32_bf16 v[112:115], v[172:175], v[192:195], v[112:115]
	v_mfma_f32_16x16x32_bf16 v[104:107], v[180:183], v[192:195], v[104:107]
	v_mfma_f32_16x16x32_bf16 v[96:99], v[172:175], v[200:203], v[96:99]
	v_mfma_f32_16x16x32_bf16 v[88:91], v[180:183], v[200:203], v[88:91]
	v_mfma_f32_16x16x32_bf16 v[80:83], v[172:175], v[208:211], v[80:83]
	v_mfma_f32_16x16x32_bf16 v[72:75], v[180:183], v[208:211], v[72:75]
	v_mfma_f32_16x16x32_bf16 v[68:71], v[172:175], v[216:219], v[68:71]
	v_mfma_f32_16x16x32_bf16 v[64:67], v[180:183], v[216:219], v[64:67]
	s_barrier
	s_add_i32 s42, s79, s61
	v_lshl_add_u64 v[144:145], v[144:145], 0, s[10:11]
	s_mov_b32 m0, s42
	ds_read_b128 v[184:187], v151 offset:49152
	ds_read_b128 v[192:195], v151 offset:50176
	ds_read_b128 v[196:199], v151 offset:51200
	ds_read_b128 v[200:203], v151 offset:52224
	ds_read_b128 v[204:207], v151 offset:53248
	ds_read_b128 v[208:211], v151 offset:54272
	ds_read_b128 v[212:215], v151 offset:55296
	ds_read_b128 v[216:219], v151 offset:56320
	global_load_lds_dwordx4 v[144:145], off
	s_add_i32 m0, s42, 0x2000
	s_add_u32 s40, s40, 0x100080
	v_lshl_add_u64 v[144:145], v[188:189], 0, s[10:11]
	s_addc_u32 s41, s41, 0
	s_add_i32 s42, s80, s61
	global_load_lds_dwordx4 v[144:145], off
	s_mov_b32 m0, s42
	s_nop 0
	global_load_lds_dwordx4 v130, s[40:41]
	s_add_i32 m0, s42, 0x2000
	s_nop 0
	global_load_lds_dwordx4 v134, s[40:41]
	v_lshl_add_u64 v[144:145], v[220:221], 0, s[10:11]
	s_mov_b32 m0, s65
	s_nop 0
	global_load_lds_dwordx4 v[144:145], off
	v_lshl_add_u64 v[144:145], v[222:223], 0, s[10:11]
	s_mov_b32 m0, s66
	s_nop 0
	global_load_lds_dwordx4 v[144:145], off
	s_waitcnt vmcnt(8)
	s_waitcnt lgkmcnt(0)
	s_barrier
	s_waitcnt lgkmcnt(0)
	v_mfma_f32_16x16x32_bf16 v[60:63], v[152:155], v[184:187], v[60:63]
	v_mfma_f32_16x16x32_bf16 v[56:59], v[160:163], v[184:187], v[56:59]
	v_mfma_f32_16x16x32_bf16 v[52:55], v[152:155], v[196:199], v[52:55]
	v_mfma_f32_16x16x32_bf16 v[44:47], v[160:163], v[196:199], v[44:47]
	v_mfma_f32_16x16x32_bf16 v[36:39], v[152:155], v[204:207], v[36:39]
	v_mfma_f32_16x16x32_bf16 v[28:31], v[160:163], v[204:207], v[28:31]
	v_mfma_f32_16x16x32_bf16 v[20:23], v[152:155], v[212:215], v[20:23]
	v_mfma_f32_16x16x32_bf16 v[12:15], v[160:163], v[212:215], v[12:15]
	v_mfma_f32_16x16x32_bf16 v[60:63], v[156:159], v[192:195], v[60:63]
	v_mfma_f32_16x16x32_bf16 v[56:59], v[164:167], v[192:195], v[56:59]
	v_mfma_f32_16x16x32_bf16 v[52:55], v[156:159], v[200:203], v[52:55]
	v_mfma_f32_16x16x32_bf16 v[44:47], v[164:167], v[200:203], v[44:47]
	v_mfma_f32_16x16x32_bf16 v[36:39], v[156:159], v[208:211], v[36:39]
	v_mfma_f32_16x16x32_bf16 v[28:31], v[164:167], v[208:211], v[28:31]
	v_mfma_f32_16x16x32_bf16 v[20:23], v[156:159], v[216:219], v[20:23]
	v_mfma_f32_16x16x32_bf16 v[12:15], v[164:167], v[216:219], v[12:15]
	v_mfma_f32_16x16x32_bf16 v[48:51], v[168:171], v[184:187], v[48:51]
	v_mfma_f32_16x16x32_bf16 v[40:43], v[176:179], v[184:187], v[40:43]
	v_mfma_f32_16x16x32_bf16 v[32:35], v[168:171], v[196:199], v[32:35]
	v_mfma_f32_16x16x32_bf16 v[24:27], v[176:179], v[196:199], v[24:27]
	v_mfma_f32_16x16x32_bf16 v[16:19], v[168:171], v[204:207], v[16:19]
	v_mfma_f32_16x16x32_bf16 v[8:11], v[176:179], v[204:207], v[8:11]
	v_mfma_f32_16x16x32_bf16 v[4:7], v[168:171], v[212:215], v[4:7]
	v_mfma_f32_16x16x32_bf16 v[0:3], v[176:179], v[212:215], v[0:3]
	v_mfma_f32_16x16x32_bf16 v[48:51], v[172:175], v[192:195], v[48:51]
	v_mfma_f32_16x16x32_bf16 v[40:43], v[180:183], v[192:195], v[40:43]
	v_mfma_f32_16x16x32_bf16 v[32:35], v[172:175], v[200:203], v[32:35]
	v_mfma_f32_16x16x32_bf16 v[24:27], v[180:183], v[200:203], v[24:27]
	v_mfma_f32_16x16x32_bf16 v[16:19], v[172:175], v[208:211], v[16:19]
	v_mfma_f32_16x16x32_bf16 v[8:11], v[180:183], v[208:211], v[8:11]
	v_mfma_f32_16x16x32_bf16 v[4:7], v[172:175], v[216:219], v[4:7]
	v_mfma_f32_16x16x32_bf16 v[0:3], v[180:183], v[216:219], v[0:3]
	s_barrier
	s_add_i32 s77, s77, 2
	s_add_u32 s34, s34, 0x100
	s_addc_u32 s35, s35, 0
	s_add_u32 s75, s75, 0x100
	s_addc_u32 s76, s76, 0
	s_cmp_gt_u32 s77, 61
	s_cbranch_scc0 .LBB0_916

.LBB0_1052:
	s_ashr_i32 s27, s26, 31
	s_lshl_b64 s[28:29], s[26:27], 19
	s_add_u32 s28, s58, s28
	s_addc_u32 s29, s59, s29
	s_and_b64 s[30:31], s[4:5], exec
	s_cselect_b32 s27, s29, s43
	s_cselect_b32 s55, s28, s42
	s_ashr_i32 s25, s24, 31
	s_lshl_b64 s[30:31], s[24:25], 19
	s_add_u32 s30, s53, s30
	s_addc_u32 s31, s64, s31
	s_and_b64 s[62:63], s[4:5], exec
	s_cselect_b32 s25, s31, s61
	s_cselect_b32 s79, s30, s60
	s_add_u32 s42, s42, 0x40080
	s_addc_u32 s43, s43, 0
	s_add_u32 s80, s60, 0x100
	s_addc_u32 s81, s61, 0
	s_mov_b32 s82, -2
	ds_read_b128 v[152:155], v149
	ds_read_b128 v[156:159], v149 offset:1024
	ds_read_b128 v[160:163], v149 offset:2048
	ds_read_b128 v[164:167], v149 offset:3072
	ds_read_b128 v[168:171], v150
	ds_read_b128 v[172:175], v150 offset:1024
	ds_read_b128 v[176:179], v150 offset:2048
	ds_read_b128 v[180:183], v150 offset:3072
	s_add_u32 s60, s42, 0xfffc0080
	s_addc_u32 s61, s43, -1
	s_cmp_eq_u32 s82, 12
	s_cselect_b32 s63, s27, s61
	s_cselect_b32 s62, s55, s60
	s_cselect_b32 s61, s25, s81
	s_cselect_b32 s60, s79, s80
	s_add_i32 m0, s35, 0xc000
	ds_read_b128 v[184:187], v151
	ds_read_b128 v[192:195], v151 offset:1024
	ds_read_b128 v[196:199], v151 offset:2048
	ds_read_b128 v[200:203], v151 offset:3072
	ds_read_b128 v[204:207], v151 offset:4096
	ds_read_b128 v[208:211], v151 offset:5120
	ds_read_b128 v[212:215], v151 offset:6144
	ds_read_b128 v[216:219], v151 offset:7168
	global_load_lds_dwordx4 v136, s[42:43]
	s_add_i32 m0, s35, 0xe000
	s_nop 0
	global_load_lds_dwordx4 v138, s[42:43]
	s_waitcnt vmcnt(8)
	s_waitcnt lgkmcnt(0)
	s_barrier
	s_waitcnt lgkmcnt(0)
	v_mfma_f32_16x16x32_bf16 v[124:127], v[152:155], v[184:187], 0
	v_mfma_f32_16x16x32_bf16 v[120:123], v[160:163], v[184:187], 0
	v_mfma_f32_16x16x32_bf16 v[116:119], v[152:155], v[196:199], 0
	v_mfma_f32_16x16x32_bf16 v[108:111], v[160:163], v[196:199], 0
	v_mfma_f32_16x16x32_bf16 v[100:103], v[152:155], v[204:207], 0
	v_mfma_f32_16x16x32_bf16 v[92:95], v[160:163], v[204:207], 0
	v_mfma_f32_16x16x32_bf16 v[84:87], v[152:155], v[212:215], 0
	v_mfma_f32_16x16x32_bf16 v[76:79], v[160:163], v[212:215], 0
	v_mfma_f32_16x16x32_bf16 v[124:127], v[156:159], v[192:195], v[124:127]
	v_mfma_f32_16x16x32_bf16 v[120:123], v[164:167], v[192:195], v[120:123]
	v_mfma_f32_16x16x32_bf16 v[116:119], v[156:159], v[200:203], v[116:119]
	v_mfma_f32_16x16x32_bf16 v[108:111], v[164:167], v[200:203], v[108:111]
	v_mfma_f32_16x16x32_bf16 v[100:103], v[156:159], v[208:211], v[100:103]
	v_mfma_f32_16x16x32_bf16 v[92:95], v[164:167], v[208:211], v[92:95]
	v_mfma_f32_16x16x32_bf16 v[84:87], v[156:159], v[216:219], v[84:87]
	v_mfma_f32_16x16x32_bf16 v[76:79], v[164:167], v[216:219], v[76:79]
	v_mfma_f32_16x16x32_bf16 v[112:115], v[168:171], v[184:187], 0
	v_mfma_f32_16x16x32_bf16 v[104:107], v[176:179], v[184:187], 0
	v_mfma_f32_16x16x32_bf16 v[96:99], v[168:171], v[196:199], 0
	v_mfma_f32_16x16x32_bf16 v[88:91], v[176:179], v[196:199], 0
	v_mfma_f32_16x16x32_bf16 v[80:83], v[168:171], v[204:207], 0
	v_mfma_f32_16x16x32_bf16 v[72:75], v[176:179], v[204:207], 0
	v_mfma_f32_16x16x32_bf16 v[68:71], v[168:171], v[212:215], 0
	v_mfma_f32_16x16x32_bf16 v[64:67], v[176:179], v[212:215], 0
	v_mfma_f32_16x16x32_bf16 v[112:115], v[172:175], v[192:195], v[112:115]
	v_mfma_f32_16x16x32_bf16 v[104:107], v[180:183], v[192:195], v[104:107]
	v_mfma_f32_16x16x32_bf16 v[96:99], v[172:175], v[200:203], v[96:99]
	v_mfma_f32_16x16x32_bf16 v[88:91], v[180:183], v[200:203], v[88:91]
	v_mfma_f32_16x16x32_bf16 v[80:83], v[172:175], v[208:211], v[80:83]
	v_mfma_f32_16x16x32_bf16 v[72:75], v[180:183], v[208:211], v[72:75]
	v_mfma_f32_16x16x32_bf16 v[68:71], v[172:175], v[216:219], v[68:71]
	v_mfma_f32_16x16x32_bf16 v[64:67], v[180:183], v[216:219], v[64:67]
	s_barrier
	s_add_i32 s83, s72, s65
	v_lshl_add_u64 v[144:145], s[60:61], 0, v[130:131]
	s_mov_b32 m0, s83
	ds_read_b128 v[184:187], v151 offset:16384
	ds_read_b128 v[192:195], v151 offset:17408
	ds_read_b128 v[196:199], v151 offset:18432
	ds_read_b128 v[200:203], v151 offset:19456
	ds_read_b128 v[204:207], v151 offset:20480
	ds_read_b128 v[208:211], v151 offset:21504
	ds_read_b128 v[212:215], v151 offset:22528
	ds_read_b128 v[216:219], v151 offset:23552
	global_load_lds_dwordx4 v[144:145], off
	s_add_i32 m0, s83, 0x2000
	s_add_u32 s84, s60, 0x40000
	v_lshl_add_u64 v[188:189], s[60:61], 0, v[134:135]
	s_addc_u32 s85, s61, 0
	s_add_i32 s83, s73, s65
	global_load_lds_dwordx4 v[188:189], off
	s_mov_b32 m0, s83
	v_lshl_add_u64 v[222:223], s[62:63], 0, v[132:133]
	global_load_lds_dwordx4 v130, s[84:85]
	s_add_i32 m0, s83, 0x2000
	s_nop 0
	global_load_lds_dwordx4 v134, s[84:85]
	v_lshl_add_u64 v[220:221], s[62:63], 0, v[128:129]
	s_mov_b32 m0, s35
	s_nop 0
	global_load_lds_dwordx4 v[220:221], off
	s_mov_b32 m0, s33
	s_nop 0
	global_load_lds_dwordx4 v[222:223], off
	s_waitcnt vmcnt(8)
	s_waitcnt lgkmcnt(0)
	s_barrier
	s_waitcnt lgkmcnt(0)
	v_mfma_f32_16x16x32_bf16 v[60:63], v[152:155], v[184:187], 0
	v_mfma_f32_16x16x32_bf16 v[56:59], v[160:163], v[184:187], 0
	v_mfma_f32_16x16x32_bf16 v[52:55], v[152:155], v[196:199], 0
	v_mfma_f32_16x16x32_bf16 v[44:47], v[160:163], v[196:199], 0
	v_mfma_f32_16x16x32_bf16 v[36:39], v[152:155], v[204:207], 0
	v_mfma_f32_16x16x32_bf16 v[28:31], v[160:163], v[204:207], 0
	v_mfma_f32_16x16x32_bf16 v[20:23], v[152:155], v[212:215], 0
	v_mfma_f32_16x16x32_bf16 v[12:15], v[160:163], v[212:215], 0
	v_mfma_f32_16x16x32_bf16 v[60:63], v[156:159], v[192:195], v[60:63]
	v_mfma_f32_16x16x32_bf16 v[56:59], v[164:167], v[192:195], v[56:59]
	v_mfma_f32_16x16x32_bf16 v[52:55], v[156:159], v[200:203], v[52:55]
	v_mfma_f32_16x16x32_bf16 v[44:47], v[164:167], v[200:203], v[44:47]
	v_mfma_f32_16x16x32_bf16 v[36:39], v[156:159], v[208:211], v[36:39]
	v_mfma_f32_16x16x32_bf16 v[28:31], v[164:167], v[208:211], v[28:31]
	v_mfma_f32_16x16x32_bf16 v[20:23], v[156:159], v[216:219], v[20:23]
	v_mfma_f32_16x16x32_bf16 v[12:15], v[164:167], v[216:219], v[12:15]
	v_mfma_f32_16x16x32_bf16 v[48:51], v[168:171], v[184:187], 0
	v_mfma_f32_16x16x32_bf16 v[40:43], v[176:179], v[184:187], 0
	v_mfma_f32_16x16x32_bf16 v[32:35], v[168:171], v[196:199], 0
	v_mfma_f32_16x16x32_bf16 v[24:27], v[176:179], v[196:199], 0
	v_mfma_f32_16x16x32_bf16 v[16:19], v[168:171], v[204:207], 0
	v_mfma_f32_16x16x32_bf16 v[8:11], v[176:179], v[204:207], 0
	v_mfma_f32_16x16x32_bf16 v[4:7], v[168:171], v[212:215], 0
	v_mfma_f32_16x16x32_bf16 v[0:3], v[176:179], v[212:215], 0
	v_mfma_f32_16x16x32_bf16 v[48:51], v[172:175], v[192:195], v[48:51]
	v_mfma_f32_16x16x32_bf16 v[40:43], v[180:183], v[192:195], v[40:43]
	v_mfma_f32_16x16x32_bf16 v[32:35], v[172:175], v[200:203], v[32:35]
	v_mfma_f32_16x16x32_bf16 v[24:27], v[180:183], v[200:203], v[24:27]
	v_mfma_f32_16x16x32_bf16 v[16:19], v[172:175], v[208:211], v[16:19]
	v_mfma_f32_16x16x32_bf16 v[8:11], v[180:183], v[208:211], v[8:11]
	v_mfma_f32_16x16x32_bf16 v[4:7], v[172:175], v[216:219], v[4:7]
	v_mfma_f32_16x16x32_bf16 v[0:3], v[180:183], v[216:219], v[0:3]
	s_barrier
	s_add_i32 s83, 0, 0x18000
	s_add_i32 s84, 0, 0x1c000
	v_add_u32_e32 v164, s83, v147
	v_add_u32_e32 v180, s84, v147
	ds_read_b128 v[152:155], v164
	ds_read_b128 v[156:159], v164 offset:1024
	ds_read_b128 v[160:163], v164 offset:2048
	ds_read_b128 v[164:167], v164 offset:3072
	ds_read_b128 v[168:171], v180
	ds_read_b128 v[172:175], v180 offset:1024
	ds_read_b128 v[176:179], v180 offset:2048
	ds_read_b128 v[180:183], v180 offset:3072
	s_add_u32 s62, s62, 0x40000
	s_addc_u32 s63, s63, 0
	s_mov_b32 m0, s66
	ds_read_b128 v[184:187], v151 offset:32768
	ds_read_b128 v[192:195], v151 offset:33792
	ds_read_b128 v[196:199], v151 offset:34816
	ds_read_b128 v[200:203], v151 offset:35840
	ds_read_b128 v[204:207], v151 offset:36864
	ds_read_b128 v[208:211], v151 offset:37888
	ds_read_b128 v[212:215], v151 offset:38912
	ds_read_b128 v[216:219], v151 offset:39936
	global_load_lds_dwordx4 v128, s[62:63]
	s_mov_b32 m0, s67
	s_nop 0
	global_load_lds_dwordx4 v132, s[62:63]
	s_waitcnt vmcnt(8)
	s_waitcnt lgkmcnt(0)
	s_barrier
	s_waitcnt lgkmcnt(0)
	v_mfma_f32_16x16x32_bf16 v[124:127], v[152:155], v[184:187], v[124:127]
	v_mfma_f32_16x16x32_bf16 v[120:123], v[160:163], v[184:187], v[120:123]
	v_mfma_f32_16x16x32_bf16 v[116:119], v[152:155], v[196:199], v[116:119]
	v_mfma_f32_16x16x32_bf16 v[108:111], v[160:163], v[196:199], v[108:111]
	v_mfma_f32_16x16x32_bf16 v[100:103], v[152:155], v[204:207], v[100:103]
	v_mfma_f32_16x16x32_bf16 v[92:95], v[160:163], v[204:207], v[92:95]
	v_mfma_f32_16x16x32_bf16 v[84:87], v[152:155], v[212:215], v[84:87]
	v_mfma_f32_16x16x32_bf16 v[76:79], v[160:163], v[212:215], v[76:79]
	v_mfma_f32_16x16x32_bf16 v[124:127], v[156:159], v[192:195], v[124:127]
	v_mfma_f32_16x16x32_bf16 v[120:123], v[164:167], v[192:195], v[120:123]
	v_mfma_f32_16x16x32_bf16 v[116:119], v[156:159], v[200:203], v[116:119]
	v_mfma_f32_16x16x32_bf16 v[108:111], v[164:167], v[200:203], v[108:111]
	v_mfma_f32_16x16x32_bf16 v[100:103], v[156:159], v[208:211], v[100:103]
	v_mfma_f32_16x16x32_bf16 v[92:95], v[164:167], v[208:211], v[92:95]
	v_mfma_f32_16x16x32_bf16 v[84:87], v[156:159], v[216:219], v[84:87]
	v_mfma_f32_16x16x32_bf16 v[76:79], v[164:167], v[216:219], v[76:79]
	v_mfma_f32_16x16x32_bf16 v[112:115], v[168:171], v[184:187], v[112:115]
	v_mfma_f32_16x16x32_bf16 v[104:107], v[176:179], v[184:187], v[104:107]
	v_mfma_f32_16x16x32_bf16 v[96:99], v[168:171], v[196:199], v[96:99]
	v_mfma_f32_16x16x32_bf16 v[88:91], v[176:179], v[196:199], v[88:91]
	v_mfma_f32_16x16x32_bf16 v[80:83], v[168:171], v[204:207], v[80:83]
	v_mfma_f32_16x16x32_bf16 v[72:75], v[176:179], v[204:207], v[72:75]
	v_mfma_f32_16x16x32_bf16 v[68:71], v[168:171], v[212:215], v[68:71]
	v_mfma_f32_16x16x32_bf16 v[64:67], v[176:179], v[212:215], v[64:67]
	v_mfma_f32_16x16x32_bf16 v[112:115], v[172:175], v[192:195], v[112:115]
	v_mfma_f32_16x16x32_bf16 v[104:107], v[180:183], v[192:195], v[104:107]
	v_mfma_f32_16x16x32_bf16 v[96:99], v[172:175], v[200:203], v[96:99]
	v_mfma_f32_16x16x32_bf16 v[88:91], v[180:183], v[200:203], v[88:91]
	v_mfma_f32_16x16x32_bf16 v[80:83], v[172:175], v[208:211], v[80:83]
	v_mfma_f32_16x16x32_bf16 v[72:75], v[180:183], v[208:211], v[72:75]
	v_mfma_f32_16x16x32_bf16 v[68:71], v[172:175], v[216:219], v[68:71]
	v_mfma_f32_16x16x32_bf16 v[64:67], v[180:183], v[216:219], v[64:67]
	s_barrier
	s_add_i32 s62, s83, s65
	v_lshl_add_u64 v[144:145], v[144:145], 0, s[12:13]
	s_mov_b32 m0, s62
	ds_read_b128 v[184:187], v151 offset:49152
	ds_read_b128 v[192:195], v151 offset:50176
	ds_read_b128 v[196:199], v151 offset:51200
	ds_read_b128 v[200:203], v151 offset:52224
	ds_read_b128 v[204:207], v151 offset:53248
	ds_read_b128 v[208:211], v151 offset:54272
	ds_read_b128 v[212:215], v151 offset:55296
	ds_read_b128 v[216:219], v151 offset:56320
	global_load_lds_dwordx4 v[144:145], off
	s_add_i32 m0, s62, 0x2000
	s_add_u32 s60, s60, 0x40080
	v_lshl_add_u64 v[144:145], v[188:189], 0, s[12:13]
	s_addc_u32 s61, s61, 0
	s_add_i32 s62, s84, s65
	global_load_lds_dwordx4 v[144:145], off
	s_mov_b32 m0, s62
	s_nop 0
	global_load_lds_dwordx4 v130, s[60:61]
	s_add_i32 m0, s62, 0x2000
	s_nop 0
	global_load_lds_dwordx4 v134, s[60:61]
	v_lshl_add_u64 v[144:145], v[220:221], 0, s[12:13]
	s_mov_b32 m0, s69
	s_nop 0
	global_load_lds_dwordx4 v[144:145], off
	v_lshl_add_u64 v[144:145], v[222:223], 0, s[12:13]
	s_mov_b32 m0, s70
	s_nop 0
	global_load_lds_dwordx4 v[144:145], off
	s_waitcnt vmcnt(8)
	s_waitcnt lgkmcnt(0)
	s_barrier
	s_waitcnt lgkmcnt(0)
	v_mfma_f32_16x16x32_bf16 v[60:63], v[152:155], v[184:187], v[60:63]
	v_mfma_f32_16x16x32_bf16 v[56:59], v[160:163], v[184:187], v[56:59]
	v_mfma_f32_16x16x32_bf16 v[52:55], v[152:155], v[196:199], v[52:55]
	v_mfma_f32_16x16x32_bf16 v[44:47], v[160:163], v[196:199], v[44:47]
	v_mfma_f32_16x16x32_bf16 v[36:39], v[152:155], v[204:207], v[36:39]
	v_mfma_f32_16x16x32_bf16 v[28:31], v[160:163], v[204:207], v[28:31]
	v_mfma_f32_16x16x32_bf16 v[20:23], v[152:155], v[212:215], v[20:23]
	v_mfma_f32_16x16x32_bf16 v[12:15], v[160:163], v[212:215], v[12:15]
	v_mfma_f32_16x16x32_bf16 v[60:63], v[156:159], v[192:195], v[60:63]
	v_mfma_f32_16x16x32_bf16 v[56:59], v[164:167], v[192:195], v[56:59]
	v_mfma_f32_16x16x32_bf16 v[52:55], v[156:159], v[200:203], v[52:55]
	v_mfma_f32_16x16x32_bf16 v[44:47], v[164:167], v[200:203], v[44:47]
	v_mfma_f32_16x16x32_bf16 v[36:39], v[156:159], v[208:211], v[36:39]
	v_mfma_f32_16x16x32_bf16 v[28:31], v[164:167], v[208:211], v[28:31]
	v_mfma_f32_16x16x32_bf16 v[20:23], v[156:159], v[216:219], v[20:23]
	v_mfma_f32_16x16x32_bf16 v[12:15], v[164:167], v[216:219], v[12:15]
	v_mfma_f32_16x16x32_bf16 v[48:51], v[168:171], v[184:187], v[48:51]
	v_mfma_f32_16x16x32_bf16 v[40:43], v[176:179], v[184:187], v[40:43]
	v_mfma_f32_16x16x32_bf16 v[32:35], v[168:171], v[196:199], v[32:35]
	v_mfma_f32_16x16x32_bf16 v[24:27], v[176:179], v[196:199], v[24:27]
	v_mfma_f32_16x16x32_bf16 v[16:19], v[168:171], v[204:207], v[16:19]
	v_mfma_f32_16x16x32_bf16 v[8:11], v[176:179], v[204:207], v[8:11]
	v_mfma_f32_16x16x32_bf16 v[4:7], v[168:171], v[212:215], v[4:7]
	v_mfma_f32_16x16x32_bf16 v[0:3], v[176:179], v[212:215], v[0:3]
	v_mfma_f32_16x16x32_bf16 v[48:51], v[172:175], v[192:195], v[48:51]
	v_mfma_f32_16x16x32_bf16 v[40:43], v[180:183], v[192:195], v[40:43]
	v_mfma_f32_16x16x32_bf16 v[32:35], v[172:175], v[200:203], v[32:35]
	v_mfma_f32_16x16x32_bf16 v[24:27], v[180:183], v[200:203], v[24:27]
	v_mfma_f32_16x16x32_bf16 v[16:19], v[172:175], v[208:211], v[16:19]
	v_mfma_f32_16x16x32_bf16 v[8:11], v[180:183], v[208:211], v[8:11]
	v_mfma_f32_16x16x32_bf16 v[4:7], v[172:175], v[216:219], v[4:7]
	v_mfma_f32_16x16x32_bf16 v[0:3], v[180:183], v[216:219], v[0:3]
	s_barrier
	s_add_i32 s82, s82, 2
	s_add_u32 s42, s42, 0x100
	s_addc_u32 s43, s43, 0
	s_add_u32 s80, s80, 0x100
	s_addc_u32 s81, s81, 0
	s_cmp_gt_u32 s82, 13
	s_cbranch_scc0 .LBB0_1053
	s_branch .Lpeel_exit5
.LBB0_1053:
	ds_read_b128 v[152:155], v149
	ds_read_b128 v[156:159], v149 offset:1024
	ds_read_b128 v[160:163], v149 offset:2048
	ds_read_b128 v[164:167], v149 offset:3072
	ds_read_b128 v[168:171], v150
	ds_read_b128 v[172:175], v150 offset:1024
	ds_read_b128 v[176:179], v150 offset:2048
	ds_read_b128 v[180:183], v150 offset:3072
	s_add_u32 s60, s42, 0xfffc0080
	s_addc_u32 s61, s43, -1
	s_cmp_eq_u32 s82, 12
	s_cselect_b32 s63, s27, s61
	s_cselect_b32 s62, s55, s60
	s_cselect_b32 s61, s25, s81
	s_cselect_b32 s60, s79, s80
	s_add_i32 m0, s35, 0xc000
	ds_read_b128 v[184:187], v151
	ds_read_b128 v[192:195], v151 offset:1024
	ds_read_b128 v[196:199], v151 offset:2048
	ds_read_b128 v[200:203], v151 offset:3072
	ds_read_b128 v[204:207], v151 offset:4096
	ds_read_b128 v[208:211], v151 offset:5120
	ds_read_b128 v[212:215], v151 offset:6144
	ds_read_b128 v[216:219], v151 offset:7168
	global_load_lds_dwordx4 v136, s[42:43]
	s_add_i32 m0, s35, 0xe000
	s_nop 0
	global_load_lds_dwordx4 v138, s[42:43]
	s_waitcnt vmcnt(8)
	s_waitcnt lgkmcnt(0)
	s_barrier
	s_waitcnt lgkmcnt(0)
	v_mfma_f32_16x16x32_bf16 v[124:127], v[152:155], v[184:187], v[124:127]
	v_mfma_f32_16x16x32_bf16 v[120:123], v[160:163], v[184:187], v[120:123]
	v_mfma_f32_16x16x32_bf16 v[116:119], v[152:155], v[196:199], v[116:119]
	v_mfma_f32_16x16x32_bf16 v[108:111], v[160:163], v[196:199], v[108:111]
	v_mfma_f32_16x16x32_bf16 v[100:103], v[152:155], v[204:207], v[100:103]
	v_mfma_f32_16x16x32_bf16 v[92:95], v[160:163], v[204:207], v[92:95]
	v_mfma_f32_16x16x32_bf16 v[84:87], v[152:155], v[212:215], v[84:87]
	v_mfma_f32_16x16x32_bf16 v[76:79], v[160:163], v[212:215], v[76:79]
	v_mfma_f32_16x16x32_bf16 v[124:127], v[156:159], v[192:195], v[124:127]
	v_mfma_f32_16x16x32_bf16 v[120:123], v[164:167], v[192:195], v[120:123]
	v_mfma_f32_16x16x32_bf16 v[116:119], v[156:159], v[200:203], v[116:119]
	v_mfma_f32_16x16x32_bf16 v[108:111], v[164:167], v[200:203], v[108:111]
	v_mfma_f32_16x16x32_bf16 v[100:103], v[156:159], v[208:211], v[100:103]
	v_mfma_f32_16x16x32_bf16 v[92:95], v[164:167], v[208:211], v[92:95]
	v_mfma_f32_16x16x32_bf16 v[84:87], v[156:159], v[216:219], v[84:87]
	v_mfma_f32_16x16x32_bf16 v[76:79], v[164:167], v[216:219], v[76:79]
	v_mfma_f32_16x16x32_bf16 v[112:115], v[168:171], v[184:187], v[112:115]
	v_mfma_f32_16x16x32_bf16 v[104:107], v[176:179], v[184:187], v[104:107]
	v_mfma_f32_16x16x32_bf16 v[96:99], v[168:171], v[196:199], v[96:99]
	v_mfma_f32_16x16x32_bf16 v[88:91], v[176:179], v[196:199], v[88:91]
	v_mfma_f32_16x16x32_bf16 v[80:83], v[168:171], v[204:207], v[80:83]
	v_mfma_f32_16x16x32_bf16 v[72:75], v[176:179], v[204:207], v[72:75]
	v_mfma_f32_16x16x32_bf16 v[68:71], v[168:171], v[212:215], v[68:71]
	v_mfma_f32_16x16x32_bf16 v[64:67], v[176:179], v[212:215], v[64:67]
	v_mfma_f32_16x16x32_bf16 v[112:115], v[172:175], v[192:195], v[112:115]
	v_mfma_f32_16x16x32_bf16 v[104:107], v[180:183], v[192:195], v[104:107]
	v_mfma_f32_16x16x32_bf16 v[96:99], v[172:175], v[200:203], v[96:99]
	v_mfma_f32_16x16x32_bf16 v[88:91], v[180:183], v[200:203], v[88:91]
	v_mfma_f32_16x16x32_bf16 v[80:83], v[172:175], v[208:211], v[80:83]
	v_mfma_f32_16x16x32_bf16 v[72:75], v[180:183], v[208:211], v[72:75]
	v_mfma_f32_16x16x32_bf16 v[68:71], v[172:175], v[216:219], v[68:71]
	v_mfma_f32_16x16x32_bf16 v[64:67], v[180:183], v[216:219], v[64:67]
	s_barrier
	s_add_i32 s83, s72, s65
	v_lshl_add_u64 v[144:145], s[60:61], 0, v[130:131]
	s_mov_b32 m0, s83
	ds_read_b128 v[184:187], v151 offset:16384
	ds_read_b128 v[192:195], v151 offset:17408
	ds_read_b128 v[196:199], v151 offset:18432
	ds_read_b128 v[200:203], v151 offset:19456
	ds_read_b128 v[204:207], v151 offset:20480
	ds_read_b128 v[208:211], v151 offset:21504
	ds_read_b128 v[212:215], v151 offset:22528
	ds_read_b128 v[216:219], v151 offset:23552
	global_load_lds_dwordx4 v[144:145], off
	s_add_i32 m0, s83, 0x2000
	s_add_u32 s84, s60, 0x40000
	v_lshl_add_u64 v[188:189], s[60:61], 0, v[134:135]
	s_addc_u32 s85, s61, 0
	s_add_i32 s83, s73, s65
	global_load_lds_dwordx4 v[188:189], off
	s_mov_b32 m0, s83
	v_lshl_add_u64 v[222:223], s[62:63], 0, v[132:133]
	global_load_lds_dwordx4 v130, s[84:85]
	s_add_i32 m0, s83, 0x2000
	s_nop 0
	global_load_lds_dwordx4 v134, s[84:85]
	v_lshl_add_u64 v[220:221], s[62:63], 0, v[128:129]
	s_mov_b32 m0, s35
	s_nop 0
	global_load_lds_dwordx4 v[220:221], off
	s_mov_b32 m0, s33
	s_nop 0
	global_load_lds_dwordx4 v[222:223], off
	s_waitcnt vmcnt(8)
	s_waitcnt lgkmcnt(0)
	s_barrier
	s_waitcnt lgkmcnt(0)
	v_mfma_f32_16x16x32_bf16 v[60:63], v[152:155], v[184:187], v[60:63]
	v_mfma_f32_16x16x32_bf16 v[56:59], v[160:163], v[184:187], v[56:59]
	v_mfma_f32_16x16x32_bf16 v[52:55], v[152:155], v[196:199], v[52:55]
	v_mfma_f32_16x16x32_bf16 v[44:47], v[160:163], v[196:199], v[44:47]
	v_mfma_f32_16x16x32_bf16 v[36:39], v[152:155], v[204:207], v[36:39]
	v_mfma_f32_16x16x32_bf16 v[28:31], v[160:163], v[204:207], v[28:31]
	v_mfma_f32_16x16x32_bf16 v[20:23], v[152:155], v[212:215], v[20:23]
	v_mfma_f32_16x16x32_bf16 v[12:15], v[160:163], v[212:215], v[12:15]
	v_mfma_f32_16x16x32_bf16 v[60:63], v[156:159], v[192:195], v[60:63]
	v_mfma_f32_16x16x32_bf16 v[56:59], v[164:167], v[192:195], v[56:59]
	v_mfma_f32_16x16x32_bf16 v[52:55], v[156:159], v[200:203], v[52:55]
	v_mfma_f32_16x16x32_bf16 v[44:47], v[164:167], v[200:203], v[44:47]
	v_mfma_f32_16x16x32_bf16 v[36:39], v[156:159], v[208:211], v[36:39]
	v_mfma_f32_16x16x32_bf16 v[28:31], v[164:167], v[208:211], v[28:31]
	v_mfma_f32_16x16x32_bf16 v[20:23], v[156:159], v[216:219], v[20:23]
	v_mfma_f32_16x16x32_bf16 v[12:15], v[164:167], v[216:219], v[12:15]
	v_mfma_f32_16x16x32_bf16 v[48:51], v[168:171], v[184:187], v[48:51]
	v_mfma_f32_16x16x32_bf16 v[40:43], v[176:179], v[184:187], v[40:43]
	v_mfma_f32_16x16x32_bf16 v[32:35], v[168:171], v[196:199], v[32:35]
	v_mfma_f32_16x16x32_bf16 v[24:27], v[176:179], v[196:199], v[24:27]
	v_mfma_f32_16x16x32_bf16 v[16:19], v[168:171], v[204:207], v[16:19]
	v_mfma_f32_16x16x32_bf16 v[8:11], v[176:179], v[204:207], v[8:11]
	v_mfma_f32_16x16x32_bf16 v[4:7], v[168:171], v[212:215], v[4:7]
	v_mfma_f32_16x16x32_bf16 v[0:3], v[176:179], v[212:215], v[0:3]
	v_mfma_f32_16x16x32_bf16 v[48:51], v[172:175], v[192:195], v[48:51]
	v_mfma_f32_16x16x32_bf16 v[40:43], v[180:183], v[192:195], v[40:43]
	v_mfma_f32_16x16x32_bf16 v[32:35], v[172:175], v[200:203], v[32:35]
	v_mfma_f32_16x16x32_bf16 v[24:27], v[180:183], v[200:203], v[24:27]
	v_mfma_f32_16x16x32_bf16 v[16:19], v[172:175], v[208:211], v[16:19]
	v_mfma_f32_16x16x32_bf16 v[8:11], v[180:183], v[208:211], v[8:11]
	v_mfma_f32_16x16x32_bf16 v[4:7], v[172:175], v[216:219], v[4:7]
	v_mfma_f32_16x16x32_bf16 v[0:3], v[180:183], v[216:219], v[0:3]
	s_barrier
	s_add_i32 s83, 0, 0x18000
	s_add_i32 s84, 0, 0x1c000
	v_add_u32_e32 v164, s83, v147
	v_add_u32_e32 v180, s84, v147
	ds_read_b128 v[152:155], v164
	ds_read_b128 v[156:159], v164 offset:1024
	ds_read_b128 v[160:163], v164 offset:2048
	ds_read_b128 v[164:167], v164 offset:3072
	ds_read_b128 v[168:171], v180
	ds_read_b128 v[172:175], v180 offset:1024
	ds_read_b128 v[176:179], v180 offset:2048
	ds_read_b128 v[180:183], v180 offset:3072
	s_add_u32 s62, s62, 0x40000
	s_addc_u32 s63, s63, 0
	s_mov_b32 m0, s66
	ds_read_b128 v[184:187], v151 offset:32768
	ds_read_b128 v[192:195], v151 offset:33792
	ds_read_b128 v[196:199], v151 offset:34816
	ds_read_b128 v[200:203], v151 offset:35840
	ds_read_b128 v[204:207], v151 offset:36864
	ds_read_b128 v[208:211], v151 offset:37888
	ds_read_b128 v[212:215], v151 offset:38912
	ds_read_b128 v[216:219], v151 offset:39936
	global_load_lds_dwordx4 v128, s[62:63]
	s_mov_b32 m0, s67
	s_nop 0
	global_load_lds_dwordx4 v132, s[62:63]
	s_waitcnt vmcnt(8)
	s_waitcnt lgkmcnt(0)
	s_barrier
	s_waitcnt lgkmcnt(0)
	v_mfma_f32_16x16x32_bf16 v[124:127], v[152:155], v[184:187], v[124:127]
	v_mfma_f32_16x16x32_bf16 v[120:123], v[160:163], v[184:187], v[120:123]
	v_mfma_f32_16x16x32_bf16 v[116:119], v[152:155], v[196:199], v[116:119]
	v_mfma_f32_16x16x32_bf16 v[108:111], v[160:163], v[196:199], v[108:111]
	v_mfma_f32_16x16x32_bf16 v[100:103], v[152:155], v[204:207], v[100:103]
	v_mfma_f32_16x16x32_bf16 v[92:95], v[160:163], v[204:207], v[92:95]
	v_mfma_f32_16x16x32_bf16 v[84:87], v[152:155], v[212:215], v[84:87]
	v_mfma_f32_16x16x32_bf16 v[76:79], v[160:163], v[212:215], v[76:79]
	v_mfma_f32_16x16x32_bf16 v[124:127], v[156:159], v[192:195], v[124:127]
	v_mfma_f32_16x16x32_bf16 v[120:123], v[164:167], v[192:195], v[120:123]
	v_mfma_f32_16x16x32_bf16 v[116:119], v[156:159], v[200:203], v[116:119]
	v_mfma_f32_16x16x32_bf16 v[108:111], v[164:167], v[200:203], v[108:111]
	v_mfma_f32_16x16x32_bf16 v[100:103], v[156:159], v[208:211], v[100:103]
	v_mfma_f32_16x16x32_bf16 v[92:95], v[164:167], v[208:211], v[92:95]
	v_mfma_f32_16x16x32_bf16 v[84:87], v[156:159], v[216:219], v[84:87]
	v_mfma_f32_16x16x32_bf16 v[76:79], v[164:167], v[216:219], v[76:79]
	v_mfma_f32_16x16x32_bf16 v[112:115], v[168:171], v[184:187], v[112:115]
	v_mfma_f32_16x16x32_bf16 v[104:107], v[176:179], v[184:187], v[104:107]
	v_mfma_f32_16x16x32_bf16 v[96:99], v[168:171], v[196:199], v[96:99]
	v_mfma_f32_16x16x32_bf16 v[88:91], v[176:179], v[196:199], v[88:91]
	v_mfma_f32_16x16x32_bf16 v[80:83], v[168:171], v[204:207], v[80:83]
	v_mfma_f32_16x16x32_bf16 v[72:75], v[176:179], v[204:207], v[72:75]
	v_mfma_f32_16x16x32_bf16 v[68:71], v[168:171], v[212:215], v[68:71]
	v_mfma_f32_16x16x32_bf16 v[64:67], v[176:179], v[212:215], v[64:67]
	v_mfma_f32_16x16x32_bf16 v[112:115], v[172:175], v[192:195], v[112:115]
	v_mfma_f32_16x16x32_bf16 v[104:107], v[180:183], v[192:195], v[104:107]
	v_mfma_f32_16x16x32_bf16 v[96:99], v[172:175], v[200:203], v[96:99]
	v_mfma_f32_16x16x32_bf16 v[88:91], v[180:183], v[200:203], v[88:91]
	v_mfma_f32_16x16x32_bf16 v[80:83], v[172:175], v[208:211], v[80:83]
	v_mfma_f32_16x16x32_bf16 v[72:75], v[180:183], v[208:211], v[72:75]
	v_mfma_f32_16x16x32_bf16 v[68:71], v[172:175], v[216:219], v[68:71]
	v_mfma_f32_16x16x32_bf16 v[64:67], v[180:183], v[216:219], v[64:67]
	s_barrier
	s_add_i32 s62, s83, s65
	v_lshl_add_u64 v[144:145], v[144:145], 0, s[12:13]
	s_mov_b32 m0, s62
	ds_read_b128 v[184:187], v151 offset:49152
	ds_read_b128 v[192:195], v151 offset:50176
	ds_read_b128 v[196:199], v151 offset:51200
	ds_read_b128 v[200:203], v151 offset:52224
	ds_read_b128 v[204:207], v151 offset:53248
	ds_read_b128 v[208:211], v151 offset:54272
	ds_read_b128 v[212:215], v151 offset:55296
	ds_read_b128 v[216:219], v151 offset:56320
	global_load_lds_dwordx4 v[144:145], off
	s_add_i32 m0, s62, 0x2000
	s_add_u32 s60, s60, 0x40080
	v_lshl_add_u64 v[144:145], v[188:189], 0, s[12:13]
	s_addc_u32 s61, s61, 0
	s_add_i32 s62, s84, s65
	global_load_lds_dwordx4 v[144:145], off
	s_mov_b32 m0, s62
	s_nop 0
	global_load_lds_dwordx4 v130, s[60:61]
	s_add_i32 m0, s62, 0x2000
	s_nop 0
	global_load_lds_dwordx4 v134, s[60:61]
	v_lshl_add_u64 v[144:145], v[220:221], 0, s[12:13]
	s_mov_b32 m0, s69
	s_nop 0
	global_load_lds_dwordx4 v[144:145], off
	v_lshl_add_u64 v[144:145], v[222:223], 0, s[12:13]
	s_mov_b32 m0, s70
	s_nop 0
	global_load_lds_dwordx4 v[144:145], off
	s_waitcnt vmcnt(8)
	s_waitcnt lgkmcnt(0)
	s_barrier
	s_waitcnt lgkmcnt(0)
	v_mfma_f32_16x16x32_bf16 v[60:63], v[152:155], v[184:187], v[60:63]
	v_mfma_f32_16x16x32_bf16 v[56:59], v[160:163], v[184:187], v[56:59]
	v_mfma_f32_16x16x32_bf16 v[52:55], v[152:155], v[196:199], v[52:55]
	v_mfma_f32_16x16x32_bf16 v[44:47], v[160:163], v[196:199], v[44:47]
	v_mfma_f32_16x16x32_bf16 v[36:39], v[152:155], v[204:207], v[36:39]
	v_mfma_f32_16x16x32_bf16 v[28:31], v[160:163], v[204:207], v[28:31]
	v_mfma_f32_16x16x32_bf16 v[20:23], v[152:155], v[212:215], v[20:23]
	v_mfma_f32_16x16x32_bf16 v[12:15], v[160:163], v[212:215], v[12:15]
	v_mfma_f32_16x16x32_bf16 v[60:63], v[156:159], v[192:195], v[60:63]
	v_mfma_f32_16x16x32_bf16 v[56:59], v[164:167], v[192:195], v[56:59]
	v_mfma_f32_16x16x32_bf16 v[52:55], v[156:159], v[200:203], v[52:55]
	v_mfma_f32_16x16x32_bf16 v[44:47], v[164:167], v[200:203], v[44:47]
	v_mfma_f32_16x16x32_bf16 v[36:39], v[156:159], v[208:211], v[36:39]
	v_mfma_f32_16x16x32_bf16 v[28:31], v[164:167], v[208:211], v[28:31]
	v_mfma_f32_16x16x32_bf16 v[20:23], v[156:159], v[216:219], v[20:23]
	v_mfma_f32_16x16x32_bf16 v[12:15], v[164:167], v[216:219], v[12:15]
	v_mfma_f32_16x16x32_bf16 v[48:51], v[168:171], v[184:187], v[48:51]
	v_mfma_f32_16x16x32_bf16 v[40:43], v[176:179], v[184:187], v[40:43]
	v_mfma_f32_16x16x32_bf16 v[32:35], v[168:171], v[196:199], v[32:35]
	v_mfma_f32_16x16x32_bf16 v[24:27], v[176:179], v[196:199], v[24:27]
	v_mfma_f32_16x16x32_bf16 v[16:19], v[168:171], v[204:207], v[16:19]
	v_mfma_f32_16x16x32_bf16 v[8:11], v[176:179], v[204:207], v[8:11]
	v_mfma_f32_16x16x32_bf16 v[4:7], v[168:171], v[212:215], v[4:7]
	v_mfma_f32_16x16x32_bf16 v[0:3], v[176:179], v[212:215], v[0:3]
	v_mfma_f32_16x16x32_bf16 v[48:51], v[172:175], v[192:195], v[48:51]
	v_mfma_f32_16x16x32_bf16 v[40:43], v[180:183], v[192:195], v[40:43]
	v_mfma_f32_16x16x32_bf16 v[32:35], v[172:175], v[200:203], v[32:35]
	v_mfma_f32_16x16x32_bf16 v[24:27], v[180:183], v[200:203], v[24:27]
	v_mfma_f32_16x16x32_bf16 v[16:19], v[172:175], v[208:211], v[16:19]
	v_mfma_f32_16x16x32_bf16 v[8:11], v[180:183], v[208:211], v[8:11]
	v_mfma_f32_16x16x32_bf16 v[4:7], v[172:175], v[216:219], v[4:7]
	v_mfma_f32_16x16x32_bf16 v[0:3], v[180:183], v[216:219], v[0:3]
	s_barrier
	s_add_i32 s82, s82, 2
	s_add_u32 s42, s42, 0x100
	s_addc_u32 s43, s43, 0
	s_add_u32 s80, s80, 0x100
	s_addc_u32 s81, s81, 0
	s_cmp_gt_u32 s82, 13
	s_cbranch_scc0 .LBB0_1053

.LBB0_1076:
	s_ashr_i32 s27, s26, 31
	s_lshl_b64 s[28:29], s[26:27], 19
	s_add_u32 s28, s40, s28
	s_addc_u32 s29, s41, s29
	s_and_b64 s[30:31], s[4:5], exec
	s_cselect_b32 s27, s29, s43
	s_cselect_b32 s55, s28, s42
	s_ashr_i32 s25, s24, 31
	s_lshl_b64 s[30:31], s[24:25], 19
	s_add_u32 s30, s53, s30
	s_addc_u32 s31, s64, s31
	s_and_b64 s[62:63], s[4:5], exec
	s_cselect_b32 s25, s31, s61
	s_cselect_b32 s79, s30, s60
	s_add_u32 s42, s42, 0x40080
	s_addc_u32 s43, s43, 0
	s_add_u32 s80, s60, 0x100
	s_addc_u32 s81, s61, 0
	s_mov_b32 s82, -2
	ds_read_b128 v[152:155], v149
	ds_read_b128 v[156:159], v149 offset:1024
	ds_read_b128 v[160:163], v149 offset:2048
	ds_read_b128 v[164:167], v149 offset:3072
	ds_read_b128 v[168:171], v150
	ds_read_b128 v[172:175], v150 offset:1024
	ds_read_b128 v[176:179], v150 offset:2048
	ds_read_b128 v[180:183], v150 offset:3072
	s_add_u32 s60, s42, 0xfffc0080
	s_addc_u32 s61, s43, -1
	s_cmp_eq_u32 s82, 12
	s_cselect_b32 s63, s27, s61
	s_cselect_b32 s62, s55, s60
	s_cselect_b32 s61, s25, s81
	s_cselect_b32 s60, s79, s80
	s_add_i32 m0, s35, 0xc000
	ds_read_b128 v[184:187], v151
	ds_read_b128 v[192:195], v151 offset:1024
	ds_read_b128 v[196:199], v151 offset:2048
	ds_read_b128 v[200:203], v151 offset:3072
	ds_read_b128 v[204:207], v151 offset:4096
	ds_read_b128 v[208:211], v151 offset:5120
	ds_read_b128 v[212:215], v151 offset:6144
	ds_read_b128 v[216:219], v151 offset:7168
	global_load_lds_dwordx4 v136, s[42:43]
	s_add_i32 m0, s35, 0xe000
	s_nop 0
	global_load_lds_dwordx4 v138, s[42:43]
	s_waitcnt vmcnt(8)
	s_waitcnt lgkmcnt(0)
	s_barrier
	s_waitcnt lgkmcnt(0)
	v_mfma_f32_16x16x32_bf16 v[124:127], v[152:155], v[184:187], 0
	v_mfma_f32_16x16x32_bf16 v[120:123], v[160:163], v[184:187], 0
	v_mfma_f32_16x16x32_bf16 v[116:119], v[152:155], v[196:199], 0
	v_mfma_f32_16x16x32_bf16 v[108:111], v[160:163], v[196:199], 0
	v_mfma_f32_16x16x32_bf16 v[100:103], v[152:155], v[204:207], 0
	v_mfma_f32_16x16x32_bf16 v[92:95], v[160:163], v[204:207], 0
	v_mfma_f32_16x16x32_bf16 v[84:87], v[152:155], v[212:215], 0
	v_mfma_f32_16x16x32_bf16 v[76:79], v[160:163], v[212:215], 0
	v_mfma_f32_16x16x32_bf16 v[124:127], v[156:159], v[192:195], v[124:127]
	v_mfma_f32_16x16x32_bf16 v[120:123], v[164:167], v[192:195], v[120:123]
	v_mfma_f32_16x16x32_bf16 v[116:119], v[156:159], v[200:203], v[116:119]
	v_mfma_f32_16x16x32_bf16 v[108:111], v[164:167], v[200:203], v[108:111]
	v_mfma_f32_16x16x32_bf16 v[100:103], v[156:159], v[208:211], v[100:103]
	v_mfma_f32_16x16x32_bf16 v[92:95], v[164:167], v[208:211], v[92:95]
	v_mfma_f32_16x16x32_bf16 v[84:87], v[156:159], v[216:219], v[84:87]
	v_mfma_f32_16x16x32_bf16 v[76:79], v[164:167], v[216:219], v[76:79]
	v_mfma_f32_16x16x32_bf16 v[112:115], v[168:171], v[184:187], 0
	v_mfma_f32_16x16x32_bf16 v[104:107], v[176:179], v[184:187], 0
	v_mfma_f32_16x16x32_bf16 v[96:99], v[168:171], v[196:199], 0
	v_mfma_f32_16x16x32_bf16 v[88:91], v[176:179], v[196:199], 0
	v_mfma_f32_16x16x32_bf16 v[80:83], v[168:171], v[204:207], 0
	v_mfma_f32_16x16x32_bf16 v[72:75], v[176:179], v[204:207], 0
	v_mfma_f32_16x16x32_bf16 v[68:71], v[168:171], v[212:215], 0
	v_mfma_f32_16x16x32_bf16 v[64:67], v[176:179], v[212:215], 0
	v_mfma_f32_16x16x32_bf16 v[112:115], v[172:175], v[192:195], v[112:115]
	v_mfma_f32_16x16x32_bf16 v[104:107], v[180:183], v[192:195], v[104:107]
	v_mfma_f32_16x16x32_bf16 v[96:99], v[172:175], v[200:203], v[96:99]
	v_mfma_f32_16x16x32_bf16 v[88:91], v[180:183], v[200:203], v[88:91]
	v_mfma_f32_16x16x32_bf16 v[80:83], v[172:175], v[208:211], v[80:83]
	v_mfma_f32_16x16x32_bf16 v[72:75], v[180:183], v[208:211], v[72:75]
	v_mfma_f32_16x16x32_bf16 v[68:71], v[172:175], v[216:219], v[68:71]
	v_mfma_f32_16x16x32_bf16 v[64:67], v[180:183], v[216:219], v[64:67]
	s_barrier
	s_add_i32 s83, s72, s65
	v_lshl_add_u64 v[144:145], s[60:61], 0, v[130:131]
	s_mov_b32 m0, s83
	ds_read_b128 v[184:187], v151 offset:16384
	ds_read_b128 v[192:195], v151 offset:17408
	ds_read_b128 v[196:199], v151 offset:18432
	ds_read_b128 v[200:203], v151 offset:19456
	ds_read_b128 v[204:207], v151 offset:20480
	ds_read_b128 v[208:211], v151 offset:21504
	ds_read_b128 v[212:215], v151 offset:22528
	ds_read_b128 v[216:219], v151 offset:23552
	global_load_lds_dwordx4 v[144:145], off
	s_add_i32 m0, s83, 0x2000
	s_add_u32 s84, s60, 0x40000
	v_lshl_add_u64 v[188:189], s[60:61], 0, v[134:135]
	s_addc_u32 s85, s61, 0
	s_add_i32 s83, s73, s65
	global_load_lds_dwordx4 v[188:189], off
	s_mov_b32 m0, s83
	v_lshl_add_u64 v[222:223], s[62:63], 0, v[132:133]
	global_load_lds_dwordx4 v130, s[84:85]
	s_add_i32 m0, s83, 0x2000
	s_nop 0
	global_load_lds_dwordx4 v134, s[84:85]
	v_lshl_add_u64 v[220:221], s[62:63], 0, v[128:129]
	s_mov_b32 m0, s35
	s_nop 0
	global_load_lds_dwordx4 v[220:221], off
	s_mov_b32 m0, s33
	s_nop 0
	global_load_lds_dwordx4 v[222:223], off
	s_waitcnt vmcnt(8)
	s_waitcnt lgkmcnt(0)
	s_barrier
	s_waitcnt lgkmcnt(0)
	v_mfma_f32_16x16x32_bf16 v[60:63], v[152:155], v[184:187], 0
	v_mfma_f32_16x16x32_bf16 v[56:59], v[160:163], v[184:187], 0
	v_mfma_f32_16x16x32_bf16 v[52:55], v[152:155], v[196:199], 0
	v_mfma_f32_16x16x32_bf16 v[44:47], v[160:163], v[196:199], 0
	v_mfma_f32_16x16x32_bf16 v[36:39], v[152:155], v[204:207], 0
	v_mfma_f32_16x16x32_bf16 v[28:31], v[160:163], v[204:207], 0
	v_mfma_f32_16x16x32_bf16 v[20:23], v[152:155], v[212:215], 0
	v_mfma_f32_16x16x32_bf16 v[12:15], v[160:163], v[212:215], 0
	v_mfma_f32_16x16x32_bf16 v[60:63], v[156:159], v[192:195], v[60:63]
	v_mfma_f32_16x16x32_bf16 v[56:59], v[164:167], v[192:195], v[56:59]
	v_mfma_f32_16x16x32_bf16 v[52:55], v[156:159], v[200:203], v[52:55]
	v_mfma_f32_16x16x32_bf16 v[44:47], v[164:167], v[200:203], v[44:47]
	v_mfma_f32_16x16x32_bf16 v[36:39], v[156:159], v[208:211], v[36:39]
	v_mfma_f32_16x16x32_bf16 v[28:31], v[164:167], v[208:211], v[28:31]
	v_mfma_f32_16x16x32_bf16 v[20:23], v[156:159], v[216:219], v[20:23]
	v_mfma_f32_16x16x32_bf16 v[12:15], v[164:167], v[216:219], v[12:15]
	v_mfma_f32_16x16x32_bf16 v[48:51], v[168:171], v[184:187], 0
	v_mfma_f32_16x16x32_bf16 v[40:43], v[176:179], v[184:187], 0
	v_mfma_f32_16x16x32_bf16 v[32:35], v[168:171], v[196:199], 0
	v_mfma_f32_16x16x32_bf16 v[24:27], v[176:179], v[196:199], 0
	v_mfma_f32_16x16x32_bf16 v[16:19], v[168:171], v[204:207], 0
	v_mfma_f32_16x16x32_bf16 v[8:11], v[176:179], v[204:207], 0
	v_mfma_f32_16x16x32_bf16 v[4:7], v[168:171], v[212:215], 0
	v_mfma_f32_16x16x32_bf16 v[0:3], v[176:179], v[212:215], 0
	v_mfma_f32_16x16x32_bf16 v[48:51], v[172:175], v[192:195], v[48:51]
	v_mfma_f32_16x16x32_bf16 v[40:43], v[180:183], v[192:195], v[40:43]
	v_mfma_f32_16x16x32_bf16 v[32:35], v[172:175], v[200:203], v[32:35]
	v_mfma_f32_16x16x32_bf16 v[24:27], v[180:183], v[200:203], v[24:27]
	v_mfma_f32_16x16x32_bf16 v[16:19], v[172:175], v[208:211], v[16:19]
	v_mfma_f32_16x16x32_bf16 v[8:11], v[180:183], v[208:211], v[8:11]
	v_mfma_f32_16x16x32_bf16 v[4:7], v[172:175], v[216:219], v[4:7]
	v_mfma_f32_16x16x32_bf16 v[0:3], v[180:183], v[216:219], v[0:3]
	s_barrier
	s_add_i32 s83, 0, 0x18000
	s_add_i32 s84, 0, 0x1c000
	v_add_u32_e32 v164, s83, v147
	v_add_u32_e32 v180, s84, v147
	ds_read_b128 v[152:155], v164
	ds_read_b128 v[156:159], v164 offset:1024
	ds_read_b128 v[160:163], v164 offset:2048
	ds_read_b128 v[164:167], v164 offset:3072
	ds_read_b128 v[168:171], v180
	ds_read_b128 v[172:175], v180 offset:1024
	ds_read_b128 v[176:179], v180 offset:2048
	ds_read_b128 v[180:183], v180 offset:3072
	s_add_u32 s62, s62, 0x40000
	s_addc_u32 s63, s63, 0
	s_mov_b32 m0, s66
	ds_read_b128 v[184:187], v151 offset:32768
	ds_read_b128 v[192:195], v151 offset:33792
	ds_read_b128 v[196:199], v151 offset:34816
	ds_read_b128 v[200:203], v151 offset:35840
	ds_read_b128 v[204:207], v151 offset:36864
	ds_read_b128 v[208:211], v151 offset:37888
	ds_read_b128 v[212:215], v151 offset:38912
	ds_read_b128 v[216:219], v151 offset:39936
	global_load_lds_dwordx4 v128, s[62:63]
	s_mov_b32 m0, s67
	s_nop 0
	global_load_lds_dwordx4 v132, s[62:63]
	s_waitcnt vmcnt(8)
	s_waitcnt lgkmcnt(0)
	s_barrier
	s_waitcnt lgkmcnt(0)
	v_mfma_f32_16x16x32_bf16 v[124:127], v[152:155], v[184:187], v[124:127]
	v_mfma_f32_16x16x32_bf16 v[120:123], v[160:163], v[184:187], v[120:123]
	v_mfma_f32_16x16x32_bf16 v[116:119], v[152:155], v[196:199], v[116:119]
	v_mfma_f32_16x16x32_bf16 v[108:111], v[160:163], v[196:199], v[108:111]
	v_mfma_f32_16x16x32_bf16 v[100:103], v[152:155], v[204:207], v[100:103]
	v_mfma_f32_16x16x32_bf16 v[92:95], v[160:163], v[204:207], v[92:95]
	v_mfma_f32_16x16x32_bf16 v[84:87], v[152:155], v[212:215], v[84:87]
	v_mfma_f32_16x16x32_bf16 v[76:79], v[160:163], v[212:215], v[76:79]
	v_mfma_f32_16x16x32_bf16 v[124:127], v[156:159], v[192:195], v[124:127]
	v_mfma_f32_16x16x32_bf16 v[120:123], v[164:167], v[192:195], v[120:123]
	v_mfma_f32_16x16x32_bf16 v[116:119], v[156:159], v[200:203], v[116:119]
	v_mfma_f32_16x16x32_bf16 v[108:111], v[164:167], v[200:203], v[108:111]
	v_mfma_f32_16x16x32_bf16 v[100:103], v[156:159], v[208:211], v[100:103]
	v_mfma_f32_16x16x32_bf16 v[92:95], v[164:167], v[208:211], v[92:95]
	v_mfma_f32_16x16x32_bf16 v[84:87], v[156:159], v[216:219], v[84:87]
	v_mfma_f32_16x16x32_bf16 v[76:79], v[164:167], v[216:219], v[76:79]
	v_mfma_f32_16x16x32_bf16 v[112:115], v[168:171], v[184:187], v[112:115]
	v_mfma_f32_16x16x32_bf16 v[104:107], v[176:179], v[184:187], v[104:107]
	v_mfma_f32_16x16x32_bf16 v[96:99], v[168:171], v[196:199], v[96:99]
	v_mfma_f32_16x16x32_bf16 v[88:91], v[176:179], v[196:199], v[88:91]
	v_mfma_f32_16x16x32_bf16 v[80:83], v[168:171], v[204:207], v[80:83]
	v_mfma_f32_16x16x32_bf16 v[72:75], v[176:179], v[204:207], v[72:75]
	v_mfma_f32_16x16x32_bf16 v[68:71], v[168:171], v[212:215], v[68:71]
	v_mfma_f32_16x16x32_bf16 v[64:67], v[176:179], v[212:215], v[64:67]
	v_mfma_f32_16x16x32_bf16 v[112:115], v[172:175], v[192:195], v[112:115]
	v_mfma_f32_16x16x32_bf16 v[104:107], v[180:183], v[192:195], v[104:107]
	v_mfma_f32_16x16x32_bf16 v[96:99], v[172:175], v[200:203], v[96:99]
	v_mfma_f32_16x16x32_bf16 v[88:91], v[180:183], v[200:203], v[88:91]
	v_mfma_f32_16x16x32_bf16 v[80:83], v[172:175], v[208:211], v[80:83]
	v_mfma_f32_16x16x32_bf16 v[72:75], v[180:183], v[208:211], v[72:75]
	v_mfma_f32_16x16x32_bf16 v[68:71], v[172:175], v[216:219], v[68:71]
	v_mfma_f32_16x16x32_bf16 v[64:67], v[180:183], v[216:219], v[64:67]
	s_barrier
	s_add_i32 s62, s83, s65
	v_lshl_add_u64 v[144:145], v[144:145], 0, s[12:13]
	s_mov_b32 m0, s62
	ds_read_b128 v[184:187], v151 offset:49152
	ds_read_b128 v[192:195], v151 offset:50176
	ds_read_b128 v[196:199], v151 offset:51200
	ds_read_b128 v[200:203], v151 offset:52224
	ds_read_b128 v[204:207], v151 offset:53248
	ds_read_b128 v[208:211], v151 offset:54272
	ds_read_b128 v[212:215], v151 offset:55296
	ds_read_b128 v[216:219], v151 offset:56320
	global_load_lds_dwordx4 v[144:145], off
	s_add_i32 m0, s62, 0x2000
	s_add_u32 s60, s60, 0x40080
	v_lshl_add_u64 v[144:145], v[188:189], 0, s[12:13]
	s_addc_u32 s61, s61, 0
	s_add_i32 s62, s84, s65
	global_load_lds_dwordx4 v[144:145], off
	s_mov_b32 m0, s62
	s_nop 0
	global_load_lds_dwordx4 v130, s[60:61]
	s_add_i32 m0, s62, 0x2000
	s_nop 0
	global_load_lds_dwordx4 v134, s[60:61]
	v_lshl_add_u64 v[144:145], v[220:221], 0, s[12:13]
	s_mov_b32 m0, s69
	s_nop 0
	global_load_lds_dwordx4 v[144:145], off
	v_lshl_add_u64 v[144:145], v[222:223], 0, s[12:13]
	s_mov_b32 m0, s70
	s_nop 0
	global_load_lds_dwordx4 v[144:145], off
	s_waitcnt vmcnt(8)
	s_waitcnt lgkmcnt(0)
	s_barrier
	s_waitcnt lgkmcnt(0)
	v_mfma_f32_16x16x32_bf16 v[60:63], v[152:155], v[184:187], v[60:63]
	v_mfma_f32_16x16x32_bf16 v[56:59], v[160:163], v[184:187], v[56:59]
	v_mfma_f32_16x16x32_bf16 v[52:55], v[152:155], v[196:199], v[52:55]
	v_mfma_f32_16x16x32_bf16 v[44:47], v[160:163], v[196:199], v[44:47]
	v_mfma_f32_16x16x32_bf16 v[36:39], v[152:155], v[204:207], v[36:39]
	v_mfma_f32_16x16x32_bf16 v[28:31], v[160:163], v[204:207], v[28:31]
	v_mfma_f32_16x16x32_bf16 v[20:23], v[152:155], v[212:215], v[20:23]
	v_mfma_f32_16x16x32_bf16 v[12:15], v[160:163], v[212:215], v[12:15]
	v_mfma_f32_16x16x32_bf16 v[60:63], v[156:159], v[192:195], v[60:63]
	v_mfma_f32_16x16x32_bf16 v[56:59], v[164:167], v[192:195], v[56:59]
	v_mfma_f32_16x16x32_bf16 v[52:55], v[156:159], v[200:203], v[52:55]
	v_mfma_f32_16x16x32_bf16 v[44:47], v[164:167], v[200:203], v[44:47]
	v_mfma_f32_16x16x32_bf16 v[36:39], v[156:159], v[208:211], v[36:39]
	v_mfma_f32_16x16x32_bf16 v[28:31], v[164:167], v[208:211], v[28:31]
	v_mfma_f32_16x16x32_bf16 v[20:23], v[156:159], v[216:219], v[20:23]
	v_mfma_f32_16x16x32_bf16 v[12:15], v[164:167], v[216:219], v[12:15]
	v_mfma_f32_16x16x32_bf16 v[48:51], v[168:171], v[184:187], v[48:51]
	v_mfma_f32_16x16x32_bf16 v[40:43], v[176:179], v[184:187], v[40:43]
	v_mfma_f32_16x16x32_bf16 v[32:35], v[168:171], v[196:199], v[32:35]
	v_mfma_f32_16x16x32_bf16 v[24:27], v[176:179], v[196:199], v[24:27]
	v_mfma_f32_16x16x32_bf16 v[16:19], v[168:171], v[204:207], v[16:19]
	v_mfma_f32_16x16x32_bf16 v[8:11], v[176:179], v[204:207], v[8:11]
	v_mfma_f32_16x16x32_bf16 v[4:7], v[168:171], v[212:215], v[4:7]
	v_mfma_f32_16x16x32_bf16 v[0:3], v[176:179], v[212:215], v[0:3]
	v_mfma_f32_16x16x32_bf16 v[48:51], v[172:175], v[192:195], v[48:51]
	v_mfma_f32_16x16x32_bf16 v[40:43], v[180:183], v[192:195], v[40:43]
	v_mfma_f32_16x16x32_bf16 v[32:35], v[172:175], v[200:203], v[32:35]
	v_mfma_f32_16x16x32_bf16 v[24:27], v[180:183], v[200:203], v[24:27]
	v_mfma_f32_16x16x32_bf16 v[16:19], v[172:175], v[208:211], v[16:19]
	v_mfma_f32_16x16x32_bf16 v[8:11], v[180:183], v[208:211], v[8:11]
	v_mfma_f32_16x16x32_bf16 v[4:7], v[172:175], v[216:219], v[4:7]
	v_mfma_f32_16x16x32_bf16 v[0:3], v[180:183], v[216:219], v[0:3]
	s_barrier
	s_add_i32 s82, s82, 2
	s_add_u32 s42, s42, 0x100
	s_addc_u32 s43, s43, 0
	s_add_u32 s80, s80, 0x100
	s_addc_u32 s81, s81, 0
	s_cmp_gt_u32 s82, 13
	s_cbranch_scc0 .LBB0_1077
	s_branch .Lpeel_exit6

.LBB0_1221:
	s_ashr_i32 s21, s20, 31
	s_lshl_b64 s[22:23], s[20:21], 17
	s_add_u32 s22, s70, s22
	s_addc_u32 s23, s71, s23
	s_and_b64 s[24:25], s[0:1], exec
	s_cselect_b32 s21, s23, s31
	s_cselect_b32 s55, s22, s30
	s_ashr_i32 s19, s18, 31
	s_lshl_b64 s[24:25], s[18:19], 17
	s_add_u32 s24, s53, s24
	s_addc_u32 s25, s72, s25
	s_and_b64 s[34:35], s[0:1], exec
	s_cselect_b32 s19, s25, s29
	s_cselect_b32 s85, s24, s28
	s_mov_b32 s60, 0
	s_mov_b64 s[34:35], -1
	s_mov_b64 s[42:43], 0
	s_add_u32 s61, s30, s60
	s_addc_u32 s66, s31, 0
	s_add_u32 s64, s61, 0x100
	s_addc_u32 s65, s66, 0
	s_and_b64 s[62:63], s[42:43], exec
	s_cselect_b32 s63, s21, s65
	s_cselect_b32 s62, s55, s64
	s_add_u32 s60, s28, s60
	s_addc_u32 s64, s29, 0
	s_add_u32 s60, s60, 0x100
	s_addc_u32 s64, s64, 0
	s_and_b64 s[42:43], s[42:43], exec
	s_cselect_b32 s65, s19, s64
	s_cselect_b32 s64, s85, s60
	s_add_u32 s68, s61, 0x10080
	ds_read_b128 v[148:151], v145
	ds_read_b128 v[152:155], v145 offset:1024
	ds_read_b128 v[156:159], v145 offset:2048
	ds_read_b128 v[160:163], v145 offset:3072
	ds_read_b128 v[164:167], v146
	ds_read_b128 v[168:171], v146 offset:1024
	ds_read_b128 v[172:175], v146 offset:2048
	ds_read_b128 v[176:179], v146 offset:3072
	s_addc_u32 s69, s66, 0
	s_add_i32 s95, s81, s73
	s_add_i32 m0, s27, 0xc000
	s_add_i32 s96, s27, 0xe000
	s_add_i32 s92, s95, 0x2000
	s_add_u32 s66, s64, 0x10000
	s_addc_u32 s67, s65, 0
	s_add_i32 s94, s82, s73
	s_add_i32 s93, s94, 0x2000
	s_add_i32 s91, 0, 0x18000
	s_add_i32 s90, 0, 0x1c000
	s_add_u32 s60, s62, 0x10000
	s_addc_u32 s61, s63, 0
	s_add_i32 s89, s91, s73
	s_add_i32 s87, s89, 0x2000
	s_add_u32 s42, s64, 0x10080
	s_addc_u32 s43, s65, 0
	s_add_i32 s88, s90, s73
	s_add_i32 s86, s88, 0x2000
	ds_read_b128 v[180:183], v147
	ds_read_b128 v[184:187], v147 offset:1024
	ds_read_b128 v[192:195], v147 offset:2048
	ds_read_b128 v[196:199], v147 offset:3072
	ds_read_b128 v[200:203], v147 offset:4096
	ds_read_b128 v[204:207], v147 offset:5120
	ds_read_b128 v[208:211], v147 offset:6144
	ds_read_b128 v[212:215], v147 offset:7168
	global_load_lds_dwordx4 v128, s[68:69]
	s_mov_b32 m0, s96
	s_nop 0
	global_load_lds_dwordx4 v132, s[68:69]
	s_waitcnt vmcnt(8)
	s_waitcnt lgkmcnt(0)
	s_barrier
	s_waitcnt lgkmcnt(0)
	v_mfma_f32_16x16x32_bf16 v[124:127], v[148:151], v[180:183], 0
	v_mfma_f32_16x16x32_bf16 v[120:123], v[156:159], v[180:183], 0
	v_mfma_f32_16x16x32_bf16 v[116:119], v[148:151], v[192:195], 0
	v_mfma_f32_16x16x32_bf16 v[108:111], v[156:159], v[192:195], 0
	v_mfma_f32_16x16x32_bf16 v[100:103], v[148:151], v[200:203], 0
	v_mfma_f32_16x16x32_bf16 v[92:95], v[156:159], v[200:203], 0
	v_mfma_f32_16x16x32_bf16 v[84:87], v[148:151], v[208:211], 0
	v_mfma_f32_16x16x32_bf16 v[76:79], v[156:159], v[208:211], 0
	v_mfma_f32_16x16x32_bf16 v[124:127], v[152:155], v[184:187], v[124:127]
	v_mfma_f32_16x16x32_bf16 v[120:123], v[160:163], v[184:187], v[120:123]
	v_mfma_f32_16x16x32_bf16 v[116:119], v[152:155], v[196:199], v[116:119]
	v_mfma_f32_16x16x32_bf16 v[108:111], v[160:163], v[196:199], v[108:111]
	v_mfma_f32_16x16x32_bf16 v[100:103], v[152:155], v[204:207], v[100:103]
	v_mfma_f32_16x16x32_bf16 v[92:95], v[160:163], v[204:207], v[92:95]
	v_mfma_f32_16x16x32_bf16 v[84:87], v[152:155], v[212:215], v[84:87]
	v_mfma_f32_16x16x32_bf16 v[76:79], v[160:163], v[212:215], v[76:79]
	v_mfma_f32_16x16x32_bf16 v[112:115], v[164:167], v[180:183], 0
	v_mfma_f32_16x16x32_bf16 v[104:107], v[172:175], v[180:183], 0
	v_mfma_f32_16x16x32_bf16 v[96:99], v[164:167], v[192:195], 0
	v_mfma_f32_16x16x32_bf16 v[88:91], v[172:175], v[192:195], 0
	v_mfma_f32_16x16x32_bf16 v[80:83], v[164:167], v[200:203], 0
	v_mfma_f32_16x16x32_bf16 v[72:75], v[172:175], v[200:203], 0
	v_mfma_f32_16x16x32_bf16 v[68:71], v[164:167], v[208:211], 0
	v_mfma_f32_16x16x32_bf16 v[64:67], v[172:175], v[208:211], 0
	v_mfma_f32_16x16x32_bf16 v[112:115], v[168:171], v[184:187], v[112:115]
	v_mfma_f32_16x16x32_bf16 v[104:107], v[176:179], v[184:187], v[104:107]
	v_mfma_f32_16x16x32_bf16 v[96:99], v[168:171], v[196:199], v[96:99]
	v_mfma_f32_16x16x32_bf16 v[88:91], v[176:179], v[196:199], v[88:91]
	v_mfma_f32_16x16x32_bf16 v[80:83], v[168:171], v[204:207], v[80:83]
	v_mfma_f32_16x16x32_bf16 v[72:75], v[176:179], v[204:207], v[72:75]
	v_mfma_f32_16x16x32_bf16 v[68:71], v[168:171], v[212:215], v[68:71]
	v_mfma_f32_16x16x32_bf16 v[64:67], v[176:179], v[212:215], v[64:67]
	s_barrier
	s_mov_b32 m0, s95
	v_lshl_add_u64 v[140:141], s[64:65], 0, v[130:131]
	ds_read_b128 v[180:183], v147 offset:16384
	ds_read_b128 v[184:187], v147 offset:17408
	ds_read_b128 v[192:195], v147 offset:18432
	ds_read_b128 v[196:199], v147 offset:19456
	ds_read_b128 v[200:203], v147 offset:20480
	ds_read_b128 v[204:207], v147 offset:21504
	ds_read_b128 v[208:211], v147 offset:22528
	ds_read_b128 v[212:215], v147 offset:23552
	global_load_lds_dwordx4 v[140:141], off
	v_lshl_add_u64 v[188:189], s[64:65], 0, v[134:135]
	s_mov_b32 m0, s92
	s_nop 0
	global_load_lds_dwordx4 v[188:189], off
	s_mov_b32 m0, s94
	v_lshl_add_u64 v[218:219], s[62:63], 0, v[132:133]
	global_load_lds_dwordx4 v130, s[66:67]
	s_mov_b32 m0, s93
	s_nop 0
	global_load_lds_dwordx4 v134, s[66:67]
	v_lshl_add_u64 v[216:217], s[62:63], 0, v[128:129]
	s_mov_b32 m0, s27
	s_nop 0
	global_load_lds_dwordx4 v[216:217], off
	s_mov_b32 m0, s33
	s_nop 0
	global_load_lds_dwordx4 v[218:219], off
	s_waitcnt vmcnt(8)
	s_waitcnt lgkmcnt(0)
	s_barrier
	s_waitcnt lgkmcnt(0)
	v_mfma_f32_16x16x32_bf16 v[60:63], v[148:151], v[180:183], 0
	v_mfma_f32_16x16x32_bf16 v[56:59], v[156:159], v[180:183], 0
	v_mfma_f32_16x16x32_bf16 v[52:55], v[148:151], v[192:195], 0
	v_mfma_f32_16x16x32_bf16 v[44:47], v[156:159], v[192:195], 0
	v_mfma_f32_16x16x32_bf16 v[36:39], v[148:151], v[200:203], 0
	v_mfma_f32_16x16x32_bf16 v[28:31], v[156:159], v[200:203], 0
	v_mfma_f32_16x16x32_bf16 v[20:23], v[148:151], v[208:211], 0
	v_mfma_f32_16x16x32_bf16 v[12:15], v[156:159], v[208:211], 0
	v_mfma_f32_16x16x32_bf16 v[60:63], v[152:155], v[184:187], v[60:63]
	v_mfma_f32_16x16x32_bf16 v[56:59], v[160:163], v[184:187], v[56:59]
	v_mfma_f32_16x16x32_bf16 v[52:55], v[152:155], v[196:199], v[52:55]
	v_mfma_f32_16x16x32_bf16 v[44:47], v[160:163], v[196:199], v[44:47]
	v_mfma_f32_16x16x32_bf16 v[36:39], v[152:155], v[204:207], v[36:39]
	v_mfma_f32_16x16x32_bf16 v[28:31], v[160:163], v[204:207], v[28:31]
	v_mfma_f32_16x16x32_bf16 v[20:23], v[152:155], v[212:215], v[20:23]
	v_mfma_f32_16x16x32_bf16 v[12:15], v[160:163], v[212:215], v[12:15]
	v_mfma_f32_16x16x32_bf16 v[48:51], v[164:167], v[180:183], 0
	v_mfma_f32_16x16x32_bf16 v[40:43], v[172:175], v[180:183], 0
	v_mfma_f32_16x16x32_bf16 v[32:35], v[164:167], v[192:195], 0
	v_mfma_f32_16x16x32_bf16 v[24:27], v[172:175], v[192:195], 0
	v_mfma_f32_16x16x32_bf16 v[16:19], v[164:167], v[200:203], 0
	v_mfma_f32_16x16x32_bf16 v[8:11], v[172:175], v[200:203], 0
	v_mfma_f32_16x16x32_bf16 v[4:7], v[164:167], v[208:211], 0
	v_mfma_f32_16x16x32_bf16 v[0:3], v[172:175], v[208:211], 0
	v_mfma_f32_16x16x32_bf16 v[48:51], v[168:171], v[184:187], v[48:51]
	v_mfma_f32_16x16x32_bf16 v[40:43], v[176:179], v[184:187], v[40:43]
	v_mfma_f32_16x16x32_bf16 v[32:35], v[168:171], v[196:199], v[32:35]
	v_mfma_f32_16x16x32_bf16 v[24:27], v[176:179], v[196:199], v[24:27]
	v_mfma_f32_16x16x32_bf16 v[16:19], v[168:171], v[204:207], v[16:19]
	v_mfma_f32_16x16x32_bf16 v[8:11], v[176:179], v[204:207], v[8:11]
	v_mfma_f32_16x16x32_bf16 v[4:7], v[168:171], v[212:215], v[4:7]
	v_mfma_f32_16x16x32_bf16 v[0:3], v[176:179], v[212:215], v[0:3]
	s_barrier
	v_add_u32_e32 v160, s91, v143
	v_add_u32_e32 v176, s90, v143
	ds_read_b128 v[148:151], v160
	ds_read_b128 v[152:155], v160 offset:1024
	ds_read_b128 v[156:159], v160 offset:2048
	ds_read_b128 v[160:163], v160 offset:3072
	ds_read_b128 v[164:167], v176
	ds_read_b128 v[168:171], v176 offset:1024
	ds_read_b128 v[172:175], v176 offset:2048
	ds_read_b128 v[176:179], v176 offset:3072
	s_mov_b32 m0, s74
	ds_read_b128 v[180:183], v147 offset:32768
	ds_read_b128 v[184:187], v147 offset:33792
	ds_read_b128 v[192:195], v147 offset:34816
	ds_read_b128 v[196:199], v147 offset:35840
	ds_read_b128 v[200:203], v147 offset:36864
	ds_read_b128 v[204:207], v147 offset:37888
	ds_read_b128 v[208:211], v147 offset:38912
	ds_read_b128 v[212:215], v147 offset:39936
	global_load_lds_dwordx4 v128, s[60:61]
	s_mov_b32 m0, s75
	s_nop 0
	global_load_lds_dwordx4 v132, s[60:61]
	s_waitcnt vmcnt(8)
	s_waitcnt lgkmcnt(0)
	s_barrier
	s_waitcnt lgkmcnt(0)
	v_mfma_f32_16x16x32_bf16 v[124:127], v[148:151], v[180:183], v[124:127]
	v_mfma_f32_16x16x32_bf16 v[120:123], v[156:159], v[180:183], v[120:123]
	v_mfma_f32_16x16x32_bf16 v[116:119], v[148:151], v[192:195], v[116:119]
	v_mfma_f32_16x16x32_bf16 v[108:111], v[156:159], v[192:195], v[108:111]
	v_mfma_f32_16x16x32_bf16 v[100:103], v[148:151], v[200:203], v[100:103]
	v_mfma_f32_16x16x32_bf16 v[92:95], v[156:159], v[200:203], v[92:95]
	v_mfma_f32_16x16x32_bf16 v[84:87], v[148:151], v[208:211], v[84:87]
	v_mfma_f32_16x16x32_bf16 v[76:79], v[156:159], v[208:211], v[76:79]
	v_mfma_f32_16x16x32_bf16 v[124:127], v[152:155], v[184:187], v[124:127]
	v_mfma_f32_16x16x32_bf16 v[120:123], v[160:163], v[184:187], v[120:123]
	v_mfma_f32_16x16x32_bf16 v[116:119], v[152:155], v[196:199], v[116:119]
	v_mfma_f32_16x16x32_bf16 v[108:111], v[160:163], v[196:199], v[108:111]
	v_mfma_f32_16x16x32_bf16 v[100:103], v[152:155], v[204:207], v[100:103]
	v_mfma_f32_16x16x32_bf16 v[92:95], v[160:163], v[204:207], v[92:95]
	v_mfma_f32_16x16x32_bf16 v[84:87], v[152:155], v[212:215], v[84:87]
	v_mfma_f32_16x16x32_bf16 v[76:79], v[160:163], v[212:215], v[76:79]
	v_mfma_f32_16x16x32_bf16 v[112:115], v[164:167], v[180:183], v[112:115]
	v_mfma_f32_16x16x32_bf16 v[104:107], v[172:175], v[180:183], v[104:107]
	v_mfma_f32_16x16x32_bf16 v[96:99], v[164:167], v[192:195], v[96:99]
	v_mfma_f32_16x16x32_bf16 v[88:91], v[172:175], v[192:195], v[88:91]
	v_mfma_f32_16x16x32_bf16 v[80:83], v[164:167], v[200:203], v[80:83]
	v_mfma_f32_16x16x32_bf16 v[72:75], v[172:175], v[200:203], v[72:75]
	v_mfma_f32_16x16x32_bf16 v[68:71], v[164:167], v[208:211], v[68:71]
	v_mfma_f32_16x16x32_bf16 v[64:67], v[172:175], v[208:211], v[64:67]
	v_mfma_f32_16x16x32_bf16 v[112:115], v[168:171], v[184:187], v[112:115]
	v_mfma_f32_16x16x32_bf16 v[104:107], v[176:179], v[184:187], v[104:107]
	v_mfma_f32_16x16x32_bf16 v[96:99], v[168:171], v[196:199], v[96:99]
	v_mfma_f32_16x16x32_bf16 v[88:91], v[176:179], v[196:199], v[88:91]
	v_mfma_f32_16x16x32_bf16 v[80:83], v[168:171], v[204:207], v[80:83]
	v_mfma_f32_16x16x32_bf16 v[72:75], v[176:179], v[204:207], v[72:75]
	v_mfma_f32_16x16x32_bf16 v[68:71], v[168:171], v[212:215], v[68:71]
	v_mfma_f32_16x16x32_bf16 v[64:67], v[176:179], v[212:215], v[64:67]
	s_barrier
	s_mov_b32 m0, s89
	v_lshl_add_u64 v[140:141], v[140:141], 0, s[12:13]
	ds_read_b128 v[180:183], v147 offset:49152
	ds_read_b128 v[184:187], v147 offset:50176
	ds_read_b128 v[192:195], v147 offset:51200
	ds_read_b128 v[196:199], v147 offset:52224
	ds_read_b128 v[200:203], v147 offset:53248
	ds_read_b128 v[204:207], v147 offset:54272
	ds_read_b128 v[208:211], v147 offset:55296
	ds_read_b128 v[212:215], v147 offset:56320
	global_load_lds_dwordx4 v[140:141], off
	v_lshl_add_u64 v[140:141], v[188:189], 0, s[12:13]
	s_mov_b32 m0, s87
	s_nop 0
	global_load_lds_dwordx4 v[140:141], off
	s_mov_b32 m0, s88
	s_nop 0
	global_load_lds_dwordx4 v130, s[42:43]
	s_mov_b32 m0, s86
	s_nop 0
	global_load_lds_dwordx4 v134, s[42:43]
	v_lshl_add_u64 v[140:141], v[216:217], 0, s[12:13]
	s_mov_b32 m0, s77
	s_nop 0
	global_load_lds_dwordx4 v[140:141], off
	v_lshl_add_u64 v[140:141], v[218:219], 0, s[12:13]
	s_mov_b32 m0, s79
	s_nop 0
	global_load_lds_dwordx4 v[140:141], off
	s_waitcnt vmcnt(8)
	s_waitcnt lgkmcnt(0)
	s_barrier
	s_waitcnt lgkmcnt(0)
	v_mfma_f32_16x16x32_bf16 v[60:63], v[148:151], v[180:183], v[60:63]
	v_mfma_f32_16x16x32_bf16 v[56:59], v[156:159], v[180:183], v[56:59]
	v_mfma_f32_16x16x32_bf16 v[52:55], v[148:151], v[192:195], v[52:55]
	v_mfma_f32_16x16x32_bf16 v[44:47], v[156:159], v[192:195], v[44:47]
	v_mfma_f32_16x16x32_bf16 v[36:39], v[148:151], v[200:203], v[36:39]
	v_mfma_f32_16x16x32_bf16 v[28:31], v[156:159], v[200:203], v[28:31]
	v_mfma_f32_16x16x32_bf16 v[20:23], v[148:151], v[208:211], v[20:23]
	v_mfma_f32_16x16x32_bf16 v[12:15], v[156:159], v[208:211], v[12:15]
	v_mfma_f32_16x16x32_bf16 v[60:63], v[152:155], v[184:187], v[60:63]
	v_mfma_f32_16x16x32_bf16 v[56:59], v[160:163], v[184:187], v[56:59]
	v_mfma_f32_16x16x32_bf16 v[52:55], v[152:155], v[196:199], v[52:55]
	v_mfma_f32_16x16x32_bf16 v[44:47], v[160:163], v[196:199], v[44:47]
	v_mfma_f32_16x16x32_bf16 v[36:39], v[152:155], v[204:207], v[36:39]
	v_mfma_f32_16x16x32_bf16 v[28:31], v[160:163], v[204:207], v[28:31]
	v_mfma_f32_16x16x32_bf16 v[20:23], v[152:155], v[212:215], v[20:23]
	v_mfma_f32_16x16x32_bf16 v[12:15], v[160:163], v[212:215], v[12:15]
	v_mfma_f32_16x16x32_bf16 v[48:51], v[164:167], v[180:183], v[48:51]
	v_mfma_f32_16x16x32_bf16 v[40:43], v[172:175], v[180:183], v[40:43]
	v_mfma_f32_16x16x32_bf16 v[32:35], v[164:167], v[192:195], v[32:35]
	v_mfma_f32_16x16x32_bf16 v[24:27], v[172:175], v[192:195], v[24:27]
	v_mfma_f32_16x16x32_bf16 v[16:19], v[164:167], v[200:203], v[16:19]
	v_mfma_f32_16x16x32_bf16 v[8:11], v[172:175], v[200:203], v[8:11]
	v_mfma_f32_16x16x32_bf16 v[4:7], v[164:167], v[208:211], v[4:7]
	v_mfma_f32_16x16x32_bf16 v[0:3], v[172:175], v[208:211], v[0:3]
	v_mfma_f32_16x16x32_bf16 v[48:51], v[168:171], v[184:187], v[48:51]
	v_mfma_f32_16x16x32_bf16 v[40:43], v[176:179], v[184:187], v[40:43]
	v_mfma_f32_16x16x32_bf16 v[32:35], v[168:171], v[196:199], v[32:35]
	v_mfma_f32_16x16x32_bf16 v[24:27], v[176:179], v[196:199], v[24:27]
	v_mfma_f32_16x16x32_bf16 v[16:19], v[168:171], v[204:207], v[16:19]
	v_mfma_f32_16x16x32_bf16 v[8:11], v[176:179], v[204:207], v[8:11]
	v_mfma_f32_16x16x32_bf16 v[4:7], v[168:171], v[212:215], v[4:7]
	v_mfma_f32_16x16x32_bf16 v[0:3], v[176:179], v[212:215], v[0:3]
	s_barrier
	s_movk_i32 s60, 0x100
	s_andn2_b64 vcc, exec, s[34:35]
	s_mov_b64 s[42:43], -1
	s_mov_b64 s[34:35], 0
	s_cbranch_vccz .LBB0_1222
	s_branch .Lpeel_exit7
.LBB0_1222:
	s_add_u32 s61, s30, s60
	s_addc_u32 s66, s31, 0
	s_add_u32 s64, s61, 0x100
	s_addc_u32 s65, s66, 0
	s_and_b64 s[62:63], s[42:43], exec
	s_cselect_b32 s63, s21, s65
	s_cselect_b32 s62, s55, s64
	s_add_u32 s60, s28, s60
	s_addc_u32 s64, s29, 0
	s_add_u32 s60, s60, 0x100
	s_addc_u32 s64, s64, 0
	s_and_b64 s[42:43], s[42:43], exec
	s_cselect_b32 s65, s19, s64
	s_cselect_b32 s64, s85, s60
	s_add_u32 s68, s61, 0x10080
	ds_read_b128 v[148:151], v145
	ds_read_b128 v[152:155], v145 offset:1024
	ds_read_b128 v[156:159], v145 offset:2048
	ds_read_b128 v[160:163], v145 offset:3072
	ds_read_b128 v[164:167], v146
	ds_read_b128 v[168:171], v146 offset:1024
	ds_read_b128 v[172:175], v146 offset:2048
	ds_read_b128 v[176:179], v146 offset:3072
	s_addc_u32 s69, s66, 0
	s_add_i32 s95, s81, s73
	s_add_i32 m0, s27, 0xc000
	s_add_i32 s96, s27, 0xe000
	s_add_i32 s92, s95, 0x2000
	s_add_u32 s66, s64, 0x10000
	s_addc_u32 s67, s65, 0
	s_add_i32 s94, s82, s73
	s_add_i32 s93, s94, 0x2000
	s_add_i32 s91, 0, 0x18000
	s_add_i32 s90, 0, 0x1c000
	s_add_u32 s60, s62, 0x10000
	s_addc_u32 s61, s63, 0
	s_add_i32 s89, s91, s73
	s_add_i32 s87, s89, 0x2000
	s_add_u32 s42, s64, 0x10080
	s_addc_u32 s43, s65, 0
	s_add_i32 s88, s90, s73
	s_add_i32 s86, s88, 0x2000
	ds_read_b128 v[180:183], v147
	ds_read_b128 v[184:187], v147 offset:1024
	ds_read_b128 v[192:195], v147 offset:2048
	ds_read_b128 v[196:199], v147 offset:3072
	ds_read_b128 v[200:203], v147 offset:4096
	ds_read_b128 v[204:207], v147 offset:5120
	ds_read_b128 v[208:211], v147 offset:6144
	ds_read_b128 v[212:215], v147 offset:7168
	global_load_lds_dwordx4 v128, s[68:69]
	s_mov_b32 m0, s96
	s_nop 0
	global_load_lds_dwordx4 v132, s[68:69]
	s_waitcnt vmcnt(8)
	s_waitcnt lgkmcnt(0)
	s_barrier
	s_waitcnt lgkmcnt(0)
	v_mfma_f32_16x16x32_bf16 v[124:127], v[148:151], v[180:183], v[124:127]
	v_mfma_f32_16x16x32_bf16 v[120:123], v[156:159], v[180:183], v[120:123]
	v_mfma_f32_16x16x32_bf16 v[116:119], v[148:151], v[192:195], v[116:119]
	v_mfma_f32_16x16x32_bf16 v[108:111], v[156:159], v[192:195], v[108:111]
	v_mfma_f32_16x16x32_bf16 v[100:103], v[148:151], v[200:203], v[100:103]
	v_mfma_f32_16x16x32_bf16 v[92:95], v[156:159], v[200:203], v[92:95]
	v_mfma_f32_16x16x32_bf16 v[84:87], v[148:151], v[208:211], v[84:87]
	v_mfma_f32_16x16x32_bf16 v[76:79], v[156:159], v[208:211], v[76:79]
	v_mfma_f32_16x16x32_bf16 v[124:127], v[152:155], v[184:187], v[124:127]
	v_mfma_f32_16x16x32_bf16 v[120:123], v[160:163], v[184:187], v[120:123]
	v_mfma_f32_16x16x32_bf16 v[116:119], v[152:155], v[196:199], v[116:119]
	v_mfma_f32_16x16x32_bf16 v[108:111], v[160:163], v[196:199], v[108:111]
	v_mfma_f32_16x16x32_bf16 v[100:103], v[152:155], v[204:207], v[100:103]
	v_mfma_f32_16x16x32_bf16 v[92:95], v[160:163], v[204:207], v[92:95]
	v_mfma_f32_16x16x32_bf16 v[84:87], v[152:155], v[212:215], v[84:87]
	v_mfma_f32_16x16x32_bf16 v[76:79], v[160:163], v[212:215], v[76:79]
	v_mfma_f32_16x16x32_bf16 v[112:115], v[164:167], v[180:183], v[112:115]
	v_mfma_f32_16x16x32_bf16 v[104:107], v[172:175], v[180:183], v[104:107]
	v_mfma_f32_16x16x32_bf16 v[96:99], v[164:167], v[192:195], v[96:99]
	v_mfma_f32_16x16x32_bf16 v[88:91], v[172:175], v[192:195], v[88:91]
	v_mfma_f32_16x16x32_bf16 v[80:83], v[164:167], v[200:203], v[80:83]
	v_mfma_f32_16x16x32_bf16 v[72:75], v[172:175], v[200:203], v[72:75]
	v_mfma_f32_16x16x32_bf16 v[68:71], v[164:167], v[208:211], v[68:71]
	v_mfma_f32_16x16x32_bf16 v[64:67], v[172:175], v[208:211], v[64:67]
	v_mfma_f32_16x16x32_bf16 v[112:115], v[168:171], v[184:187], v[112:115]
	v_mfma_f32_16x16x32_bf16 v[104:107], v[176:179], v[184:187], v[104:107]
	v_mfma_f32_16x16x32_bf16 v[96:99], v[168:171], v[196:199], v[96:99]
	v_mfma_f32_16x16x32_bf16 v[88:91], v[176:179], v[196:199], v[88:91]
	v_mfma_f32_16x16x32_bf16 v[80:83], v[168:171], v[204:207], v[80:83]
	v_mfma_f32_16x16x32_bf16 v[72:75], v[176:179], v[204:207], v[72:75]
	v_mfma_f32_16x16x32_bf16 v[68:71], v[168:171], v[212:215], v[68:71]
	v_mfma_f32_16x16x32_bf16 v[64:67], v[176:179], v[212:215], v[64:67]
	s_barrier
	s_mov_b32 m0, s95
	v_lshl_add_u64 v[140:141], s[64:65], 0, v[130:131]
	ds_read_b128 v[180:183], v147 offset:16384
	ds_read_b128 v[184:187], v147 offset:17408
	ds_read_b128 v[192:195], v147 offset:18432
	ds_read_b128 v[196:199], v147 offset:19456
	ds_read_b128 v[200:203], v147 offset:20480
	ds_read_b128 v[204:207], v147 offset:21504
	ds_read_b128 v[208:211], v147 offset:22528
	ds_read_b128 v[212:215], v147 offset:23552
	global_load_lds_dwordx4 v[140:141], off
	v_lshl_add_u64 v[188:189], s[64:65], 0, v[134:135]
	s_mov_b32 m0, s92
	s_nop 0
	global_load_lds_dwordx4 v[188:189], off
	s_mov_b32 m0, s94
	v_lshl_add_u64 v[218:219], s[62:63], 0, v[132:133]
	global_load_lds_dwordx4 v130, s[66:67]
	s_mov_b32 m0, s93
	s_nop 0
	global_load_lds_dwordx4 v134, s[66:67]
	v_lshl_add_u64 v[216:217], s[62:63], 0, v[128:129]
	s_mov_b32 m0, s27
	s_nop 0
	global_load_lds_dwordx4 v[216:217], off
	s_mov_b32 m0, s33
	s_nop 0
	global_load_lds_dwordx4 v[218:219], off
	s_waitcnt vmcnt(8)
	s_waitcnt lgkmcnt(0)
	s_barrier
	s_waitcnt lgkmcnt(0)
	v_mfma_f32_16x16x32_bf16 v[60:63], v[148:151], v[180:183], v[60:63]
	v_mfma_f32_16x16x32_bf16 v[56:59], v[156:159], v[180:183], v[56:59]
	v_mfma_f32_16x16x32_bf16 v[52:55], v[148:151], v[192:195], v[52:55]
	v_mfma_f32_16x16x32_bf16 v[44:47], v[156:159], v[192:195], v[44:47]
	v_mfma_f32_16x16x32_bf16 v[36:39], v[148:151], v[200:203], v[36:39]
	v_mfma_f32_16x16x32_bf16 v[28:31], v[156:159], v[200:203], v[28:31]
	v_mfma_f32_16x16x32_bf16 v[20:23], v[148:151], v[208:211], v[20:23]
	v_mfma_f32_16x16x32_bf16 v[12:15], v[156:159], v[208:211], v[12:15]
	v_mfma_f32_16x16x32_bf16 v[60:63], v[152:155], v[184:187], v[60:63]
	v_mfma_f32_16x16x32_bf16 v[56:59], v[160:163], v[184:187], v[56:59]
	v_mfma_f32_16x16x32_bf16 v[52:55], v[152:155], v[196:199], v[52:55]
	v_mfma_f32_16x16x32_bf16 v[44:47], v[160:163], v[196:199], v[44:47]
	v_mfma_f32_16x16x32_bf16 v[36:39], v[152:155], v[204:207], v[36:39]
	v_mfma_f32_16x16x32_bf16 v[28:31], v[160:163], v[204:207], v[28:31]
	v_mfma_f32_16x16x32_bf16 v[20:23], v[152:155], v[212:215], v[20:23]
	v_mfma_f32_16x16x32_bf16 v[12:15], v[160:163], v[212:215], v[12:15]
	v_mfma_f32_16x16x32_bf16 v[48:51], v[164:167], v[180:183], v[48:51]
	v_mfma_f32_16x16x32_bf16 v[40:43], v[172:175], v[180:183], v[40:43]
	v_mfma_f32_16x16x32_bf16 v[32:35], v[164:167], v[192:195], v[32:35]
	v_mfma_f32_16x16x32_bf16 v[24:27], v[172:175], v[192:195], v[24:27]
	v_mfma_f32_16x16x32_bf16 v[16:19], v[164:167], v[200:203], v[16:19]
	v_mfma_f32_16x16x32_bf16 v[8:11], v[172:175], v[200:203], v[8:11]
	v_mfma_f32_16x16x32_bf16 v[4:7], v[164:167], v[208:211], v[4:7]
	v_mfma_f32_16x16x32_bf16 v[0:3], v[172:175], v[208:211], v[0:3]
	v_mfma_f32_16x16x32_bf16 v[48:51], v[168:171], v[184:187], v[48:51]
	v_mfma_f32_16x16x32_bf16 v[40:43], v[176:179], v[184:187], v[40:43]
	v_mfma_f32_16x16x32_bf16 v[32:35], v[168:171], v[196:199], v[32:35]
	v_mfma_f32_16x16x32_bf16 v[24:27], v[176:179], v[196:199], v[24:27]
	v_mfma_f32_16x16x32_bf16 v[16:19], v[168:171], v[204:207], v[16:19]
	v_mfma_f32_16x16x32_bf16 v[8:11], v[176:179], v[204:207], v[8:11]
	v_mfma_f32_16x16x32_bf16 v[4:7], v[168:171], v[212:215], v[4:7]
	v_mfma_f32_16x16x32_bf16 v[0:3], v[176:179], v[212:215], v[0:3]
	s_barrier
	v_add_u32_e32 v160, s91, v143
	v_add_u32_e32 v176, s90, v143
	ds_read_b128 v[148:151], v160
	ds_read_b128 v[152:155], v160 offset:1024
	ds_read_b128 v[156:159], v160 offset:2048
	ds_read_b128 v[160:163], v160 offset:3072
	ds_read_b128 v[164:167], v176
	ds_read_b128 v[168:171], v176 offset:1024
	ds_read_b128 v[172:175], v176 offset:2048
	ds_read_b128 v[176:179], v176 offset:3072
	s_mov_b32 m0, s74
	ds_read_b128 v[180:183], v147 offset:32768
	ds_read_b128 v[184:187], v147 offset:33792
	ds_read_b128 v[192:195], v147 offset:34816
	ds_read_b128 v[196:199], v147 offset:35840
	ds_read_b128 v[200:203], v147 offset:36864
	ds_read_b128 v[204:207], v147 offset:37888
	ds_read_b128 v[208:211], v147 offset:38912
	ds_read_b128 v[212:215], v147 offset:39936
	global_load_lds_dwordx4 v128, s[60:61]
	s_mov_b32 m0, s75
	s_nop 0
	global_load_lds_dwordx4 v132, s[60:61]
	s_waitcnt vmcnt(8)
	s_waitcnt lgkmcnt(0)
	s_barrier
	s_waitcnt lgkmcnt(0)
	v_mfma_f32_16x16x32_bf16 v[124:127], v[148:151], v[180:183], v[124:127]
	v_mfma_f32_16x16x32_bf16 v[120:123], v[156:159], v[180:183], v[120:123]
	v_mfma_f32_16x16x32_bf16 v[116:119], v[148:151], v[192:195], v[116:119]
	v_mfma_f32_16x16x32_bf16 v[108:111], v[156:159], v[192:195], v[108:111]
	v_mfma_f32_16x16x32_bf16 v[100:103], v[148:151], v[200:203], v[100:103]
	v_mfma_f32_16x16x32_bf16 v[92:95], v[156:159], v[200:203], v[92:95]
	v_mfma_f32_16x16x32_bf16 v[84:87], v[148:151], v[208:211], v[84:87]
	v_mfma_f32_16x16x32_bf16 v[76:79], v[156:159], v[208:211], v[76:79]
	v_mfma_f32_16x16x32_bf16 v[124:127], v[152:155], v[184:187], v[124:127]
	v_mfma_f32_16x16x32_bf16 v[120:123], v[160:163], v[184:187], v[120:123]
	v_mfma_f32_16x16x32_bf16 v[116:119], v[152:155], v[196:199], v[116:119]
	v_mfma_f32_16x16x32_bf16 v[108:111], v[160:163], v[196:199], v[108:111]
	v_mfma_f32_16x16x32_bf16 v[100:103], v[152:155], v[204:207], v[100:103]
	v_mfma_f32_16x16x32_bf16 v[92:95], v[160:163], v[204:207], v[92:95]
	v_mfma_f32_16x16x32_bf16 v[84:87], v[152:155], v[212:215], v[84:87]
	v_mfma_f32_16x16x32_bf16 v[76:79], v[160:163], v[212:215], v[76:79]
	v_mfma_f32_16x16x32_bf16 v[112:115], v[164:167], v[180:183], v[112:115]
	v_mfma_f32_16x16x32_bf16 v[104:107], v[172:175], v[180:183], v[104:107]
	v_mfma_f32_16x16x32_bf16 v[96:99], v[164:167], v[192:195], v[96:99]
	v_mfma_f32_16x16x32_bf16 v[88:91], v[172:175], v[192:195], v[88:91]
	v_mfma_f32_16x16x32_bf16 v[80:83], v[164:167], v[200:203], v[80:83]
	v_mfma_f32_16x16x32_bf16 v[72:75], v[172:175], v[200:203], v[72:75]
	v_mfma_f32_16x16x32_bf16 v[68:71], v[164:167], v[208:211], v[68:71]
	v_mfma_f32_16x16x32_bf16 v[64:67], v[172:175], v[208:211], v[64:67]
	v_mfma_f32_16x16x32_bf16 v[112:115], v[168:171], v[184:187], v[112:115]
	v_mfma_f32_16x16x32_bf16 v[104:107], v[176:179], v[184:187], v[104:107]
	v_mfma_f32_16x16x32_bf16 v[96:99], v[168:171], v[196:199], v[96:99]
	v_mfma_f32_16x16x32_bf16 v[88:91], v[176:179], v[196:199], v[88:91]
	v_mfma_f32_16x16x32_bf16 v[80:83], v[168:171], v[204:207], v[80:83]
	v_mfma_f32_16x16x32_bf16 v[72:75], v[176:179], v[204:207], v[72:75]
	v_mfma_f32_16x16x32_bf16 v[68:71], v[168:171], v[212:215], v[68:71]
	v_mfma_f32_16x16x32_bf16 v[64:67], v[176:179], v[212:215], v[64:67]
	s_barrier
	s_mov_b32 m0, s89
	v_lshl_add_u64 v[140:141], v[140:141], 0, s[12:13]
	ds_read_b128 v[180:183], v147 offset:49152
	ds_read_b128 v[184:187], v147 offset:50176
	ds_read_b128 v[192:195], v147 offset:51200
	ds_read_b128 v[196:199], v147 offset:52224
	ds_read_b128 v[200:203], v147 offset:53248
	ds_read_b128 v[204:207], v147 offset:54272
	ds_read_b128 v[208:211], v147 offset:55296
	ds_read_b128 v[212:215], v147 offset:56320
	global_load_lds_dwordx4 v[140:141], off
	v_lshl_add_u64 v[140:141], v[188:189], 0, s[12:13]
	s_mov_b32 m0, s87
	s_nop 0
	global_load_lds_dwordx4 v[140:141], off
	s_mov_b32 m0, s88
	s_nop 0
	global_load_lds_dwordx4 v130, s[42:43]
	s_mov_b32 m0, s86
	s_nop 0
	global_load_lds_dwordx4 v134, s[42:43]
	v_lshl_add_u64 v[140:141], v[216:217], 0, s[12:13]
	s_mov_b32 m0, s77
	s_nop 0
	global_load_lds_dwordx4 v[140:141], off
	v_lshl_add_u64 v[140:141], v[218:219], 0, s[12:13]
	s_mov_b32 m0, s79
	s_nop 0
	global_load_lds_dwordx4 v[140:141], off
	s_waitcnt vmcnt(8)
	s_waitcnt lgkmcnt(0)
	s_barrier
	s_waitcnt lgkmcnt(0)
	v_mfma_f32_16x16x32_bf16 v[60:63], v[148:151], v[180:183], v[60:63]
	v_mfma_f32_16x16x32_bf16 v[56:59], v[156:159], v[180:183], v[56:59]
	v_mfma_f32_16x16x32_bf16 v[52:55], v[148:151], v[192:195], v[52:55]
	v_mfma_f32_16x16x32_bf16 v[44:47], v[156:159], v[192:195], v[44:47]
	v_mfma_f32_16x16x32_bf16 v[36:39], v[148:151], v[200:203], v[36:39]
	v_mfma_f32_16x16x32_bf16 v[28:31], v[156:159], v[200:203], v[28:31]
	v_mfma_f32_16x16x32_bf16 v[20:23], v[148:151], v[208:211], v[20:23]
	v_mfma_f32_16x16x32_bf16 v[12:15], v[156:159], v[208:211], v[12:15]
	v_mfma_f32_16x16x32_bf16 v[60:63], v[152:155], v[184:187], v[60:63]
	v_mfma_f32_16x16x32_bf16 v[56:59], v[160:163], v[184:187], v[56:59]
	v_mfma_f32_16x16x32_bf16 v[52:55], v[152:155], v[196:199], v[52:55]
	v_mfma_f32_16x16x32_bf16 v[44:47], v[160:163], v[196:199], v[44:47]
	v_mfma_f32_16x16x32_bf16 v[36:39], v[152:155], v[204:207], v[36:39]
	v_mfma_f32_16x16x32_bf16 v[28:31], v[160:163], v[204:207], v[28:31]
	v_mfma_f32_16x16x32_bf16 v[20:23], v[152:155], v[212:215], v[20:23]
	v_mfma_f32_16x16x32_bf16 v[12:15], v[160:163], v[212:215], v[12:15]
	v_mfma_f32_16x16x32_bf16 v[48:51], v[164:167], v[180:183], v[48:51]
	v_mfma_f32_16x16x32_bf16 v[40:43], v[172:175], v[180:183], v[40:43]
	v_mfma_f32_16x16x32_bf16 v[32:35], v[164:167], v[192:195], v[32:35]
	v_mfma_f32_16x16x32_bf16 v[24:27], v[172:175], v[192:195], v[24:27]
	v_mfma_f32_16x16x32_bf16 v[16:19], v[164:167], v[200:203], v[16:19]
	v_mfma_f32_16x16x32_bf16 v[8:11], v[172:175], v[200:203], v[8:11]
	v_mfma_f32_16x16x32_bf16 v[4:7], v[164:167], v[208:211], v[4:7]
	v_mfma_f32_16x16x32_bf16 v[0:3], v[172:175], v[208:211], v[0:3]
	v_mfma_f32_16x16x32_bf16 v[48:51], v[168:171], v[184:187], v[48:51]
	v_mfma_f32_16x16x32_bf16 v[40:43], v[176:179], v[184:187], v[40:43]
	v_mfma_f32_16x16x32_bf16 v[32:35], v[168:171], v[196:199], v[32:35]
	v_mfma_f32_16x16x32_bf16 v[24:27], v[176:179], v[196:199], v[24:27]
	v_mfma_f32_16x16x32_bf16 v[16:19], v[168:171], v[204:207], v[16:19]
	v_mfma_f32_16x16x32_bf16 v[8:11], v[176:179], v[204:207], v[8:11]
	v_mfma_f32_16x16x32_bf16 v[4:7], v[168:171], v[212:215], v[4:7]
	v_mfma_f32_16x16x32_bf16 v[0:3], v[176:179], v[212:215], v[0:3]
	s_barrier
	s_movk_i32 s60, 0x100
	s_andn2_b64 vcc, exec, s[34:35]
	s_mov_b64 s[42:43], -1
	s_mov_b64 s[34:35], 0
	s_cbranch_vccz .LBB0_1222

.LBB0_1245:
	s_ashr_i32 s21, s20, 31
	s_lshl_b64 s[22:23], s[20:21], 17
	s_add_u32 s22, s52, s22
	s_addc_u32 s23, s53, s23
	s_and_b64 s[24:25], s[0:1], exec
	s_cselect_b32 s21, s23, s31
	s_cselect_b32 s55, s22, s30
	s_ashr_i32 s19, s18, 31
	s_lshl_b64 s[24:25], s[18:19], 17
	s_add_u32 s24, s70, s24
	s_addc_u32 s25, s71, s25
	s_and_b64 s[34:35], s[0:1], exec
	s_cselect_b32 s19, s25, s29
	s_cselect_b32 s86, s24, s28
	s_mov_b32 s60, 0
	s_mov_b64 s[34:35], -1
	s_mov_b64 s[42:43], 0
	s_add_u32 s61, s30, s60
	s_addc_u32 s66, s31, 0
	s_add_u32 s64, s61, 0x100
	s_addc_u32 s65, s66, 0
	s_and_b64 s[62:63], s[42:43], exec
	s_cselect_b32 s63, s21, s65
	s_cselect_b32 s62, s55, s64
	s_add_u32 s60, s28, s60
	s_addc_u32 s64, s29, 0
	s_add_u32 s60, s60, 0x100
	s_addc_u32 s64, s64, 0
	s_and_b64 s[42:43], s[42:43], exec
	s_cselect_b32 s65, s19, s64
	s_cselect_b32 s64, s86, s60
	s_add_u32 s68, s61, 0x10080
	ds_read_b128 v[148:151], v145
	ds_read_b128 v[152:155], v145 offset:1024
	ds_read_b128 v[156:159], v145 offset:2048
	ds_read_b128 v[160:163], v145 offset:3072
	ds_read_b128 v[164:167], v146
	ds_read_b128 v[168:171], v146 offset:1024
	ds_read_b128 v[172:175], v146 offset:2048
	ds_read_b128 v[176:179], v146 offset:3072
	s_addc_u32 s69, s66, 0
	s_add_i32 s96, s81, s73
	s_add_i32 m0, s27, 0xc000
	s_add_i32 s97, s27, 0xe000
	s_add_i32 s93, s96, 0x2000
	s_add_u32 s66, s64, 0x10000
	s_addc_u32 s67, s65, 0
	s_add_i32 s95, s82, s73
	s_add_i32 s94, s95, 0x2000
	s_add_i32 s92, 0, 0x18000
	s_add_i32 s91, 0, 0x1c000
	s_add_u32 s60, s62, 0x10000
	s_addc_u32 s61, s63, 0
	s_add_i32 s90, s92, s73
	s_add_i32 s88, s90, 0x2000
	s_add_u32 s42, s64, 0x10080
	s_addc_u32 s43, s65, 0
	s_add_i32 s89, s91, s73
	s_add_i32 s87, s89, 0x2000
	ds_read_b128 v[180:183], v147
	ds_read_b128 v[184:187], v147 offset:1024
	ds_read_b128 v[192:195], v147 offset:2048
	ds_read_b128 v[196:199], v147 offset:3072
	ds_read_b128 v[200:203], v147 offset:4096
	ds_read_b128 v[204:207], v147 offset:5120
	ds_read_b128 v[208:211], v147 offset:6144
	ds_read_b128 v[212:215], v147 offset:7168
	global_load_lds_dwordx4 v128, s[68:69]
	s_mov_b32 m0, s97
	s_nop 0
	global_load_lds_dwordx4 v132, s[68:69]
	s_waitcnt vmcnt(8)
	s_waitcnt lgkmcnt(0)
	s_barrier
	s_waitcnt lgkmcnt(0)
	v_mfma_f32_16x16x32_bf16 v[124:127], v[148:151], v[180:183], 0
	v_mfma_f32_16x16x32_bf16 v[120:123], v[156:159], v[180:183], 0
	v_mfma_f32_16x16x32_bf16 v[116:119], v[148:151], v[192:195], 0
	v_mfma_f32_16x16x32_bf16 v[108:111], v[156:159], v[192:195], 0
	v_mfma_f32_16x16x32_bf16 v[100:103], v[148:151], v[200:203], 0
	v_mfma_f32_16x16x32_bf16 v[92:95], v[156:159], v[200:203], 0
	v_mfma_f32_16x16x32_bf16 v[84:87], v[148:151], v[208:211], 0
	v_mfma_f32_16x16x32_bf16 v[76:79], v[156:159], v[208:211], 0
	v_mfma_f32_16x16x32_bf16 v[124:127], v[152:155], v[184:187], v[124:127]
	v_mfma_f32_16x16x32_bf16 v[120:123], v[160:163], v[184:187], v[120:123]
	v_mfma_f32_16x16x32_bf16 v[116:119], v[152:155], v[196:199], v[116:119]
	v_mfma_f32_16x16x32_bf16 v[108:111], v[160:163], v[196:199], v[108:111]
	v_mfma_f32_16x16x32_bf16 v[100:103], v[152:155], v[204:207], v[100:103]
	v_mfma_f32_16x16x32_bf16 v[92:95], v[160:163], v[204:207], v[92:95]
	v_mfma_f32_16x16x32_bf16 v[84:87], v[152:155], v[212:215], v[84:87]
	v_mfma_f32_16x16x32_bf16 v[76:79], v[160:163], v[212:215], v[76:79]
	v_mfma_f32_16x16x32_bf16 v[112:115], v[164:167], v[180:183], 0
	v_mfma_f32_16x16x32_bf16 v[104:107], v[172:175], v[180:183], 0
	v_mfma_f32_16x16x32_bf16 v[96:99], v[164:167], v[192:195], 0
	v_mfma_f32_16x16x32_bf16 v[88:91], v[172:175], v[192:195], 0
	v_mfma_f32_16x16x32_bf16 v[80:83], v[164:167], v[200:203], 0
	v_mfma_f32_16x16x32_bf16 v[72:75], v[172:175], v[200:203], 0
	v_mfma_f32_16x16x32_bf16 v[68:71], v[164:167], v[208:211], 0
	v_mfma_f32_16x16x32_bf16 v[64:67], v[172:175], v[208:211], 0
	v_mfma_f32_16x16x32_bf16 v[112:115], v[168:171], v[184:187], v[112:115]
	v_mfma_f32_16x16x32_bf16 v[104:107], v[176:179], v[184:187], v[104:107]
	v_mfma_f32_16x16x32_bf16 v[96:99], v[168:171], v[196:199], v[96:99]
	v_mfma_f32_16x16x32_bf16 v[88:91], v[176:179], v[196:199], v[88:91]
	v_mfma_f32_16x16x32_bf16 v[80:83], v[168:171], v[204:207], v[80:83]
	v_mfma_f32_16x16x32_bf16 v[72:75], v[176:179], v[204:207], v[72:75]
	v_mfma_f32_16x16x32_bf16 v[68:71], v[168:171], v[212:215], v[68:71]
	v_mfma_f32_16x16x32_bf16 v[64:67], v[176:179], v[212:215], v[64:67]
	s_barrier
	s_mov_b32 m0, s96
	v_lshl_add_u64 v[140:141], s[64:65], 0, v[130:131]
	ds_read_b128 v[180:183], v147 offset:16384
	ds_read_b128 v[184:187], v147 offset:17408
	ds_read_b128 v[192:195], v147 offset:18432
	ds_read_b128 v[196:199], v147 offset:19456
	ds_read_b128 v[200:203], v147 offset:20480
	ds_read_b128 v[204:207], v147 offset:21504
	ds_read_b128 v[208:211], v147 offset:22528
	ds_read_b128 v[212:215], v147 offset:23552
	global_load_lds_dwordx4 v[140:141], off
	v_lshl_add_u64 v[188:189], s[64:65], 0, v[134:135]
	s_mov_b32 m0, s93
	s_nop 0
	global_load_lds_dwordx4 v[188:189], off
	s_mov_b32 m0, s95
	v_lshl_add_u64 v[218:219], s[62:63], 0, v[132:133]
	global_load_lds_dwordx4 v130, s[66:67]
	s_mov_b32 m0, s94
	s_nop 0
	global_load_lds_dwordx4 v134, s[66:67]
	v_lshl_add_u64 v[216:217], s[62:63], 0, v[128:129]
	s_mov_b32 m0, s27
	s_nop 0
	global_load_lds_dwordx4 v[216:217], off
	s_mov_b32 m0, s33
	s_nop 0
	global_load_lds_dwordx4 v[218:219], off
	s_waitcnt vmcnt(8)
	s_waitcnt lgkmcnt(0)
	s_barrier
	s_waitcnt lgkmcnt(0)
	v_mfma_f32_16x16x32_bf16 v[60:63], v[148:151], v[180:183], 0
	v_mfma_f32_16x16x32_bf16 v[56:59], v[156:159], v[180:183], 0
	v_mfma_f32_16x16x32_bf16 v[52:55], v[148:151], v[192:195], 0
	v_mfma_f32_16x16x32_bf16 v[44:47], v[156:159], v[192:195], 0
	v_mfma_f32_16x16x32_bf16 v[36:39], v[148:151], v[200:203], 0
	v_mfma_f32_16x16x32_bf16 v[28:31], v[156:159], v[200:203], 0
	v_mfma_f32_16x16x32_bf16 v[20:23], v[148:151], v[208:211], 0
	v_mfma_f32_16x16x32_bf16 v[12:15], v[156:159], v[208:211], 0
	v_mfma_f32_16x16x32_bf16 v[60:63], v[152:155], v[184:187], v[60:63]
	v_mfma_f32_16x16x32_bf16 v[56:59], v[160:163], v[184:187], v[56:59]
	v_mfma_f32_16x16x32_bf16 v[52:55], v[152:155], v[196:199], v[52:55]
	v_mfma_f32_16x16x32_bf16 v[44:47], v[160:163], v[196:199], v[44:47]
	v_mfma_f32_16x16x32_bf16 v[36:39], v[152:155], v[204:207], v[36:39]
	v_mfma_f32_16x16x32_bf16 v[28:31], v[160:163], v[204:207], v[28:31]
	v_mfma_f32_16x16x32_bf16 v[20:23], v[152:155], v[212:215], v[20:23]
	v_mfma_f32_16x16x32_bf16 v[12:15], v[160:163], v[212:215], v[12:15]
	v_mfma_f32_16x16x32_bf16 v[48:51], v[164:167], v[180:183], 0
	v_mfma_f32_16x16x32_bf16 v[40:43], v[172:175], v[180:183], 0
	v_mfma_f32_16x16x32_bf16 v[32:35], v[164:167], v[192:195], 0
	v_mfma_f32_16x16x32_bf16 v[24:27], v[172:175], v[192:195], 0
	v_mfma_f32_16x16x32_bf16 v[16:19], v[164:167], v[200:203], 0
	v_mfma_f32_16x16x32_bf16 v[8:11], v[172:175], v[200:203], 0
	v_mfma_f32_16x16x32_bf16 v[4:7], v[164:167], v[208:211], 0
	v_mfma_f32_16x16x32_bf16 v[0:3], v[172:175], v[208:211], 0
	v_mfma_f32_16x16x32_bf16 v[48:51], v[168:171], v[184:187], v[48:51]
	v_mfma_f32_16x16x32_bf16 v[40:43], v[176:179], v[184:187], v[40:43]
	v_mfma_f32_16x16x32_bf16 v[32:35], v[168:171], v[196:199], v[32:35]
	v_mfma_f32_16x16x32_bf16 v[24:27], v[176:179], v[196:199], v[24:27]
	v_mfma_f32_16x16x32_bf16 v[16:19], v[168:171], v[204:207], v[16:19]
	v_mfma_f32_16x16x32_bf16 v[8:11], v[176:179], v[204:207], v[8:11]
	v_mfma_f32_16x16x32_bf16 v[4:7], v[168:171], v[212:215], v[4:7]
	v_mfma_f32_16x16x32_bf16 v[0:3], v[176:179], v[212:215], v[0:3]
	s_barrier
	v_add_u32_e32 v160, s92, v143
	v_add_u32_e32 v176, s91, v143
	ds_read_b128 v[148:151], v160
	ds_read_b128 v[152:155], v160 offset:1024
	ds_read_b128 v[156:159], v160 offset:2048
	ds_read_b128 v[160:163], v160 offset:3072
	ds_read_b128 v[164:167], v176
	ds_read_b128 v[168:171], v176 offset:1024
	ds_read_b128 v[172:175], v176 offset:2048
	ds_read_b128 v[176:179], v176 offset:3072
	s_mov_b32 m0, s74
	ds_read_b128 v[180:183], v147 offset:32768
	ds_read_b128 v[184:187], v147 offset:33792
	ds_read_b128 v[192:195], v147 offset:34816
	ds_read_b128 v[196:199], v147 offset:35840
	ds_read_b128 v[200:203], v147 offset:36864
	ds_read_b128 v[204:207], v147 offset:37888
	ds_read_b128 v[208:211], v147 offset:38912
	ds_read_b128 v[212:215], v147 offset:39936
	global_load_lds_dwordx4 v128, s[60:61]
	s_mov_b32 m0, s75
	s_nop 0
	global_load_lds_dwordx4 v132, s[60:61]
	s_waitcnt vmcnt(8)
	s_waitcnt lgkmcnt(0)
	s_barrier
	s_waitcnt lgkmcnt(0)
	v_mfma_f32_16x16x32_bf16 v[124:127], v[148:151], v[180:183], v[124:127]
	v_mfma_f32_16x16x32_bf16 v[120:123], v[156:159], v[180:183], v[120:123]
	v_mfma_f32_16x16x32_bf16 v[116:119], v[148:151], v[192:195], v[116:119]
	v_mfma_f32_16x16x32_bf16 v[108:111], v[156:159], v[192:195], v[108:111]
	v_mfma_f32_16x16x32_bf16 v[100:103], v[148:151], v[200:203], v[100:103]
	v_mfma_f32_16x16x32_bf16 v[92:95], v[156:159], v[200:203], v[92:95]
	v_mfma_f32_16x16x32_bf16 v[84:87], v[148:151], v[208:211], v[84:87]
	v_mfma_f32_16x16x32_bf16 v[76:79], v[156:159], v[208:211], v[76:79]
	v_mfma_f32_16x16x32_bf16 v[124:127], v[152:155], v[184:187], v[124:127]
	v_mfma_f32_16x16x32_bf16 v[120:123], v[160:163], v[184:187], v[120:123]
	v_mfma_f32_16x16x32_bf16 v[116:119], v[152:155], v[196:199], v[116:119]
	v_mfma_f32_16x16x32_bf16 v[108:111], v[160:163], v[196:199], v[108:111]
	v_mfma_f32_16x16x32_bf16 v[100:103], v[152:155], v[204:207], v[100:103]
	v_mfma_f32_16x16x32_bf16 v[92:95], v[160:163], v[204:207], v[92:95]
	v_mfma_f32_16x16x32_bf16 v[84:87], v[152:155], v[212:215], v[84:87]
	v_mfma_f32_16x16x32_bf16 v[76:79], v[160:163], v[212:215], v[76:79]
	v_mfma_f32_16x16x32_bf16 v[112:115], v[164:167], v[180:183], v[112:115]
	v_mfma_f32_16x16x32_bf16 v[104:107], v[172:175], v[180:183], v[104:107]
	v_mfma_f32_16x16x32_bf16 v[96:99], v[164:167], v[192:195], v[96:99]
	v_mfma_f32_16x16x32_bf16 v[88:91], v[172:175], v[192:195], v[88:91]
	v_mfma_f32_16x16x32_bf16 v[80:83], v[164:167], v[200:203], v[80:83]
	v_mfma_f32_16x16x32_bf16 v[72:75], v[172:175], v[200:203], v[72:75]
	v_mfma_f32_16x16x32_bf16 v[68:71], v[164:167], v[208:211], v[68:71]
	v_mfma_f32_16x16x32_bf16 v[64:67], v[172:175], v[208:211], v[64:67]
	v_mfma_f32_16x16x32_bf16 v[112:115], v[168:171], v[184:187], v[112:115]
	v_mfma_f32_16x16x32_bf16 v[104:107], v[176:179], v[184:187], v[104:107]
	v_mfma_f32_16x16x32_bf16 v[96:99], v[168:171], v[196:199], v[96:99]
	v_mfma_f32_16x16x32_bf16 v[88:91], v[176:179], v[196:199], v[88:91]
	v_mfma_f32_16x16x32_bf16 v[80:83], v[168:171], v[204:207], v[80:83]
	v_mfma_f32_16x16x32_bf16 v[72:75], v[176:179], v[204:207], v[72:75]
	v_mfma_f32_16x16x32_bf16 v[68:71], v[168:171], v[212:215], v[68:71]
	v_mfma_f32_16x16x32_bf16 v[64:67], v[176:179], v[212:215], v[64:67]
	s_barrier
	s_mov_b32 m0, s90
	v_lshl_add_u64 v[140:141], v[140:141], 0, s[10:11]
	ds_read_b128 v[180:183], v147 offset:49152
	ds_read_b128 v[184:187], v147 offset:50176
	ds_read_b128 v[192:195], v147 offset:51200
	ds_read_b128 v[196:199], v147 offset:52224
	ds_read_b128 v[200:203], v147 offset:53248
	ds_read_b128 v[204:207], v147 offset:54272
	ds_read_b128 v[208:211], v147 offset:55296
	ds_read_b128 v[212:215], v147 offset:56320
	global_load_lds_dwordx4 v[140:141], off
	v_lshl_add_u64 v[140:141], v[188:189], 0, s[10:11]
	s_mov_b32 m0, s88
	s_nop 0
	global_load_lds_dwordx4 v[140:141], off
	s_mov_b32 m0, s89
	s_nop 0
	global_load_lds_dwordx4 v130, s[42:43]
	s_mov_b32 m0, s87
	s_nop 0
	global_load_lds_dwordx4 v134, s[42:43]
	v_lshl_add_u64 v[140:141], v[216:217], 0, s[10:11]
	s_mov_b32 m0, s77
	s_nop 0
	global_load_lds_dwordx4 v[140:141], off
	v_lshl_add_u64 v[140:141], v[218:219], 0, s[10:11]
	s_mov_b32 m0, s79
	s_nop 0
	global_load_lds_dwordx4 v[140:141], off
	s_waitcnt vmcnt(8)
	s_waitcnt lgkmcnt(0)
	s_barrier
	s_waitcnt lgkmcnt(0)
	v_mfma_f32_16x16x32_bf16 v[60:63], v[148:151], v[180:183], v[60:63]
	v_mfma_f32_16x16x32_bf16 v[56:59], v[156:159], v[180:183], v[56:59]
	v_mfma_f32_16x16x32_bf16 v[52:55], v[148:151], v[192:195], v[52:55]
	v_mfma_f32_16x16x32_bf16 v[44:47], v[156:159], v[192:195], v[44:47]
	v_mfma_f32_16x16x32_bf16 v[36:39], v[148:151], v[200:203], v[36:39]
	v_mfma_f32_16x16x32_bf16 v[28:31], v[156:159], v[200:203], v[28:31]
	v_mfma_f32_16x16x32_bf16 v[20:23], v[148:151], v[208:211], v[20:23]
	v_mfma_f32_16x16x32_bf16 v[12:15], v[156:159], v[208:211], v[12:15]
	v_mfma_f32_16x16x32_bf16 v[60:63], v[152:155], v[184:187], v[60:63]
	v_mfma_f32_16x16x32_bf16 v[56:59], v[160:163], v[184:187], v[56:59]
	v_mfma_f32_16x16x32_bf16 v[52:55], v[152:155], v[196:199], v[52:55]
	v_mfma_f32_16x16x32_bf16 v[44:47], v[160:163], v[196:199], v[44:47]
	v_mfma_f32_16x16x32_bf16 v[36:39], v[152:155], v[204:207], v[36:39]
	v_mfma_f32_16x16x32_bf16 v[28:31], v[160:163], v[204:207], v[28:31]
	v_mfma_f32_16x16x32_bf16 v[20:23], v[152:155], v[212:215], v[20:23]
	v_mfma_f32_16x16x32_bf16 v[12:15], v[160:163], v[212:215], v[12:15]
	v_mfma_f32_16x16x32_bf16 v[48:51], v[164:167], v[180:183], v[48:51]
	v_mfma_f32_16x16x32_bf16 v[40:43], v[172:175], v[180:183], v[40:43]
	v_mfma_f32_16x16x32_bf16 v[32:35], v[164:167], v[192:195], v[32:35]
	v_mfma_f32_16x16x32_bf16 v[24:27], v[172:175], v[192:195], v[24:27]
	v_mfma_f32_16x16x32_bf16 v[16:19], v[164:167], v[200:203], v[16:19]
	v_mfma_f32_16x16x32_bf16 v[8:11], v[172:175], v[200:203], v[8:11]
	v_mfma_f32_16x16x32_bf16 v[4:7], v[164:167], v[208:211], v[4:7]
	v_mfma_f32_16x16x32_bf16 v[0:3], v[172:175], v[208:211], v[0:3]
	v_mfma_f32_16x16x32_bf16 v[48:51], v[168:171], v[184:187], v[48:51]
	v_mfma_f32_16x16x32_bf16 v[40:43], v[176:179], v[184:187], v[40:43]
	v_mfma_f32_16x16x32_bf16 v[32:35], v[168:171], v[196:199], v[32:35]
	v_mfma_f32_16x16x32_bf16 v[24:27], v[176:179], v[196:199], v[24:27]
	v_mfma_f32_16x16x32_bf16 v[16:19], v[168:171], v[204:207], v[16:19]
	v_mfma_f32_16x16x32_bf16 v[8:11], v[176:179], v[204:207], v[8:11]
	v_mfma_f32_16x16x32_bf16 v[4:7], v[168:171], v[212:215], v[4:7]
	v_mfma_f32_16x16x32_bf16 v[0:3], v[176:179], v[212:215], v[0:3]
	s_barrier
	s_movk_i32 s60, 0x100
	s_andn2_b64 vcc, exec, s[34:35]
	s_mov_b64 s[42:43], -1
	s_mov_b64 s[34:35], 0
	s_cbranch_vccz .LBB0_1246
	s_branch .Lpeel_exit8
.LBB0_1246:
	s_add_u32 s61, s30, s60
	s_addc_u32 s66, s31, 0
	s_add_u32 s64, s61, 0x100
	s_addc_u32 s65, s66, 0
	s_and_b64 s[62:63], s[42:43], exec
	s_cselect_b32 s63, s21, s65
	s_cselect_b32 s62, s55, s64
	s_add_u32 s60, s28, s60
	s_addc_u32 s64, s29, 0
	s_add_u32 s60, s60, 0x100
	s_addc_u32 s64, s64, 0
	s_and_b64 s[42:43], s[42:43], exec
	s_cselect_b32 s65, s19, s64
	s_cselect_b32 s64, s86, s60
	s_add_u32 s68, s61, 0x10080
	ds_read_b128 v[148:151], v145
	ds_read_b128 v[152:155], v145 offset:1024
	ds_read_b128 v[156:159], v145 offset:2048
	ds_read_b128 v[160:163], v145 offset:3072
	ds_read_b128 v[164:167], v146
	ds_read_b128 v[168:171], v146 offset:1024
	ds_read_b128 v[172:175], v146 offset:2048
	ds_read_b128 v[176:179], v146 offset:3072
	s_addc_u32 s69, s66, 0
	s_add_i32 s96, s81, s73
	s_add_i32 m0, s27, 0xc000
	s_add_i32 s97, s27, 0xe000
	s_add_i32 s93, s96, 0x2000
	s_add_u32 s66, s64, 0x10000
	s_addc_u32 s67, s65, 0
	s_add_i32 s95, s82, s73
	s_add_i32 s94, s95, 0x2000
	s_add_i32 s92, 0, 0x18000
	s_add_i32 s91, 0, 0x1c000
	s_add_u32 s60, s62, 0x10000
	s_addc_u32 s61, s63, 0
	s_add_i32 s90, s92, s73
	s_add_i32 s88, s90, 0x2000
	s_add_u32 s42, s64, 0x10080
	s_addc_u32 s43, s65, 0
	s_add_i32 s89, s91, s73
	s_add_i32 s87, s89, 0x2000
	ds_read_b128 v[180:183], v147
	ds_read_b128 v[184:187], v147 offset:1024
	ds_read_b128 v[192:195], v147 offset:2048
	ds_read_b128 v[196:199], v147 offset:3072
	ds_read_b128 v[200:203], v147 offset:4096
	ds_read_b128 v[204:207], v147 offset:5120
	ds_read_b128 v[208:211], v147 offset:6144
	ds_read_b128 v[212:215], v147 offset:7168
	global_load_lds_dwordx4 v128, s[68:69]
	s_mov_b32 m0, s97
	s_nop 0
	global_load_lds_dwordx4 v132, s[68:69]
	s_waitcnt vmcnt(8)
	s_waitcnt lgkmcnt(0)
	s_barrier
	s_waitcnt lgkmcnt(0)
	v_mfma_f32_16x16x32_bf16 v[124:127], v[148:151], v[180:183], v[124:127]
	v_mfma_f32_16x16x32_bf16 v[120:123], v[156:159], v[180:183], v[120:123]
	v_mfma_f32_16x16x32_bf16 v[116:119], v[148:151], v[192:195], v[116:119]
	v_mfma_f32_16x16x32_bf16 v[108:111], v[156:159], v[192:195], v[108:111]
	v_mfma_f32_16x16x32_bf16 v[100:103], v[148:151], v[200:203], v[100:103]
	v_mfma_f32_16x16x32_bf16 v[92:95], v[156:159], v[200:203], v[92:95]
	v_mfma_f32_16x16x32_bf16 v[84:87], v[148:151], v[208:211], v[84:87]
	v_mfma_f32_16x16x32_bf16 v[76:79], v[156:159], v[208:211], v[76:79]
	v_mfma_f32_16x16x32_bf16 v[124:127], v[152:155], v[184:187], v[124:127]
	v_mfma_f32_16x16x32_bf16 v[120:123], v[160:163], v[184:187], v[120:123]
	v_mfma_f32_16x16x32_bf16 v[116:119], v[152:155], v[196:199], v[116:119]
	v_mfma_f32_16x16x32_bf16 v[108:111], v[160:163], v[196:199], v[108:111]
	v_mfma_f32_16x16x32_bf16 v[100:103], v[152:155], v[204:207], v[100:103]
	v_mfma_f32_16x16x32_bf16 v[92:95], v[160:163], v[204:207], v[92:95]
	v_mfma_f32_16x16x32_bf16 v[84:87], v[152:155], v[212:215], v[84:87]
	v_mfma_f32_16x16x32_bf16 v[76:79], v[160:163], v[212:215], v[76:79]
	v_mfma_f32_16x16x32_bf16 v[112:115], v[164:167], v[180:183], v[112:115]
	v_mfma_f32_16x16x32_bf16 v[104:107], v[172:175], v[180:183], v[104:107]
	v_mfma_f32_16x16x32_bf16 v[96:99], v[164:167], v[192:195], v[96:99]
	v_mfma_f32_16x16x32_bf16 v[88:91], v[172:175], v[192:195], v[88:91]
	v_mfma_f32_16x16x32_bf16 v[80:83], v[164:167], v[200:203], v[80:83]
	v_mfma_f32_16x16x32_bf16 v[72:75], v[172:175], v[200:203], v[72:75]
	v_mfma_f32_16x16x32_bf16 v[68:71], v[164:167], v[208:211], v[68:71]
	v_mfma_f32_16x16x32_bf16 v[64:67], v[172:175], v[208:211], v[64:67]
	v_mfma_f32_16x16x32_bf16 v[112:115], v[168:171], v[184:187], v[112:115]
	v_mfma_f32_16x16x32_bf16 v[104:107], v[176:179], v[184:187], v[104:107]
	v_mfma_f32_16x16x32_bf16 v[96:99], v[168:171], v[196:199], v[96:99]
	v_mfma_f32_16x16x32_bf16 v[88:91], v[176:179], v[196:199], v[88:91]
	v_mfma_f32_16x16x32_bf16 v[80:83], v[168:171], v[204:207], v[80:83]
	v_mfma_f32_16x16x32_bf16 v[72:75], v[176:179], v[204:207], v[72:75]
	v_mfma_f32_16x16x32_bf16 v[68:71], v[168:171], v[212:215], v[68:71]
	v_mfma_f32_16x16x32_bf16 v[64:67], v[176:179], v[212:215], v[64:67]
	s_barrier
	s_mov_b32 m0, s96
	v_lshl_add_u64 v[140:141], s[64:65], 0, v[130:131]
	ds_read_b128 v[180:183], v147 offset:16384
	ds_read_b128 v[184:187], v147 offset:17408
	ds_read_b128 v[192:195], v147 offset:18432
	ds_read_b128 v[196:199], v147 offset:19456
	ds_read_b128 v[200:203], v147 offset:20480
	ds_read_b128 v[204:207], v147 offset:21504
	ds_read_b128 v[208:211], v147 offset:22528
	ds_read_b128 v[212:215], v147 offset:23552
	global_load_lds_dwordx4 v[140:141], off
	v_lshl_add_u64 v[188:189], s[64:65], 0, v[134:135]
	s_mov_b32 m0, s93
	s_nop 0
	global_load_lds_dwordx4 v[188:189], off
	s_mov_b32 m0, s95
	v_lshl_add_u64 v[218:219], s[62:63], 0, v[132:133]
	global_load_lds_dwordx4 v130, s[66:67]
	s_mov_b32 m0, s94
	s_nop 0
	global_load_lds_dwordx4 v134, s[66:67]
	v_lshl_add_u64 v[216:217], s[62:63], 0, v[128:129]
	s_mov_b32 m0, s27
	s_nop 0
	global_load_lds_dwordx4 v[216:217], off
	s_mov_b32 m0, s33
	s_nop 0
	global_load_lds_dwordx4 v[218:219], off
	s_waitcnt vmcnt(8)
	s_waitcnt lgkmcnt(0)
	s_barrier
	s_waitcnt lgkmcnt(0)
	v_mfma_f32_16x16x32_bf16 v[60:63], v[148:151], v[180:183], v[60:63]
	v_mfma_f32_16x16x32_bf16 v[56:59], v[156:159], v[180:183], v[56:59]
	v_mfma_f32_16x16x32_bf16 v[52:55], v[148:151], v[192:195], v[52:55]
	v_mfma_f32_16x16x32_bf16 v[44:47], v[156:159], v[192:195], v[44:47]
	v_mfma_f32_16x16x32_bf16 v[36:39], v[148:151], v[200:203], v[36:39]
	v_mfma_f32_16x16x32_bf16 v[28:31], v[156:159], v[200:203], v[28:31]
	v_mfma_f32_16x16x32_bf16 v[20:23], v[148:151], v[208:211], v[20:23]
	v_mfma_f32_16x16x32_bf16 v[12:15], v[156:159], v[208:211], v[12:15]
	v_mfma_f32_16x16x32_bf16 v[60:63], v[152:155], v[184:187], v[60:63]
	v_mfma_f32_16x16x32_bf16 v[56:59], v[160:163], v[184:187], v[56:59]
	v_mfma_f32_16x16x32_bf16 v[52:55], v[152:155], v[196:199], v[52:55]
	v_mfma_f32_16x16x32_bf16 v[44:47], v[160:163], v[196:199], v[44:47]
	v_mfma_f32_16x16x32_bf16 v[36:39], v[152:155], v[204:207], v[36:39]
	v_mfma_f32_16x16x32_bf16 v[28:31], v[160:163], v[204:207], v[28:31]
	v_mfma_f32_16x16x32_bf16 v[20:23], v[152:155], v[212:215], v[20:23]
	v_mfma_f32_16x16x32_bf16 v[12:15], v[160:163], v[212:215], v[12:15]
	v_mfma_f32_16x16x32_bf16 v[48:51], v[164:167], v[180:183], v[48:51]
	v_mfma_f32_16x16x32_bf16 v[40:43], v[172:175], v[180:183], v[40:43]
	v_mfma_f32_16x16x32_bf16 v[32:35], v[164:167], v[192:195], v[32:35]
	v_mfma_f32_16x16x32_bf16 v[24:27], v[172:175], v[192:195], v[24:27]
	v_mfma_f32_16x16x32_bf16 v[16:19], v[164:167], v[200:203], v[16:19]
	v_mfma_f32_16x16x32_bf16 v[8:11], v[172:175], v[200:203], v[8:11]
	v_mfma_f32_16x16x32_bf16 v[4:7], v[164:167], v[208:211], v[4:7]
	v_mfma_f32_16x16x32_bf16 v[0:3], v[172:175], v[208:211], v[0:3]
	v_mfma_f32_16x16x32_bf16 v[48:51], v[168:171], v[184:187], v[48:51]
	v_mfma_f32_16x16x32_bf16 v[40:43], v[176:179], v[184:187], v[40:43]
	v_mfma_f32_16x16x32_bf16 v[32:35], v[168:171], v[196:199], v[32:35]
	v_mfma_f32_16x16x32_bf16 v[24:27], v[176:179], v[196:199], v[24:27]
	v_mfma_f32_16x16x32_bf16 v[16:19], v[168:171], v[204:207], v[16:19]
	v_mfma_f32_16x16x32_bf16 v[8:11], v[176:179], v[204:207], v[8:11]
	v_mfma_f32_16x16x32_bf16 v[4:7], v[168:171], v[212:215], v[4:7]
	v_mfma_f32_16x16x32_bf16 v[0:3], v[176:179], v[212:215], v[0:3]
	s_barrier
	v_add_u32_e32 v160, s92, v143
	v_add_u32_e32 v176, s91, v143
	ds_read_b128 v[148:151], v160
	ds_read_b128 v[152:155], v160 offset:1024
	ds_read_b128 v[156:159], v160 offset:2048
	ds_read_b128 v[160:163], v160 offset:3072
	ds_read_b128 v[164:167], v176
	ds_read_b128 v[168:171], v176 offset:1024
	ds_read_b128 v[172:175], v176 offset:2048
	ds_read_b128 v[176:179], v176 offset:3072
	s_mov_b32 m0, s74
	ds_read_b128 v[180:183], v147 offset:32768
	ds_read_b128 v[184:187], v147 offset:33792
	ds_read_b128 v[192:195], v147 offset:34816
	ds_read_b128 v[196:199], v147 offset:35840
	ds_read_b128 v[200:203], v147 offset:36864
	ds_read_b128 v[204:207], v147 offset:37888
	ds_read_b128 v[208:211], v147 offset:38912
	ds_read_b128 v[212:215], v147 offset:39936
	global_load_lds_dwordx4 v128, s[60:61]
	s_mov_b32 m0, s75
	s_nop 0
	global_load_lds_dwordx4 v132, s[60:61]
	s_waitcnt vmcnt(8)
	s_waitcnt lgkmcnt(0)
	s_barrier
	s_waitcnt lgkmcnt(0)
	v_mfma_f32_16x16x32_bf16 v[124:127], v[148:151], v[180:183], v[124:127]
	v_mfma_f32_16x16x32_bf16 v[120:123], v[156:159], v[180:183], v[120:123]
	v_mfma_f32_16x16x32_bf16 v[116:119], v[148:151], v[192:195], v[116:119]
	v_mfma_f32_16x16x32_bf16 v[108:111], v[156:159], v[192:195], v[108:111]
	v_mfma_f32_16x16x32_bf16 v[100:103], v[148:151], v[200:203], v[100:103]
	v_mfma_f32_16x16x32_bf16 v[92:95], v[156:159], v[200:203], v[92:95]
	v_mfma_f32_16x16x32_bf16 v[84:87], v[148:151], v[208:211], v[84:87]
	v_mfma_f32_16x16x32_bf16 v[76:79], v[156:159], v[208:211], v[76:79]
	v_mfma_f32_16x16x32_bf16 v[124:127], v[152:155], v[184:187], v[124:127]
	v_mfma_f32_16x16x32_bf16 v[120:123], v[160:163], v[184:187], v[120:123]
	v_mfma_f32_16x16x32_bf16 v[116:119], v[152:155], v[196:199], v[116:119]
	v_mfma_f32_16x16x32_bf16 v[108:111], v[160:163], v[196:199], v[108:111]
	v_mfma_f32_16x16x32_bf16 v[100:103], v[152:155], v[204:207], v[100:103]
	v_mfma_f32_16x16x32_bf16 v[92:95], v[160:163], v[204:207], v[92:95]
	v_mfma_f32_16x16x32_bf16 v[84:87], v[152:155], v[212:215], v[84:87]
	v_mfma_f32_16x16x32_bf16 v[76:79], v[160:163], v[212:215], v[76:79]
	v_mfma_f32_16x16x32_bf16 v[112:115], v[164:167], v[180:183], v[112:115]
	v_mfma_f32_16x16x32_bf16 v[104:107], v[172:175], v[180:183], v[104:107]
	v_mfma_f32_16x16x32_bf16 v[96:99], v[164:167], v[192:195], v[96:99]
	v_mfma_f32_16x16x32_bf16 v[88:91], v[172:175], v[192:195], v[88:91]
	v_mfma_f32_16x16x32_bf16 v[80:83], v[164:167], v[200:203], v[80:83]
	v_mfma_f32_16x16x32_bf16 v[72:75], v[172:175], v[200:203], v[72:75]
	v_mfma_f32_16x16x32_bf16 v[68:71], v[164:167], v[208:211], v[68:71]
	v_mfma_f32_16x16x32_bf16 v[64:67], v[172:175], v[208:211], v[64:67]
	v_mfma_f32_16x16x32_bf16 v[112:115], v[168:171], v[184:187], v[112:115]
	v_mfma_f32_16x16x32_bf16 v[104:107], v[176:179], v[184:187], v[104:107]
	v_mfma_f32_16x16x32_bf16 v[96:99], v[168:171], v[196:199], v[96:99]
	v_mfma_f32_16x16x32_bf16 v[88:91], v[176:179], v[196:199], v[88:91]
	v_mfma_f32_16x16x32_bf16 v[80:83], v[168:171], v[204:207], v[80:83]
	v_mfma_f32_16x16x32_bf16 v[72:75], v[176:179], v[204:207], v[72:75]
	v_mfma_f32_16x16x32_bf16 v[68:71], v[168:171], v[212:215], v[68:71]
	v_mfma_f32_16x16x32_bf16 v[64:67], v[176:179], v[212:215], v[64:67]
	s_barrier
	s_mov_b32 m0, s90
	v_lshl_add_u64 v[140:141], v[140:141], 0, s[10:11]
	ds_read_b128 v[180:183], v147 offset:49152
	ds_read_b128 v[184:187], v147 offset:50176
	ds_read_b128 v[192:195], v147 offset:51200
	ds_read_b128 v[196:199], v147 offset:52224
	ds_read_b128 v[200:203], v147 offset:53248
	ds_read_b128 v[204:207], v147 offset:54272
	ds_read_b128 v[208:211], v147 offset:55296
	ds_read_b128 v[212:215], v147 offset:56320
	global_load_lds_dwordx4 v[140:141], off
	v_lshl_add_u64 v[140:141], v[188:189], 0, s[10:11]
	s_mov_b32 m0, s88
	s_nop 0
	global_load_lds_dwordx4 v[140:141], off
	s_mov_b32 m0, s89
	s_nop 0
	global_load_lds_dwordx4 v130, s[42:43]
	s_mov_b32 m0, s87
	s_nop 0
	global_load_lds_dwordx4 v134, s[42:43]
	v_lshl_add_u64 v[140:141], v[216:217], 0, s[10:11]
	s_mov_b32 m0, s77
	s_nop 0
	global_load_lds_dwordx4 v[140:141], off
	v_lshl_add_u64 v[140:141], v[218:219], 0, s[10:11]
	s_mov_b32 m0, s79
	s_nop 0
	global_load_lds_dwordx4 v[140:141], off
	s_waitcnt vmcnt(8)
	s_waitcnt lgkmcnt(0)
	s_barrier
	s_waitcnt lgkmcnt(0)
	v_mfma_f32_16x16x32_bf16 v[60:63], v[148:151], v[180:183], v[60:63]
	v_mfma_f32_16x16x32_bf16 v[56:59], v[156:159], v[180:183], v[56:59]
	v_mfma_f32_16x16x32_bf16 v[52:55], v[148:151], v[192:195], v[52:55]
	v_mfma_f32_16x16x32_bf16 v[44:47], v[156:159], v[192:195], v[44:47]
	v_mfma_f32_16x16x32_bf16 v[36:39], v[148:151], v[200:203], v[36:39]
	v_mfma_f32_16x16x32_bf16 v[28:31], v[156:159], v[200:203], v[28:31]
	v_mfma_f32_16x16x32_bf16 v[20:23], v[148:151], v[208:211], v[20:23]
	v_mfma_f32_16x16x32_bf16 v[12:15], v[156:159], v[208:211], v[12:15]
	v_mfma_f32_16x16x32_bf16 v[60:63], v[152:155], v[184:187], v[60:63]
	v_mfma_f32_16x16x32_bf16 v[56:59], v[160:163], v[184:187], v[56:59]
	v_mfma_f32_16x16x32_bf16 v[52:55], v[152:155], v[196:199], v[52:55]
	v_mfma_f32_16x16x32_bf16 v[44:47], v[160:163], v[196:199], v[44:47]
	v_mfma_f32_16x16x32_bf16 v[36:39], v[152:155], v[204:207], v[36:39]
	v_mfma_f32_16x16x32_bf16 v[28:31], v[160:163], v[204:207], v[28:31]
	v_mfma_f32_16x16x32_bf16 v[20:23], v[152:155], v[212:215], v[20:23]
	v_mfma_f32_16x16x32_bf16 v[12:15], v[160:163], v[212:215], v[12:15]
	v_mfma_f32_16x16x32_bf16 v[48:51], v[164:167], v[180:183], v[48:51]
	v_mfma_f32_16x16x32_bf16 v[40:43], v[172:175], v[180:183], v[40:43]
	v_mfma_f32_16x16x32_bf16 v[32:35], v[164:167], v[192:195], v[32:35]
	v_mfma_f32_16x16x32_bf16 v[24:27], v[172:175], v[192:195], v[24:27]
	v_mfma_f32_16x16x32_bf16 v[16:19], v[164:167], v[200:203], v[16:19]
	v_mfma_f32_16x16x32_bf16 v[8:11], v[172:175], v[200:203], v[8:11]
	v_mfma_f32_16x16x32_bf16 v[4:7], v[164:167], v[208:211], v[4:7]
	v_mfma_f32_16x16x32_bf16 v[0:3], v[172:175], v[208:211], v[0:3]
	v_mfma_f32_16x16x32_bf16 v[48:51], v[168:171], v[184:187], v[48:51]
	v_mfma_f32_16x16x32_bf16 v[40:43], v[176:179], v[184:187], v[40:43]
	v_mfma_f32_16x16x32_bf16 v[32:35], v[168:171], v[196:199], v[32:35]
	v_mfma_f32_16x16x32_bf16 v[24:27], v[176:179], v[196:199], v[24:27]
	v_mfma_f32_16x16x32_bf16 v[16:19], v[168:171], v[204:207], v[16:19]
	v_mfma_f32_16x16x32_bf16 v[8:11], v[176:179], v[204:207], v[8:11]
	v_mfma_f32_16x16x32_bf16 v[4:7], v[168:171], v[212:215], v[4:7]
	v_mfma_f32_16x16x32_bf16 v[0:3], v[176:179], v[212:215], v[0:3]
	s_barrier
	s_movk_i32 s60, 0x100
	s_andn2_b64 vcc, exec, s[34:35]
	s_mov_b64 s[42:43], -1
	s_mov_b64 s[34:35], 0
	s_cbranch_vccz .LBB0_1246

.LBB0_1265:
	s_add_u32 s65, s18, 0x100
	s_addc_u32 s66, s19, 0
	s_mov_b32 s67, -2
	ds_read_b128 v[144:147], v151
	ds_read_b128 v[154:157], v151 offset:1024
	ds_read_b128 v[158:161], v151 offset:2048
	ds_read_b128 v[162:165], v151 offset:3072
	ds_read_b128 v[166:169], v152
	ds_read_b128 v[170:173], v152 offset:1024
	ds_read_b128 v[174:177], v152 offset:2048
	ds_read_b128 v[178:181], v152 offset:3072
	s_add_u32 s18, s16, 0x100
	s_addc_u32 s19, s17, 0
	s_cmp_eq_u32 s67, 2
	s_cselect_b32 s23, s5, s19
	s_cselect_b32 s22, s4, s18
	s_cselect_b32 s21, s15, s66
	s_cselect_b32 s20, s14, s65
	v_lshl_add_u64 v[216:217], s[16:17], 0, v[136:137]
	s_add_i32 m0, s31, 0xc000
	ds_read_b128 v[182:185], v153
	ds_read_b128 v[186:189], v153 offset:1024
	ds_read_b128 v[192:195], v153 offset:2048
	ds_read_b128 v[196:199], v153 offset:3072
	ds_read_b128 v[200:203], v153 offset:4096
	ds_read_b128 v[204:207], v153 offset:5120
	ds_read_b128 v[208:211], v153 offset:6144
	ds_read_b128 v[212:215], v153 offset:7168
	global_load_lds_dwordx4 v[216:217], off
	v_lshl_add_u64 v[216:217], s[16:17], 0, v[138:139]
	s_add_i32 m0, s31, 0xe000
	s_nop 0
	global_load_lds_dwordx4 v[216:217], off
	s_waitcnt vmcnt(8)
	s_waitcnt lgkmcnt(0)
	s_barrier
	s_waitcnt lgkmcnt(0)
	v_mfma_f32_16x16x32_bf16 v[124:127], v[144:147], v[182:185], 0
	v_mfma_f32_16x16x32_bf16 v[120:123], v[158:161], v[182:185], 0
	v_mfma_f32_16x16x32_bf16 v[116:119], v[144:147], v[192:195], 0
	v_mfma_f32_16x16x32_bf16 v[108:111], v[158:161], v[192:195], 0
	v_mfma_f32_16x16x32_bf16 v[100:103], v[144:147], v[200:203], 0
	v_mfma_f32_16x16x32_bf16 v[92:95], v[158:161], v[200:203], 0
	v_mfma_f32_16x16x32_bf16 v[84:87], v[144:147], v[208:211], 0
	v_mfma_f32_16x16x32_bf16 v[76:79], v[158:161], v[208:211], 0
	v_mfma_f32_16x16x32_bf16 v[124:127], v[154:157], v[186:189], v[124:127]
	v_mfma_f32_16x16x32_bf16 v[120:123], v[162:165], v[186:189], v[120:123]
	v_mfma_f32_16x16x32_bf16 v[116:119], v[154:157], v[196:199], v[116:119]
	v_mfma_f32_16x16x32_bf16 v[108:111], v[162:165], v[196:199], v[108:111]
	v_mfma_f32_16x16x32_bf16 v[100:103], v[154:157], v[204:207], v[100:103]
	v_mfma_f32_16x16x32_bf16 v[92:95], v[162:165], v[204:207], v[92:95]
	v_mfma_f32_16x16x32_bf16 v[84:87], v[154:157], v[212:215], v[84:87]
	v_mfma_f32_16x16x32_bf16 v[76:79], v[162:165], v[212:215], v[76:79]
	v_mfma_f32_16x16x32_bf16 v[112:115], v[166:169], v[182:185], 0
	v_mfma_f32_16x16x32_bf16 v[104:107], v[174:177], v[182:185], 0
	v_mfma_f32_16x16x32_bf16 v[96:99], v[166:169], v[192:195], 0
	v_mfma_f32_16x16x32_bf16 v[88:91], v[174:177], v[192:195], 0
	v_mfma_f32_16x16x32_bf16 v[80:83], v[166:169], v[200:203], 0
	v_mfma_f32_16x16x32_bf16 v[72:75], v[174:177], v[200:203], 0
	v_mfma_f32_16x16x32_bf16 v[68:71], v[166:169], v[208:211], 0
	v_mfma_f32_16x16x32_bf16 v[64:67], v[174:177], v[208:211], 0
	v_mfma_f32_16x16x32_bf16 v[112:115], v[170:173], v[186:189], v[112:115]
	v_mfma_f32_16x16x32_bf16 v[104:107], v[178:181], v[186:189], v[104:107]
	v_mfma_f32_16x16x32_bf16 v[96:99], v[170:173], v[196:199], v[96:99]
	v_mfma_f32_16x16x32_bf16 v[88:91], v[178:181], v[196:199], v[88:91]
	v_mfma_f32_16x16x32_bf16 v[80:83], v[170:173], v[204:207], v[80:83]
	v_mfma_f32_16x16x32_bf16 v[72:75], v[178:181], v[204:207], v[72:75]
	v_mfma_f32_16x16x32_bf16 v[68:71], v[170:173], v[212:215], v[68:71]
	v_mfma_f32_16x16x32_bf16 v[64:67], v[178:181], v[212:215], v[64:67]
	s_barrier
	s_add_i32 s16, s60, s28
	v_lshl_add_u64 v[216:217], s[20:21], 0, v[132:133]
	s_mov_b32 m0, s16
	ds_read_b128 v[182:185], v153 offset:16384
	ds_read_b128 v[186:189], v153 offset:17408
	ds_read_b128 v[192:195], v153 offset:18432
	ds_read_b128 v[196:199], v153 offset:19456
	ds_read_b128 v[200:203], v153 offset:20480
	ds_read_b128 v[204:207], v153 offset:21504
	ds_read_b128 v[208:211], v153 offset:22528
	ds_read_b128 v[212:215], v153 offset:23552
	global_load_lds_dwordx4 v[216:217], off
	s_add_i32 m0, s16, 0x2000
	s_add_u32 s16, s20, 0x18000
	v_lshl_add_u64 v[218:219], s[20:21], 0, v[128:129]
	s_addc_u32 s17, s21, 0
	s_add_i32 s68, s61, s28
	global_load_lds_dwordx4 v[218:219], off
	s_mov_b32 m0, s68
	v_lshl_add_u64 v[222:223], s[22:23], 0, v[130:131]
	global_load_lds_dwordx4 v132, s[16:17]
	s_add_i32 m0, s68, 0x2000
	s_nop 0
	global_load_lds_dwordx4 v128, s[16:17]
	v_lshl_add_u64 v[220:221], s[22:23], 0, v[134:135]
	s_mov_b32 m0, s31
	s_nop 0
	global_load_lds_dwordx4 v[220:221], off
	s_mov_b32 m0, s33
	s_nop 0
	global_load_lds_dwordx4 v[222:223], off
	s_waitcnt vmcnt(8)
	s_waitcnt lgkmcnt(0)
	s_barrier
	s_waitcnt lgkmcnt(0)
	v_mfma_f32_16x16x32_bf16 v[60:63], v[144:147], v[182:185], 0
	v_mfma_f32_16x16x32_bf16 v[56:59], v[158:161], v[182:185], 0
	v_mfma_f32_16x16x32_bf16 v[52:55], v[144:147], v[192:195], 0
	v_mfma_f32_16x16x32_bf16 v[44:47], v[158:161], v[192:195], 0
	v_mfma_f32_16x16x32_bf16 v[36:39], v[144:147], v[200:203], 0
	v_mfma_f32_16x16x32_bf16 v[28:31], v[158:161], v[200:203], 0
	v_mfma_f32_16x16x32_bf16 v[20:23], v[144:147], v[208:211], 0
	v_mfma_f32_16x16x32_bf16 v[12:15], v[158:161], v[208:211], 0
	v_mfma_f32_16x16x32_bf16 v[60:63], v[154:157], v[186:189], v[60:63]
	v_mfma_f32_16x16x32_bf16 v[56:59], v[162:165], v[186:189], v[56:59]
	v_mfma_f32_16x16x32_bf16 v[52:55], v[154:157], v[196:199], v[52:55]
	v_mfma_f32_16x16x32_bf16 v[44:47], v[162:165], v[196:199], v[44:47]
	v_mfma_f32_16x16x32_bf16 v[36:39], v[154:157], v[204:207], v[36:39]
	v_mfma_f32_16x16x32_bf16 v[28:31], v[162:165], v[204:207], v[28:31]
	v_mfma_f32_16x16x32_bf16 v[20:23], v[154:157], v[212:215], v[20:23]
	v_mfma_f32_16x16x32_bf16 v[12:15], v[162:165], v[212:215], v[12:15]
	v_mfma_f32_16x16x32_bf16 v[48:51], v[166:169], v[182:185], 0
	v_mfma_f32_16x16x32_bf16 v[40:43], v[174:177], v[182:185], 0
	v_mfma_f32_16x16x32_bf16 v[32:35], v[166:169], v[192:195], 0
	v_mfma_f32_16x16x32_bf16 v[24:27], v[174:177], v[192:195], 0
	v_mfma_f32_16x16x32_bf16 v[16:19], v[166:169], v[200:203], 0
	v_mfma_f32_16x16x32_bf16 v[8:11], v[174:177], v[200:203], 0
	v_mfma_f32_16x16x32_bf16 v[4:7], v[166:169], v[208:211], 0
	v_mfma_f32_16x16x32_bf16 v[0:3], v[174:177], v[208:211], 0
	v_mfma_f32_16x16x32_bf16 v[48:51], v[170:173], v[186:189], v[48:51]
	v_mfma_f32_16x16x32_bf16 v[40:43], v[178:181], v[186:189], v[40:43]
	v_mfma_f32_16x16x32_bf16 v[32:35], v[170:173], v[196:199], v[32:35]
	v_mfma_f32_16x16x32_bf16 v[24:27], v[178:181], v[196:199], v[24:27]
	v_mfma_f32_16x16x32_bf16 v[16:19], v[170:173], v[204:207], v[16:19]
	v_mfma_f32_16x16x32_bf16 v[8:11], v[178:181], v[204:207], v[8:11]
	v_mfma_f32_16x16x32_bf16 v[4:7], v[170:173], v[212:215], v[4:7]
	v_mfma_f32_16x16x32_bf16 v[0:3], v[178:181], v[212:215], v[0:3]
	s_barrier
	s_add_i32 s68, 0, 0x18000
	s_add_i32 s69, 0, 0x1c000
	v_add_u32_e32 v162, s68, v149
	v_add_u32_e32 v178, s69, v149
	ds_read_b128 v[144:147], v162
	ds_read_b128 v[154:157], v162 offset:1024
	ds_read_b128 v[158:161], v162 offset:2048
	ds_read_b128 v[162:165], v162 offset:3072
	ds_read_b128 v[166:169], v178
	ds_read_b128 v[170:173], v178 offset:1024
	ds_read_b128 v[174:177], v178 offset:2048
	ds_read_b128 v[178:181], v178 offset:3072
	s_add_u32 s16, s22, 0x18000
	s_addc_u32 s17, s23, 0
	s_mov_b32 m0, s34
	ds_read_b128 v[182:185], v153 offset:32768
	ds_read_b128 v[186:189], v153 offset:33792
	ds_read_b128 v[192:195], v153 offset:34816
	ds_read_b128 v[196:199], v153 offset:35840
	ds_read_b128 v[200:203], v153 offset:36864
	ds_read_b128 v[204:207], v153 offset:37888
	ds_read_b128 v[208:211], v153 offset:38912
	ds_read_b128 v[212:215], v153 offset:39936
	global_load_lds_dwordx4 v134, s[16:17]
	s_mov_b32 m0, s35
	s_nop 0
	global_load_lds_dwordx4 v130, s[16:17]
	s_waitcnt vmcnt(8)
	s_waitcnt lgkmcnt(0)
	s_barrier
	s_waitcnt lgkmcnt(0)
	v_mfma_f32_16x16x32_bf16 v[124:127], v[144:147], v[182:185], v[124:127]
	v_mfma_f32_16x16x32_bf16 v[120:123], v[158:161], v[182:185], v[120:123]
	v_mfma_f32_16x16x32_bf16 v[116:119], v[144:147], v[192:195], v[116:119]
	v_mfma_f32_16x16x32_bf16 v[108:111], v[158:161], v[192:195], v[108:111]
	v_mfma_f32_16x16x32_bf16 v[100:103], v[144:147], v[200:203], v[100:103]
	v_mfma_f32_16x16x32_bf16 v[92:95], v[158:161], v[200:203], v[92:95]
	v_mfma_f32_16x16x32_bf16 v[84:87], v[144:147], v[208:211], v[84:87]
	v_mfma_f32_16x16x32_bf16 v[76:79], v[158:161], v[208:211], v[76:79]
	v_mfma_f32_16x16x32_bf16 v[124:127], v[154:157], v[186:189], v[124:127]
	v_mfma_f32_16x16x32_bf16 v[120:123], v[162:165], v[186:189], v[120:123]
	v_mfma_f32_16x16x32_bf16 v[116:119], v[154:157], v[196:199], v[116:119]
	v_mfma_f32_16x16x32_bf16 v[108:111], v[162:165], v[196:199], v[108:111]
	v_mfma_f32_16x16x32_bf16 v[100:103], v[154:157], v[204:207], v[100:103]
	v_mfma_f32_16x16x32_bf16 v[92:95], v[162:165], v[204:207], v[92:95]
	v_mfma_f32_16x16x32_bf16 v[84:87], v[154:157], v[212:215], v[84:87]
	v_mfma_f32_16x16x32_bf16 v[76:79], v[162:165], v[212:215], v[76:79]
	v_mfma_f32_16x16x32_bf16 v[112:115], v[166:169], v[182:185], v[112:115]
	v_mfma_f32_16x16x32_bf16 v[104:107], v[174:177], v[182:185], v[104:107]
	v_mfma_f32_16x16x32_bf16 v[96:99], v[166:169], v[192:195], v[96:99]
	v_mfma_f32_16x16x32_bf16 v[88:91], v[174:177], v[192:195], v[88:91]
	v_mfma_f32_16x16x32_bf16 v[80:83], v[166:169], v[200:203], v[80:83]
	v_mfma_f32_16x16x32_bf16 v[72:75], v[174:177], v[200:203], v[72:75]
	v_mfma_f32_16x16x32_bf16 v[68:71], v[166:169], v[208:211], v[68:71]
	v_mfma_f32_16x16x32_bf16 v[64:67], v[174:177], v[208:211], v[64:67]
	v_mfma_f32_16x16x32_bf16 v[112:115], v[170:173], v[186:189], v[112:115]
	v_mfma_f32_16x16x32_bf16 v[104:107], v[178:181], v[186:189], v[104:107]
	v_mfma_f32_16x16x32_bf16 v[96:99], v[170:173], v[196:199], v[96:99]
	v_mfma_f32_16x16x32_bf16 v[88:91], v[178:181], v[196:199], v[88:91]
	v_mfma_f32_16x16x32_bf16 v[80:83], v[170:173], v[204:207], v[80:83]
	v_mfma_f32_16x16x32_bf16 v[72:75], v[178:181], v[204:207], v[72:75]
	v_mfma_f32_16x16x32_bf16 v[68:71], v[170:173], v[212:215], v[68:71]
	v_mfma_f32_16x16x32_bf16 v[64:67], v[178:181], v[212:215], v[64:67]
	s_barrier
	s_add_i32 s16, s68, s28
	v_lshl_add_u64 v[216:217], v[216:217], 0, s[10:11]
	s_mov_b32 m0, s16
	ds_read_b128 v[182:185], v153 offset:49152
	ds_read_b128 v[186:189], v153 offset:50176
	ds_read_b128 v[192:195], v153 offset:51200
	ds_read_b128 v[196:199], v153 offset:52224
	ds_read_b128 v[200:203], v153 offset:53248
	ds_read_b128 v[204:207], v153 offset:54272
	ds_read_b128 v[208:211], v153 offset:55296
	ds_read_b128 v[212:215], v153 offset:56320
	global_load_lds_dwordx4 v[216:217], off
	s_add_i32 m0, s16, 0x2000
	s_add_u32 s16, s20, 0x18080
	v_lshl_add_u64 v[216:217], v[218:219], 0, s[10:11]
	s_addc_u32 s17, s21, 0
	s_add_i32 s20, s69, s28
	global_load_lds_dwordx4 v[216:217], off
	s_mov_b32 m0, s20
	s_nop 0
	global_load_lds_dwordx4 v132, s[16:17]
	s_add_i32 m0, s20, 0x2000
	s_nop 0
	global_load_lds_dwordx4 v128, s[16:17]
	v_lshl_add_u64 v[216:217], v[220:221], 0, s[10:11]
	s_mov_b32 m0, s43
	s_nop 0
	global_load_lds_dwordx4 v[216:217], off
	v_lshl_add_u64 v[216:217], v[222:223], 0, s[10:11]
	s_mov_b32 m0, s52
	s_nop 0
	global_load_lds_dwordx4 v[216:217], off
	s_waitcnt vmcnt(8)
	s_waitcnt lgkmcnt(0)
	s_barrier
	s_waitcnt lgkmcnt(0)
	v_mfma_f32_16x16x32_bf16 v[60:63], v[144:147], v[182:185], v[60:63]
	v_mfma_f32_16x16x32_bf16 v[56:59], v[158:161], v[182:185], v[56:59]
	v_mfma_f32_16x16x32_bf16 v[52:55], v[144:147], v[192:195], v[52:55]
	v_mfma_f32_16x16x32_bf16 v[44:47], v[158:161], v[192:195], v[44:47]
	v_mfma_f32_16x16x32_bf16 v[36:39], v[144:147], v[200:203], v[36:39]
	v_mfma_f32_16x16x32_bf16 v[28:31], v[158:161], v[200:203], v[28:31]
	v_mfma_f32_16x16x32_bf16 v[20:23], v[144:147], v[208:211], v[20:23]
	v_mfma_f32_16x16x32_bf16 v[12:15], v[158:161], v[208:211], v[12:15]
	v_mfma_f32_16x16x32_bf16 v[60:63], v[154:157], v[186:189], v[60:63]
	v_mfma_f32_16x16x32_bf16 v[56:59], v[162:165], v[186:189], v[56:59]
	v_mfma_f32_16x16x32_bf16 v[52:55], v[154:157], v[196:199], v[52:55]
	v_mfma_f32_16x16x32_bf16 v[44:47], v[162:165], v[196:199], v[44:47]
	v_mfma_f32_16x16x32_bf16 v[36:39], v[154:157], v[204:207], v[36:39]
	v_mfma_f32_16x16x32_bf16 v[28:31], v[162:165], v[204:207], v[28:31]
	v_mfma_f32_16x16x32_bf16 v[20:23], v[154:157], v[212:215], v[20:23]
	v_mfma_f32_16x16x32_bf16 v[12:15], v[162:165], v[212:215], v[12:15]
	v_mfma_f32_16x16x32_bf16 v[48:51], v[166:169], v[182:185], v[48:51]
	v_mfma_f32_16x16x32_bf16 v[40:43], v[174:177], v[182:185], v[40:43]
	v_mfma_f32_16x16x32_bf16 v[32:35], v[166:169], v[192:195], v[32:35]
	v_mfma_f32_16x16x32_bf16 v[24:27], v[174:177], v[192:195], v[24:27]
	v_mfma_f32_16x16x32_bf16 v[16:19], v[166:169], v[200:203], v[16:19]
	v_mfma_f32_16x16x32_bf16 v[8:11], v[174:177], v[200:203], v[8:11]
	v_mfma_f32_16x16x32_bf16 v[4:7], v[166:169], v[208:211], v[4:7]
	v_mfma_f32_16x16x32_bf16 v[0:3], v[174:177], v[208:211], v[0:3]
	v_mfma_f32_16x16x32_bf16 v[48:51], v[170:173], v[186:189], v[48:51]
	v_mfma_f32_16x16x32_bf16 v[40:43], v[178:181], v[186:189], v[40:43]
	v_mfma_f32_16x16x32_bf16 v[32:35], v[170:173], v[196:199], v[32:35]
	v_mfma_f32_16x16x32_bf16 v[24:27], v[178:181], v[196:199], v[24:27]
	v_mfma_f32_16x16x32_bf16 v[16:19], v[170:173], v[204:207], v[16:19]
	v_mfma_f32_16x16x32_bf16 v[8:11], v[178:181], v[204:207], v[8:11]
	v_mfma_f32_16x16x32_bf16 v[4:7], v[170:173], v[212:215], v[4:7]
	v_mfma_f32_16x16x32_bf16 v[0:3], v[178:181], v[212:215], v[0:3]
	s_barrier
	s_add_i32 s67, s67, 2
	s_add_u32 s65, s65, 0x100
	s_addc_u32 s66, s66, 0
	s_cmp_gt_u32 s67, 3
	s_mov_b64 s[16:17], s[18:19]
	s_cbranch_scc0 .LBB0_1266
	s_branch .Lpeel_exit9
.LBB0_1266:
	ds_read_b128 v[144:147], v151
	ds_read_b128 v[154:157], v151 offset:1024
	ds_read_b128 v[158:161], v151 offset:2048
	ds_read_b128 v[162:165], v151 offset:3072
	ds_read_b128 v[166:169], v152
	ds_read_b128 v[170:173], v152 offset:1024
	ds_read_b128 v[174:177], v152 offset:2048
	ds_read_b128 v[178:181], v152 offset:3072
	s_add_u32 s18, s16, 0x100
	s_addc_u32 s19, s17, 0
	s_cmp_eq_u32 s67, 2
	s_cselect_b32 s23, s5, s19
	s_cselect_b32 s22, s4, s18
	s_cselect_b32 s21, s15, s66
	s_cselect_b32 s20, s14, s65
	v_lshl_add_u64 v[216:217], s[16:17], 0, v[136:137]
	s_add_i32 m0, s31, 0xc000
	ds_read_b128 v[182:185], v153
	ds_read_b128 v[186:189], v153 offset:1024
	ds_read_b128 v[192:195], v153 offset:2048
	ds_read_b128 v[196:199], v153 offset:3072
	ds_read_b128 v[200:203], v153 offset:4096
	ds_read_b128 v[204:207], v153 offset:5120
	ds_read_b128 v[208:211], v153 offset:6144
	ds_read_b128 v[212:215], v153 offset:7168
	global_load_lds_dwordx4 v[216:217], off
	v_lshl_add_u64 v[216:217], s[16:17], 0, v[138:139]
	s_add_i32 m0, s31, 0xe000
	s_nop 0
	global_load_lds_dwordx4 v[216:217], off
	s_waitcnt vmcnt(8)
	s_waitcnt lgkmcnt(0)
	s_barrier
	s_waitcnt lgkmcnt(0)
	v_mfma_f32_16x16x32_bf16 v[124:127], v[144:147], v[182:185], v[124:127]
	v_mfma_f32_16x16x32_bf16 v[120:123], v[158:161], v[182:185], v[120:123]
	v_mfma_f32_16x16x32_bf16 v[116:119], v[144:147], v[192:195], v[116:119]
	v_mfma_f32_16x16x32_bf16 v[108:111], v[158:161], v[192:195], v[108:111]
	v_mfma_f32_16x16x32_bf16 v[100:103], v[144:147], v[200:203], v[100:103]
	v_mfma_f32_16x16x32_bf16 v[92:95], v[158:161], v[200:203], v[92:95]
	v_mfma_f32_16x16x32_bf16 v[84:87], v[144:147], v[208:211], v[84:87]
	v_mfma_f32_16x16x32_bf16 v[76:79], v[158:161], v[208:211], v[76:79]
	v_mfma_f32_16x16x32_bf16 v[124:127], v[154:157], v[186:189], v[124:127]
	v_mfma_f32_16x16x32_bf16 v[120:123], v[162:165], v[186:189], v[120:123]
	v_mfma_f32_16x16x32_bf16 v[116:119], v[154:157], v[196:199], v[116:119]
	v_mfma_f32_16x16x32_bf16 v[108:111], v[162:165], v[196:199], v[108:111]
	v_mfma_f32_16x16x32_bf16 v[100:103], v[154:157], v[204:207], v[100:103]
	v_mfma_f32_16x16x32_bf16 v[92:95], v[162:165], v[204:207], v[92:95]
	v_mfma_f32_16x16x32_bf16 v[84:87], v[154:157], v[212:215], v[84:87]
	v_mfma_f32_16x16x32_bf16 v[76:79], v[162:165], v[212:215], v[76:79]
	v_mfma_f32_16x16x32_bf16 v[112:115], v[166:169], v[182:185], v[112:115]
	v_mfma_f32_16x16x32_bf16 v[104:107], v[174:177], v[182:185], v[104:107]
	v_mfma_f32_16x16x32_bf16 v[96:99], v[166:169], v[192:195], v[96:99]
	v_mfma_f32_16x16x32_bf16 v[88:91], v[174:177], v[192:195], v[88:91]
	v_mfma_f32_16x16x32_bf16 v[80:83], v[166:169], v[200:203], v[80:83]
	v_mfma_f32_16x16x32_bf16 v[72:75], v[174:177], v[200:203], v[72:75]
	v_mfma_f32_16x16x32_bf16 v[68:71], v[166:169], v[208:211], v[68:71]
	v_mfma_f32_16x16x32_bf16 v[64:67], v[174:177], v[208:211], v[64:67]
	v_mfma_f32_16x16x32_bf16 v[112:115], v[170:173], v[186:189], v[112:115]
	v_mfma_f32_16x16x32_bf16 v[104:107], v[178:181], v[186:189], v[104:107]
	v_mfma_f32_16x16x32_bf16 v[96:99], v[170:173], v[196:199], v[96:99]
	v_mfma_f32_16x16x32_bf16 v[88:91], v[178:181], v[196:199], v[88:91]
	v_mfma_f32_16x16x32_bf16 v[80:83], v[170:173], v[204:207], v[80:83]
	v_mfma_f32_16x16x32_bf16 v[72:75], v[178:181], v[204:207], v[72:75]
	v_mfma_f32_16x16x32_bf16 v[68:71], v[170:173], v[212:215], v[68:71]
	v_mfma_f32_16x16x32_bf16 v[64:67], v[178:181], v[212:215], v[64:67]
	s_barrier
	s_add_i32 s16, s60, s28
	v_lshl_add_u64 v[216:217], s[20:21], 0, v[132:133]
	s_mov_b32 m0, s16
	ds_read_b128 v[182:185], v153 offset:16384
	ds_read_b128 v[186:189], v153 offset:17408
	ds_read_b128 v[192:195], v153 offset:18432
	ds_read_b128 v[196:199], v153 offset:19456
	ds_read_b128 v[200:203], v153 offset:20480
	ds_read_b128 v[204:207], v153 offset:21504
	ds_read_b128 v[208:211], v153 offset:22528
	ds_read_b128 v[212:215], v153 offset:23552
	global_load_lds_dwordx4 v[216:217], off
	s_add_i32 m0, s16, 0x2000
	s_add_u32 s16, s20, 0x18000
	v_lshl_add_u64 v[218:219], s[20:21], 0, v[128:129]
	s_addc_u32 s17, s21, 0
	s_add_i32 s68, s61, s28
	global_load_lds_dwordx4 v[218:219], off
	s_mov_b32 m0, s68
	v_lshl_add_u64 v[222:223], s[22:23], 0, v[130:131]
	global_load_lds_dwordx4 v132, s[16:17]
	s_add_i32 m0, s68, 0x2000
	s_nop 0
	global_load_lds_dwordx4 v128, s[16:17]
	v_lshl_add_u64 v[220:221], s[22:23], 0, v[134:135]
	s_mov_b32 m0, s31
	s_nop 0
	global_load_lds_dwordx4 v[220:221], off
	s_mov_b32 m0, s33
	s_nop 0
	global_load_lds_dwordx4 v[222:223], off
	s_waitcnt vmcnt(8)
	s_waitcnt lgkmcnt(0)
	s_barrier
	s_waitcnt lgkmcnt(0)
	v_mfma_f32_16x16x32_bf16 v[60:63], v[144:147], v[182:185], v[60:63]
	v_mfma_f32_16x16x32_bf16 v[56:59], v[158:161], v[182:185], v[56:59]
	v_mfma_f32_16x16x32_bf16 v[52:55], v[144:147], v[192:195], v[52:55]
	v_mfma_f32_16x16x32_bf16 v[44:47], v[158:161], v[192:195], v[44:47]
	v_mfma_f32_16x16x32_bf16 v[36:39], v[144:147], v[200:203], v[36:39]
	v_mfma_f32_16x16x32_bf16 v[28:31], v[158:161], v[200:203], v[28:31]
	v_mfma_f32_16x16x32_bf16 v[20:23], v[144:147], v[208:211], v[20:23]
	v_mfma_f32_16x16x32_bf16 v[12:15], v[158:161], v[208:211], v[12:15]
	v_mfma_f32_16x16x32_bf16 v[60:63], v[154:157], v[186:189], v[60:63]
	v_mfma_f32_16x16x32_bf16 v[56:59], v[162:165], v[186:189], v[56:59]
	v_mfma_f32_16x16x32_bf16 v[52:55], v[154:157], v[196:199], v[52:55]
	v_mfma_f32_16x16x32_bf16 v[44:47], v[162:165], v[196:199], v[44:47]
	v_mfma_f32_16x16x32_bf16 v[36:39], v[154:157], v[204:207], v[36:39]
	v_mfma_f32_16x16x32_bf16 v[28:31], v[162:165], v[204:207], v[28:31]
	v_mfma_f32_16x16x32_bf16 v[20:23], v[154:157], v[212:215], v[20:23]
	v_mfma_f32_16x16x32_bf16 v[12:15], v[162:165], v[212:215], v[12:15]
	v_mfma_f32_16x16x32_bf16 v[48:51], v[166:169], v[182:185], v[48:51]
	v_mfma_f32_16x16x32_bf16 v[40:43], v[174:177], v[182:185], v[40:43]
	v_mfma_f32_16x16x32_bf16 v[32:35], v[166:169], v[192:195], v[32:35]
	v_mfma_f32_16x16x32_bf16 v[24:27], v[174:177], v[192:195], v[24:27]
	v_mfma_f32_16x16x32_bf16 v[16:19], v[166:169], v[200:203], v[16:19]
	v_mfma_f32_16x16x32_bf16 v[8:11], v[174:177], v[200:203], v[8:11]
	v_mfma_f32_16x16x32_bf16 v[4:7], v[166:169], v[208:211], v[4:7]
	v_mfma_f32_16x16x32_bf16 v[0:3], v[174:177], v[208:211], v[0:3]
	v_mfma_f32_16x16x32_bf16 v[48:51], v[170:173], v[186:189], v[48:51]
	v_mfma_f32_16x16x32_bf16 v[40:43], v[178:181], v[186:189], v[40:43]
	v_mfma_f32_16x16x32_bf16 v[32:35], v[170:173], v[196:199], v[32:35]
	v_mfma_f32_16x16x32_bf16 v[24:27], v[178:181], v[196:199], v[24:27]
	v_mfma_f32_16x16x32_bf16 v[16:19], v[170:173], v[204:207], v[16:19]
	v_mfma_f32_16x16x32_bf16 v[8:11], v[178:181], v[204:207], v[8:11]
	v_mfma_f32_16x16x32_bf16 v[4:7], v[170:173], v[212:215], v[4:7]
	v_mfma_f32_16x16x32_bf16 v[0:3], v[178:181], v[212:215], v[0:3]
	s_barrier
	s_add_i32 s68, 0, 0x18000
	s_add_i32 s69, 0, 0x1c000
	v_add_u32_e32 v162, s68, v149
	v_add_u32_e32 v178, s69, v149
	ds_read_b128 v[144:147], v162
	ds_read_b128 v[154:157], v162 offset:1024
	ds_read_b128 v[158:161], v162 offset:2048
	ds_read_b128 v[162:165], v162 offset:3072
	ds_read_b128 v[166:169], v178
	ds_read_b128 v[170:173], v178 offset:1024
	ds_read_b128 v[174:177], v178 offset:2048
	ds_read_b128 v[178:181], v178 offset:3072
	s_add_u32 s16, s22, 0x18000
	s_addc_u32 s17, s23, 0
	s_mov_b32 m0, s34
	ds_read_b128 v[182:185], v153 offset:32768
	ds_read_b128 v[186:189], v153 offset:33792
	ds_read_b128 v[192:195], v153 offset:34816
	ds_read_b128 v[196:199], v153 offset:35840
	ds_read_b128 v[200:203], v153 offset:36864
	ds_read_b128 v[204:207], v153 offset:37888
	ds_read_b128 v[208:211], v153 offset:38912
	ds_read_b128 v[212:215], v153 offset:39936
	global_load_lds_dwordx4 v134, s[16:17]
	s_mov_b32 m0, s35
	s_nop 0
	global_load_lds_dwordx4 v130, s[16:17]
	s_waitcnt vmcnt(8)
	s_waitcnt lgkmcnt(0)
	s_barrier
	s_waitcnt lgkmcnt(0)
	v_mfma_f32_16x16x32_bf16 v[124:127], v[144:147], v[182:185], v[124:127]
	v_mfma_f32_16x16x32_bf16 v[120:123], v[158:161], v[182:185], v[120:123]
	v_mfma_f32_16x16x32_bf16 v[116:119], v[144:147], v[192:195], v[116:119]
	v_mfma_f32_16x16x32_bf16 v[108:111], v[158:161], v[192:195], v[108:111]
	v_mfma_f32_16x16x32_bf16 v[100:103], v[144:147], v[200:203], v[100:103]
	v_mfma_f32_16x16x32_bf16 v[92:95], v[158:161], v[200:203], v[92:95]
	v_mfma_f32_16x16x32_bf16 v[84:87], v[144:147], v[208:211], v[84:87]
	v_mfma_f32_16x16x32_bf16 v[76:79], v[158:161], v[208:211], v[76:79]
	v_mfma_f32_16x16x32_bf16 v[124:127], v[154:157], v[186:189], v[124:127]
	v_mfma_f32_16x16x32_bf16 v[120:123], v[162:165], v[186:189], v[120:123]
	v_mfma_f32_16x16x32_bf16 v[116:119], v[154:157], v[196:199], v[116:119]
	v_mfma_f32_16x16x32_bf16 v[108:111], v[162:165], v[196:199], v[108:111]
	v_mfma_f32_16x16x32_bf16 v[100:103], v[154:157], v[204:207], v[100:103]
	v_mfma_f32_16x16x32_bf16 v[92:95], v[162:165], v[204:207], v[92:95]
	v_mfma_f32_16x16x32_bf16 v[84:87], v[154:157], v[212:215], v[84:87]
	v_mfma_f32_16x16x32_bf16 v[76:79], v[162:165], v[212:215], v[76:79]
	v_mfma_f32_16x16x32_bf16 v[112:115], v[166:169], v[182:185], v[112:115]
	v_mfma_f32_16x16x32_bf16 v[104:107], v[174:177], v[182:185], v[104:107]
	v_mfma_f32_16x16x32_bf16 v[96:99], v[166:169], v[192:195], v[96:99]
	v_mfma_f32_16x16x32_bf16 v[88:91], v[174:177], v[192:195], v[88:91]
	v_mfma_f32_16x16x32_bf16 v[80:83], v[166:169], v[200:203], v[80:83]
	v_mfma_f32_16x16x32_bf16 v[72:75], v[174:177], v[200:203], v[72:75]
	v_mfma_f32_16x16x32_bf16 v[68:71], v[166:169], v[208:211], v[68:71]
	v_mfma_f32_16x16x32_bf16 v[64:67], v[174:177], v[208:211], v[64:67]
	v_mfma_f32_16x16x32_bf16 v[112:115], v[170:173], v[186:189], v[112:115]
	v_mfma_f32_16x16x32_bf16 v[104:107], v[178:181], v[186:189], v[104:107]
	v_mfma_f32_16x16x32_bf16 v[96:99], v[170:173], v[196:199], v[96:99]
	v_mfma_f32_16x16x32_bf16 v[88:91], v[178:181], v[196:199], v[88:91]
	v_mfma_f32_16x16x32_bf16 v[80:83], v[170:173], v[204:207], v[80:83]
	v_mfma_f32_16x16x32_bf16 v[72:75], v[178:181], v[204:207], v[72:75]
	v_mfma_f32_16x16x32_bf16 v[68:71], v[170:173], v[212:215], v[68:71]
	v_mfma_f32_16x16x32_bf16 v[64:67], v[178:181], v[212:215], v[64:67]
	s_barrier
	s_add_i32 s16, s68, s28
	v_lshl_add_u64 v[216:217], v[216:217], 0, s[10:11]
	s_mov_b32 m0, s16
	ds_read_b128 v[182:185], v153 offset:49152
	ds_read_b128 v[186:189], v153 offset:50176
	ds_read_b128 v[192:195], v153 offset:51200
	ds_read_b128 v[196:199], v153 offset:52224
	ds_read_b128 v[200:203], v153 offset:53248
	ds_read_b128 v[204:207], v153 offset:54272
	ds_read_b128 v[208:211], v153 offset:55296
	ds_read_b128 v[212:215], v153 offset:56320
	global_load_lds_dwordx4 v[216:217], off
	s_add_i32 m0, s16, 0x2000
	s_add_u32 s16, s20, 0x18080
	v_lshl_add_u64 v[216:217], v[218:219], 0, s[10:11]
	s_addc_u32 s17, s21, 0
	s_add_i32 s20, s69, s28
	global_load_lds_dwordx4 v[216:217], off
	s_mov_b32 m0, s20
	s_nop 0
	global_load_lds_dwordx4 v132, s[16:17]
	s_add_i32 m0, s20, 0x2000
	s_nop 0
	global_load_lds_dwordx4 v128, s[16:17]
	v_lshl_add_u64 v[216:217], v[220:221], 0, s[10:11]
	s_mov_b32 m0, s43
	s_nop 0
	global_load_lds_dwordx4 v[216:217], off
	v_lshl_add_u64 v[216:217], v[222:223], 0, s[10:11]
	s_mov_b32 m0, s52
	s_nop 0
	global_load_lds_dwordx4 v[216:217], off
	s_waitcnt vmcnt(8)
	s_waitcnt lgkmcnt(0)
	s_barrier
	s_waitcnt lgkmcnt(0)
	v_mfma_f32_16x16x32_bf16 v[60:63], v[144:147], v[182:185], v[60:63]
	v_mfma_f32_16x16x32_bf16 v[56:59], v[158:161], v[182:185], v[56:59]
	v_mfma_f32_16x16x32_bf16 v[52:55], v[144:147], v[192:195], v[52:55]
	v_mfma_f32_16x16x32_bf16 v[44:47], v[158:161], v[192:195], v[44:47]
	v_mfma_f32_16x16x32_bf16 v[36:39], v[144:147], v[200:203], v[36:39]
	v_mfma_f32_16x16x32_bf16 v[28:31], v[158:161], v[200:203], v[28:31]
	v_mfma_f32_16x16x32_bf16 v[20:23], v[144:147], v[208:211], v[20:23]
	v_mfma_f32_16x16x32_bf16 v[12:15], v[158:161], v[208:211], v[12:15]
	v_mfma_f32_16x16x32_bf16 v[60:63], v[154:157], v[186:189], v[60:63]
	v_mfma_f32_16x16x32_bf16 v[56:59], v[162:165], v[186:189], v[56:59]
	v_mfma_f32_16x16x32_bf16 v[52:55], v[154:157], v[196:199], v[52:55]
	v_mfma_f32_16x16x32_bf16 v[44:47], v[162:165], v[196:199], v[44:47]
	v_mfma_f32_16x16x32_bf16 v[36:39], v[154:157], v[204:207], v[36:39]
	v_mfma_f32_16x16x32_bf16 v[28:31], v[162:165], v[204:207], v[28:31]
	v_mfma_f32_16x16x32_bf16 v[20:23], v[154:157], v[212:215], v[20:23]
	v_mfma_f32_16x16x32_bf16 v[12:15], v[162:165], v[212:215], v[12:15]
	v_mfma_f32_16x16x32_bf16 v[48:51], v[166:169], v[182:185], v[48:51]
	v_mfma_f32_16x16x32_bf16 v[40:43], v[174:177], v[182:185], v[40:43]
	v_mfma_f32_16x16x32_bf16 v[32:35], v[166:169], v[192:195], v[32:35]
	v_mfma_f32_16x16x32_bf16 v[24:27], v[174:177], v[192:195], v[24:27]
	v_mfma_f32_16x16x32_bf16 v[16:19], v[166:169], v[200:203], v[16:19]
	v_mfma_f32_16x16x32_bf16 v[8:11], v[174:177], v[200:203], v[8:11]
	v_mfma_f32_16x16x32_bf16 v[4:7], v[166:169], v[208:211], v[4:7]
	v_mfma_f32_16x16x32_bf16 v[0:3], v[174:177], v[208:211], v[0:3]
	v_mfma_f32_16x16x32_bf16 v[48:51], v[170:173], v[186:189], v[48:51]
	v_mfma_f32_16x16x32_bf16 v[40:43], v[178:181], v[186:189], v[40:43]
	v_mfma_f32_16x16x32_bf16 v[32:35], v[170:173], v[196:199], v[32:35]
	v_mfma_f32_16x16x32_bf16 v[24:27], v[178:181], v[196:199], v[24:27]
	v_mfma_f32_16x16x32_bf16 v[16:19], v[170:173], v[204:207], v[16:19]
	v_mfma_f32_16x16x32_bf16 v[8:11], v[178:181], v[204:207], v[8:11]
	v_mfma_f32_16x16x32_bf16 v[4:7], v[170:173], v[212:215], v[4:7]
	v_mfma_f32_16x16x32_bf16 v[0:3], v[178:181], v[212:215], v[0:3]
	s_barrier
	s_add_i32 s67, s67, 2
	s_add_u32 s65, s65, 0x100
	s_addc_u32 s66, s66, 0
	s_cmp_gt_u32 s67, 3
	s_mov_b64 s[16:17], s[18:19]
	s_cbranch_scc0 .LBB0_1266

.LBB0_1433:
	s_ashr_i32 s23, s22, 31
	s_lshl_b64 s[24:25], s[22:23], 19
	s_add_u32 s24, s56, s24
	s_addc_u32 s25, s57, s25
	s_and_b64 s[26:27], s[0:1], exec
	s_cselect_b32 s23, s25, s31
	s_cselect_b32 s55, s24, s30
	s_ashr_i32 s21, s20, 31
	s_lshl_b64 s[26:27], s[20:21], 19
	s_add_u32 s26, s53, s26
	s_addc_u32 s27, s60, s27
	s_and_b64 s[42:43], s[0:1], exec
	s_cselect_b32 s21, s27, s35
	s_cselect_b32 s74, s26, s34
	s_add_u32 s30, s30, 0x40080
	s_addc_u32 s31, s31, 0
	s_add_u32 s75, s34, 0x100
	s_addc_u32 s76, s35, 0
	s_mov_b32 s77, -2
	ds_read_b128 v[152:155], v149
	ds_read_b128 v[156:159], v149 offset:1024
	ds_read_b128 v[160:163], v149 offset:2048
	ds_read_b128 v[164:167], v149 offset:3072
	ds_read_b128 v[168:171], v150
	ds_read_b128 v[172:175], v150 offset:1024
	ds_read_b128 v[176:179], v150 offset:2048
	ds_read_b128 v[180:183], v150 offset:3072
	s_add_u32 s34, s30, 0xfffc0080
	s_addc_u32 s35, s31, -1
	s_cmp_eq_u32 s77, 12
	s_cselect_b32 s43, s23, s35
	s_cselect_b32 s42, s55, s34
	s_cselect_b32 s35, s21, s76
	s_cselect_b32 s34, s74, s75
	s_add_i32 m0, s29, 0xc000
	ds_read_b128 v[184:187], v151
	ds_read_b128 v[192:195], v151 offset:1024
	ds_read_b128 v[196:199], v151 offset:2048
	ds_read_b128 v[200:203], v151 offset:3072
	ds_read_b128 v[204:207], v151 offset:4096
	ds_read_b128 v[208:211], v151 offset:5120
	ds_read_b128 v[212:215], v151 offset:6144
	ds_read_b128 v[216:219], v151 offset:7168
	global_load_lds_dwordx4 v136, s[30:31]
	s_add_i32 m0, s29, 0xe000
	s_nop 0
	global_load_lds_dwordx4 v138, s[30:31]
	s_waitcnt vmcnt(8)
	s_waitcnt lgkmcnt(0)
	s_barrier
	s_waitcnt lgkmcnt(0)
	v_mfma_f32_16x16x32_bf16 v[124:127], v[152:155], v[184:187], 0
	v_mfma_f32_16x16x32_bf16 v[120:123], v[160:163], v[184:187], 0
	v_mfma_f32_16x16x32_bf16 v[116:119], v[152:155], v[196:199], 0
	v_mfma_f32_16x16x32_bf16 v[108:111], v[160:163], v[196:199], 0
	v_mfma_f32_16x16x32_bf16 v[100:103], v[152:155], v[204:207], 0
	v_mfma_f32_16x16x32_bf16 v[92:95], v[160:163], v[204:207], 0
	v_mfma_f32_16x16x32_bf16 v[84:87], v[152:155], v[212:215], 0
	v_mfma_f32_16x16x32_bf16 v[76:79], v[160:163], v[212:215], 0
	v_mfma_f32_16x16x32_bf16 v[124:127], v[156:159], v[192:195], v[124:127]
	v_mfma_f32_16x16x32_bf16 v[120:123], v[164:167], v[192:195], v[120:123]
	v_mfma_f32_16x16x32_bf16 v[116:119], v[156:159], v[200:203], v[116:119]
	v_mfma_f32_16x16x32_bf16 v[108:111], v[164:167], v[200:203], v[108:111]
	v_mfma_f32_16x16x32_bf16 v[100:103], v[156:159], v[208:211], v[100:103]
	v_mfma_f32_16x16x32_bf16 v[92:95], v[164:167], v[208:211], v[92:95]
	v_mfma_f32_16x16x32_bf16 v[84:87], v[156:159], v[216:219], v[84:87]
	v_mfma_f32_16x16x32_bf16 v[76:79], v[164:167], v[216:219], v[76:79]
	v_mfma_f32_16x16x32_bf16 v[112:115], v[168:171], v[184:187], 0
	v_mfma_f32_16x16x32_bf16 v[104:107], v[176:179], v[184:187], 0
	v_mfma_f32_16x16x32_bf16 v[96:99], v[168:171], v[196:199], 0
	v_mfma_f32_16x16x32_bf16 v[88:91], v[176:179], v[196:199], 0
	v_mfma_f32_16x16x32_bf16 v[80:83], v[168:171], v[204:207], 0
	v_mfma_f32_16x16x32_bf16 v[72:75], v[176:179], v[204:207], 0
	v_mfma_f32_16x16x32_bf16 v[68:71], v[168:171], v[212:215], 0
	v_mfma_f32_16x16x32_bf16 v[64:67], v[176:179], v[212:215], 0
	v_mfma_f32_16x16x32_bf16 v[112:115], v[172:175], v[192:195], v[112:115]
	v_mfma_f32_16x16x32_bf16 v[104:107], v[180:183], v[192:195], v[104:107]
	v_mfma_f32_16x16x32_bf16 v[96:99], v[172:175], v[200:203], v[96:99]
	v_mfma_f32_16x16x32_bf16 v[88:91], v[180:183], v[200:203], v[88:91]
	v_mfma_f32_16x16x32_bf16 v[80:83], v[172:175], v[208:211], v[80:83]
	v_mfma_f32_16x16x32_bf16 v[72:75], v[180:183], v[208:211], v[72:75]
	v_mfma_f32_16x16x32_bf16 v[68:71], v[172:175], v[216:219], v[68:71]
	v_mfma_f32_16x16x32_bf16 v[64:67], v[180:183], v[216:219], v[64:67]
	s_barrier
	s_add_i32 s79, s68, s61
	v_lshl_add_u64 v[144:145], s[34:35], 0, v[130:131]
	s_mov_b32 m0, s79
	ds_read_b128 v[184:187], v151 offset:16384
	ds_read_b128 v[192:195], v151 offset:17408
	ds_read_b128 v[196:199], v151 offset:18432
	ds_read_b128 v[200:203], v151 offset:19456
	ds_read_b128 v[204:207], v151 offset:20480
	ds_read_b128 v[208:211], v151 offset:21504
	ds_read_b128 v[212:215], v151 offset:22528
	ds_read_b128 v[216:219], v151 offset:23552
	global_load_lds_dwordx4 v[144:145], off
	s_add_i32 m0, s79, 0x2000
	s_add_u32 s80, s34, 0x40000
	v_lshl_add_u64 v[188:189], s[34:35], 0, v[134:135]
	s_addc_u32 s81, s35, 0
	s_add_i32 s79, s69, s61
	global_load_lds_dwordx4 v[188:189], off
	s_mov_b32 m0, s79
	v_lshl_add_u64 v[222:223], s[42:43], 0, v[132:133]
	global_load_lds_dwordx4 v130, s[80:81]
	s_add_i32 m0, s79, 0x2000
	s_nop 0
	global_load_lds_dwordx4 v134, s[80:81]
	v_lshl_add_u64 v[220:221], s[42:43], 0, v[128:129]
	s_mov_b32 m0, s29
	s_nop 0
	global_load_lds_dwordx4 v[220:221], off
	s_mov_b32 m0, s33
	s_nop 0
	global_load_lds_dwordx4 v[222:223], off
	s_waitcnt vmcnt(8)
	s_waitcnt lgkmcnt(0)
	s_barrier
	s_waitcnt lgkmcnt(0)
	v_mfma_f32_16x16x32_bf16 v[60:63], v[152:155], v[184:187], 0
	v_mfma_f32_16x16x32_bf16 v[56:59], v[160:163], v[184:187], 0
	v_mfma_f32_16x16x32_bf16 v[52:55], v[152:155], v[196:199], 0
	v_mfma_f32_16x16x32_bf16 v[44:47], v[160:163], v[196:199], 0
	v_mfma_f32_16x16x32_bf16 v[36:39], v[152:155], v[204:207], 0
	v_mfma_f32_16x16x32_bf16 v[28:31], v[160:163], v[204:207], 0
	v_mfma_f32_16x16x32_bf16 v[20:23], v[152:155], v[212:215], 0
	v_mfma_f32_16x16x32_bf16 v[12:15], v[160:163], v[212:215], 0
	v_mfma_f32_16x16x32_bf16 v[60:63], v[156:159], v[192:195], v[60:63]
	v_mfma_f32_16x16x32_bf16 v[56:59], v[164:167], v[192:195], v[56:59]
	v_mfma_f32_16x16x32_bf16 v[52:55], v[156:159], v[200:203], v[52:55]
	v_mfma_f32_16x16x32_bf16 v[44:47], v[164:167], v[200:203], v[44:47]
	v_mfma_f32_16x16x32_bf16 v[36:39], v[156:159], v[208:211], v[36:39]
	v_mfma_f32_16x16x32_bf16 v[28:31], v[164:167], v[208:211], v[28:31]
	v_mfma_f32_16x16x32_bf16 v[20:23], v[156:159], v[216:219], v[20:23]
	v_mfma_f32_16x16x32_bf16 v[12:15], v[164:167], v[216:219], v[12:15]
	v_mfma_f32_16x16x32_bf16 v[48:51], v[168:171], v[184:187], 0
	v_mfma_f32_16x16x32_bf16 v[40:43], v[176:179], v[184:187], 0
	v_mfma_f32_16x16x32_bf16 v[32:35], v[168:171], v[196:199], 0
	v_mfma_f32_16x16x32_bf16 v[24:27], v[176:179], v[196:199], 0
	v_mfma_f32_16x16x32_bf16 v[16:19], v[168:171], v[204:207], 0
	v_mfma_f32_16x16x32_bf16 v[8:11], v[176:179], v[204:207], 0
	v_mfma_f32_16x16x32_bf16 v[4:7], v[168:171], v[212:215], 0
	v_mfma_f32_16x16x32_bf16 v[0:3], v[176:179], v[212:215], 0
	v_mfma_f32_16x16x32_bf16 v[48:51], v[172:175], v[192:195], v[48:51]
	v_mfma_f32_16x16x32_bf16 v[40:43], v[180:183], v[192:195], v[40:43]
	v_mfma_f32_16x16x32_bf16 v[32:35], v[172:175], v[200:203], v[32:35]
	v_mfma_f32_16x16x32_bf16 v[24:27], v[180:183], v[200:203], v[24:27]
	v_mfma_f32_16x16x32_bf16 v[16:19], v[172:175], v[208:211], v[16:19]
	v_mfma_f32_16x16x32_bf16 v[8:11], v[180:183], v[208:211], v[8:11]
	v_mfma_f32_16x16x32_bf16 v[4:7], v[172:175], v[216:219], v[4:7]
	v_mfma_f32_16x16x32_bf16 v[0:3], v[180:183], v[216:219], v[0:3]
	s_barrier
	s_add_i32 s79, 0, 0x18000
	s_add_i32 s80, 0, 0x1c000
	v_add_u32_e32 v164, s79, v147
	v_add_u32_e32 v180, s80, v147
	ds_read_b128 v[152:155], v164
	ds_read_b128 v[156:159], v164 offset:1024
	ds_read_b128 v[160:163], v164 offset:2048
	ds_read_b128 v[164:167], v164 offset:3072
	ds_read_b128 v[168:171], v180
	ds_read_b128 v[172:175], v180 offset:1024
	ds_read_b128 v[176:179], v180 offset:2048
	ds_read_b128 v[180:183], v180 offset:3072
	s_add_u32 s42, s42, 0x40000
	s_addc_u32 s43, s43, 0
	s_mov_b32 m0, s62
	ds_read_b128 v[184:187], v151 offset:32768
	ds_read_b128 v[192:195], v151 offset:33792
	ds_read_b128 v[196:199], v151 offset:34816
	ds_read_b128 v[200:203], v151 offset:35840
	ds_read_b128 v[204:207], v151 offset:36864
	ds_read_b128 v[208:211], v151 offset:37888
	ds_read_b128 v[212:215], v151 offset:38912
	ds_read_b128 v[216:219], v151 offset:39936
	global_load_lds_dwordx4 v128, s[42:43]
	s_mov_b32 m0, s63
	s_nop 0
	global_load_lds_dwordx4 v132, s[42:43]
	s_waitcnt vmcnt(8)
	s_waitcnt lgkmcnt(0)
	s_barrier
	s_waitcnt lgkmcnt(0)
	v_mfma_f32_16x16x32_bf16 v[124:127], v[152:155], v[184:187], v[124:127]
	v_mfma_f32_16x16x32_bf16 v[120:123], v[160:163], v[184:187], v[120:123]
	v_mfma_f32_16x16x32_bf16 v[116:119], v[152:155], v[196:199], v[116:119]
	v_mfma_f32_16x16x32_bf16 v[108:111], v[160:163], v[196:199], v[108:111]
	v_mfma_f32_16x16x32_bf16 v[100:103], v[152:155], v[204:207], v[100:103]
	v_mfma_f32_16x16x32_bf16 v[92:95], v[160:163], v[204:207], v[92:95]
	v_mfma_f32_16x16x32_bf16 v[84:87], v[152:155], v[212:215], v[84:87]
	v_mfma_f32_16x16x32_bf16 v[76:79], v[160:163], v[212:215], v[76:79]
	v_mfma_f32_16x16x32_bf16 v[124:127], v[156:159], v[192:195], v[124:127]
	v_mfma_f32_16x16x32_bf16 v[120:123], v[164:167], v[192:195], v[120:123]
	v_mfma_f32_16x16x32_bf16 v[116:119], v[156:159], v[200:203], v[116:119]
	v_mfma_f32_16x16x32_bf16 v[108:111], v[164:167], v[200:203], v[108:111]
	v_mfma_f32_16x16x32_bf16 v[100:103], v[156:159], v[208:211], v[100:103]
	v_mfma_f32_16x16x32_bf16 v[92:95], v[164:167], v[208:211], v[92:95]
	v_mfma_f32_16x16x32_bf16 v[84:87], v[156:159], v[216:219], v[84:87]
	v_mfma_f32_16x16x32_bf16 v[76:79], v[164:167], v[216:219], v[76:79]
	v_mfma_f32_16x16x32_bf16 v[112:115], v[168:171], v[184:187], v[112:115]
	v_mfma_f32_16x16x32_bf16 v[104:107], v[176:179], v[184:187], v[104:107]
	v_mfma_f32_16x16x32_bf16 v[96:99], v[168:171], v[196:199], v[96:99]
	v_mfma_f32_16x16x32_bf16 v[88:91], v[176:179], v[196:199], v[88:91]
	v_mfma_f32_16x16x32_bf16 v[80:83], v[168:171], v[204:207], v[80:83]
	v_mfma_f32_16x16x32_bf16 v[72:75], v[176:179], v[204:207], v[72:75]
	v_mfma_f32_16x16x32_bf16 v[68:71], v[168:171], v[212:215], v[68:71]
	v_mfma_f32_16x16x32_bf16 v[64:67], v[176:179], v[212:215], v[64:67]
	v_mfma_f32_16x16x32_bf16 v[112:115], v[172:175], v[192:195], v[112:115]
	v_mfma_f32_16x16x32_bf16 v[104:107], v[180:183], v[192:195], v[104:107]
	v_mfma_f32_16x16x32_bf16 v[96:99], v[172:175], v[200:203], v[96:99]
	v_mfma_f32_16x16x32_bf16 v[88:91], v[180:183], v[200:203], v[88:91]
	v_mfma_f32_16x16x32_bf16 v[80:83], v[172:175], v[208:211], v[80:83]
	v_mfma_f32_16x16x32_bf16 v[72:75], v[180:183], v[208:211], v[72:75]
	v_mfma_f32_16x16x32_bf16 v[68:71], v[172:175], v[216:219], v[68:71]
	v_mfma_f32_16x16x32_bf16 v[64:67], v[180:183], v[216:219], v[64:67]
	s_barrier
	s_add_i32 s42, s79, s61
	v_lshl_add_u64 v[144:145], v[144:145], 0, s[10:11]
	s_mov_b32 m0, s42
	ds_read_b128 v[184:187], v151 offset:49152
	ds_read_b128 v[192:195], v151 offset:50176
	ds_read_b128 v[196:199], v151 offset:51200
	ds_read_b128 v[200:203], v151 offset:52224
	ds_read_b128 v[204:207], v151 offset:53248
	ds_read_b128 v[208:211], v151 offset:54272
	ds_read_b128 v[212:215], v151 offset:55296
	ds_read_b128 v[216:219], v151 offset:56320
	global_load_lds_dwordx4 v[144:145], off
	s_add_i32 m0, s42, 0x2000
	s_add_u32 s34, s34, 0x40080
	v_lshl_add_u64 v[144:145], v[188:189], 0, s[10:11]
	s_addc_u32 s35, s35, 0
	s_add_i32 s42, s80, s61
	global_load_lds_dwordx4 v[144:145], off
	s_mov_b32 m0, s42
	s_nop 0
	global_load_lds_dwordx4 v130, s[34:35]
	s_add_i32 m0, s42, 0x2000
	s_nop 0
	global_load_lds_dwordx4 v134, s[34:35]
	v_lshl_add_u64 v[144:145], v[220:221], 0, s[10:11]
	s_mov_b32 m0, s65
	s_nop 0
	global_load_lds_dwordx4 v[144:145], off
	v_lshl_add_u64 v[144:145], v[222:223], 0, s[10:11]
	s_mov_b32 m0, s66
	s_nop 0
	global_load_lds_dwordx4 v[144:145], off
	s_waitcnt vmcnt(8)
	s_waitcnt lgkmcnt(0)
	s_barrier
	s_waitcnt lgkmcnt(0)
	v_mfma_f32_16x16x32_bf16 v[60:63], v[152:155], v[184:187], v[60:63]
	v_mfma_f32_16x16x32_bf16 v[56:59], v[160:163], v[184:187], v[56:59]
	v_mfma_f32_16x16x32_bf16 v[52:55], v[152:155], v[196:199], v[52:55]
	v_mfma_f32_16x16x32_bf16 v[44:47], v[160:163], v[196:199], v[44:47]
	v_mfma_f32_16x16x32_bf16 v[36:39], v[152:155], v[204:207], v[36:39]
	v_mfma_f32_16x16x32_bf16 v[28:31], v[160:163], v[204:207], v[28:31]
	v_mfma_f32_16x16x32_bf16 v[20:23], v[152:155], v[212:215], v[20:23]
	v_mfma_f32_16x16x32_bf16 v[12:15], v[160:163], v[212:215], v[12:15]
	v_mfma_f32_16x16x32_bf16 v[60:63], v[156:159], v[192:195], v[60:63]
	v_mfma_f32_16x16x32_bf16 v[56:59], v[164:167], v[192:195], v[56:59]
	v_mfma_f32_16x16x32_bf16 v[52:55], v[156:159], v[200:203], v[52:55]
	v_mfma_f32_16x16x32_bf16 v[44:47], v[164:167], v[200:203], v[44:47]
	v_mfma_f32_16x16x32_bf16 v[36:39], v[156:159], v[208:211], v[36:39]
	v_mfma_f32_16x16x32_bf16 v[28:31], v[164:167], v[208:211], v[28:31]
	v_mfma_f32_16x16x32_bf16 v[20:23], v[156:159], v[216:219], v[20:23]
	v_mfma_f32_16x16x32_bf16 v[12:15], v[164:167], v[216:219], v[12:15]
	v_mfma_f32_16x16x32_bf16 v[48:51], v[168:171], v[184:187], v[48:51]
	v_mfma_f32_16x16x32_bf16 v[40:43], v[176:179], v[184:187], v[40:43]
	v_mfma_f32_16x16x32_bf16 v[32:35], v[168:171], v[196:199], v[32:35]
	v_mfma_f32_16x16x32_bf16 v[24:27], v[176:179], v[196:199], v[24:27]
	v_mfma_f32_16x16x32_bf16 v[16:19], v[168:171], v[204:207], v[16:19]
	v_mfma_f32_16x16x32_bf16 v[8:11], v[176:179], v[204:207], v[8:11]
	v_mfma_f32_16x16x32_bf16 v[4:7], v[168:171], v[212:215], v[4:7]
	v_mfma_f32_16x16x32_bf16 v[0:3], v[176:179], v[212:215], v[0:3]
	v_mfma_f32_16x16x32_bf16 v[48:51], v[172:175], v[192:195], v[48:51]
	v_mfma_f32_16x16x32_bf16 v[40:43], v[180:183], v[192:195], v[40:43]
	v_mfma_f32_16x16x32_bf16 v[32:35], v[172:175], v[200:203], v[32:35]
	v_mfma_f32_16x16x32_bf16 v[24:27], v[180:183], v[200:203], v[24:27]
	v_mfma_f32_16x16x32_bf16 v[16:19], v[172:175], v[208:211], v[16:19]
	v_mfma_f32_16x16x32_bf16 v[8:11], v[180:183], v[208:211], v[8:11]
	v_mfma_f32_16x16x32_bf16 v[4:7], v[172:175], v[216:219], v[4:7]
	v_mfma_f32_16x16x32_bf16 v[0:3], v[180:183], v[216:219], v[0:3]
	s_barrier
	s_add_i32 s77, s77, 2
	s_add_u32 s30, s30, 0x100
	s_addc_u32 s31, s31, 0
	s_add_u32 s75, s75, 0x100
	s_addc_u32 s76, s76, 0
	s_cmp_gt_u32 s77, 13
	s_cbranch_scc0 .LBB0_1434
	s_branch .Lpeel_exit10
.LBB0_1434:
	ds_read_b128 v[152:155], v149
	ds_read_b128 v[156:159], v149 offset:1024
	ds_read_b128 v[160:163], v149 offset:2048
	ds_read_b128 v[164:167], v149 offset:3072
	ds_read_b128 v[168:171], v150
	ds_read_b128 v[172:175], v150 offset:1024
	ds_read_b128 v[176:179], v150 offset:2048
	ds_read_b128 v[180:183], v150 offset:3072
	s_add_u32 s34, s30, 0xfffc0080
	s_addc_u32 s35, s31, -1
	s_cmp_eq_u32 s77, 12
	s_cselect_b32 s43, s23, s35
	s_cselect_b32 s42, s55, s34
	s_cselect_b32 s35, s21, s76
	s_cselect_b32 s34, s74, s75
	s_add_i32 m0, s29, 0xc000
	ds_read_b128 v[184:187], v151
	ds_read_b128 v[192:195], v151 offset:1024
	ds_read_b128 v[196:199], v151 offset:2048
	ds_read_b128 v[200:203], v151 offset:3072
	ds_read_b128 v[204:207], v151 offset:4096
	ds_read_b128 v[208:211], v151 offset:5120
	ds_read_b128 v[212:215], v151 offset:6144
	ds_read_b128 v[216:219], v151 offset:7168
	global_load_lds_dwordx4 v136, s[30:31]
	s_add_i32 m0, s29, 0xe000
	s_nop 0
	global_load_lds_dwordx4 v138, s[30:31]
	s_waitcnt vmcnt(8)
	s_waitcnt lgkmcnt(0)
	s_barrier
	s_waitcnt lgkmcnt(0)
	v_mfma_f32_16x16x32_bf16 v[124:127], v[152:155], v[184:187], v[124:127]
	v_mfma_f32_16x16x32_bf16 v[120:123], v[160:163], v[184:187], v[120:123]
	v_mfma_f32_16x16x32_bf16 v[116:119], v[152:155], v[196:199], v[116:119]
	v_mfma_f32_16x16x32_bf16 v[108:111], v[160:163], v[196:199], v[108:111]
	v_mfma_f32_16x16x32_bf16 v[100:103], v[152:155], v[204:207], v[100:103]
	v_mfma_f32_16x16x32_bf16 v[92:95], v[160:163], v[204:207], v[92:95]
	v_mfma_f32_16x16x32_bf16 v[84:87], v[152:155], v[212:215], v[84:87]
	v_mfma_f32_16x16x32_bf16 v[76:79], v[160:163], v[212:215], v[76:79]
	v_mfma_f32_16x16x32_bf16 v[124:127], v[156:159], v[192:195], v[124:127]
	v_mfma_f32_16x16x32_bf16 v[120:123], v[164:167], v[192:195], v[120:123]
	v_mfma_f32_16x16x32_bf16 v[116:119], v[156:159], v[200:203], v[116:119]
	v_mfma_f32_16x16x32_bf16 v[108:111], v[164:167], v[200:203], v[108:111]
	v_mfma_f32_16x16x32_bf16 v[100:103], v[156:159], v[208:211], v[100:103]
	v_mfma_f32_16x16x32_bf16 v[92:95], v[164:167], v[208:211], v[92:95]
	v_mfma_f32_16x16x32_bf16 v[84:87], v[156:159], v[216:219], v[84:87]
	v_mfma_f32_16x16x32_bf16 v[76:79], v[164:167], v[216:219], v[76:79]
	v_mfma_f32_16x16x32_bf16 v[112:115], v[168:171], v[184:187], v[112:115]
	v_mfma_f32_16x16x32_bf16 v[104:107], v[176:179], v[184:187], v[104:107]
	v_mfma_f32_16x16x32_bf16 v[96:99], v[168:171], v[196:199], v[96:99]
	v_mfma_f32_16x16x32_bf16 v[88:91], v[176:179], v[196:199], v[88:91]
	v_mfma_f32_16x16x32_bf16 v[80:83], v[168:171], v[204:207], v[80:83]
	v_mfma_f32_16x16x32_bf16 v[72:75], v[176:179], v[204:207], v[72:75]
	v_mfma_f32_16x16x32_bf16 v[68:71], v[168:171], v[212:215], v[68:71]
	v_mfma_f32_16x16x32_bf16 v[64:67], v[176:179], v[212:215], v[64:67]
	v_mfma_f32_16x16x32_bf16 v[112:115], v[172:175], v[192:195], v[112:115]
	v_mfma_f32_16x16x32_bf16 v[104:107], v[180:183], v[192:195], v[104:107]
	v_mfma_f32_16x16x32_bf16 v[96:99], v[172:175], v[200:203], v[96:99]
	v_mfma_f32_16x16x32_bf16 v[88:91], v[180:183], v[200:203], v[88:91]
	v_mfma_f32_16x16x32_bf16 v[80:83], v[172:175], v[208:211], v[80:83]
	v_mfma_f32_16x16x32_bf16 v[72:75], v[180:183], v[208:211], v[72:75]
	v_mfma_f32_16x16x32_bf16 v[68:71], v[172:175], v[216:219], v[68:71]
	v_mfma_f32_16x16x32_bf16 v[64:67], v[180:183], v[216:219], v[64:67]
	s_barrier
	s_add_i32 s79, s68, s61
	v_lshl_add_u64 v[144:145], s[34:35], 0, v[130:131]
	s_mov_b32 m0, s79
	ds_read_b128 v[184:187], v151 offset:16384
	ds_read_b128 v[192:195], v151 offset:17408
	ds_read_b128 v[196:199], v151 offset:18432
	ds_read_b128 v[200:203], v151 offset:19456
	ds_read_b128 v[204:207], v151 offset:20480
	ds_read_b128 v[208:211], v151 offset:21504
	ds_read_b128 v[212:215], v151 offset:22528
	ds_read_b128 v[216:219], v151 offset:23552
	global_load_lds_dwordx4 v[144:145], off
	s_add_i32 m0, s79, 0x2000
	s_add_u32 s80, s34, 0x40000
	v_lshl_add_u64 v[188:189], s[34:35], 0, v[134:135]
	s_addc_u32 s81, s35, 0
	s_add_i32 s79, s69, s61
	global_load_lds_dwordx4 v[188:189], off
	s_mov_b32 m0, s79
	v_lshl_add_u64 v[222:223], s[42:43], 0, v[132:133]
	global_load_lds_dwordx4 v130, s[80:81]
	s_add_i32 m0, s79, 0x2000
	s_nop 0
	global_load_lds_dwordx4 v134, s[80:81]
	v_lshl_add_u64 v[220:221], s[42:43], 0, v[128:129]
	s_mov_b32 m0, s29
	s_nop 0
	global_load_lds_dwordx4 v[220:221], off
	s_mov_b32 m0, s33
	s_nop 0
	global_load_lds_dwordx4 v[222:223], off
	s_waitcnt vmcnt(8)
	s_waitcnt lgkmcnt(0)
	s_barrier
	s_waitcnt lgkmcnt(0)
	v_mfma_f32_16x16x32_bf16 v[60:63], v[152:155], v[184:187], v[60:63]
	v_mfma_f32_16x16x32_bf16 v[56:59], v[160:163], v[184:187], v[56:59]
	v_mfma_f32_16x16x32_bf16 v[52:55], v[152:155], v[196:199], v[52:55]
	v_mfma_f32_16x16x32_bf16 v[44:47], v[160:163], v[196:199], v[44:47]
	v_mfma_f32_16x16x32_bf16 v[36:39], v[152:155], v[204:207], v[36:39]
	v_mfma_f32_16x16x32_bf16 v[28:31], v[160:163], v[204:207], v[28:31]
	v_mfma_f32_16x16x32_bf16 v[20:23], v[152:155], v[212:215], v[20:23]
	v_mfma_f32_16x16x32_bf16 v[12:15], v[160:163], v[212:215], v[12:15]
	v_mfma_f32_16x16x32_bf16 v[60:63], v[156:159], v[192:195], v[60:63]
	v_mfma_f32_16x16x32_bf16 v[56:59], v[164:167], v[192:195], v[56:59]
	v_mfma_f32_16x16x32_bf16 v[52:55], v[156:159], v[200:203], v[52:55]
	v_mfma_f32_16x16x32_bf16 v[44:47], v[164:167], v[200:203], v[44:47]
	v_mfma_f32_16x16x32_bf16 v[36:39], v[156:159], v[208:211], v[36:39]
	v_mfma_f32_16x16x32_bf16 v[28:31], v[164:167], v[208:211], v[28:31]
	v_mfma_f32_16x16x32_bf16 v[20:23], v[156:159], v[216:219], v[20:23]
	v_mfma_f32_16x16x32_bf16 v[12:15], v[164:167], v[216:219], v[12:15]
	v_mfma_f32_16x16x32_bf16 v[48:51], v[168:171], v[184:187], v[48:51]
	v_mfma_f32_16x16x32_bf16 v[40:43], v[176:179], v[184:187], v[40:43]
	v_mfma_f32_16x16x32_bf16 v[32:35], v[168:171], v[196:199], v[32:35]
	v_mfma_f32_16x16x32_bf16 v[24:27], v[176:179], v[196:199], v[24:27]
	v_mfma_f32_16x16x32_bf16 v[16:19], v[168:171], v[204:207], v[16:19]
	v_mfma_f32_16x16x32_bf16 v[8:11], v[176:179], v[204:207], v[8:11]
	v_mfma_f32_16x16x32_bf16 v[4:7], v[168:171], v[212:215], v[4:7]
	v_mfma_f32_16x16x32_bf16 v[0:3], v[176:179], v[212:215], v[0:3]
	v_mfma_f32_16x16x32_bf16 v[48:51], v[172:175], v[192:195], v[48:51]
	v_mfma_f32_16x16x32_bf16 v[40:43], v[180:183], v[192:195], v[40:43]
	v_mfma_f32_16x16x32_bf16 v[32:35], v[172:175], v[200:203], v[32:35]
	v_mfma_f32_16x16x32_bf16 v[24:27], v[180:183], v[200:203], v[24:27]
	v_mfma_f32_16x16x32_bf16 v[16:19], v[172:175], v[208:211], v[16:19]
	v_mfma_f32_16x16x32_bf16 v[8:11], v[180:183], v[208:211], v[8:11]
	v_mfma_f32_16x16x32_bf16 v[4:7], v[172:175], v[216:219], v[4:7]
	v_mfma_f32_16x16x32_bf16 v[0:3], v[180:183], v[216:219], v[0:3]
	s_barrier
	s_add_i32 s79, 0, 0x18000
	s_add_i32 s80, 0, 0x1c000
	v_add_u32_e32 v164, s79, v147
	v_add_u32_e32 v180, s80, v147
	ds_read_b128 v[152:155], v164
	ds_read_b128 v[156:159], v164 offset:1024
	ds_read_b128 v[160:163], v164 offset:2048
	ds_read_b128 v[164:167], v164 offset:3072
	ds_read_b128 v[168:171], v180
	ds_read_b128 v[172:175], v180 offset:1024
	ds_read_b128 v[176:179], v180 offset:2048
	ds_read_b128 v[180:183], v180 offset:3072
	s_add_u32 s42, s42, 0x40000
	s_addc_u32 s43, s43, 0
	s_mov_b32 m0, s62
	ds_read_b128 v[184:187], v151 offset:32768
	ds_read_b128 v[192:195], v151 offset:33792
	ds_read_b128 v[196:199], v151 offset:34816
	ds_read_b128 v[200:203], v151 offset:35840
	ds_read_b128 v[204:207], v151 offset:36864
	ds_read_b128 v[208:211], v151 offset:37888
	ds_read_b128 v[212:215], v151 offset:38912
	ds_read_b128 v[216:219], v151 offset:39936
	global_load_lds_dwordx4 v128, s[42:43]
	s_mov_b32 m0, s63
	s_nop 0
	global_load_lds_dwordx4 v132, s[42:43]
	s_waitcnt vmcnt(8)
	s_waitcnt lgkmcnt(0)
	s_barrier
	s_waitcnt lgkmcnt(0)
	v_mfma_f32_16x16x32_bf16 v[124:127], v[152:155], v[184:187], v[124:127]
	v_mfma_f32_16x16x32_bf16 v[120:123], v[160:163], v[184:187], v[120:123]
	v_mfma_f32_16x16x32_bf16 v[116:119], v[152:155], v[196:199], v[116:119]
	v_mfma_f32_16x16x32_bf16 v[108:111], v[160:163], v[196:199], v[108:111]
	v_mfma_f32_16x16x32_bf16 v[100:103], v[152:155], v[204:207], v[100:103]
	v_mfma_f32_16x16x32_bf16 v[92:95], v[160:163], v[204:207], v[92:95]
	v_mfma_f32_16x16x32_bf16 v[84:87], v[152:155], v[212:215], v[84:87]
	v_mfma_f32_16x16x32_bf16 v[76:79], v[160:163], v[212:215], v[76:79]
	v_mfma_f32_16x16x32_bf16 v[124:127], v[156:159], v[192:195], v[124:127]
	v_mfma_f32_16x16x32_bf16 v[120:123], v[164:167], v[192:195], v[120:123]
	v_mfma_f32_16x16x32_bf16 v[116:119], v[156:159], v[200:203], v[116:119]
	v_mfma_f32_16x16x32_bf16 v[108:111], v[164:167], v[200:203], v[108:111]
	v_mfma_f32_16x16x32_bf16 v[100:103], v[156:159], v[208:211], v[100:103]
	v_mfma_f32_16x16x32_bf16 v[92:95], v[164:167], v[208:211], v[92:95]
	v_mfma_f32_16x16x32_bf16 v[84:87], v[156:159], v[216:219], v[84:87]
	v_mfma_f32_16x16x32_bf16 v[76:79], v[164:167], v[216:219], v[76:79]
	v_mfma_f32_16x16x32_bf16 v[112:115], v[168:171], v[184:187], v[112:115]
	v_mfma_f32_16x16x32_bf16 v[104:107], v[176:179], v[184:187], v[104:107]
	v_mfma_f32_16x16x32_bf16 v[96:99], v[168:171], v[196:199], v[96:99]
	v_mfma_f32_16x16x32_bf16 v[88:91], v[176:179], v[196:199], v[88:91]
	v_mfma_f32_16x16x32_bf16 v[80:83], v[168:171], v[204:207], v[80:83]
	v_mfma_f32_16x16x32_bf16 v[72:75], v[176:179], v[204:207], v[72:75]
	v_mfma_f32_16x16x32_bf16 v[68:71], v[168:171], v[212:215], v[68:71]
	v_mfma_f32_16x16x32_bf16 v[64:67], v[176:179], v[212:215], v[64:67]
	v_mfma_f32_16x16x32_bf16 v[112:115], v[172:175], v[192:195], v[112:115]
	v_mfma_f32_16x16x32_bf16 v[104:107], v[180:183], v[192:195], v[104:107]
	v_mfma_f32_16x16x32_bf16 v[96:99], v[172:175], v[200:203], v[96:99]
	v_mfma_f32_16x16x32_bf16 v[88:91], v[180:183], v[200:203], v[88:91]
	v_mfma_f32_16x16x32_bf16 v[80:83], v[172:175], v[208:211], v[80:83]
	v_mfma_f32_16x16x32_bf16 v[72:75], v[180:183], v[208:211], v[72:75]
	v_mfma_f32_16x16x32_bf16 v[68:71], v[172:175], v[216:219], v[68:71]
	v_mfma_f32_16x16x32_bf16 v[64:67], v[180:183], v[216:219], v[64:67]
	s_barrier
	s_add_i32 s42, s79, s61
	v_lshl_add_u64 v[144:145], v[144:145], 0, s[10:11]
	s_mov_b32 m0, s42
	ds_read_b128 v[184:187], v151 offset:49152
	ds_read_b128 v[192:195], v151 offset:50176
	ds_read_b128 v[196:199], v151 offset:51200
	ds_read_b128 v[200:203], v151 offset:52224
	ds_read_b128 v[204:207], v151 offset:53248
	ds_read_b128 v[208:211], v151 offset:54272
	ds_read_b128 v[212:215], v151 offset:55296
	ds_read_b128 v[216:219], v151 offset:56320
	global_load_lds_dwordx4 v[144:145], off
	s_add_i32 m0, s42, 0x2000
	s_add_u32 s34, s34, 0x40080
	v_lshl_add_u64 v[144:145], v[188:189], 0, s[10:11]
	s_addc_u32 s35, s35, 0
	s_add_i32 s42, s80, s61
	global_load_lds_dwordx4 v[144:145], off
	s_mov_b32 m0, s42
	s_nop 0
	global_load_lds_dwordx4 v130, s[34:35]
	s_add_i32 m0, s42, 0x2000
	s_nop 0
	global_load_lds_dwordx4 v134, s[34:35]
	v_lshl_add_u64 v[144:145], v[220:221], 0, s[10:11]
	s_mov_b32 m0, s65
	s_nop 0
	global_load_lds_dwordx4 v[144:145], off
	v_lshl_add_u64 v[144:145], v[222:223], 0, s[10:11]
	s_mov_b32 m0, s66
	s_nop 0
	global_load_lds_dwordx4 v[144:145], off
	s_waitcnt vmcnt(8)
	s_waitcnt lgkmcnt(0)
	s_barrier
	s_waitcnt lgkmcnt(0)
	v_mfma_f32_16x16x32_bf16 v[60:63], v[152:155], v[184:187], v[60:63]
	v_mfma_f32_16x16x32_bf16 v[56:59], v[160:163], v[184:187], v[56:59]
	v_mfma_f32_16x16x32_bf16 v[52:55], v[152:155], v[196:199], v[52:55]
	v_mfma_f32_16x16x32_bf16 v[44:47], v[160:163], v[196:199], v[44:47]
	v_mfma_f32_16x16x32_bf16 v[36:39], v[152:155], v[204:207], v[36:39]
	v_mfma_f32_16x16x32_bf16 v[28:31], v[160:163], v[204:207], v[28:31]
	v_mfma_f32_16x16x32_bf16 v[20:23], v[152:155], v[212:215], v[20:23]
	v_mfma_f32_16x16x32_bf16 v[12:15], v[160:163], v[212:215], v[12:15]
	v_mfma_f32_16x16x32_bf16 v[60:63], v[156:159], v[192:195], v[60:63]
	v_mfma_f32_16x16x32_bf16 v[56:59], v[164:167], v[192:195], v[56:59]
	v_mfma_f32_16x16x32_bf16 v[52:55], v[156:159], v[200:203], v[52:55]
	v_mfma_f32_16x16x32_bf16 v[44:47], v[164:167], v[200:203], v[44:47]
	v_mfma_f32_16x16x32_bf16 v[36:39], v[156:159], v[208:211], v[36:39]
	v_mfma_f32_16x16x32_bf16 v[28:31], v[164:167], v[208:211], v[28:31]
	v_mfma_f32_16x16x32_bf16 v[20:23], v[156:159], v[216:219], v[20:23]
	v_mfma_f32_16x16x32_bf16 v[12:15], v[164:167], v[216:219], v[12:15]
	v_mfma_f32_16x16x32_bf16 v[48:51], v[168:171], v[184:187], v[48:51]
	v_mfma_f32_16x16x32_bf16 v[40:43], v[176:179], v[184:187], v[40:43]
	v_mfma_f32_16x16x32_bf16 v[32:35], v[168:171], v[196:199], v[32:35]
	v_mfma_f32_16x16x32_bf16 v[24:27], v[176:179], v[196:199], v[24:27]
	v_mfma_f32_16x16x32_bf16 v[16:19], v[168:171], v[204:207], v[16:19]
	v_mfma_f32_16x16x32_bf16 v[8:11], v[176:179], v[204:207], v[8:11]
	v_mfma_f32_16x16x32_bf16 v[4:7], v[168:171], v[212:215], v[4:7]
	v_mfma_f32_16x16x32_bf16 v[0:3], v[176:179], v[212:215], v[0:3]
	v_mfma_f32_16x16x32_bf16 v[48:51], v[172:175], v[192:195], v[48:51]
	v_mfma_f32_16x16x32_bf16 v[40:43], v[180:183], v[192:195], v[40:43]
	v_mfma_f32_16x16x32_bf16 v[32:35], v[172:175], v[200:203], v[32:35]
	v_mfma_f32_16x16x32_bf16 v[24:27], v[180:183], v[200:203], v[24:27]
	v_mfma_f32_16x16x32_bf16 v[16:19], v[172:175], v[208:211], v[16:19]
	v_mfma_f32_16x16x32_bf16 v[8:11], v[180:183], v[208:211], v[8:11]
	v_mfma_f32_16x16x32_bf16 v[4:7], v[172:175], v[216:219], v[4:7]
	v_mfma_f32_16x16x32_bf16 v[0:3], v[180:183], v[216:219], v[0:3]
	s_barrier
	s_add_i32 s77, s77, 2
	s_add_u32 s30, s30, 0x100
	s_addc_u32 s31, s31, 0
	s_add_u32 s75, s75, 0x100
	s_addc_u32 s76, s76, 0
	s_cmp_gt_u32 s77, 13
	s_cbranch_scc0 .LBB0_1434

.LBB0_1570:
	s_ashr_i32 s23, s22, 31
	s_lshl_b64 s[24:25], s[22:23], 19
	s_add_u32 s24, s58, s24
	s_addc_u32 s25, s59, s25
	s_and_b64 s[26:27], s[0:1], exec
	s_cselect_b32 s23, s25, s31
	s_cselect_b32 s54, s24, s30
	s_ashr_i32 s21, s20, 31
	s_lshl_b64 s[26:27], s[20:21], 19
	s_add_u32 s26, s61, s26
	s_addc_u32 s27, s62, s27
	s_and_b64 s[42:43], s[0:1], exec
	s_cselect_b32 s21, s27, s35
	s_cselect_b32 s55, s26, s34
	s_add_u32 s30, s30, 0x40080
	s_addc_u32 s31, s31, 0
	s_add_u32 s75, s34, 0x100
	s_addc_u32 s76, s35, 0
	s_mov_b32 s77, -2
	ds_read_b128 v[152:155], v149
	ds_read_b128 v[156:159], v149 offset:1024
	ds_read_b128 v[160:163], v149 offset:2048
	ds_read_b128 v[164:167], v149 offset:3072
	ds_read_b128 v[168:171], v150
	ds_read_b128 v[172:175], v150 offset:1024
	ds_read_b128 v[176:179], v150 offset:2048
	ds_read_b128 v[180:183], v150 offset:3072
	s_add_u32 s34, s30, 0xfffc0080
	s_addc_u32 s35, s31, -1
	s_cmp_eq_u32 s77, 12
	s_cselect_b32 s43, s23, s35
	s_cselect_b32 s42, s54, s34
	s_cselect_b32 s35, s21, s76
	s_cselect_b32 s34, s55, s75
	s_add_i32 m0, s29, 0xc000
	ds_read_b128 v[184:187], v151
	ds_read_b128 v[192:195], v151 offset:1024
	ds_read_b128 v[196:199], v151 offset:2048
	ds_read_b128 v[200:203], v151 offset:3072
	ds_read_b128 v[204:207], v151 offset:4096
	ds_read_b128 v[208:211], v151 offset:5120
	ds_read_b128 v[212:215], v151 offset:6144
	ds_read_b128 v[216:219], v151 offset:7168
	global_load_lds_dwordx4 v136, s[30:31]
	s_add_i32 m0, s29, 0xe000
	s_nop 0
	global_load_lds_dwordx4 v138, s[30:31]
	s_waitcnt vmcnt(8)
	s_waitcnt lgkmcnt(0)
	s_barrier
	s_waitcnt lgkmcnt(0)
	v_mfma_f32_16x16x32_bf16 v[124:127], v[152:155], v[184:187], 0
	v_mfma_f32_16x16x32_bf16 v[120:123], v[160:163], v[184:187], 0
	v_mfma_f32_16x16x32_bf16 v[108:111], v[152:155], v[196:199], 0
	v_mfma_f32_16x16x32_bf16 v[104:107], v[160:163], v[196:199], 0
	v_mfma_f32_16x16x32_bf16 v[92:95], v[152:155], v[204:207], 0
	v_mfma_f32_16x16x32_bf16 v[88:91], v[160:163], v[204:207], 0
	v_mfma_f32_16x16x32_bf16 v[76:79], v[152:155], v[212:215], 0
	v_mfma_f32_16x16x32_bf16 v[72:75], v[160:163], v[212:215], 0
	v_mfma_f32_16x16x32_bf16 v[124:127], v[156:159], v[192:195], v[124:127]
	v_mfma_f32_16x16x32_bf16 v[120:123], v[164:167], v[192:195], v[120:123]
	v_mfma_f32_16x16x32_bf16 v[108:111], v[156:159], v[200:203], v[108:111]
	v_mfma_f32_16x16x32_bf16 v[104:107], v[164:167], v[200:203], v[104:107]
	v_mfma_f32_16x16x32_bf16 v[92:95], v[156:159], v[208:211], v[92:95]
	v_mfma_f32_16x16x32_bf16 v[88:91], v[164:167], v[208:211], v[88:91]
	v_mfma_f32_16x16x32_bf16 v[76:79], v[156:159], v[216:219], v[76:79]
	v_mfma_f32_16x16x32_bf16 v[72:75], v[164:167], v[216:219], v[72:75]
	v_mfma_f32_16x16x32_bf16 v[116:119], v[168:171], v[184:187], 0
	v_mfma_f32_16x16x32_bf16 v[112:115], v[176:179], v[184:187], 0
	v_mfma_f32_16x16x32_bf16 v[100:103], v[168:171], v[196:199], 0
	v_mfma_f32_16x16x32_bf16 v[96:99], v[176:179], v[196:199], 0
	v_mfma_f32_16x16x32_bf16 v[84:87], v[168:171], v[204:207], 0
	v_mfma_f32_16x16x32_bf16 v[80:83], v[176:179], v[204:207], 0
	v_mfma_f32_16x16x32_bf16 v[68:71], v[168:171], v[212:215], 0
	v_mfma_f32_16x16x32_bf16 v[64:67], v[176:179], v[212:215], 0
	v_mfma_f32_16x16x32_bf16 v[116:119], v[172:175], v[192:195], v[116:119]
	v_mfma_f32_16x16x32_bf16 v[112:115], v[180:183], v[192:195], v[112:115]
	v_mfma_f32_16x16x32_bf16 v[100:103], v[172:175], v[200:203], v[100:103]
	v_mfma_f32_16x16x32_bf16 v[96:99], v[180:183], v[200:203], v[96:99]
	v_mfma_f32_16x16x32_bf16 v[84:87], v[172:175], v[208:211], v[84:87]
	v_mfma_f32_16x16x32_bf16 v[80:83], v[180:183], v[208:211], v[80:83]
	v_mfma_f32_16x16x32_bf16 v[68:71], v[172:175], v[216:219], v[68:71]
	v_mfma_f32_16x16x32_bf16 v[64:67], v[180:183], v[216:219], v[64:67]
	s_barrier
	s_add_i32 s79, s69, s63
	v_lshl_add_u64 v[144:145], s[34:35], 0, v[130:131]
	s_mov_b32 m0, s79
	ds_read_b128 v[184:187], v151 offset:16384
	ds_read_b128 v[192:195], v151 offset:17408
	ds_read_b128 v[196:199], v151 offset:18432
	ds_read_b128 v[200:203], v151 offset:19456
	ds_read_b128 v[204:207], v151 offset:20480
	ds_read_b128 v[208:211], v151 offset:21504
	ds_read_b128 v[212:215], v151 offset:22528
	ds_read_b128 v[216:219], v151 offset:23552
	global_load_lds_dwordx4 v[144:145], off
	s_add_i32 m0, s79, 0x2000
	s_add_u32 s80, s34, 0x40000
	v_lshl_add_u64 v[188:189], s[34:35], 0, v[134:135]
	s_addc_u32 s81, s35, 0
	s_add_i32 s79, s70, s63
	global_load_lds_dwordx4 v[188:189], off
	s_mov_b32 m0, s79
	v_lshl_add_u64 v[222:223], s[42:43], 0, v[132:133]
	global_load_lds_dwordx4 v130, s[80:81]
	s_add_i32 m0, s79, 0x2000
	s_nop 0
	global_load_lds_dwordx4 v134, s[80:81]
	v_lshl_add_u64 v[220:221], s[42:43], 0, v[128:129]
	s_mov_b32 m0, s29
	s_nop 0
	global_load_lds_dwordx4 v[220:221], off
	s_mov_b32 m0, s64
	s_nop 0
	global_load_lds_dwordx4 v[222:223], off
	s_waitcnt vmcnt(8)
	s_waitcnt lgkmcnt(0)
	s_barrier
	s_waitcnt lgkmcnt(0)
	v_mfma_f32_16x16x32_bf16 v[60:63], v[152:155], v[184:187], 0
	v_mfma_f32_16x16x32_bf16 v[56:59], v[160:163], v[184:187], 0
	v_mfma_f32_16x16x32_bf16 v[44:47], v[152:155], v[196:199], 0
	v_mfma_f32_16x16x32_bf16 v[40:43], v[160:163], v[196:199], 0
	v_mfma_f32_16x16x32_bf16 v[28:31], v[152:155], v[204:207], 0
	v_mfma_f32_16x16x32_bf16 v[24:27], v[160:163], v[204:207], 0
	v_mfma_f32_16x16x32_bf16 v[12:15], v[152:155], v[212:215], 0
	v_mfma_f32_16x16x32_bf16 v[8:11], v[160:163], v[212:215], 0
	v_mfma_f32_16x16x32_bf16 v[60:63], v[156:159], v[192:195], v[60:63]
	v_mfma_f32_16x16x32_bf16 v[56:59], v[164:167], v[192:195], v[56:59]
	v_mfma_f32_16x16x32_bf16 v[44:47], v[156:159], v[200:203], v[44:47]
	v_mfma_f32_16x16x32_bf16 v[40:43], v[164:167], v[200:203], v[40:43]
	v_mfma_f32_16x16x32_bf16 v[28:31], v[156:159], v[208:211], v[28:31]
	v_mfma_f32_16x16x32_bf16 v[24:27], v[164:167], v[208:211], v[24:27]
	v_mfma_f32_16x16x32_bf16 v[12:15], v[156:159], v[216:219], v[12:15]
	v_mfma_f32_16x16x32_bf16 v[8:11], v[164:167], v[216:219], v[8:11]
	v_mfma_f32_16x16x32_bf16 v[52:55], v[168:171], v[184:187], 0
	v_mfma_f32_16x16x32_bf16 v[48:51], v[176:179], v[184:187], 0
	v_mfma_f32_16x16x32_bf16 v[36:39], v[168:171], v[196:199], 0
	v_mfma_f32_16x16x32_bf16 v[32:35], v[176:179], v[196:199], 0
	v_mfma_f32_16x16x32_bf16 v[20:23], v[168:171], v[204:207], 0
	v_mfma_f32_16x16x32_bf16 v[16:19], v[176:179], v[204:207], 0
	v_mfma_f32_16x16x32_bf16 v[4:7], v[168:171], v[212:215], 0
	v_mfma_f32_16x16x32_bf16 v[0:3], v[176:179], v[212:215], 0
	v_mfma_f32_16x16x32_bf16 v[52:55], v[172:175], v[192:195], v[52:55]
	v_mfma_f32_16x16x32_bf16 v[48:51], v[180:183], v[192:195], v[48:51]
	v_mfma_f32_16x16x32_bf16 v[36:39], v[172:175], v[200:203], v[36:39]
	v_mfma_f32_16x16x32_bf16 v[32:35], v[180:183], v[200:203], v[32:35]
	v_mfma_f32_16x16x32_bf16 v[20:23], v[172:175], v[208:211], v[20:23]
	v_mfma_f32_16x16x32_bf16 v[16:19], v[180:183], v[208:211], v[16:19]
	v_mfma_f32_16x16x32_bf16 v[4:7], v[172:175], v[216:219], v[4:7]
	v_mfma_f32_16x16x32_bf16 v[0:3], v[180:183], v[216:219], v[0:3]
	s_barrier
	s_add_i32 s79, 0, 0x18000
	s_add_i32 s80, 0, 0x1c000
	v_add_u32_e32 v164, s79, v147
	v_add_u32_e32 v180, s80, v147
	ds_read_b128 v[152:155], v164
	ds_read_b128 v[156:159], v164 offset:1024
	ds_read_b128 v[160:163], v164 offset:2048
	ds_read_b128 v[164:167], v164 offset:3072
	ds_read_b128 v[168:171], v180
	ds_read_b128 v[172:175], v180 offset:1024
	ds_read_b128 v[176:179], v180 offset:2048
	ds_read_b128 v[180:183], v180 offset:3072
	s_add_u32 s42, s42, 0x40000
	s_addc_u32 s43, s43, 0
	s_mov_b32 m0, s65
	ds_read_b128 v[184:187], v151 offset:32768
	ds_read_b128 v[192:195], v151 offset:33792
	ds_read_b128 v[196:199], v151 offset:34816
	ds_read_b128 v[200:203], v151 offset:35840
	ds_read_b128 v[204:207], v151 offset:36864
	ds_read_b128 v[208:211], v151 offset:37888
	ds_read_b128 v[212:215], v151 offset:38912
	ds_read_b128 v[216:219], v151 offset:39936
	global_load_lds_dwordx4 v128, s[42:43]
	s_mov_b32 m0, s66
	s_nop 0
	global_load_lds_dwordx4 v132, s[42:43]
	s_waitcnt vmcnt(8)
	s_waitcnt lgkmcnt(0)
	s_barrier
	s_waitcnt lgkmcnt(0)
	v_mfma_f32_16x16x32_bf16 v[124:127], v[152:155], v[184:187], v[124:127]
	v_mfma_f32_16x16x32_bf16 v[120:123], v[160:163], v[184:187], v[120:123]
	v_mfma_f32_16x16x32_bf16 v[108:111], v[152:155], v[196:199], v[108:111]
	v_mfma_f32_16x16x32_bf16 v[104:107], v[160:163], v[196:199], v[104:107]
	v_mfma_f32_16x16x32_bf16 v[92:95], v[152:155], v[204:207], v[92:95]
	v_mfma_f32_16x16x32_bf16 v[88:91], v[160:163], v[204:207], v[88:91]
	v_mfma_f32_16x16x32_bf16 v[76:79], v[152:155], v[212:215], v[76:79]
	v_mfma_f32_16x16x32_bf16 v[72:75], v[160:163], v[212:215], v[72:75]
	v_mfma_f32_16x16x32_bf16 v[124:127], v[156:159], v[192:195], v[124:127]
	v_mfma_f32_16x16x32_bf16 v[120:123], v[164:167], v[192:195], v[120:123]
	v_mfma_f32_16x16x32_bf16 v[108:111], v[156:159], v[200:203], v[108:111]
	v_mfma_f32_16x16x32_bf16 v[104:107], v[164:167], v[200:203], v[104:107]
	v_mfma_f32_16x16x32_bf16 v[92:95], v[156:159], v[208:211], v[92:95]
	v_mfma_f32_16x16x32_bf16 v[88:91], v[164:167], v[208:211], v[88:91]
	v_mfma_f32_16x16x32_bf16 v[76:79], v[156:159], v[216:219], v[76:79]
	v_mfma_f32_16x16x32_bf16 v[72:75], v[164:167], v[216:219], v[72:75]
	v_mfma_f32_16x16x32_bf16 v[116:119], v[168:171], v[184:187], v[116:119]
	v_mfma_f32_16x16x32_bf16 v[112:115], v[176:179], v[184:187], v[112:115]
	v_mfma_f32_16x16x32_bf16 v[100:103], v[168:171], v[196:199], v[100:103]
	v_mfma_f32_16x16x32_bf16 v[96:99], v[176:179], v[196:199], v[96:99]
	v_mfma_f32_16x16x32_bf16 v[84:87], v[168:171], v[204:207], v[84:87]
	v_mfma_f32_16x16x32_bf16 v[80:83], v[176:179], v[204:207], v[80:83]
	v_mfma_f32_16x16x32_bf16 v[68:71], v[168:171], v[212:215], v[68:71]
	v_mfma_f32_16x16x32_bf16 v[64:67], v[176:179], v[212:215], v[64:67]
	v_mfma_f32_16x16x32_bf16 v[116:119], v[172:175], v[192:195], v[116:119]
	v_mfma_f32_16x16x32_bf16 v[112:115], v[180:183], v[192:195], v[112:115]
	v_mfma_f32_16x16x32_bf16 v[100:103], v[172:175], v[200:203], v[100:103]
	v_mfma_f32_16x16x32_bf16 v[96:99], v[180:183], v[200:203], v[96:99]
	v_mfma_f32_16x16x32_bf16 v[84:87], v[172:175], v[208:211], v[84:87]
	v_mfma_f32_16x16x32_bf16 v[80:83], v[180:183], v[208:211], v[80:83]
	v_mfma_f32_16x16x32_bf16 v[68:71], v[172:175], v[216:219], v[68:71]
	v_mfma_f32_16x16x32_bf16 v[64:67], v[180:183], v[216:219], v[64:67]
	s_barrier
	s_add_i32 s42, s79, s63
	v_lshl_add_u64 v[144:145], v[144:145], 0, s[8:9]
	s_mov_b32 m0, s42
	ds_read_b128 v[184:187], v151 offset:49152
	ds_read_b128 v[192:195], v151 offset:50176
	ds_read_b128 v[196:199], v151 offset:51200
	ds_read_b128 v[200:203], v151 offset:52224
	ds_read_b128 v[204:207], v151 offset:53248
	ds_read_b128 v[208:211], v151 offset:54272
	ds_read_b128 v[212:215], v151 offset:55296
	ds_read_b128 v[216:219], v151 offset:56320
	global_load_lds_dwordx4 v[144:145], off
	s_add_i32 m0, s42, 0x2000
	s_add_u32 s34, s34, 0x40080
	v_lshl_add_u64 v[144:145], v[188:189], 0, s[8:9]
	s_addc_u32 s35, s35, 0
	s_add_i32 s42, s80, s63
	global_load_lds_dwordx4 v[144:145], off
	s_mov_b32 m0, s42
	s_nop 0
	global_load_lds_dwordx4 v130, s[34:35]
	s_add_i32 m0, s42, 0x2000
	s_nop 0
	global_load_lds_dwordx4 v134, s[34:35]
	v_lshl_add_u64 v[144:145], v[220:221], 0, s[8:9]
	s_mov_b32 m0, s52
	s_nop 0
	global_load_lds_dwordx4 v[144:145], off
	v_lshl_add_u64 v[144:145], v[222:223], 0, s[8:9]
	s_mov_b32 m0, s53
	s_nop 0
	global_load_lds_dwordx4 v[144:145], off
	s_waitcnt vmcnt(8)
	s_waitcnt lgkmcnt(0)
	s_barrier
	s_waitcnt lgkmcnt(0)
	v_mfma_f32_16x16x32_bf16 v[60:63], v[152:155], v[184:187], v[60:63]
	v_mfma_f32_16x16x32_bf16 v[56:59], v[160:163], v[184:187], v[56:59]
	v_mfma_f32_16x16x32_bf16 v[44:47], v[152:155], v[196:199], v[44:47]
	v_mfma_f32_16x16x32_bf16 v[40:43], v[160:163], v[196:199], v[40:43]
	v_mfma_f32_16x16x32_bf16 v[28:31], v[152:155], v[204:207], v[28:31]
	v_mfma_f32_16x16x32_bf16 v[24:27], v[160:163], v[204:207], v[24:27]
	v_mfma_f32_16x16x32_bf16 v[12:15], v[152:155], v[212:215], v[12:15]
	v_mfma_f32_16x16x32_bf16 v[8:11], v[160:163], v[212:215], v[8:11]
	v_mfma_f32_16x16x32_bf16 v[60:63], v[156:159], v[192:195], v[60:63]
	v_mfma_f32_16x16x32_bf16 v[56:59], v[164:167], v[192:195], v[56:59]
	v_mfma_f32_16x16x32_bf16 v[44:47], v[156:159], v[200:203], v[44:47]
	v_mfma_f32_16x16x32_bf16 v[40:43], v[164:167], v[200:203], v[40:43]
	v_mfma_f32_16x16x32_bf16 v[28:31], v[156:159], v[208:211], v[28:31]
	v_mfma_f32_16x16x32_bf16 v[24:27], v[164:167], v[208:211], v[24:27]
	v_mfma_f32_16x16x32_bf16 v[12:15], v[156:159], v[216:219], v[12:15]
	v_mfma_f32_16x16x32_bf16 v[8:11], v[164:167], v[216:219], v[8:11]
	v_mfma_f32_16x16x32_bf16 v[52:55], v[168:171], v[184:187], v[52:55]
	v_mfma_f32_16x16x32_bf16 v[48:51], v[176:179], v[184:187], v[48:51]
	v_mfma_f32_16x16x32_bf16 v[36:39], v[168:171], v[196:199], v[36:39]
	v_mfma_f32_16x16x32_bf16 v[32:35], v[176:179], v[196:199], v[32:35]
	v_mfma_f32_16x16x32_bf16 v[20:23], v[168:171], v[204:207], v[20:23]
	v_mfma_f32_16x16x32_bf16 v[16:19], v[176:179], v[204:207], v[16:19]
	v_mfma_f32_16x16x32_bf16 v[4:7], v[168:171], v[212:215], v[4:7]
	v_mfma_f32_16x16x32_bf16 v[0:3], v[176:179], v[212:215], v[0:3]
	v_mfma_f32_16x16x32_bf16 v[52:55], v[172:175], v[192:195], v[52:55]
	v_mfma_f32_16x16x32_bf16 v[48:51], v[180:183], v[192:195], v[48:51]
	v_mfma_f32_16x16x32_bf16 v[36:39], v[172:175], v[200:203], v[36:39]
	v_mfma_f32_16x16x32_bf16 v[32:35], v[180:183], v[200:203], v[32:35]
	v_mfma_f32_16x16x32_bf16 v[20:23], v[172:175], v[208:211], v[20:23]
	v_mfma_f32_16x16x32_bf16 v[16:19], v[180:183], v[208:211], v[16:19]
	v_mfma_f32_16x16x32_bf16 v[4:7], v[172:175], v[216:219], v[4:7]
	v_mfma_f32_16x16x32_bf16 v[0:3], v[180:183], v[216:219], v[0:3]
	s_barrier
	s_add_i32 s77, s77, 2
	s_add_u32 s30, s30, 0x100
	s_addc_u32 s31, s31, 0
	s_add_u32 s75, s75, 0x100
	s_addc_u32 s76, s76, 0
	s_cmp_gt_u32 s77, 13
	s_cbranch_scc0 .LBB0_1571
	s_branch .Lpeel_exit11
.LBB0_1571:
	ds_read_b128 v[152:155], v149
	ds_read_b128 v[156:159], v149 offset:1024
	ds_read_b128 v[160:163], v149 offset:2048
	ds_read_b128 v[164:167], v149 offset:3072
	ds_read_b128 v[168:171], v150
	ds_read_b128 v[172:175], v150 offset:1024
	ds_read_b128 v[176:179], v150 offset:2048
	ds_read_b128 v[180:183], v150 offset:3072
	s_add_u32 s34, s30, 0xfffc0080
	s_addc_u32 s35, s31, -1
	s_cmp_eq_u32 s77, 12
	s_cselect_b32 s43, s23, s35
	s_cselect_b32 s42, s54, s34
	s_cselect_b32 s35, s21, s76
	s_cselect_b32 s34, s55, s75
	s_add_i32 m0, s29, 0xc000
	ds_read_b128 v[184:187], v151
	ds_read_b128 v[192:195], v151 offset:1024
	ds_read_b128 v[196:199], v151 offset:2048
	ds_read_b128 v[200:203], v151 offset:3072
	ds_read_b128 v[204:207], v151 offset:4096
	ds_read_b128 v[208:211], v151 offset:5120
	ds_read_b128 v[212:215], v151 offset:6144
	ds_read_b128 v[216:219], v151 offset:7168
	global_load_lds_dwordx4 v136, s[30:31]
	s_add_i32 m0, s29, 0xe000
	s_nop 0
	global_load_lds_dwordx4 v138, s[30:31]
	s_waitcnt vmcnt(8)
	s_waitcnt lgkmcnt(0)
	s_barrier
	s_waitcnt lgkmcnt(0)
	v_mfma_f32_16x16x32_bf16 v[124:127], v[152:155], v[184:187], v[124:127]
	v_mfma_f32_16x16x32_bf16 v[120:123], v[160:163], v[184:187], v[120:123]
	v_mfma_f32_16x16x32_bf16 v[108:111], v[152:155], v[196:199], v[108:111]
	v_mfma_f32_16x16x32_bf16 v[104:107], v[160:163], v[196:199], v[104:107]
	v_mfma_f32_16x16x32_bf16 v[92:95], v[152:155], v[204:207], v[92:95]
	v_mfma_f32_16x16x32_bf16 v[88:91], v[160:163], v[204:207], v[88:91]
	v_mfma_f32_16x16x32_bf16 v[76:79], v[152:155], v[212:215], v[76:79]
	v_mfma_f32_16x16x32_bf16 v[72:75], v[160:163], v[212:215], v[72:75]
	v_mfma_f32_16x16x32_bf16 v[124:127], v[156:159], v[192:195], v[124:127]
	v_mfma_f32_16x16x32_bf16 v[120:123], v[164:167], v[192:195], v[120:123]
	v_mfma_f32_16x16x32_bf16 v[108:111], v[156:159], v[200:203], v[108:111]
	v_mfma_f32_16x16x32_bf16 v[104:107], v[164:167], v[200:203], v[104:107]
	v_mfma_f32_16x16x32_bf16 v[92:95], v[156:159], v[208:211], v[92:95]
	v_mfma_f32_16x16x32_bf16 v[88:91], v[164:167], v[208:211], v[88:91]
	v_mfma_f32_16x16x32_bf16 v[76:79], v[156:159], v[216:219], v[76:79]
	v_mfma_f32_16x16x32_bf16 v[72:75], v[164:167], v[216:219], v[72:75]
	v_mfma_f32_16x16x32_bf16 v[116:119], v[168:171], v[184:187], v[116:119]
	v_mfma_f32_16x16x32_bf16 v[112:115], v[176:179], v[184:187], v[112:115]
	v_mfma_f32_16x16x32_bf16 v[100:103], v[168:171], v[196:199], v[100:103]
	v_mfma_f32_16x16x32_bf16 v[96:99], v[176:179], v[196:199], v[96:99]
	v_mfma_f32_16x16x32_bf16 v[84:87], v[168:171], v[204:207], v[84:87]
	v_mfma_f32_16x16x32_bf16 v[80:83], v[176:179], v[204:207], v[80:83]
	v_mfma_f32_16x16x32_bf16 v[68:71], v[168:171], v[212:215], v[68:71]
	v_mfma_f32_16x16x32_bf16 v[64:67], v[176:179], v[212:215], v[64:67]
	v_mfma_f32_16x16x32_bf16 v[116:119], v[172:175], v[192:195], v[116:119]
	v_mfma_f32_16x16x32_bf16 v[112:115], v[180:183], v[192:195], v[112:115]
	v_mfma_f32_16x16x32_bf16 v[100:103], v[172:175], v[200:203], v[100:103]
	v_mfma_f32_16x16x32_bf16 v[96:99], v[180:183], v[200:203], v[96:99]
	v_mfma_f32_16x16x32_bf16 v[84:87], v[172:175], v[208:211], v[84:87]
	v_mfma_f32_16x16x32_bf16 v[80:83], v[180:183], v[208:211], v[80:83]
	v_mfma_f32_16x16x32_bf16 v[68:71], v[172:175], v[216:219], v[68:71]
	v_mfma_f32_16x16x32_bf16 v[64:67], v[180:183], v[216:219], v[64:67]
	s_barrier
	s_add_i32 s79, s69, s63
	v_lshl_add_u64 v[144:145], s[34:35], 0, v[130:131]
	s_mov_b32 m0, s79
	ds_read_b128 v[184:187], v151 offset:16384
	ds_read_b128 v[192:195], v151 offset:17408
	ds_read_b128 v[196:199], v151 offset:18432
	ds_read_b128 v[200:203], v151 offset:19456
	ds_read_b128 v[204:207], v151 offset:20480
	ds_read_b128 v[208:211], v151 offset:21504
	ds_read_b128 v[212:215], v151 offset:22528
	ds_read_b128 v[216:219], v151 offset:23552
	global_load_lds_dwordx4 v[144:145], off
	s_add_i32 m0, s79, 0x2000
	s_add_u32 s80, s34, 0x40000
	v_lshl_add_u64 v[188:189], s[34:35], 0, v[134:135]
	s_addc_u32 s81, s35, 0
	s_add_i32 s79, s70, s63
	global_load_lds_dwordx4 v[188:189], off
	s_mov_b32 m0, s79
	v_lshl_add_u64 v[222:223], s[42:43], 0, v[132:133]
	global_load_lds_dwordx4 v130, s[80:81]
	s_add_i32 m0, s79, 0x2000
	s_nop 0
	global_load_lds_dwordx4 v134, s[80:81]
	v_lshl_add_u64 v[220:221], s[42:43], 0, v[128:129]
	s_mov_b32 m0, s29
	s_nop 0
	global_load_lds_dwordx4 v[220:221], off
	s_mov_b32 m0, s64
	s_nop 0
	global_load_lds_dwordx4 v[222:223], off
	s_waitcnt vmcnt(8)
	s_waitcnt lgkmcnt(0)
	s_barrier
	s_waitcnt lgkmcnt(0)
	v_mfma_f32_16x16x32_bf16 v[60:63], v[152:155], v[184:187], v[60:63]
	v_mfma_f32_16x16x32_bf16 v[56:59], v[160:163], v[184:187], v[56:59]
	v_mfma_f32_16x16x32_bf16 v[44:47], v[152:155], v[196:199], v[44:47]
	v_mfma_f32_16x16x32_bf16 v[40:43], v[160:163], v[196:199], v[40:43]
	v_mfma_f32_16x16x32_bf16 v[28:31], v[152:155], v[204:207], v[28:31]
	v_mfma_f32_16x16x32_bf16 v[24:27], v[160:163], v[204:207], v[24:27]
	v_mfma_f32_16x16x32_bf16 v[12:15], v[152:155], v[212:215], v[12:15]
	v_mfma_f32_16x16x32_bf16 v[8:11], v[160:163], v[212:215], v[8:11]
	v_mfma_f32_16x16x32_bf16 v[60:63], v[156:159], v[192:195], v[60:63]
	v_mfma_f32_16x16x32_bf16 v[56:59], v[164:167], v[192:195], v[56:59]
	v_mfma_f32_16x16x32_bf16 v[44:47], v[156:159], v[200:203], v[44:47]
	v_mfma_f32_16x16x32_bf16 v[40:43], v[164:167], v[200:203], v[40:43]
	v_mfma_f32_16x16x32_bf16 v[28:31], v[156:159], v[208:211], v[28:31]
	v_mfma_f32_16x16x32_bf16 v[24:27], v[164:167], v[208:211], v[24:27]
	v_mfma_f32_16x16x32_bf16 v[12:15], v[156:159], v[216:219], v[12:15]
	v_mfma_f32_16x16x32_bf16 v[8:11], v[164:167], v[216:219], v[8:11]
	v_mfma_f32_16x16x32_bf16 v[52:55], v[168:171], v[184:187], v[52:55]
	v_mfma_f32_16x16x32_bf16 v[48:51], v[176:179], v[184:187], v[48:51]
	v_mfma_f32_16x16x32_bf16 v[36:39], v[168:171], v[196:199], v[36:39]
	v_mfma_f32_16x16x32_bf16 v[32:35], v[176:179], v[196:199], v[32:35]
	v_mfma_f32_16x16x32_bf16 v[20:23], v[168:171], v[204:207], v[20:23]
	v_mfma_f32_16x16x32_bf16 v[16:19], v[176:179], v[204:207], v[16:19]
	v_mfma_f32_16x16x32_bf16 v[4:7], v[168:171], v[212:215], v[4:7]
	v_mfma_f32_16x16x32_bf16 v[0:3], v[176:179], v[212:215], v[0:3]
	v_mfma_f32_16x16x32_bf16 v[52:55], v[172:175], v[192:195], v[52:55]
	v_mfma_f32_16x16x32_bf16 v[48:51], v[180:183], v[192:195], v[48:51]
	v_mfma_f32_16x16x32_bf16 v[36:39], v[172:175], v[200:203], v[36:39]
	v_mfma_f32_16x16x32_bf16 v[32:35], v[180:183], v[200:203], v[32:35]
	v_mfma_f32_16x16x32_bf16 v[20:23], v[172:175], v[208:211], v[20:23]
	v_mfma_f32_16x16x32_bf16 v[16:19], v[180:183], v[208:211], v[16:19]
	v_mfma_f32_16x16x32_bf16 v[4:7], v[172:175], v[216:219], v[4:7]
	v_mfma_f32_16x16x32_bf16 v[0:3], v[180:183], v[216:219], v[0:3]
	s_barrier
	s_add_i32 s79, 0, 0x18000
	s_add_i32 s80, 0, 0x1c000
	v_add_u32_e32 v164, s79, v147
	v_add_u32_e32 v180, s80, v147
	ds_read_b128 v[152:155], v164
	ds_read_b128 v[156:159], v164 offset:1024
	ds_read_b128 v[160:163], v164 offset:2048
	ds_read_b128 v[164:167], v164 offset:3072
	ds_read_b128 v[168:171], v180
	ds_read_b128 v[172:175], v180 offset:1024
	ds_read_b128 v[176:179], v180 offset:2048
	ds_read_b128 v[180:183], v180 offset:3072
	s_add_u32 s42, s42, 0x40000
	s_addc_u32 s43, s43, 0
	s_mov_b32 m0, s65
	ds_read_b128 v[184:187], v151 offset:32768
	ds_read_b128 v[192:195], v151 offset:33792
	ds_read_b128 v[196:199], v151 offset:34816
	ds_read_b128 v[200:203], v151 offset:35840
	ds_read_b128 v[204:207], v151 offset:36864
	ds_read_b128 v[208:211], v151 offset:37888
	ds_read_b128 v[212:215], v151 offset:38912
	ds_read_b128 v[216:219], v151 offset:39936
	global_load_lds_dwordx4 v128, s[42:43]
	s_mov_b32 m0, s66
	s_nop 0
	global_load_lds_dwordx4 v132, s[42:43]
	s_waitcnt vmcnt(8)
	s_waitcnt lgkmcnt(0)
	s_barrier
	s_waitcnt lgkmcnt(0)
	v_mfma_f32_16x16x32_bf16 v[124:127], v[152:155], v[184:187], v[124:127]
	v_mfma_f32_16x16x32_bf16 v[120:123], v[160:163], v[184:187], v[120:123]
	v_mfma_f32_16x16x32_bf16 v[108:111], v[152:155], v[196:199], v[108:111]
	v_mfma_f32_16x16x32_bf16 v[104:107], v[160:163], v[196:199], v[104:107]
	v_mfma_f32_16x16x32_bf16 v[92:95], v[152:155], v[204:207], v[92:95]
	v_mfma_f32_16x16x32_bf16 v[88:91], v[160:163], v[204:207], v[88:91]
	v_mfma_f32_16x16x32_bf16 v[76:79], v[152:155], v[212:215], v[76:79]
	v_mfma_f32_16x16x32_bf16 v[72:75], v[160:163], v[212:215], v[72:75]
	v_mfma_f32_16x16x32_bf16 v[124:127], v[156:159], v[192:195], v[124:127]
	v_mfma_f32_16x16x32_bf16 v[120:123], v[164:167], v[192:195], v[120:123]
	v_mfma_f32_16x16x32_bf16 v[108:111], v[156:159], v[200:203], v[108:111]
	v_mfma_f32_16x16x32_bf16 v[104:107], v[164:167], v[200:203], v[104:107]
	v_mfma_f32_16x16x32_bf16 v[92:95], v[156:159], v[208:211], v[92:95]
	v_mfma_f32_16x16x32_bf16 v[88:91], v[164:167], v[208:211], v[88:91]
	v_mfma_f32_16x16x32_bf16 v[76:79], v[156:159], v[216:219], v[76:79]
	v_mfma_f32_16x16x32_bf16 v[72:75], v[164:167], v[216:219], v[72:75]
	v_mfma_f32_16x16x32_bf16 v[116:119], v[168:171], v[184:187], v[116:119]
	v_mfma_f32_16x16x32_bf16 v[112:115], v[176:179], v[184:187], v[112:115]
	v_mfma_f32_16x16x32_bf16 v[100:103], v[168:171], v[196:199], v[100:103]
	v_mfma_f32_16x16x32_bf16 v[96:99], v[176:179], v[196:199], v[96:99]
	v_mfma_f32_16x16x32_bf16 v[84:87], v[168:171], v[204:207], v[84:87]
	v_mfma_f32_16x16x32_bf16 v[80:83], v[176:179], v[204:207], v[80:83]
	v_mfma_f32_16x16x32_bf16 v[68:71], v[168:171], v[212:215], v[68:71]
	v_mfma_f32_16x16x32_bf16 v[64:67], v[176:179], v[212:215], v[64:67]
	v_mfma_f32_16x16x32_bf16 v[116:119], v[172:175], v[192:195], v[116:119]
	v_mfma_f32_16x16x32_bf16 v[112:115], v[180:183], v[192:195], v[112:115]
	v_mfma_f32_16x16x32_bf16 v[100:103], v[172:175], v[200:203], v[100:103]
	v_mfma_f32_16x16x32_bf16 v[96:99], v[180:183], v[200:203], v[96:99]
	v_mfma_f32_16x16x32_bf16 v[84:87], v[172:175], v[208:211], v[84:87]
	v_mfma_f32_16x16x32_bf16 v[80:83], v[180:183], v[208:211], v[80:83]
	v_mfma_f32_16x16x32_bf16 v[68:71], v[172:175], v[216:219], v[68:71]
	v_mfma_f32_16x16x32_bf16 v[64:67], v[180:183], v[216:219], v[64:67]
	s_barrier
	s_add_i32 s42, s79, s63
	v_lshl_add_u64 v[144:145], v[144:145], 0, s[8:9]
	s_mov_b32 m0, s42
	ds_read_b128 v[184:187], v151 offset:49152
	ds_read_b128 v[192:195], v151 offset:50176
	ds_read_b128 v[196:199], v151 offset:51200
	ds_read_b128 v[200:203], v151 offset:52224
	ds_read_b128 v[204:207], v151 offset:53248
	ds_read_b128 v[208:211], v151 offset:54272
	ds_read_b128 v[212:215], v151 offset:55296
	ds_read_b128 v[216:219], v151 offset:56320
	global_load_lds_dwordx4 v[144:145], off
	s_add_i32 m0, s42, 0x2000
	s_add_u32 s34, s34, 0x40080
	v_lshl_add_u64 v[144:145], v[188:189], 0, s[8:9]
	s_addc_u32 s35, s35, 0
	s_add_i32 s42, s80, s63
	global_load_lds_dwordx4 v[144:145], off
	s_mov_b32 m0, s42
	s_nop 0
	global_load_lds_dwordx4 v130, s[34:35]
	s_add_i32 m0, s42, 0x2000
	s_nop 0
	global_load_lds_dwordx4 v134, s[34:35]
	v_lshl_add_u64 v[144:145], v[220:221], 0, s[8:9]
	s_mov_b32 m0, s52
	s_nop 0
	global_load_lds_dwordx4 v[144:145], off
	v_lshl_add_u64 v[144:145], v[222:223], 0, s[8:9]
	s_mov_b32 m0, s53
	s_nop 0
	global_load_lds_dwordx4 v[144:145], off
	s_waitcnt vmcnt(8)
	s_waitcnt lgkmcnt(0)
	s_barrier
	s_waitcnt lgkmcnt(0)
	v_mfma_f32_16x16x32_bf16 v[60:63], v[152:155], v[184:187], v[60:63]
	v_mfma_f32_16x16x32_bf16 v[56:59], v[160:163], v[184:187], v[56:59]
	v_mfma_f32_16x16x32_bf16 v[44:47], v[152:155], v[196:199], v[44:47]
	v_mfma_f32_16x16x32_bf16 v[40:43], v[160:163], v[196:199], v[40:43]
	v_mfma_f32_16x16x32_bf16 v[28:31], v[152:155], v[204:207], v[28:31]
	v_mfma_f32_16x16x32_bf16 v[24:27], v[160:163], v[204:207], v[24:27]
	v_mfma_f32_16x16x32_bf16 v[12:15], v[152:155], v[212:215], v[12:15]
	v_mfma_f32_16x16x32_bf16 v[8:11], v[160:163], v[212:215], v[8:11]
	v_mfma_f32_16x16x32_bf16 v[60:63], v[156:159], v[192:195], v[60:63]
	v_mfma_f32_16x16x32_bf16 v[56:59], v[164:167], v[192:195], v[56:59]
	v_mfma_f32_16x16x32_bf16 v[44:47], v[156:159], v[200:203], v[44:47]
	v_mfma_f32_16x16x32_bf16 v[40:43], v[164:167], v[200:203], v[40:43]
	v_mfma_f32_16x16x32_bf16 v[28:31], v[156:159], v[208:211], v[28:31]
	v_mfma_f32_16x16x32_bf16 v[24:27], v[164:167], v[208:211], v[24:27]
	v_mfma_f32_16x16x32_bf16 v[12:15], v[156:159], v[216:219], v[12:15]
	v_mfma_f32_16x16x32_bf16 v[8:11], v[164:167], v[216:219], v[8:11]
	v_mfma_f32_16x16x32_bf16 v[52:55], v[168:171], v[184:187], v[52:55]
	v_mfma_f32_16x16x32_bf16 v[48:51], v[176:179], v[184:187], v[48:51]
	v_mfma_f32_16x16x32_bf16 v[36:39], v[168:171], v[196:199], v[36:39]
	v_mfma_f32_16x16x32_bf16 v[32:35], v[176:179], v[196:199], v[32:35]
	v_mfma_f32_16x16x32_bf16 v[20:23], v[168:171], v[204:207], v[20:23]
	v_mfma_f32_16x16x32_bf16 v[16:19], v[176:179], v[204:207], v[16:19]
	v_mfma_f32_16x16x32_bf16 v[4:7], v[168:171], v[212:215], v[4:7]
	v_mfma_f32_16x16x32_bf16 v[0:3], v[176:179], v[212:215], v[0:3]
	v_mfma_f32_16x16x32_bf16 v[52:55], v[172:175], v[192:195], v[52:55]
	v_mfma_f32_16x16x32_bf16 v[48:51], v[180:183], v[192:195], v[48:51]
	v_mfma_f32_16x16x32_bf16 v[36:39], v[172:175], v[200:203], v[36:39]
	v_mfma_f32_16x16x32_bf16 v[32:35], v[180:183], v[200:203], v[32:35]
	v_mfma_f32_16x16x32_bf16 v[20:23], v[172:175], v[208:211], v[20:23]
	v_mfma_f32_16x16x32_bf16 v[16:19], v[180:183], v[208:211], v[16:19]
	v_mfma_f32_16x16x32_bf16 v[4:7], v[172:175], v[216:219], v[4:7]
	v_mfma_f32_16x16x32_bf16 v[0:3], v[180:183], v[216:219], v[0:3]
	s_barrier
	s_add_i32 s77, s77, 2
	s_add_u32 s30, s30, 0x100
	s_addc_u32 s31, s31, 0
	s_add_u32 s75, s75, 0x100
	s_addc_u32 s76, s76, 0
	s_cmp_gt_u32 s77, 13
	s_cbranch_scc0 .LBB0_1571

.LBB0_1649:
	s_ashr_i32 s23, s22, 31
	s_lshl_b64 s[24:25], s[22:23], 21
	s_add_u32 s24, s56, s24
	s_addc_u32 s25, s57, s25
	s_and_b64 s[26:27], s[0:1], exec
	s_cselect_b32 s23, s25, s31
	s_cselect_b32 s55, s24, s30
	s_ashr_i32 s21, s20, 31
	s_lshl_b64 s[26:27], s[20:21], 21
	s_add_u32 s26, s53, s26
	s_addc_u32 s27, s58, s27
	s_and_b64 s[42:43], s[0:1], exec
	s_cselect_b32 s21, s27, s35
	s_cselect_b32 s72, s26, s34
	s_add_u32 s30, s30, 0x100080
	s_addc_u32 s31, s31, 0
	s_add_u32 s73, s34, 0x100
	s_addc_u32 s74, s35, 0
	s_mov_b32 s75, -2
	ds_read_b128 v[152:155], v149
	ds_read_b128 v[156:159], v149 offset:1024
	ds_read_b128 v[160:163], v149 offset:2048
	ds_read_b128 v[164:167], v149 offset:3072
	ds_read_b128 v[168:171], v150
	ds_read_b128 v[172:175], v150 offset:1024
	ds_read_b128 v[176:179], v150 offset:2048
	ds_read_b128 v[180:183], v150 offset:3072
	s_add_u32 s34, s30, 0xfff00080
	s_addc_u32 s35, s31, -1
	s_cmp_eq_u32 s75, 60
	s_cselect_b32 s43, s23, s35
	s_cselect_b32 s42, s55, s34
	s_cselect_b32 s35, s21, s74
	s_cselect_b32 s34, s72, s73
	s_add_i32 m0, s29, 0xc000
	ds_read_b128 v[184:187], v151
	ds_read_b128 v[192:195], v151 offset:1024
	ds_read_b128 v[196:199], v151 offset:2048
	ds_read_b128 v[200:203], v151 offset:3072
	ds_read_b128 v[204:207], v151 offset:4096
	ds_read_b128 v[208:211], v151 offset:5120
	ds_read_b128 v[212:215], v151 offset:6144
	ds_read_b128 v[216:219], v151 offset:7168
	global_load_lds_dwordx4 v136, s[30:31]
	s_add_i32 m0, s29, 0xe000
	s_nop 0
	global_load_lds_dwordx4 v138, s[30:31]
	s_waitcnt vmcnt(8)
	s_waitcnt lgkmcnt(0)
	s_barrier
	s_waitcnt lgkmcnt(0)
	v_mfma_f32_16x16x32_bf16 v[124:127], v[152:155], v[184:187], 0
	v_mfma_f32_16x16x32_bf16 v[120:123], v[160:163], v[184:187], 0
	v_mfma_f32_16x16x32_bf16 v[116:119], v[152:155], v[196:199], 0
	v_mfma_f32_16x16x32_bf16 v[108:111], v[160:163], v[196:199], 0
	v_mfma_f32_16x16x32_bf16 v[100:103], v[152:155], v[204:207], 0
	v_mfma_f32_16x16x32_bf16 v[92:95], v[160:163], v[204:207], 0
	v_mfma_f32_16x16x32_bf16 v[84:87], v[152:155], v[212:215], 0
	v_mfma_f32_16x16x32_bf16 v[76:79], v[160:163], v[212:215], 0
	v_mfma_f32_16x16x32_bf16 v[124:127], v[156:159], v[192:195], v[124:127]
	v_mfma_f32_16x16x32_bf16 v[120:123], v[164:167], v[192:195], v[120:123]
	v_mfma_f32_16x16x32_bf16 v[116:119], v[156:159], v[200:203], v[116:119]
	v_mfma_f32_16x16x32_bf16 v[108:111], v[164:167], v[200:203], v[108:111]
	v_mfma_f32_16x16x32_bf16 v[100:103], v[156:159], v[208:211], v[100:103]
	v_mfma_f32_16x16x32_bf16 v[92:95], v[164:167], v[208:211], v[92:95]
	v_mfma_f32_16x16x32_bf16 v[84:87], v[156:159], v[216:219], v[84:87]
	v_mfma_f32_16x16x32_bf16 v[76:79], v[164:167], v[216:219], v[76:79]
	v_mfma_f32_16x16x32_bf16 v[112:115], v[168:171], v[184:187], 0
	v_mfma_f32_16x16x32_bf16 v[104:107], v[176:179], v[184:187], 0
	v_mfma_f32_16x16x32_bf16 v[96:99], v[168:171], v[196:199], 0
	v_mfma_f32_16x16x32_bf16 v[88:91], v[176:179], v[196:199], 0
	v_mfma_f32_16x16x32_bf16 v[80:83], v[168:171], v[204:207], 0
	v_mfma_f32_16x16x32_bf16 v[72:75], v[176:179], v[204:207], 0
	v_mfma_f32_16x16x32_bf16 v[68:71], v[168:171], v[212:215], 0
	v_mfma_f32_16x16x32_bf16 v[64:67], v[176:179], v[212:215], 0
	v_mfma_f32_16x16x32_bf16 v[112:115], v[172:175], v[192:195], v[112:115]
	v_mfma_f32_16x16x32_bf16 v[104:107], v[180:183], v[192:195], v[104:107]
	v_mfma_f32_16x16x32_bf16 v[96:99], v[172:175], v[200:203], v[96:99]
	v_mfma_f32_16x16x32_bf16 v[88:91], v[180:183], v[200:203], v[88:91]
	v_mfma_f32_16x16x32_bf16 v[80:83], v[172:175], v[208:211], v[80:83]
	v_mfma_f32_16x16x32_bf16 v[72:75], v[180:183], v[208:211], v[72:75]
	v_mfma_f32_16x16x32_bf16 v[68:71], v[172:175], v[216:219], v[68:71]
	v_mfma_f32_16x16x32_bf16 v[64:67], v[180:183], v[216:219], v[64:67]
	s_barrier
	s_add_i32 s76, s66, s59
	v_lshl_add_u64 v[144:145], s[34:35], 0, v[130:131]
	s_mov_b32 m0, s76
	ds_read_b128 v[184:187], v151 offset:16384
	ds_read_b128 v[192:195], v151 offset:17408
	ds_read_b128 v[196:199], v151 offset:18432
	ds_read_b128 v[200:203], v151 offset:19456
	ds_read_b128 v[204:207], v151 offset:20480
	ds_read_b128 v[208:211], v151 offset:21504
	ds_read_b128 v[212:215], v151 offset:22528
	ds_read_b128 v[216:219], v151 offset:23552
	global_load_lds_dwordx4 v[144:145], off
	s_add_i32 m0, s76, 0x2000
	s_add_u32 s76, s34, 0x100000
	v_lshl_add_u64 v[188:189], s[34:35], 0, v[134:135]
	s_addc_u32 s77, s35, 0
	s_add_i32 s79, s67, s59
	global_load_lds_dwordx4 v[188:189], off
	s_mov_b32 m0, s79
	v_lshl_add_u64 v[222:223], s[42:43], 0, v[132:133]
	global_load_lds_dwordx4 v130, s[76:77]
	s_add_i32 m0, s79, 0x2000
	s_nop 0
	global_load_lds_dwordx4 v134, s[76:77]
	v_lshl_add_u64 v[220:221], s[42:43], 0, v[128:129]
	s_mov_b32 m0, s29
	s_nop 0
	global_load_lds_dwordx4 v[220:221], off
	s_mov_b32 m0, s33
	s_nop 0
	global_load_lds_dwordx4 v[222:223], off
	s_waitcnt vmcnt(8)
	s_waitcnt lgkmcnt(0)
	s_barrier
	s_waitcnt lgkmcnt(0)
	v_mfma_f32_16x16x32_bf16 v[60:63], v[152:155], v[184:187], 0
	v_mfma_f32_16x16x32_bf16 v[56:59], v[160:163], v[184:187], 0
	v_mfma_f32_16x16x32_bf16 v[52:55], v[152:155], v[196:199], 0
	v_mfma_f32_16x16x32_bf16 v[44:47], v[160:163], v[196:199], 0
	v_mfma_f32_16x16x32_bf16 v[36:39], v[152:155], v[204:207], 0
	v_mfma_f32_16x16x32_bf16 v[28:31], v[160:163], v[204:207], 0
	v_mfma_f32_16x16x32_bf16 v[20:23], v[152:155], v[212:215], 0
	v_mfma_f32_16x16x32_bf16 v[12:15], v[160:163], v[212:215], 0
	v_mfma_f32_16x16x32_bf16 v[60:63], v[156:159], v[192:195], v[60:63]
	v_mfma_f32_16x16x32_bf16 v[56:59], v[164:167], v[192:195], v[56:59]
	v_mfma_f32_16x16x32_bf16 v[52:55], v[156:159], v[200:203], v[52:55]
	v_mfma_f32_16x16x32_bf16 v[44:47], v[164:167], v[200:203], v[44:47]
	v_mfma_f32_16x16x32_bf16 v[36:39], v[156:159], v[208:211], v[36:39]
	v_mfma_f32_16x16x32_bf16 v[28:31], v[164:167], v[208:211], v[28:31]
	v_mfma_f32_16x16x32_bf16 v[20:23], v[156:159], v[216:219], v[20:23]
	v_mfma_f32_16x16x32_bf16 v[12:15], v[164:167], v[216:219], v[12:15]
	v_mfma_f32_16x16x32_bf16 v[48:51], v[168:171], v[184:187], 0
	v_mfma_f32_16x16x32_bf16 v[40:43], v[176:179], v[184:187], 0
	v_mfma_f32_16x16x32_bf16 v[32:35], v[168:171], v[196:199], 0
	v_mfma_f32_16x16x32_bf16 v[24:27], v[176:179], v[196:199], 0
	v_mfma_f32_16x16x32_bf16 v[16:19], v[168:171], v[204:207], 0
	v_mfma_f32_16x16x32_bf16 v[8:11], v[176:179], v[204:207], 0
	v_mfma_f32_16x16x32_bf16 v[4:7], v[168:171], v[212:215], 0
	v_mfma_f32_16x16x32_bf16 v[0:3], v[176:179], v[212:215], 0
	v_mfma_f32_16x16x32_bf16 v[48:51], v[172:175], v[192:195], v[48:51]
	v_mfma_f32_16x16x32_bf16 v[40:43], v[180:183], v[192:195], v[40:43]
	v_mfma_f32_16x16x32_bf16 v[32:35], v[172:175], v[200:203], v[32:35]
	v_mfma_f32_16x16x32_bf16 v[24:27], v[180:183], v[200:203], v[24:27]
	v_mfma_f32_16x16x32_bf16 v[16:19], v[172:175], v[208:211], v[16:19]
	v_mfma_f32_16x16x32_bf16 v[8:11], v[180:183], v[208:211], v[8:11]
	v_mfma_f32_16x16x32_bf16 v[4:7], v[172:175], v[216:219], v[4:7]
	v_mfma_f32_16x16x32_bf16 v[0:3], v[180:183], v[216:219], v[0:3]
	s_barrier
	s_add_i32 s76, 0, 0x18000
	s_add_i32 s77, 0, 0x1c000
	v_add_u32_e32 v164, s76, v147
	v_add_u32_e32 v180, s77, v147
	ds_read_b128 v[152:155], v164
	ds_read_b128 v[156:159], v164 offset:1024
	ds_read_b128 v[160:163], v164 offset:2048
	ds_read_b128 v[164:167], v164 offset:3072
	ds_read_b128 v[168:171], v180
	ds_read_b128 v[172:175], v180 offset:1024
	ds_read_b128 v[176:179], v180 offset:2048
	ds_read_b128 v[180:183], v180 offset:3072
	s_add_u32 s42, s42, 0x100000
	s_addc_u32 s43, s43, 0
	s_mov_b32 m0, s60
	ds_read_b128 v[184:187], v151 offset:32768
	ds_read_b128 v[192:195], v151 offset:33792
	ds_read_b128 v[196:199], v151 offset:34816
	ds_read_b128 v[200:203], v151 offset:35840
	ds_read_b128 v[204:207], v151 offset:36864
	ds_read_b128 v[208:211], v151 offset:37888
	ds_read_b128 v[212:215], v151 offset:38912
	ds_read_b128 v[216:219], v151 offset:39936
	global_load_lds_dwordx4 v128, s[42:43]
	s_mov_b32 m0, s61
	s_nop 0
	global_load_lds_dwordx4 v132, s[42:43]
	s_waitcnt vmcnt(8)
	s_waitcnt lgkmcnt(0)
	s_barrier
	s_waitcnt lgkmcnt(0)
	v_mfma_f32_16x16x32_bf16 v[124:127], v[152:155], v[184:187], v[124:127]
	v_mfma_f32_16x16x32_bf16 v[120:123], v[160:163], v[184:187], v[120:123]
	v_mfma_f32_16x16x32_bf16 v[116:119], v[152:155], v[196:199], v[116:119]
	v_mfma_f32_16x16x32_bf16 v[108:111], v[160:163], v[196:199], v[108:111]
	v_mfma_f32_16x16x32_bf16 v[100:103], v[152:155], v[204:207], v[100:103]
	v_mfma_f32_16x16x32_bf16 v[92:95], v[160:163], v[204:207], v[92:95]
	v_mfma_f32_16x16x32_bf16 v[84:87], v[152:155], v[212:215], v[84:87]
	v_mfma_f32_16x16x32_bf16 v[76:79], v[160:163], v[212:215], v[76:79]
	v_mfma_f32_16x16x32_bf16 v[124:127], v[156:159], v[192:195], v[124:127]
	v_mfma_f32_16x16x32_bf16 v[120:123], v[164:167], v[192:195], v[120:123]
	v_mfma_f32_16x16x32_bf16 v[116:119], v[156:159], v[200:203], v[116:119]
	v_mfma_f32_16x16x32_bf16 v[108:111], v[164:167], v[200:203], v[108:111]
	v_mfma_f32_16x16x32_bf16 v[100:103], v[156:159], v[208:211], v[100:103]
	v_mfma_f32_16x16x32_bf16 v[92:95], v[164:167], v[208:211], v[92:95]
	v_mfma_f32_16x16x32_bf16 v[84:87], v[156:159], v[216:219], v[84:87]
	v_mfma_f32_16x16x32_bf16 v[76:79], v[164:167], v[216:219], v[76:79]
	v_mfma_f32_16x16x32_bf16 v[112:115], v[168:171], v[184:187], v[112:115]
	v_mfma_f32_16x16x32_bf16 v[104:107], v[176:179], v[184:187], v[104:107]
	v_mfma_f32_16x16x32_bf16 v[96:99], v[168:171], v[196:199], v[96:99]
	v_mfma_f32_16x16x32_bf16 v[88:91], v[176:179], v[196:199], v[88:91]
	v_mfma_f32_16x16x32_bf16 v[80:83], v[168:171], v[204:207], v[80:83]
	v_mfma_f32_16x16x32_bf16 v[72:75], v[176:179], v[204:207], v[72:75]
	v_mfma_f32_16x16x32_bf16 v[68:71], v[168:171], v[212:215], v[68:71]
	v_mfma_f32_16x16x32_bf16 v[64:67], v[176:179], v[212:215], v[64:67]
	v_mfma_f32_16x16x32_bf16 v[112:115], v[172:175], v[192:195], v[112:115]
	v_mfma_f32_16x16x32_bf16 v[104:107], v[180:183], v[192:195], v[104:107]
	v_mfma_f32_16x16x32_bf16 v[96:99], v[172:175], v[200:203], v[96:99]
	v_mfma_f32_16x16x32_bf16 v[88:91], v[180:183], v[200:203], v[88:91]
	v_mfma_f32_16x16x32_bf16 v[80:83], v[172:175], v[208:211], v[80:83]
	v_mfma_f32_16x16x32_bf16 v[72:75], v[180:183], v[208:211], v[72:75]
	v_mfma_f32_16x16x32_bf16 v[68:71], v[172:175], v[216:219], v[68:71]
	v_mfma_f32_16x16x32_bf16 v[64:67], v[180:183], v[216:219], v[64:67]
	s_barrier
	s_add_i32 s42, s76, s59
	v_lshl_add_u64 v[144:145], v[144:145], 0, s[8:9]
	s_mov_b32 m0, s42
	ds_read_b128 v[184:187], v151 offset:49152
	ds_read_b128 v[192:195], v151 offset:50176
	ds_read_b128 v[196:199], v151 offset:51200
	ds_read_b128 v[200:203], v151 offset:52224
	ds_read_b128 v[204:207], v151 offset:53248
	ds_read_b128 v[208:211], v151 offset:54272
	ds_read_b128 v[212:215], v151 offset:55296
	ds_read_b128 v[216:219], v151 offset:56320
	global_load_lds_dwordx4 v[144:145], off
	s_add_i32 m0, s42, 0x2000
	s_add_u32 s34, s34, 0x100080
	v_lshl_add_u64 v[144:145], v[188:189], 0, s[8:9]
	s_addc_u32 s35, s35, 0
	s_add_i32 s42, s77, s59
	global_load_lds_dwordx4 v[144:145], off
	s_mov_b32 m0, s42
	s_nop 0
	global_load_lds_dwordx4 v130, s[34:35]
	s_add_i32 m0, s42, 0x2000
	s_nop 0
	global_load_lds_dwordx4 v134, s[34:35]
	v_lshl_add_u64 v[144:145], v[220:221], 0, s[8:9]
	s_mov_b32 m0, s63
	s_nop 0
	global_load_lds_dwordx4 v[144:145], off
	v_lshl_add_u64 v[144:145], v[222:223], 0, s[8:9]
	s_mov_b32 m0, s64
	s_nop 0
	global_load_lds_dwordx4 v[144:145], off
	s_waitcnt vmcnt(8)
	s_waitcnt lgkmcnt(0)
	s_barrier
	s_waitcnt lgkmcnt(0)
	v_mfma_f32_16x16x32_bf16 v[60:63], v[152:155], v[184:187], v[60:63]
	v_mfma_f32_16x16x32_bf16 v[56:59], v[160:163], v[184:187], v[56:59]
	v_mfma_f32_16x16x32_bf16 v[52:55], v[152:155], v[196:199], v[52:55]
	v_mfma_f32_16x16x32_bf16 v[44:47], v[160:163], v[196:199], v[44:47]
	v_mfma_f32_16x16x32_bf16 v[36:39], v[152:155], v[204:207], v[36:39]
	v_mfma_f32_16x16x32_bf16 v[28:31], v[160:163], v[204:207], v[28:31]
	v_mfma_f32_16x16x32_bf16 v[20:23], v[152:155], v[212:215], v[20:23]
	v_mfma_f32_16x16x32_bf16 v[12:15], v[160:163], v[212:215], v[12:15]
	v_mfma_f32_16x16x32_bf16 v[60:63], v[156:159], v[192:195], v[60:63]
	v_mfma_f32_16x16x32_bf16 v[56:59], v[164:167], v[192:195], v[56:59]
	v_mfma_f32_16x16x32_bf16 v[52:55], v[156:159], v[200:203], v[52:55]
	v_mfma_f32_16x16x32_bf16 v[44:47], v[164:167], v[200:203], v[44:47]
	v_mfma_f32_16x16x32_bf16 v[36:39], v[156:159], v[208:211], v[36:39]
	v_mfma_f32_16x16x32_bf16 v[28:31], v[164:167], v[208:211], v[28:31]
	v_mfma_f32_16x16x32_bf16 v[20:23], v[156:159], v[216:219], v[20:23]
	v_mfma_f32_16x16x32_bf16 v[12:15], v[164:167], v[216:219], v[12:15]
	v_mfma_f32_16x16x32_bf16 v[48:51], v[168:171], v[184:187], v[48:51]
	v_mfma_f32_16x16x32_bf16 v[40:43], v[176:179], v[184:187], v[40:43]
	v_mfma_f32_16x16x32_bf16 v[32:35], v[168:171], v[196:199], v[32:35]
	v_mfma_f32_16x16x32_bf16 v[24:27], v[176:179], v[196:199], v[24:27]
	v_mfma_f32_16x16x32_bf16 v[16:19], v[168:171], v[204:207], v[16:19]
	v_mfma_f32_16x16x32_bf16 v[8:11], v[176:179], v[204:207], v[8:11]
	v_mfma_f32_16x16x32_bf16 v[4:7], v[168:171], v[212:215], v[4:7]
	v_mfma_f32_16x16x32_bf16 v[0:3], v[176:179], v[212:215], v[0:3]
	v_mfma_f32_16x16x32_bf16 v[48:51], v[172:175], v[192:195], v[48:51]
	v_mfma_f32_16x16x32_bf16 v[40:43], v[180:183], v[192:195], v[40:43]
	v_mfma_f32_16x16x32_bf16 v[32:35], v[172:175], v[200:203], v[32:35]
	v_mfma_f32_16x16x32_bf16 v[24:27], v[180:183], v[200:203], v[24:27]
	v_mfma_f32_16x16x32_bf16 v[16:19], v[172:175], v[208:211], v[16:19]
	v_mfma_f32_16x16x32_bf16 v[8:11], v[180:183], v[208:211], v[8:11]
	v_mfma_f32_16x16x32_bf16 v[4:7], v[172:175], v[216:219], v[4:7]
	v_mfma_f32_16x16x32_bf16 v[0:3], v[180:183], v[216:219], v[0:3]
	s_barrier
	s_add_i32 s75, s75, 2
	s_add_u32 s30, s30, 0x100
	s_addc_u32 s31, s31, 0
	s_add_u32 s73, s73, 0x100
	s_addc_u32 s74, s74, 0
	s_cmp_gt_u32 s75, 61
	s_cbranch_scc0 .LBB0_1650
	s_branch .Lpeel_exit12
.LBB0_1650:
	ds_read_b128 v[152:155], v149
	ds_read_b128 v[156:159], v149 offset:1024
	ds_read_b128 v[160:163], v149 offset:2048
	ds_read_b128 v[164:167], v149 offset:3072
	ds_read_b128 v[168:171], v150
	ds_read_b128 v[172:175], v150 offset:1024
	ds_read_b128 v[176:179], v150 offset:2048
	ds_read_b128 v[180:183], v150 offset:3072
	s_add_u32 s34, s30, 0xfff00080
	s_addc_u32 s35, s31, -1
	s_cmp_eq_u32 s75, 60
	s_cselect_b32 s43, s23, s35
	s_cselect_b32 s42, s55, s34
	s_cselect_b32 s35, s21, s74
	s_cselect_b32 s34, s72, s73
	s_add_i32 m0, s29, 0xc000
	ds_read_b128 v[184:187], v151
	ds_read_b128 v[192:195], v151 offset:1024
	ds_read_b128 v[196:199], v151 offset:2048
	ds_read_b128 v[200:203], v151 offset:3072
	ds_read_b128 v[204:207], v151 offset:4096
	ds_read_b128 v[208:211], v151 offset:5120
	ds_read_b128 v[212:215], v151 offset:6144
	ds_read_b128 v[216:219], v151 offset:7168
	global_load_lds_dwordx4 v136, s[30:31]
	s_add_i32 m0, s29, 0xe000
	s_nop 0
	global_load_lds_dwordx4 v138, s[30:31]
	s_waitcnt vmcnt(8)
	s_waitcnt lgkmcnt(0)
	s_barrier
	s_waitcnt lgkmcnt(0)
	v_mfma_f32_16x16x32_bf16 v[124:127], v[152:155], v[184:187], v[124:127]
	v_mfma_f32_16x16x32_bf16 v[120:123], v[160:163], v[184:187], v[120:123]
	v_mfma_f32_16x16x32_bf16 v[116:119], v[152:155], v[196:199], v[116:119]
	v_mfma_f32_16x16x32_bf16 v[108:111], v[160:163], v[196:199], v[108:111]
	v_mfma_f32_16x16x32_bf16 v[100:103], v[152:155], v[204:207], v[100:103]
	v_mfma_f32_16x16x32_bf16 v[92:95], v[160:163], v[204:207], v[92:95]
	v_mfma_f32_16x16x32_bf16 v[84:87], v[152:155], v[212:215], v[84:87]
	v_mfma_f32_16x16x32_bf16 v[76:79], v[160:163], v[212:215], v[76:79]
	v_mfma_f32_16x16x32_bf16 v[124:127], v[156:159], v[192:195], v[124:127]
	v_mfma_f32_16x16x32_bf16 v[120:123], v[164:167], v[192:195], v[120:123]
	v_mfma_f32_16x16x32_bf16 v[116:119], v[156:159], v[200:203], v[116:119]
	v_mfma_f32_16x16x32_bf16 v[108:111], v[164:167], v[200:203], v[108:111]
	v_mfma_f32_16x16x32_bf16 v[100:103], v[156:159], v[208:211], v[100:103]
	v_mfma_f32_16x16x32_bf16 v[92:95], v[164:167], v[208:211], v[92:95]
	v_mfma_f32_16x16x32_bf16 v[84:87], v[156:159], v[216:219], v[84:87]
	v_mfma_f32_16x16x32_bf16 v[76:79], v[164:167], v[216:219], v[76:79]
	v_mfma_f32_16x16x32_bf16 v[112:115], v[168:171], v[184:187], v[112:115]
	v_mfma_f32_16x16x32_bf16 v[104:107], v[176:179], v[184:187], v[104:107]
	v_mfma_f32_16x16x32_bf16 v[96:99], v[168:171], v[196:199], v[96:99]
	v_mfma_f32_16x16x32_bf16 v[88:91], v[176:179], v[196:199], v[88:91]
	v_mfma_f32_16x16x32_bf16 v[80:83], v[168:171], v[204:207], v[80:83]
	v_mfma_f32_16x16x32_bf16 v[72:75], v[176:179], v[204:207], v[72:75]
	v_mfma_f32_16x16x32_bf16 v[68:71], v[168:171], v[212:215], v[68:71]
	v_mfma_f32_16x16x32_bf16 v[64:67], v[176:179], v[212:215], v[64:67]
	v_mfma_f32_16x16x32_bf16 v[112:115], v[172:175], v[192:195], v[112:115]
	v_mfma_f32_16x16x32_bf16 v[104:107], v[180:183], v[192:195], v[104:107]
	v_mfma_f32_16x16x32_bf16 v[96:99], v[172:175], v[200:203], v[96:99]
	v_mfma_f32_16x16x32_bf16 v[88:91], v[180:183], v[200:203], v[88:91]
	v_mfma_f32_16x16x32_bf16 v[80:83], v[172:175], v[208:211], v[80:83]
	v_mfma_f32_16x16x32_bf16 v[72:75], v[180:183], v[208:211], v[72:75]
	v_mfma_f32_16x16x32_bf16 v[68:71], v[172:175], v[216:219], v[68:71]
	v_mfma_f32_16x16x32_bf16 v[64:67], v[180:183], v[216:219], v[64:67]
	s_barrier
	s_add_i32 s76, s66, s59
	v_lshl_add_u64 v[144:145], s[34:35], 0, v[130:131]
	s_mov_b32 m0, s76
	ds_read_b128 v[184:187], v151 offset:16384
	ds_read_b128 v[192:195], v151 offset:17408
	ds_read_b128 v[196:199], v151 offset:18432
	ds_read_b128 v[200:203], v151 offset:19456
	ds_read_b128 v[204:207], v151 offset:20480
	ds_read_b128 v[208:211], v151 offset:21504
	ds_read_b128 v[212:215], v151 offset:22528
	ds_read_b128 v[216:219], v151 offset:23552
	global_load_lds_dwordx4 v[144:145], off
	s_add_i32 m0, s76, 0x2000
	s_add_u32 s76, s34, 0x100000
	v_lshl_add_u64 v[188:189], s[34:35], 0, v[134:135]
	s_addc_u32 s77, s35, 0
	s_add_i32 s79, s67, s59
	global_load_lds_dwordx4 v[188:189], off
	s_mov_b32 m0, s79
	v_lshl_add_u64 v[222:223], s[42:43], 0, v[132:133]
	global_load_lds_dwordx4 v130, s[76:77]
	s_add_i32 m0, s79, 0x2000
	s_nop 0
	global_load_lds_dwordx4 v134, s[76:77]
	v_lshl_add_u64 v[220:221], s[42:43], 0, v[128:129]
	s_mov_b32 m0, s29
	s_nop 0
	global_load_lds_dwordx4 v[220:221], off
	s_mov_b32 m0, s33
	s_nop 0
	global_load_lds_dwordx4 v[222:223], off
	s_waitcnt vmcnt(8)
	s_waitcnt lgkmcnt(0)
	s_barrier
	s_waitcnt lgkmcnt(0)
	v_mfma_f32_16x16x32_bf16 v[60:63], v[152:155], v[184:187], v[60:63]
	v_mfma_f32_16x16x32_bf16 v[56:59], v[160:163], v[184:187], v[56:59]
	v_mfma_f32_16x16x32_bf16 v[52:55], v[152:155], v[196:199], v[52:55]
	v_mfma_f32_16x16x32_bf16 v[44:47], v[160:163], v[196:199], v[44:47]
	v_mfma_f32_16x16x32_bf16 v[36:39], v[152:155], v[204:207], v[36:39]
	v_mfma_f32_16x16x32_bf16 v[28:31], v[160:163], v[204:207], v[28:31]
	v_mfma_f32_16x16x32_bf16 v[20:23], v[152:155], v[212:215], v[20:23]
	v_mfma_f32_16x16x32_bf16 v[12:15], v[160:163], v[212:215], v[12:15]
	v_mfma_f32_16x16x32_bf16 v[60:63], v[156:159], v[192:195], v[60:63]
	v_mfma_f32_16x16x32_bf16 v[56:59], v[164:167], v[192:195], v[56:59]
	v_mfma_f32_16x16x32_bf16 v[52:55], v[156:159], v[200:203], v[52:55]
	v_mfma_f32_16x16x32_bf16 v[44:47], v[164:167], v[200:203], v[44:47]
	v_mfma_f32_16x16x32_bf16 v[36:39], v[156:159], v[208:211], v[36:39]
	v_mfma_f32_16x16x32_bf16 v[28:31], v[164:167], v[208:211], v[28:31]
	v_mfma_f32_16x16x32_bf16 v[20:23], v[156:159], v[216:219], v[20:23]
	v_mfma_f32_16x16x32_bf16 v[12:15], v[164:167], v[216:219], v[12:15]
	v_mfma_f32_16x16x32_bf16 v[48:51], v[168:171], v[184:187], v[48:51]
	v_mfma_f32_16x16x32_bf16 v[40:43], v[176:179], v[184:187], v[40:43]
	v_mfma_f32_16x16x32_bf16 v[32:35], v[168:171], v[196:199], v[32:35]
	v_mfma_f32_16x16x32_bf16 v[24:27], v[176:179], v[196:199], v[24:27]
	v_mfma_f32_16x16x32_bf16 v[16:19], v[168:171], v[204:207], v[16:19]
	v_mfma_f32_16x16x32_bf16 v[8:11], v[176:179], v[204:207], v[8:11]
	v_mfma_f32_16x16x32_bf16 v[4:7], v[168:171], v[212:215], v[4:7]
	v_mfma_f32_16x16x32_bf16 v[0:3], v[176:179], v[212:215], v[0:3]
	v_mfma_f32_16x16x32_bf16 v[48:51], v[172:175], v[192:195], v[48:51]
	v_mfma_f32_16x16x32_bf16 v[40:43], v[180:183], v[192:195], v[40:43]
	v_mfma_f32_16x16x32_bf16 v[32:35], v[172:175], v[200:203], v[32:35]
	v_mfma_f32_16x16x32_bf16 v[24:27], v[180:183], v[200:203], v[24:27]
	v_mfma_f32_16x16x32_bf16 v[16:19], v[172:175], v[208:211], v[16:19]
	v_mfma_f32_16x16x32_bf16 v[8:11], v[180:183], v[208:211], v[8:11]
	v_mfma_f32_16x16x32_bf16 v[4:7], v[172:175], v[216:219], v[4:7]
	v_mfma_f32_16x16x32_bf16 v[0:3], v[180:183], v[216:219], v[0:3]
	s_barrier
	s_add_i32 s76, 0, 0x18000
	s_add_i32 s77, 0, 0x1c000
	v_add_u32_e32 v164, s76, v147
	v_add_u32_e32 v180, s77, v147
	ds_read_b128 v[152:155], v164
	ds_read_b128 v[156:159], v164 offset:1024
	ds_read_b128 v[160:163], v164 offset:2048
	ds_read_b128 v[164:167], v164 offset:3072
	ds_read_b128 v[168:171], v180
	ds_read_b128 v[172:175], v180 offset:1024
	ds_read_b128 v[176:179], v180 offset:2048
	ds_read_b128 v[180:183], v180 offset:3072
	s_add_u32 s42, s42, 0x100000
	s_addc_u32 s43, s43, 0
	s_mov_b32 m0, s60
	ds_read_b128 v[184:187], v151 offset:32768
	ds_read_b128 v[192:195], v151 offset:33792
	ds_read_b128 v[196:199], v151 offset:34816
	ds_read_b128 v[200:203], v151 offset:35840
	ds_read_b128 v[204:207], v151 offset:36864
	ds_read_b128 v[208:211], v151 offset:37888
	ds_read_b128 v[212:215], v151 offset:38912
	ds_read_b128 v[216:219], v151 offset:39936
	global_load_lds_dwordx4 v128, s[42:43]
	s_mov_b32 m0, s61
	s_nop 0
	global_load_lds_dwordx4 v132, s[42:43]
	s_waitcnt vmcnt(8)
	s_waitcnt lgkmcnt(0)
	s_barrier
	s_waitcnt lgkmcnt(0)
	v_mfma_f32_16x16x32_bf16 v[124:127], v[152:155], v[184:187], v[124:127]
	v_mfma_f32_16x16x32_bf16 v[120:123], v[160:163], v[184:187], v[120:123]
	v_mfma_f32_16x16x32_bf16 v[116:119], v[152:155], v[196:199], v[116:119]
	v_mfma_f32_16x16x32_bf16 v[108:111], v[160:163], v[196:199], v[108:111]
	v_mfma_f32_16x16x32_bf16 v[100:103], v[152:155], v[204:207], v[100:103]
	v_mfma_f32_16x16x32_bf16 v[92:95], v[160:163], v[204:207], v[92:95]
	v_mfma_f32_16x16x32_bf16 v[84:87], v[152:155], v[212:215], v[84:87]
	v_mfma_f32_16x16x32_bf16 v[76:79], v[160:163], v[212:215], v[76:79]
	v_mfma_f32_16x16x32_bf16 v[124:127], v[156:159], v[192:195], v[124:127]
	v_mfma_f32_16x16x32_bf16 v[120:123], v[164:167], v[192:195], v[120:123]
	v_mfma_f32_16x16x32_bf16 v[116:119], v[156:159], v[200:203], v[116:119]
	v_mfma_f32_16x16x32_bf16 v[108:111], v[164:167], v[200:203], v[108:111]
	v_mfma_f32_16x16x32_bf16 v[100:103], v[156:159], v[208:211], v[100:103]
	v_mfma_f32_16x16x32_bf16 v[92:95], v[164:167], v[208:211], v[92:95]
	v_mfma_f32_16x16x32_bf16 v[84:87], v[156:159], v[216:219], v[84:87]
	v_mfma_f32_16x16x32_bf16 v[76:79], v[164:167], v[216:219], v[76:79]
	v_mfma_f32_16x16x32_bf16 v[112:115], v[168:171], v[184:187], v[112:115]
	v_mfma_f32_16x16x32_bf16 v[104:107], v[176:179], v[184:187], v[104:107]
	v_mfma_f32_16x16x32_bf16 v[96:99], v[168:171], v[196:199], v[96:99]
	v_mfma_f32_16x16x32_bf16 v[88:91], v[176:179], v[196:199], v[88:91]
	v_mfma_f32_16x16x32_bf16 v[80:83], v[168:171], v[204:207], v[80:83]
	v_mfma_f32_16x16x32_bf16 v[72:75], v[176:179], v[204:207], v[72:75]
	v_mfma_f32_16x16x32_bf16 v[68:71], v[168:171], v[212:215], v[68:71]
	v_mfma_f32_16x16x32_bf16 v[64:67], v[176:179], v[212:215], v[64:67]
	v_mfma_f32_16x16x32_bf16 v[112:115], v[172:175], v[192:195], v[112:115]
	v_mfma_f32_16x16x32_bf16 v[104:107], v[180:183], v[192:195], v[104:107]
	v_mfma_f32_16x16x32_bf16 v[96:99], v[172:175], v[200:203], v[96:99]
	v_mfma_f32_16x16x32_bf16 v[88:91], v[180:183], v[200:203], v[88:91]
	v_mfma_f32_16x16x32_bf16 v[80:83], v[172:175], v[208:211], v[80:83]
	v_mfma_f32_16x16x32_bf16 v[72:75], v[180:183], v[208:211], v[72:75]
	v_mfma_f32_16x16x32_bf16 v[68:71], v[172:175], v[216:219], v[68:71]
	v_mfma_f32_16x16x32_bf16 v[64:67], v[180:183], v[216:219], v[64:67]
	s_barrier
	s_add_i32 s42, s76, s59
	v_lshl_add_u64 v[144:145], v[144:145], 0, s[8:9]
	s_mov_b32 m0, s42
	ds_read_b128 v[184:187], v151 offset:49152
	ds_read_b128 v[192:195], v151 offset:50176
	ds_read_b128 v[196:199], v151 offset:51200
	ds_read_b128 v[200:203], v151 offset:52224
	ds_read_b128 v[204:207], v151 offset:53248
	ds_read_b128 v[208:211], v151 offset:54272
	ds_read_b128 v[212:215], v151 offset:55296
	ds_read_b128 v[216:219], v151 offset:56320
	global_load_lds_dwordx4 v[144:145], off
	s_add_i32 m0, s42, 0x2000
	s_add_u32 s34, s34, 0x100080
	v_lshl_add_u64 v[144:145], v[188:189], 0, s[8:9]
	s_addc_u32 s35, s35, 0
	s_add_i32 s42, s77, s59
	global_load_lds_dwordx4 v[144:145], off
	s_mov_b32 m0, s42
	s_nop 0
	global_load_lds_dwordx4 v130, s[34:35]
	s_add_i32 m0, s42, 0x2000
	s_nop 0
	global_load_lds_dwordx4 v134, s[34:35]
	v_lshl_add_u64 v[144:145], v[220:221], 0, s[8:9]
	s_mov_b32 m0, s63
	s_nop 0
	global_load_lds_dwordx4 v[144:145], off
	v_lshl_add_u64 v[144:145], v[222:223], 0, s[8:9]
	s_mov_b32 m0, s64
	s_nop 0
	global_load_lds_dwordx4 v[144:145], off
	s_waitcnt vmcnt(8)
	s_waitcnt lgkmcnt(0)
	s_barrier
	s_waitcnt lgkmcnt(0)
	v_mfma_f32_16x16x32_bf16 v[60:63], v[152:155], v[184:187], v[60:63]
	v_mfma_f32_16x16x32_bf16 v[56:59], v[160:163], v[184:187], v[56:59]
	v_mfma_f32_16x16x32_bf16 v[52:55], v[152:155], v[196:199], v[52:55]
	v_mfma_f32_16x16x32_bf16 v[44:47], v[160:163], v[196:199], v[44:47]
	v_mfma_f32_16x16x32_bf16 v[36:39], v[152:155], v[204:207], v[36:39]
	v_mfma_f32_16x16x32_bf16 v[28:31], v[160:163], v[204:207], v[28:31]
	v_mfma_f32_16x16x32_bf16 v[20:23], v[152:155], v[212:215], v[20:23]
	v_mfma_f32_16x16x32_bf16 v[12:15], v[160:163], v[212:215], v[12:15]
	v_mfma_f32_16x16x32_bf16 v[60:63], v[156:159], v[192:195], v[60:63]
	v_mfma_f32_16x16x32_bf16 v[56:59], v[164:167], v[192:195], v[56:59]
	v_mfma_f32_16x16x32_bf16 v[52:55], v[156:159], v[200:203], v[52:55]
	v_mfma_f32_16x16x32_bf16 v[44:47], v[164:167], v[200:203], v[44:47]
	v_mfma_f32_16x16x32_bf16 v[36:39], v[156:159], v[208:211], v[36:39]
	v_mfma_f32_16x16x32_bf16 v[28:31], v[164:167], v[208:211], v[28:31]
	v_mfma_f32_16x16x32_bf16 v[20:23], v[156:159], v[216:219], v[20:23]
	v_mfma_f32_16x16x32_bf16 v[12:15], v[164:167], v[216:219], v[12:15]
	v_mfma_f32_16x16x32_bf16 v[48:51], v[168:171], v[184:187], v[48:51]
	v_mfma_f32_16x16x32_bf16 v[40:43], v[176:179], v[184:187], v[40:43]
	v_mfma_f32_16x16x32_bf16 v[32:35], v[168:171], v[196:199], v[32:35]
	v_mfma_f32_16x16x32_bf16 v[24:27], v[176:179], v[196:199], v[24:27]
	v_mfma_f32_16x16x32_bf16 v[16:19], v[168:171], v[204:207], v[16:19]
	v_mfma_f32_16x16x32_bf16 v[8:11], v[176:179], v[204:207], v[8:11]
	v_mfma_f32_16x16x32_bf16 v[4:7], v[168:171], v[212:215], v[4:7]
	v_mfma_f32_16x16x32_bf16 v[0:3], v[176:179], v[212:215], v[0:3]
	v_mfma_f32_16x16x32_bf16 v[48:51], v[172:175], v[192:195], v[48:51]
	v_mfma_f32_16x16x32_bf16 v[40:43], v[180:183], v[192:195], v[40:43]
	v_mfma_f32_16x16x32_bf16 v[32:35], v[172:175], v[200:203], v[32:35]
	v_mfma_f32_16x16x32_bf16 v[24:27], v[180:183], v[200:203], v[24:27]
	v_mfma_f32_16x16x32_bf16 v[16:19], v[172:175], v[208:211], v[16:19]
	v_mfma_f32_16x16x32_bf16 v[8:11], v[180:183], v[208:211], v[8:11]
	v_mfma_f32_16x16x32_bf16 v[4:7], v[172:175], v[216:219], v[4:7]
	v_mfma_f32_16x16x32_bf16 v[0:3], v[180:183], v[216:219], v[0:3]
	s_barrier
	s_add_i32 s75, s75, 2
	s_add_u32 s30, s30, 0x100
	s_addc_u32 s31, s31, 0
	s_add_u32 s73, s73, 0x100
	s_addc_u32 s74, s74, 0
	s_cmp_gt_u32 s75, 61
	s_cbranch_scc0 .LBB0_1650
